# A/B (6.3 rule 2): hipcc's per-phase s_setprio flips deleted from the 14 GEMM k-loops
# speedup vs baseline: 1.0125x; 1.0125x over previous
; #define PG8_STAGE(bufoff, gbase, voff) do { _Pragma("unroll") for (int _i = 0; _i < 2; ++_i) \
;         __builtin_amdgcn_global_load_lds((const unsigned*)((const char*)(gbase) + (voff)[_i]), (LAS unsigned*)(lds + (bufoff) + ldsw + _i * 8192), 16, 0, 0); } while (0)
; #define PG8_LDA(dst, b, h) do { _Pragma("unroll") for (int m = 0; m < 4; ++m) _Pragma("unroll") for (int k = 0; k < 2; ++k) dst[m][k] = *(const LAS bf16x8*)(lds + PG8_SA(b, h) + aoff + m * 2048 + k * 1024); } while (0)
; #define PG8_LDB(dst, b, h) do { _Pragma("unroll") for (int n = 0; n < 2; ++n) _Pragma("unroll") for (int k = 0; k < 2; ++k) dst[n][k] = *(const LAS bf16x8*)(lds + PG8_SB(b, h) + boff + n * 2048 + k * 1024); } while (0)
; #define PG8_MMA(ai, bj, At, Bt) do { __builtin_amdgcn_s_setprio(1); _Pragma("unroll") for (int m = 0; m < 4; ++m) _Pragma("unroll") for (int n = 0; n < 2; ++n) _Pragma("unroll") for (int k = 0; k < 2; ++k) \
;         acc[ai][bj][m][n] = __builtin_amdgcn_mfma_f32_16x16x32_bf16(Bt[n][k], At[m][k], acc[ai][bj][m][n], 0, 0, 0); __builtin_amdgcn_s_setprio(0); } while (0)
; #define PG8_WAIT_V(n) asm volatile("s_waitcnt vmcnt(" #n ")" ::: "memory")
; #define PG8_WAIT_L(n) asm volatile("s_waitcnt lgkmcnt(" #n ")" ::: "memory")
; #define PG8_BAR __builtin_amdgcn_s_barrier()
; #define PG8_SCHED __builtin_amdgcn_sched_barrier(0)
; template <class Epi, bool ALIGN_EPI = PG8_ALIGN>
; __device__ __forceinline__ void gemm_phase(LAS unsigned char* lds, const Gemm g, const StaticOrder S, const Epi E) {
;     ...
;             PG8_LDB(B0, 0, 0); PG8_LDB(B1, 0, 1); PG8_SCHED; PG8_LDA(At, 0, 0); PG8_STAGE(PG8_SA(1, 1), a1 + hstepA, voffA);
;             PG8_WAIT_V(8); PG8_WAIT_L(0); PG8_BAR; PG8_MMA(0, 0, At, B0); PG8_MMA(0, 1, At, B1); PG8_BAR; PG8_SCHED;
;             PG8_LDA(At, 0, 1); PG8_STAGE(PG8_SB(0, 0), b2, voffB); PG8_STAGE(PG8_SB(0, 1), b2 + hstepB, voffB); PG8_STAGE(PG8_SA(0, 0), a2, voffA);
;             PG8_WAIT_V(8); PG8_WAIT_L(0); PG8_BAR; PG8_MMA(1, 0, At, B0); PG8_MMA(1, 1, At, B1); PG8_BAR; PG8_SCHED;
;             PG8_LDB(B0, 1, 0); PG8_LDB(B1, 1, 1); PG8_SCHED; PG8_LDA(At, 1, 0); PG8_STAGE(PG8_SA(0, 1), a2 + hstepA, voffA);
;             PG8_WAIT_V(8); PG8_WAIT_L(0); PG8_BAR; PG8_MMA(0, 0, At, B0); PG8_MMA(0, 1, At, B1); PG8_BAR; PG8_SCHED;
.LBB0_335:
	ds_read_b128 v[150:153], v147
	ds_read_b128 v[154:157], v147 offset:1024
	ds_read_b128 v[158:161], v147 offset:2048
	ds_read_b128 v[162:165], v147 offset:3072
	ds_read_b128 v[166:169], v148
	ds_read_b128 v[170:173], v148 offset:1024
	ds_read_b128 v[174:177], v148 offset:2048
	ds_read_b128 v[178:181], v148 offset:3072
	s_add_u32 s58, s50, 0xfff80080
	s_addc_u32 s59, s51, -1
	s_cmp_eq_u32 s74, 28
	s_cselect_b32 s61, s14, s59
	s_cselect_b32 s60, s35, s58
	s_cselect_b32 s59, s11, s73
	s_cselect_b32 s58, s43, s72
	v_lshl_add_u64 v[182:183], s[50:51], 0, v[136:137]
	s_add_i32 m0, s65, 0xc000
	ds_read_b128 v[186:189], v149
	ds_read_b128 v[190:193], v149 offset:1024
	ds_read_b128 v[194:197], v149 offset:2048
	ds_read_b128 v[198:201], v149 offset:3072
	ds_read_b128 v[202:205], v149 offset:4096
	ds_read_b128 v[206:209], v149 offset:5120
	ds_read_b128 v[210:213], v149 offset:6144
	ds_read_b128 v[214:217], v149 offset:7168
	global_load_lds_dwordx4 v[182:183], off
	v_lshl_add_u64 v[182:183], s[50:51], 0, v[138:139]
	s_add_i32 m0, s65, 0xe000
	s_nop 0
	global_load_lds_dwordx4 v[182:183], off
	s_waitcnt vmcnt(8)
	s_waitcnt lgkmcnt(0)
	s_barrier
	s_waitcnt lgkmcnt(0)
	v_mfma_f32_16x16x32_bf16 v[124:127], v[150:153], v[186:189], v[124:127]
	v_mfma_f32_16x16x32_bf16 v[116:119], v[158:161], v[186:189], v[116:119]
	v_mfma_f32_16x16x32_bf16 v[108:111], v[150:153], v[194:197], v[108:111]
	v_mfma_f32_16x16x32_bf16 v[100:103], v[158:161], v[194:197], v[100:103]
	v_mfma_f32_16x16x32_bf16 v[92:95], v[150:153], v[202:205], v[92:95]
	v_mfma_f32_16x16x32_bf16 v[84:87], v[158:161], v[202:205], v[84:87]
	v_mfma_f32_16x16x32_bf16 v[76:79], v[150:153], v[210:213], v[76:79]
	v_mfma_f32_16x16x32_bf16 v[68:71], v[158:161], v[210:213], v[68:71]
	v_mfma_f32_16x16x32_bf16 v[124:127], v[154:157], v[190:193], v[124:127]
	v_mfma_f32_16x16x32_bf16 v[116:119], v[162:165], v[190:193], v[116:119]
	v_mfma_f32_16x16x32_bf16 v[108:111], v[154:157], v[198:201], v[108:111]
	v_mfma_f32_16x16x32_bf16 v[100:103], v[162:165], v[198:201], v[100:103]
	v_mfma_f32_16x16x32_bf16 v[92:95], v[154:157], v[206:209], v[92:95]
	v_mfma_f32_16x16x32_bf16 v[84:87], v[162:165], v[206:209], v[84:87]
	v_mfma_f32_16x16x32_bf16 v[76:79], v[154:157], v[214:217], v[76:79]
	v_mfma_f32_16x16x32_bf16 v[68:71], v[162:165], v[214:217], v[68:71]
	v_mfma_f32_16x16x32_bf16 v[120:123], v[166:169], v[186:189], v[120:123]
	v_mfma_f32_16x16x32_bf16 v[112:115], v[174:177], v[186:189], v[112:115]
	v_mfma_f32_16x16x32_bf16 v[104:107], v[166:169], v[194:197], v[104:107]
	v_mfma_f32_16x16x32_bf16 v[96:99], v[174:177], v[194:197], v[96:99]
	v_mfma_f32_16x16x32_bf16 v[88:91], v[166:169], v[202:205], v[88:91]
	v_mfma_f32_16x16x32_bf16 v[80:83], v[174:177], v[202:205], v[80:83]
	v_mfma_f32_16x16x32_bf16 v[72:75], v[166:169], v[210:213], v[72:75]
	v_mfma_f32_16x16x32_bf16 v[64:67], v[174:177], v[210:213], v[64:67]
	v_mfma_f32_16x16x32_bf16 v[120:123], v[170:173], v[190:193], v[120:123]
	v_mfma_f32_16x16x32_bf16 v[112:115], v[178:181], v[190:193], v[112:115]
	v_mfma_f32_16x16x32_bf16 v[104:107], v[170:173], v[198:201], v[104:107]
	v_mfma_f32_16x16x32_bf16 v[96:99], v[178:181], v[198:201], v[96:99]
	v_mfma_f32_16x16x32_bf16 v[88:91], v[170:173], v[206:209], v[88:91]
	v_mfma_f32_16x16x32_bf16 v[80:83], v[178:181], v[206:209], v[80:83]
	v_mfma_f32_16x16x32_bf16 v[72:75], v[170:173], v[214:217], v[72:75]
	v_mfma_f32_16x16x32_bf16 v[64:67], v[178:181], v[214:217], v[64:67]
	s_barrier
	s_add_i32 s75, s17, s62
	v_lshl_add_u64 v[182:183], s[58:59], 0, v[132:133]
	s_mov_b32 m0, s75
	ds_read_b128 v[186:189], v149 offset:16384
	ds_read_b128 v[190:193], v149 offset:17408
	ds_read_b128 v[194:197], v149 offset:18432
	ds_read_b128 v[198:201], v149 offset:19456
	ds_read_b128 v[202:205], v149 offset:20480
	ds_read_b128 v[206:209], v149 offset:21504
	ds_read_b128 v[210:213], v149 offset:22528
	ds_read_b128 v[214:217], v149 offset:23552
	global_load_lds_dwordx4 v[182:183], off
	s_add_i32 m0, s75, 0x2000
	s_add_u32 s76, s58, 0x80000
	v_lshl_add_u64 v[218:219], s[58:59], 0, v[128:129]
	s_addc_u32 s77, s59, 0
	s_add_i32 s75, s33, s62
	global_load_lds_dwordx4 v[218:219], off
	v_lshl_add_u64 v[220:221], s[76:77], 0, v[132:133]
	s_mov_b32 m0, s75
	v_lshl_add_u64 v[222:223], s[60:61], 0, v[130:131]
	global_load_lds_dwordx4 v[220:221], off
	v_lshl_add_u64 v[220:221], s[76:77], 0, v[128:129]
	s_add_i32 m0, s75, 0x2000
	s_nop 0
	global_load_lds_dwordx4 v[220:221], off
	v_lshl_add_u64 v[220:221], s[60:61], 0, v[134:135]
	s_mov_b32 m0, s65
	s_nop 0
	global_load_lds_dwordx4 v[220:221], off
	s_mov_b32 m0, s66
	s_nop 0
	global_load_lds_dwordx4 v[222:223], off
	s_waitcnt vmcnt(8)
	s_waitcnt lgkmcnt(0)
	s_barrier
; #define PG8_STAGE(bufoff, gbase, voff) do { _Pragma("unroll") for (int _i = 0; _i < 2; ++_i) \
;         __builtin_amdgcn_global_load_lds((const unsigned*)((const char*)(gbase) + (voff)[_i]), (LAS unsigned*)(lds + (bufoff) + ldsw + _i * 8192), 16, 0, 0); } while (0)
; #define PG8_LDA(dst, b, h) do { _Pragma("unroll") for (int m = 0; m < 4; ++m) _Pragma("unroll") for (int k = 0; k < 2; ++k) dst[m][k] = *(const LAS bf16x8*)(lds + PG8_SA(b, h) + aoff + m * 2048 + k * 1024); } while (0)
; #define PG8_LDB(dst, b, h) do { _Pragma("unroll") for (int n = 0; n < 2; ++n) _Pragma("unroll") for (int k = 0; k < 2; ++k) dst[n][k] = *(const LAS bf16x8*)(lds + PG8_SB(b, h) + boff + n * 2048 + k * 1024); } while (0)
; #define PG8_MMA(ai, bj, At, Bt) do { __builtin_amdgcn_s_setprio(1); _Pragma("unroll") for (int m = 0; m < 4; ++m) _Pragma("unroll") for (int n = 0; n < 2; ++n) _Pragma("unroll") for (int k = 0; k < 2; ++k) \
;         acc[ai][bj][m][n] = __builtin_amdgcn_mfma_f32_16x16x32_bf16(Bt[n][k], At[m][k], acc[ai][bj][m][n], 0, 0, 0); __builtin_amdgcn_s_setprio(0); } while (0)
; #define PG8_WAIT_V(n) asm volatile("s_waitcnt vmcnt(" #n ")" ::: "memory")
; #define PG8_WAIT_L(n) asm volatile("s_waitcnt lgkmcnt(" #n ")" ::: "memory")
; #define PG8_BAR __builtin_amdgcn_s_barrier()
; #define PG8_SCHED __builtin_amdgcn_sched_barrier(0)
; template <class Epi, bool ALIGN_EPI = PG8_ALIGN>
; __device__ __forceinline__ void gemm_phase(LAS unsigned char* lds, const Gemm g, const StaticOrder S, const Epi E) {
;     ...
;             PG8_WAIT_V(8); PG8_WAIT_L(0); PG8_BAR; PG8_MMA(1, 0, At, B0); PG8_MMA(1, 1, At, B1); PG8_BAR; PG8_SCHED;
;             PG8_LDB(B0, 1, 0); PG8_LDB(B1, 1, 1); PG8_SCHED; PG8_LDA(At, 1, 0); PG8_STAGE(PG8_SA(0, 1), a2 + hstepA, voffA);
;             PG8_WAIT_V(8); PG8_WAIT_L(0); PG8_BAR; PG8_MMA(0, 0, At, B0); PG8_MMA(0, 1, At, B1); PG8_BAR; PG8_SCHED;
;             PG8_LDA(At, 1, 1); PG8_STAGE(PG8_SB(1, 0), b3, voffB); PG8_STAGE(PG8_SB(1, 1), b3 + hstepB, voffB); PG8_STAGE(PG8_SA(1, 0), a3, voffA);
;             PG8_WAIT_V(8); PG8_WAIT_L(0); PG8_BAR; PG8_MMA(1, 0, At, B0); PG8_MMA(1, 1, At, B1); PG8_BAR; PG8_SCHED;
	s_waitcnt lgkmcnt(0)
	v_mfma_f32_16x16x32_bf16 v[60:63], v[150:153], v[186:189], v[60:63]
	v_mfma_f32_16x16x32_bf16 v[52:55], v[158:161], v[186:189], v[52:55]
	v_mfma_f32_16x16x32_bf16 v[44:47], v[150:153], v[194:197], v[44:47]
	v_mfma_f32_16x16x32_bf16 v[36:39], v[158:161], v[194:197], v[36:39]
	v_mfma_f32_16x16x32_bf16 v[28:31], v[150:153], v[202:205], v[28:31]
	v_mfma_f32_16x16x32_bf16 v[20:23], v[158:161], v[202:205], v[20:23]
	v_mfma_f32_16x16x32_bf16 v[12:15], v[150:153], v[210:213], v[12:15]
	v_mfma_f32_16x16x32_bf16 v[4:7], v[158:161], v[210:213], v[4:7]
	v_mfma_f32_16x16x32_bf16 v[60:63], v[154:157], v[190:193], v[60:63]
	v_mfma_f32_16x16x32_bf16 v[52:55], v[162:165], v[190:193], v[52:55]
	v_mfma_f32_16x16x32_bf16 v[44:47], v[154:157], v[198:201], v[44:47]
	v_mfma_f32_16x16x32_bf16 v[36:39], v[162:165], v[198:201], v[36:39]
	v_mfma_f32_16x16x32_bf16 v[28:31], v[154:157], v[206:209], v[28:31]
	v_mfma_f32_16x16x32_bf16 v[20:23], v[162:165], v[206:209], v[20:23]
	v_mfma_f32_16x16x32_bf16 v[12:15], v[154:157], v[214:217], v[12:15]
	v_mfma_f32_16x16x32_bf16 v[4:7], v[162:165], v[214:217], v[4:7]
	v_mfma_f32_16x16x32_bf16 v[56:59], v[166:169], v[186:189], v[56:59]
	v_mfma_f32_16x16x32_bf16 v[48:51], v[174:177], v[186:189], v[48:51]
	v_mfma_f32_16x16x32_bf16 v[40:43], v[166:169], v[194:197], v[40:43]
	v_mfma_f32_16x16x32_bf16 v[32:35], v[174:177], v[194:197], v[32:35]
	v_mfma_f32_16x16x32_bf16 v[24:27], v[166:169], v[202:205], v[24:27]
	v_mfma_f32_16x16x32_bf16 v[16:19], v[174:177], v[202:205], v[16:19]
	v_mfma_f32_16x16x32_bf16 v[8:11], v[166:169], v[210:213], v[8:11]
	v_mfma_f32_16x16x32_bf16 v[0:3], v[174:177], v[210:213], v[0:3]
	v_mfma_f32_16x16x32_bf16 v[56:59], v[170:173], v[190:193], v[56:59]
	v_mfma_f32_16x16x32_bf16 v[48:51], v[178:181], v[190:193], v[48:51]
	v_mfma_f32_16x16x32_bf16 v[40:43], v[170:173], v[198:201], v[40:43]
	v_mfma_f32_16x16x32_bf16 v[32:35], v[178:181], v[198:201], v[32:35]
	v_mfma_f32_16x16x32_bf16 v[24:27], v[170:173], v[206:209], v[24:27]
	v_mfma_f32_16x16x32_bf16 v[16:19], v[178:181], v[206:209], v[16:19]
	v_mfma_f32_16x16x32_bf16 v[8:11], v[170:173], v[214:217], v[8:11]
	v_mfma_f32_16x16x32_bf16 v[0:3], v[178:181], v[214:217], v[0:3]
	s_barrier
	s_add_i32 s75, 0, 0x18000
	s_add_i32 s76, 0, 0x1c000
	v_add_u32_e32 v162, s75, v145
	v_add_u32_e32 v178, s76, v145
	ds_read_b128 v[150:153], v162
	ds_read_b128 v[154:157], v162 offset:1024
	ds_read_b128 v[158:161], v162 offset:2048
	ds_read_b128 v[162:165], v162 offset:3072
	ds_read_b128 v[166:169], v178
	ds_read_b128 v[170:173], v178 offset:1024
	ds_read_b128 v[174:177], v178 offset:2048
	ds_read_b128 v[178:181], v178 offset:3072
	s_add_u32 s60, s60, 0x80000
	s_addc_u32 s61, s61, 0
	s_mov_b32 m0, s67
	v_lshl_add_u64 v[224:225], s[60:61], 0, v[134:135]
	ds_read_b128 v[186:189], v149 offset:32768
	ds_read_b128 v[190:193], v149 offset:33792
	ds_read_b128 v[194:197], v149 offset:34816
	ds_read_b128 v[198:201], v149 offset:35840
	ds_read_b128 v[202:205], v149 offset:36864
	ds_read_b128 v[206:209], v149 offset:37888
	ds_read_b128 v[210:213], v149 offset:38912
	ds_read_b128 v[214:217], v149 offset:39936
	global_load_lds_dwordx4 v[224:225], off
	v_lshl_add_u64 v[224:225], s[60:61], 0, v[130:131]
	s_mov_b32 m0, s68
	s_nop 0
	global_load_lds_dwordx4 v[224:225], off
	s_waitcnt vmcnt(8)
	s_waitcnt lgkmcnt(0)
	s_barrier
	s_waitcnt lgkmcnt(0)
	v_mfma_f32_16x16x32_bf16 v[124:127], v[150:153], v[186:189], v[124:127]
	v_mfma_f32_16x16x32_bf16 v[116:119], v[158:161], v[186:189], v[116:119]
	v_mfma_f32_16x16x32_bf16 v[108:111], v[150:153], v[194:197], v[108:111]
	v_mfma_f32_16x16x32_bf16 v[100:103], v[158:161], v[194:197], v[100:103]
	v_mfma_f32_16x16x32_bf16 v[92:95], v[150:153], v[202:205], v[92:95]
	v_mfma_f32_16x16x32_bf16 v[84:87], v[158:161], v[202:205], v[84:87]
	v_mfma_f32_16x16x32_bf16 v[76:79], v[150:153], v[210:213], v[76:79]
	v_mfma_f32_16x16x32_bf16 v[68:71], v[158:161], v[210:213], v[68:71]
	v_mfma_f32_16x16x32_bf16 v[124:127], v[154:157], v[190:193], v[124:127]
	v_mfma_f32_16x16x32_bf16 v[116:119], v[162:165], v[190:193], v[116:119]
	v_mfma_f32_16x16x32_bf16 v[108:111], v[154:157], v[198:201], v[108:111]
	v_mfma_f32_16x16x32_bf16 v[100:103], v[162:165], v[198:201], v[100:103]
	v_mfma_f32_16x16x32_bf16 v[92:95], v[154:157], v[206:209], v[92:95]
	v_mfma_f32_16x16x32_bf16 v[84:87], v[162:165], v[206:209], v[84:87]
	v_mfma_f32_16x16x32_bf16 v[76:79], v[154:157], v[214:217], v[76:79]
	v_mfma_f32_16x16x32_bf16 v[68:71], v[162:165], v[214:217], v[68:71]
	v_mfma_f32_16x16x32_bf16 v[120:123], v[166:169], v[186:189], v[120:123]
	v_mfma_f32_16x16x32_bf16 v[112:115], v[174:177], v[186:189], v[112:115]
	v_mfma_f32_16x16x32_bf16 v[104:107], v[166:169], v[194:197], v[104:107]
	v_mfma_f32_16x16x32_bf16 v[96:99], v[174:177], v[194:197], v[96:99]
	v_mfma_f32_16x16x32_bf16 v[88:91], v[166:169], v[202:205], v[88:91]
	v_mfma_f32_16x16x32_bf16 v[80:83], v[174:177], v[202:205], v[80:83]
	v_mfma_f32_16x16x32_bf16 v[72:75], v[166:169], v[210:213], v[72:75]
	v_mfma_f32_16x16x32_bf16 v[64:67], v[174:177], v[210:213], v[64:67]
	v_mfma_f32_16x16x32_bf16 v[120:123], v[170:173], v[190:193], v[120:123]
	v_mfma_f32_16x16x32_bf16 v[112:115], v[178:181], v[190:193], v[112:115]
	v_mfma_f32_16x16x32_bf16 v[104:107], v[170:173], v[198:201], v[104:107]
	v_mfma_f32_16x16x32_bf16 v[96:99], v[178:181], v[198:201], v[96:99]
	v_mfma_f32_16x16x32_bf16 v[88:91], v[170:173], v[206:209], v[88:91]
	v_mfma_f32_16x16x32_bf16 v[80:83], v[178:181], v[206:209], v[80:83]
	v_mfma_f32_16x16x32_bf16 v[72:75], v[170:173], v[214:217], v[72:75]
	v_mfma_f32_16x16x32_bf16 v[64:67], v[178:181], v[214:217], v[64:67]
	s_barrier
; #define PG8_STAGE(bufoff, gbase, voff) do { _Pragma("unroll") for (int _i = 0; _i < 2; ++_i) \
;         __builtin_amdgcn_global_load_lds((const unsigned*)((const char*)(gbase) + (voff)[_i]), (LAS unsigned*)(lds + (bufoff) + ldsw + _i * 8192), 16, 0, 0); } while (0)
; #define PG8_LDA(dst, b, h) do { _Pragma("unroll") for (int m = 0; m < 4; ++m) _Pragma("unroll") for (int k = 0; k < 2; ++k) dst[m][k] = *(const LAS bf16x8*)(lds + PG8_SA(b, h) + aoff + m * 2048 + k * 1024); } while (0)
; #define PG8_MMA(ai, bj, At, Bt) do { __builtin_amdgcn_s_setprio(1); _Pragma("unroll") for (int m = 0; m < 4; ++m) _Pragma("unroll") for (int n = 0; n < 2; ++n) _Pragma("unroll") for (int k = 0; k < 2; ++k) \
;         acc[ai][bj][m][n] = __builtin_amdgcn_mfma_f32_16x16x32_bf16(Bt[n][k], At[m][k], acc[ai][bj][m][n], 0, 0, 0); __builtin_amdgcn_s_setprio(0); } while (0)
; #define PG8_WAIT_V(n) asm volatile("s_waitcnt vmcnt(" #n ")" ::: "memory")
; #define PG8_WAIT_L(n) asm volatile("s_waitcnt lgkmcnt(" #n ")" ::: "memory")
; #define PG8_BAR __builtin_amdgcn_s_barrier()
; #define PG8_SCHED __builtin_amdgcn_sched_barrier(0)
; template <class Epi, bool ALIGN_EPI = PG8_ALIGN>
; __device__ __forceinline__ void gemm_phase(LAS unsigned char* lds, const Gemm g, const StaticOrder S, const Epi E) {
;     ...
;             PG8_LDA(At, 1, 1); PG8_STAGE(PG8_SB(1, 0), b3, voffB); PG8_STAGE(PG8_SB(1, 1), b3 + hstepB, voffB); PG8_STAGE(PG8_SA(1, 0), a3, voffA);
;             PG8_WAIT_V(8); PG8_WAIT_L(0); PG8_BAR; PG8_MMA(1, 0, At, B0); PG8_MMA(1, 1, At, B1); PG8_BAR; PG8_SCHED;
;         }
;         if (ALIGN_EPI) { if (wr == 0) PG8_BAR; }
	s_add_i32 s60, s75, s62
	v_lshl_add_u64 v[182:183], v[182:183], 0, s[6:7]
	s_mov_b32 m0, s60
	ds_read_b128 v[186:189], v149 offset:49152
	ds_read_b128 v[190:193], v149 offset:50176
	ds_read_b128 v[194:197], v149 offset:51200
	ds_read_b128 v[198:201], v149 offset:52224
	ds_read_b128 v[202:205], v149 offset:53248
	ds_read_b128 v[206:209], v149 offset:54272
	ds_read_b128 v[210:213], v149 offset:55296
	ds_read_b128 v[214:217], v149 offset:56320
	global_load_lds_dwordx4 v[182:183], off
	s_add_i32 m0, s60, 0x2000
	s_add_u32 s58, s58, 0x80080
	v_lshl_add_u64 v[182:183], v[218:219], 0, s[6:7]
	s_addc_u32 s59, s59, 0
	s_add_i32 s60, s76, s62
	global_load_lds_dwordx4 v[182:183], off
	v_lshl_add_u64 v[182:183], s[58:59], 0, v[132:133]
	s_mov_b32 m0, s60
	s_nop 0
	global_load_lds_dwordx4 v[182:183], off
	v_lshl_add_u64 v[182:183], s[58:59], 0, v[128:129]
	s_add_i32 m0, s60, 0x2000
	s_nop 0
	global_load_lds_dwordx4 v[182:183], off
	v_lshl_add_u64 v[182:183], v[220:221], 0, s[6:7]
	s_mov_b32 m0, s70
	s_nop 0
	global_load_lds_dwordx4 v[182:183], off
	v_lshl_add_u64 v[182:183], v[222:223], 0, s[6:7]
	s_mov_b32 m0, s71
	s_nop 0
	global_load_lds_dwordx4 v[182:183], off
	s_waitcnt vmcnt(8)
	s_waitcnt lgkmcnt(0)
	s_barrier
	s_waitcnt lgkmcnt(0)
	v_mfma_f32_16x16x32_bf16 v[60:63], v[150:153], v[186:189], v[60:63]
	v_mfma_f32_16x16x32_bf16 v[52:55], v[158:161], v[186:189], v[52:55]
	v_mfma_f32_16x16x32_bf16 v[44:47], v[150:153], v[194:197], v[44:47]
	v_mfma_f32_16x16x32_bf16 v[36:39], v[158:161], v[194:197], v[36:39]
	v_mfma_f32_16x16x32_bf16 v[28:31], v[150:153], v[202:205], v[28:31]
	v_mfma_f32_16x16x32_bf16 v[20:23], v[158:161], v[202:205], v[20:23]
	v_mfma_f32_16x16x32_bf16 v[12:15], v[150:153], v[210:213], v[12:15]
	v_mfma_f32_16x16x32_bf16 v[4:7], v[158:161], v[210:213], v[4:7]
	v_mfma_f32_16x16x32_bf16 v[60:63], v[154:157], v[190:193], v[60:63]
	v_mfma_f32_16x16x32_bf16 v[52:55], v[162:165], v[190:193], v[52:55]
	v_mfma_f32_16x16x32_bf16 v[44:47], v[154:157], v[198:201], v[44:47]
	v_mfma_f32_16x16x32_bf16 v[36:39], v[162:165], v[198:201], v[36:39]
	v_mfma_f32_16x16x32_bf16 v[28:31], v[154:157], v[206:209], v[28:31]
	v_mfma_f32_16x16x32_bf16 v[20:23], v[162:165], v[206:209], v[20:23]
	v_mfma_f32_16x16x32_bf16 v[12:15], v[154:157], v[214:217], v[12:15]
	v_mfma_f32_16x16x32_bf16 v[4:7], v[162:165], v[214:217], v[4:7]
	v_mfma_f32_16x16x32_bf16 v[56:59], v[166:169], v[186:189], v[56:59]
	v_mfma_f32_16x16x32_bf16 v[48:51], v[174:177], v[186:189], v[48:51]
	v_mfma_f32_16x16x32_bf16 v[40:43], v[166:169], v[194:197], v[40:43]
	v_mfma_f32_16x16x32_bf16 v[32:35], v[174:177], v[194:197], v[32:35]
	v_mfma_f32_16x16x32_bf16 v[24:27], v[166:169], v[202:205], v[24:27]
	v_mfma_f32_16x16x32_bf16 v[16:19], v[174:177], v[202:205], v[16:19]
	v_mfma_f32_16x16x32_bf16 v[8:11], v[166:169], v[210:213], v[8:11]
	v_mfma_f32_16x16x32_bf16 v[0:3], v[174:177], v[210:213], v[0:3]
	v_mfma_f32_16x16x32_bf16 v[56:59], v[170:173], v[190:193], v[56:59]
	v_mfma_f32_16x16x32_bf16 v[48:51], v[178:181], v[190:193], v[48:51]
	v_mfma_f32_16x16x32_bf16 v[40:43], v[170:173], v[198:201], v[40:43]
	v_mfma_f32_16x16x32_bf16 v[32:35], v[178:181], v[198:201], v[32:35]
	v_mfma_f32_16x16x32_bf16 v[24:27], v[170:173], v[206:209], v[24:27]
	v_mfma_f32_16x16x32_bf16 v[16:19], v[178:181], v[206:209], v[16:19]
	v_mfma_f32_16x16x32_bf16 v[8:11], v[170:173], v[214:217], v[8:11]
	v_mfma_f32_16x16x32_bf16 v[0:3], v[178:181], v[214:217], v[0:3]
	s_barrier
	s_add_i32 s74, s74, 2
	s_add_u32 s50, s50, 0x100
	s_addc_u32 s51, s51, 0
	s_add_u32 s72, s72, 0x100
	s_addc_u32 s73, s73, 0
	s_cmp_gt_u32 s74, 29
	s_cbranch_scc0 .LBB0_335
	s_and_b64 vcc, exec, s[8:9]
	s_cbranch_vccz .LBB0_338
	s_barrier

; #define PG8_STAGE(bufoff, gbase, voff) do { _Pragma("unroll") for (int _i = 0; _i < 2; ++_i) \
;         __builtin_amdgcn_global_load_lds((const unsigned*)((const char*)(gbase) + (voff)[_i]), (LAS unsigned*)(lds + (bufoff) + ldsw + _i * 8192), 16, 0, 0); } while (0)
; #define PG8_LDA(dst, b, h) do { _Pragma("unroll") for (int m = 0; m < 4; ++m) _Pragma("unroll") for (int k = 0; k < 2; ++k) dst[m][k] = *(const LAS bf16x8*)(lds + PG8_SA(b, h) + aoff + m * 2048 + k * 1024); } while (0)
; #define PG8_LDB(dst, b, h) do { _Pragma("unroll") for (int n = 0; n < 2; ++n) _Pragma("unroll") for (int k = 0; k < 2; ++k) dst[n][k] = *(const LAS bf16x8*)(lds + PG8_SB(b, h) + boff + n * 2048 + k * 1024); } while (0)
; #define PG8_MMA(ai, bj, At, Bt) do { __builtin_amdgcn_s_setprio(1); _Pragma("unroll") for (int m = 0; m < 4; ++m) _Pragma("unroll") for (int n = 0; n < 2; ++n) _Pragma("unroll") for (int k = 0; k < 2; ++k) \
;         acc[ai][bj][m][n] = __builtin_amdgcn_mfma_f32_16x16x32_bf16(Bt[n][k], At[m][k], acc[ai][bj][m][n], 0, 0, 0); __builtin_amdgcn_s_setprio(0); } while (0)
; #define PG8_WAIT_V(n) asm volatile("s_waitcnt vmcnt(" #n ")" ::: "memory")
; #define PG8_WAIT_L(n) asm volatile("s_waitcnt lgkmcnt(" #n ")" ::: "memory")
; #define PG8_BAR __builtin_amdgcn_s_barrier()
; #define PG8_SCHED __builtin_amdgcn_sched_barrier(0)
; template <class Epi, bool ALIGN_EPI = PG8_ALIGN>
; __device__ __forceinline__ void gemm_phase(LAS unsigned char* lds, const Gemm g, const StaticOrder S, const Epi E) {
;     ...
;         for (int t = 0; t < nt; t += 2) {
;             const bool last = (t == nt - 2);
;             const char* a1 = cA + (size_t)(t + 1) * kstep;
;             const char* a2 = last ? nA : cA + (size_t)(t + 2) * kstep; const char* b2 = last ? nB : cB + (size_t)(t + 2) * kstep;
;             const char* a3 = a2 + kstep; const char* b3 = b2 + kstep;
;             PG8_LDB(B0, 0, 0); PG8_LDB(B1, 0, 1); PG8_SCHED; PG8_LDA(At, 0, 0); PG8_STAGE(PG8_SA(1, 1), a1 + hstepA, voffA);
;             PG8_WAIT_V(8); PG8_WAIT_L(0); PG8_BAR; PG8_MMA(0, 0, At, B0); PG8_MMA(0, 1, At, B1); PG8_BAR; PG8_SCHED;
;             PG8_LDA(At, 0, 1); PG8_STAGE(PG8_SB(0, 0), b2, voffB); PG8_STAGE(PG8_SB(0, 1), b2 + hstepB, voffB); PG8_STAGE(PG8_SA(0, 0), a2, voffA);
;             PG8_WAIT_V(8); PG8_WAIT_L(0); PG8_BAR; PG8_MMA(1, 0, At, B0); PG8_MMA(1, 1, At, B1); PG8_BAR; PG8_SCHED;
.LBB0_420:
	ds_read_b128 v[146:149], v151
	ds_read_b128 v[154:157], v151 offset:1024
	ds_read_b128 v[158:161], v151 offset:2048
	ds_read_b128 v[162:165], v151 offset:3072
	ds_read_b128 v[166:169], v152
	ds_read_b128 v[170:173], v152 offset:1024
	ds_read_b128 v[174:177], v152 offset:2048
	ds_read_b128 v[178:181], v152 offset:3072
	s_add_u32 s35, s12, 0xffea0080
	s_addc_u32 s48, s13, -1
	s_cmpk_eq_i32 s34, 0x54
	s_cselect_b32 s51, s1, s48
	s_cselect_b32 s50, s0, s35
	s_cselect_b32 s49, s47, s33
	s_cselect_b32 s48, s46, s17
	v_lshl_add_u64 v[182:183], s[12:13], 0, v[138:139]
	s_add_i32 m0, s59, 0xc000
	ds_read_b128 v[186:189], v153
	ds_read_b128 v[190:193], v153 offset:1024
	ds_read_b128 v[194:197], v153 offset:2048
	ds_read_b128 v[198:201], v153 offset:3072
	ds_read_b128 v[202:205], v153 offset:4096
	ds_read_b128 v[206:209], v153 offset:5120
	ds_read_b128 v[210:213], v153 offset:6144
	ds_read_b128 v[214:217], v153 offset:7168
	global_load_lds_dwordx4 v[182:183], off
	v_lshl_add_u64 v[182:183], s[12:13], 0, v[140:141]
	s_add_i32 m0, s59, 0xe000
	s_nop 0
	global_load_lds_dwordx4 v[182:183], off
	s_waitcnt vmcnt(8)
	s_waitcnt lgkmcnt(0)
	s_barrier
	s_waitcnt lgkmcnt(0)
	v_mfma_f32_16x16x32_bf16 v[124:127], v[146:149], v[186:189], v[124:127]
	v_mfma_f32_16x16x32_bf16 v[120:123], v[158:161], v[186:189], v[120:123]
	v_mfma_f32_16x16x32_bf16 v[108:111], v[146:149], v[194:197], v[108:111]
	v_mfma_f32_16x16x32_bf16 v[104:107], v[158:161], v[194:197], v[104:107]
	v_mfma_f32_16x16x32_bf16 v[92:95], v[146:149], v[202:205], v[92:95]
	v_mfma_f32_16x16x32_bf16 v[88:91], v[158:161], v[202:205], v[88:91]
	v_mfma_f32_16x16x32_bf16 v[76:79], v[146:149], v[210:213], v[76:79]
	v_mfma_f32_16x16x32_bf16 v[72:75], v[158:161], v[210:213], v[72:75]
	v_mfma_f32_16x16x32_bf16 v[124:127], v[154:157], v[190:193], v[124:127]
	v_mfma_f32_16x16x32_bf16 v[120:123], v[162:165], v[190:193], v[120:123]
	v_mfma_f32_16x16x32_bf16 v[108:111], v[154:157], v[198:201], v[108:111]
	v_mfma_f32_16x16x32_bf16 v[104:107], v[162:165], v[198:201], v[104:107]
	v_mfma_f32_16x16x32_bf16 v[92:95], v[154:157], v[206:209], v[92:95]
	v_mfma_f32_16x16x32_bf16 v[88:91], v[162:165], v[206:209], v[88:91]
	v_mfma_f32_16x16x32_bf16 v[76:79], v[154:157], v[214:217], v[76:79]
	v_mfma_f32_16x16x32_bf16 v[72:75], v[162:165], v[214:217], v[72:75]
	v_mfma_f32_16x16x32_bf16 v[116:119], v[166:169], v[186:189], v[116:119]
	v_mfma_f32_16x16x32_bf16 v[112:115], v[174:177], v[186:189], v[112:115]
	v_mfma_f32_16x16x32_bf16 v[100:103], v[166:169], v[194:197], v[100:103]
	v_mfma_f32_16x16x32_bf16 v[96:99], v[174:177], v[194:197], v[96:99]
	v_mfma_f32_16x16x32_bf16 v[84:87], v[166:169], v[202:205], v[84:87]
	v_mfma_f32_16x16x32_bf16 v[80:83], v[174:177], v[202:205], v[80:83]
	v_mfma_f32_16x16x32_bf16 v[68:71], v[166:169], v[210:213], v[68:71]
	v_mfma_f32_16x16x32_bf16 v[64:67], v[174:177], v[210:213], v[64:67]
	v_mfma_f32_16x16x32_bf16 v[116:119], v[170:173], v[190:193], v[116:119]
	v_mfma_f32_16x16x32_bf16 v[112:115], v[178:181], v[190:193], v[112:115]
	v_mfma_f32_16x16x32_bf16 v[100:103], v[170:173], v[198:201], v[100:103]
	v_mfma_f32_16x16x32_bf16 v[96:99], v[178:181], v[198:201], v[96:99]
	v_mfma_f32_16x16x32_bf16 v[84:87], v[170:173], v[206:209], v[84:87]
	v_mfma_f32_16x16x32_bf16 v[80:83], v[178:181], v[206:209], v[80:83]
	v_mfma_f32_16x16x32_bf16 v[68:71], v[170:173], v[214:217], v[68:71]
	v_mfma_f32_16x16x32_bf16 v[64:67], v[178:181], v[214:217], v[64:67]
	s_barrier
	s_add_i32 s35, s68, s58
	v_lshl_add_u64 v[182:183], s[48:49], 0, v[130:131]
	s_mov_b32 m0, s35
	ds_read_b128 v[186:189], v153 offset:16384
	ds_read_b128 v[190:193], v153 offset:17408
	ds_read_b128 v[194:197], v153 offset:18432
	ds_read_b128 v[198:201], v153 offset:19456
	ds_read_b128 v[202:205], v153 offset:20480
	ds_read_b128 v[206:209], v153 offset:21504
	ds_read_b128 v[210:213], v153 offset:22528
	ds_read_b128 v[214:217], v153 offset:23552
	global_load_lds_dwordx4 v[182:183], off
	s_add_i32 m0, s35, 0x2000
	s_add_u32 s72, s48, 0x160000
	v_lshl_add_u64 v[218:219], s[48:49], 0, v[134:135]
	s_addc_u32 s73, s49, 0
	s_add_i32 s35, s69, s58
	global_load_lds_dwordx4 v[218:219], off
	v_lshl_add_u64 v[220:221], s[72:73], 0, v[130:131]
	s_mov_b32 m0, s35
	v_lshl_add_u64 v[222:223], s[50:51], 0, v[132:133]
	global_load_lds_dwordx4 v[220:221], off
	v_lshl_add_u64 v[220:221], s[72:73], 0, v[134:135]
	s_add_i32 m0, s35, 0x2000
	s_nop 0
	global_load_lds_dwordx4 v[220:221], off
	v_lshl_add_u64 v[220:221], s[50:51], 0, v[128:129]
	s_mov_b32 m0, s59
	s_nop 0
	global_load_lds_dwordx4 v[220:221], off
	s_mov_b32 m0, s60
	s_nop 0
	global_load_lds_dwordx4 v[222:223], off
	s_waitcnt vmcnt(8)
	s_waitcnt lgkmcnt(0)
	s_barrier
; #define PG8_STAGE(bufoff, gbase, voff) do { _Pragma("unroll") for (int _i = 0; _i < 2; ++_i) \
;         __builtin_amdgcn_global_load_lds((const unsigned*)((const char*)(gbase) + (voff)[_i]), (LAS unsigned*)(lds + (bufoff) + ldsw + _i * 8192), 16, 0, 0); } while (0)
; #define PG8_LDA(dst, b, h) do { _Pragma("unroll") for (int m = 0; m < 4; ++m) _Pragma("unroll") for (int k = 0; k < 2; ++k) dst[m][k] = *(const LAS bf16x8*)(lds + PG8_SA(b, h) + aoff + m * 2048 + k * 1024); } while (0)
; #define PG8_LDB(dst, b, h) do { _Pragma("unroll") for (int n = 0; n < 2; ++n) _Pragma("unroll") for (int k = 0; k < 2; ++k) dst[n][k] = *(const LAS bf16x8*)(lds + PG8_SB(b, h) + boff + n * 2048 + k * 1024); } while (0)
; #define PG8_MMA(ai, bj, At, Bt) do { __builtin_amdgcn_s_setprio(1); _Pragma("unroll") for (int m = 0; m < 4; ++m) _Pragma("unroll") for (int n = 0; n < 2; ++n) _Pragma("unroll") for (int k = 0; k < 2; ++k) \
;         acc[ai][bj][m][n] = __builtin_amdgcn_mfma_f32_16x16x32_bf16(Bt[n][k], At[m][k], acc[ai][bj][m][n], 0, 0, 0); __builtin_amdgcn_s_setprio(0); } while (0)
; #define PG8_WAIT_V(n) asm volatile("s_waitcnt vmcnt(" #n ")" ::: "memory")
; #define PG8_WAIT_L(n) asm volatile("s_waitcnt lgkmcnt(" #n ")" ::: "memory")
; #define PG8_BAR __builtin_amdgcn_s_barrier()
; #define PG8_SCHED __builtin_amdgcn_sched_barrier(0)
; template <class Epi, bool ALIGN_EPI = PG8_ALIGN>
; __device__ __forceinline__ void gemm_phase(LAS unsigned char* lds, const Gemm g, const StaticOrder S, const Epi E) {
;     ...
;             PG8_WAIT_V(8); PG8_WAIT_L(0); PG8_BAR; PG8_MMA(1, 0, At, B0); PG8_MMA(1, 1, At, B1); PG8_BAR; PG8_SCHED;
;             PG8_LDB(B0, 1, 0); PG8_LDB(B1, 1, 1); PG8_SCHED; PG8_LDA(At, 1, 0); PG8_STAGE(PG8_SA(0, 1), a2 + hstepA, voffA);
;             PG8_WAIT_V(8); PG8_WAIT_L(0); PG8_BAR; PG8_MMA(0, 0, At, B0); PG8_MMA(0, 1, At, B1); PG8_BAR; PG8_SCHED;
;             PG8_LDA(At, 1, 1); PG8_STAGE(PG8_SB(1, 0), b3, voffB); PG8_STAGE(PG8_SB(1, 1), b3 + hstepB, voffB); PG8_STAGE(PG8_SA(1, 0), a3, voffA);
;             PG8_WAIT_V(8); PG8_WAIT_L(0); PG8_BAR; PG8_MMA(1, 0, At, B0); PG8_MMA(1, 1, At, B1); PG8_BAR; PG8_SCHED;
	s_waitcnt lgkmcnt(0)
	v_mfma_f32_16x16x32_bf16 v[60:63], v[146:149], v[186:189], v[60:63]
	v_mfma_f32_16x16x32_bf16 v[56:59], v[158:161], v[186:189], v[56:59]
	v_mfma_f32_16x16x32_bf16 v[44:47], v[146:149], v[194:197], v[44:47]
	v_mfma_f32_16x16x32_bf16 v[40:43], v[158:161], v[194:197], v[40:43]
	v_mfma_f32_16x16x32_bf16 v[28:31], v[146:149], v[202:205], v[28:31]
	v_mfma_f32_16x16x32_bf16 v[24:27], v[158:161], v[202:205], v[24:27]
	v_mfma_f32_16x16x32_bf16 v[12:15], v[146:149], v[210:213], v[12:15]
	v_mfma_f32_16x16x32_bf16 v[8:11], v[158:161], v[210:213], v[8:11]
	v_mfma_f32_16x16x32_bf16 v[60:63], v[154:157], v[190:193], v[60:63]
	v_mfma_f32_16x16x32_bf16 v[56:59], v[162:165], v[190:193], v[56:59]
	v_mfma_f32_16x16x32_bf16 v[44:47], v[154:157], v[198:201], v[44:47]
	v_mfma_f32_16x16x32_bf16 v[40:43], v[162:165], v[198:201], v[40:43]
	v_mfma_f32_16x16x32_bf16 v[28:31], v[154:157], v[206:209], v[28:31]
	v_mfma_f32_16x16x32_bf16 v[24:27], v[162:165], v[206:209], v[24:27]
	v_mfma_f32_16x16x32_bf16 v[12:15], v[154:157], v[214:217], v[12:15]
	v_mfma_f32_16x16x32_bf16 v[8:11], v[162:165], v[214:217], v[8:11]
	v_mfma_f32_16x16x32_bf16 v[52:55], v[166:169], v[186:189], v[52:55]
	v_mfma_f32_16x16x32_bf16 v[48:51], v[174:177], v[186:189], v[48:51]
	v_mfma_f32_16x16x32_bf16 v[36:39], v[166:169], v[194:197], v[36:39]
	v_mfma_f32_16x16x32_bf16 v[32:35], v[174:177], v[194:197], v[32:35]
	v_mfma_f32_16x16x32_bf16 v[20:23], v[166:169], v[202:205], v[20:23]
	v_mfma_f32_16x16x32_bf16 v[16:19], v[174:177], v[202:205], v[16:19]
	v_mfma_f32_16x16x32_bf16 v[4:7], v[166:169], v[210:213], v[4:7]
	v_mfma_f32_16x16x32_bf16 v[0:3], v[174:177], v[210:213], v[0:3]
	v_mfma_f32_16x16x32_bf16 v[52:55], v[170:173], v[190:193], v[52:55]
	v_mfma_f32_16x16x32_bf16 v[48:51], v[178:181], v[190:193], v[48:51]
	v_mfma_f32_16x16x32_bf16 v[36:39], v[170:173], v[198:201], v[36:39]
	v_mfma_f32_16x16x32_bf16 v[32:35], v[178:181], v[198:201], v[32:35]
	v_mfma_f32_16x16x32_bf16 v[20:23], v[170:173], v[206:209], v[20:23]
	v_mfma_f32_16x16x32_bf16 v[16:19], v[178:181], v[206:209], v[16:19]
	v_mfma_f32_16x16x32_bf16 v[4:7], v[170:173], v[214:217], v[4:7]
	v_mfma_f32_16x16x32_bf16 v[0:3], v[178:181], v[214:217], v[0:3]
	s_barrier
	s_add_i32 s35, 0, 0x18000
	s_add_i32 s72, 0, 0x1c000
	v_add_u32_e32 v162, s35, v150
	v_add_u32_e32 v178, s72, v150
	ds_read_b128 v[146:149], v162
	ds_read_b128 v[154:157], v162 offset:1024
	ds_read_b128 v[158:161], v162 offset:2048
	ds_read_b128 v[162:165], v162 offset:3072
	ds_read_b128 v[166:169], v178
	ds_read_b128 v[170:173], v178 offset:1024
	ds_read_b128 v[174:177], v178 offset:2048
	ds_read_b128 v[178:181], v178 offset:3072
	s_add_u32 s50, s50, 0x160000
	s_addc_u32 s51, s51, 0
	s_mov_b32 m0, s61
	v_lshl_add_u64 v[224:225], s[50:51], 0, v[128:129]
	ds_read_b128 v[186:189], v153 offset:32768
	ds_read_b128 v[190:193], v153 offset:33792
	ds_read_b128 v[194:197], v153 offset:34816
	ds_read_b128 v[198:201], v153 offset:35840
	ds_read_b128 v[202:205], v153 offset:36864
	ds_read_b128 v[206:209], v153 offset:37888
	ds_read_b128 v[210:213], v153 offset:38912
	ds_read_b128 v[214:217], v153 offset:39936
	global_load_lds_dwordx4 v[224:225], off
	v_lshl_add_u64 v[224:225], s[50:51], 0, v[132:133]
	s_mov_b32 m0, s62
	s_nop 0
	global_load_lds_dwordx4 v[224:225], off
	s_waitcnt vmcnt(8)
	s_waitcnt lgkmcnt(0)
	s_barrier
	s_waitcnt lgkmcnt(0)
	v_mfma_f32_16x16x32_bf16 v[124:127], v[146:149], v[186:189], v[124:127]
	v_mfma_f32_16x16x32_bf16 v[120:123], v[158:161], v[186:189], v[120:123]
	v_mfma_f32_16x16x32_bf16 v[108:111], v[146:149], v[194:197], v[108:111]
	v_mfma_f32_16x16x32_bf16 v[104:107], v[158:161], v[194:197], v[104:107]
	v_mfma_f32_16x16x32_bf16 v[92:95], v[146:149], v[202:205], v[92:95]
	v_mfma_f32_16x16x32_bf16 v[88:91], v[158:161], v[202:205], v[88:91]
	v_mfma_f32_16x16x32_bf16 v[76:79], v[146:149], v[210:213], v[76:79]
	v_mfma_f32_16x16x32_bf16 v[72:75], v[158:161], v[210:213], v[72:75]
	v_mfma_f32_16x16x32_bf16 v[124:127], v[154:157], v[190:193], v[124:127]
	v_mfma_f32_16x16x32_bf16 v[120:123], v[162:165], v[190:193], v[120:123]
	v_mfma_f32_16x16x32_bf16 v[108:111], v[154:157], v[198:201], v[108:111]
	v_mfma_f32_16x16x32_bf16 v[104:107], v[162:165], v[198:201], v[104:107]
	v_mfma_f32_16x16x32_bf16 v[92:95], v[154:157], v[206:209], v[92:95]
	v_mfma_f32_16x16x32_bf16 v[88:91], v[162:165], v[206:209], v[88:91]
	v_mfma_f32_16x16x32_bf16 v[76:79], v[154:157], v[214:217], v[76:79]
	v_mfma_f32_16x16x32_bf16 v[72:75], v[162:165], v[214:217], v[72:75]
	v_mfma_f32_16x16x32_bf16 v[116:119], v[166:169], v[186:189], v[116:119]
	v_mfma_f32_16x16x32_bf16 v[112:115], v[174:177], v[186:189], v[112:115]
	v_mfma_f32_16x16x32_bf16 v[100:103], v[166:169], v[194:197], v[100:103]
	v_mfma_f32_16x16x32_bf16 v[96:99], v[174:177], v[194:197], v[96:99]
	v_mfma_f32_16x16x32_bf16 v[84:87], v[166:169], v[202:205], v[84:87]
	v_mfma_f32_16x16x32_bf16 v[80:83], v[174:177], v[202:205], v[80:83]
	v_mfma_f32_16x16x32_bf16 v[68:71], v[166:169], v[210:213], v[68:71]
	v_mfma_f32_16x16x32_bf16 v[64:67], v[174:177], v[210:213], v[64:67]
	v_mfma_f32_16x16x32_bf16 v[116:119], v[170:173], v[190:193], v[116:119]
	v_mfma_f32_16x16x32_bf16 v[112:115], v[178:181], v[190:193], v[112:115]
	v_mfma_f32_16x16x32_bf16 v[100:103], v[170:173], v[198:201], v[100:103]
	v_mfma_f32_16x16x32_bf16 v[96:99], v[178:181], v[198:201], v[96:99]
	v_mfma_f32_16x16x32_bf16 v[84:87], v[170:173], v[206:209], v[84:87]
	v_mfma_f32_16x16x32_bf16 v[80:83], v[178:181], v[206:209], v[80:83]
	v_mfma_f32_16x16x32_bf16 v[68:71], v[170:173], v[214:217], v[68:71]
	v_mfma_f32_16x16x32_bf16 v[64:67], v[178:181], v[214:217], v[64:67]
	s_barrier
; #define PG8_STAGE(bufoff, gbase, voff) do { _Pragma("unroll") for (int _i = 0; _i < 2; ++_i) \
;         __builtin_amdgcn_global_load_lds((const unsigned*)((const char*)(gbase) + (voff)[_i]), (LAS unsigned*)(lds + (bufoff) + ldsw + _i * 8192), 16, 0, 0); } while (0)
; #define PG8_LDA(dst, b, h) do { _Pragma("unroll") for (int m = 0; m < 4; ++m) _Pragma("unroll") for (int k = 0; k < 2; ++k) dst[m][k] = *(const LAS bf16x8*)(lds + PG8_SA(b, h) + aoff + m * 2048 + k * 1024); } while (0)
; #define PG8_MMA(ai, bj, At, Bt) do { __builtin_amdgcn_s_setprio(1); _Pragma("unroll") for (int m = 0; m < 4; ++m) _Pragma("unroll") for (int n = 0; n < 2; ++n) _Pragma("unroll") for (int k = 0; k < 2; ++k) \
;         acc[ai][bj][m][n] = __builtin_amdgcn_mfma_f32_16x16x32_bf16(Bt[n][k], At[m][k], acc[ai][bj][m][n], 0, 0, 0); __builtin_amdgcn_s_setprio(0); } while (0)
; #define PG8_WAIT_V(n) asm volatile("s_waitcnt vmcnt(" #n ")" ::: "memory")
; #define PG8_WAIT_L(n) asm volatile("s_waitcnt lgkmcnt(" #n ")" ::: "memory")
; #define PG8_BAR __builtin_amdgcn_s_barrier()
; #define PG8_SCHED __builtin_amdgcn_sched_barrier(0)
; template <class Epi, bool ALIGN_EPI = PG8_ALIGN>
; __device__ __forceinline__ void gemm_phase(LAS unsigned char* lds, const Gemm g, const StaticOrder S, const Epi E) {
;     ...
;             PG8_LDA(At, 1, 1); PG8_STAGE(PG8_SB(1, 0), b3, voffB); PG8_STAGE(PG8_SB(1, 1), b3 + hstepB, voffB); PG8_STAGE(PG8_SA(1, 0), a3, voffA);
;             PG8_WAIT_V(8); PG8_WAIT_L(0); PG8_BAR; PG8_MMA(1, 0, At, B0); PG8_MMA(1, 1, At, B1); PG8_BAR; PG8_SCHED;
;         }
;         if (ALIGN_EPI) { if (wr == 0) PG8_BAR; }
	s_add_i32 s35, s35, s58
	v_lshl_add_u64 v[182:183], v[182:183], 0, s[10:11]
	s_mov_b32 m0, s35
	ds_read_b128 v[186:189], v153 offset:49152
	ds_read_b128 v[190:193], v153 offset:50176
	ds_read_b128 v[194:197], v153 offset:51200
	ds_read_b128 v[198:201], v153 offset:52224
	ds_read_b128 v[202:205], v153 offset:53248
	ds_read_b128 v[206:209], v153 offset:54272
	ds_read_b128 v[210:213], v153 offset:55296
	ds_read_b128 v[214:217], v153 offset:56320
	global_load_lds_dwordx4 v[182:183], off
	s_add_i32 m0, s35, 0x2000
	s_add_u32 s48, s48, 0x160080
	v_lshl_add_u64 v[182:183], v[218:219], 0, s[10:11]
	s_addc_u32 s49, s49, 0
	s_add_i32 s35, s72, s58
	global_load_lds_dwordx4 v[182:183], off
	v_lshl_add_u64 v[182:183], s[48:49], 0, v[130:131]
	s_mov_b32 m0, s35
	s_nop 0
	global_load_lds_dwordx4 v[182:183], off
	v_lshl_add_u64 v[182:183], s[48:49], 0, v[134:135]
	s_add_i32 m0, s35, 0x2000
	s_nop 0
	global_load_lds_dwordx4 v[182:183], off
	v_lshl_add_u64 v[182:183], v[220:221], 0, s[10:11]
	s_mov_b32 m0, s65
	s_nop 0
	global_load_lds_dwordx4 v[182:183], off
	v_lshl_add_u64 v[182:183], v[222:223], 0, s[10:11]
	s_mov_b32 m0, s66
	s_nop 0
	global_load_lds_dwordx4 v[182:183], off
	s_waitcnt vmcnt(8)
	s_waitcnt lgkmcnt(0)
	s_barrier
	s_waitcnt lgkmcnt(0)
	v_mfma_f32_16x16x32_bf16 v[60:63], v[146:149], v[186:189], v[60:63]
	v_mfma_f32_16x16x32_bf16 v[56:59], v[158:161], v[186:189], v[56:59]
	v_mfma_f32_16x16x32_bf16 v[44:47], v[146:149], v[194:197], v[44:47]
	v_mfma_f32_16x16x32_bf16 v[40:43], v[158:161], v[194:197], v[40:43]
	v_mfma_f32_16x16x32_bf16 v[28:31], v[146:149], v[202:205], v[28:31]
	v_mfma_f32_16x16x32_bf16 v[24:27], v[158:161], v[202:205], v[24:27]
	v_mfma_f32_16x16x32_bf16 v[12:15], v[146:149], v[210:213], v[12:15]
	v_mfma_f32_16x16x32_bf16 v[8:11], v[158:161], v[210:213], v[8:11]
	v_mfma_f32_16x16x32_bf16 v[60:63], v[154:157], v[190:193], v[60:63]
	v_mfma_f32_16x16x32_bf16 v[56:59], v[162:165], v[190:193], v[56:59]
	v_mfma_f32_16x16x32_bf16 v[44:47], v[154:157], v[198:201], v[44:47]
	v_mfma_f32_16x16x32_bf16 v[40:43], v[162:165], v[198:201], v[40:43]
	v_mfma_f32_16x16x32_bf16 v[28:31], v[154:157], v[206:209], v[28:31]
	v_mfma_f32_16x16x32_bf16 v[24:27], v[162:165], v[206:209], v[24:27]
	v_mfma_f32_16x16x32_bf16 v[12:15], v[154:157], v[214:217], v[12:15]
	v_mfma_f32_16x16x32_bf16 v[8:11], v[162:165], v[214:217], v[8:11]
	v_mfma_f32_16x16x32_bf16 v[52:55], v[166:169], v[186:189], v[52:55]
	v_mfma_f32_16x16x32_bf16 v[48:51], v[174:177], v[186:189], v[48:51]
	v_mfma_f32_16x16x32_bf16 v[36:39], v[166:169], v[194:197], v[36:39]
	v_mfma_f32_16x16x32_bf16 v[32:35], v[174:177], v[194:197], v[32:35]
	v_mfma_f32_16x16x32_bf16 v[20:23], v[166:169], v[202:205], v[20:23]
	v_mfma_f32_16x16x32_bf16 v[16:19], v[174:177], v[202:205], v[16:19]
	v_mfma_f32_16x16x32_bf16 v[4:7], v[166:169], v[210:213], v[4:7]
	v_mfma_f32_16x16x32_bf16 v[0:3], v[174:177], v[210:213], v[0:3]
	v_mfma_f32_16x16x32_bf16 v[52:55], v[170:173], v[190:193], v[52:55]
	v_mfma_f32_16x16x32_bf16 v[48:51], v[178:181], v[190:193], v[48:51]
	v_mfma_f32_16x16x32_bf16 v[36:39], v[170:173], v[198:201], v[36:39]
	v_mfma_f32_16x16x32_bf16 v[32:35], v[178:181], v[198:201], v[32:35]
	v_mfma_f32_16x16x32_bf16 v[20:23], v[170:173], v[206:209], v[20:23]
	v_mfma_f32_16x16x32_bf16 v[16:19], v[178:181], v[206:209], v[16:19]
	v_mfma_f32_16x16x32_bf16 v[4:7], v[170:173], v[214:217], v[4:7]
	v_mfma_f32_16x16x32_bf16 v[0:3], v[178:181], v[214:217], v[0:3]
	s_barrier
	s_add_i32 s34, s34, 2
	s_add_u32 s12, s12, 0x100
	s_addc_u32 s13, s13, 0
	s_add_u32 s17, s17, 0x100
	s_addc_u32 s33, s33, 0
	s_cmpk_gt_u32 s34, 0x55
	s_cbranch_scc0 .LBB0_420
	s_and_b64 vcc, exec, s[42:43]
	s_cbranch_vccz .LBB0_423
	s_barrier

; #define PG8_STAGE(bufoff, gbase, voff) do { _Pragma("unroll") for (int _i = 0; _i < 2; ++_i) \
;         __builtin_amdgcn_global_load_lds((const unsigned*)((const char*)(gbase) + (voff)[_i]), (LAS unsigned*)(lds + (bufoff) + ldsw + _i * 8192), 16, 0, 0); } while (0)
; #define PG8_LDA(dst, b, h) do { _Pragma("unroll") for (int m = 0; m < 4; ++m) _Pragma("unroll") for (int k = 0; k < 2; ++k) dst[m][k] = *(const LAS bf16x8*)(lds + PG8_SA(b, h) + aoff + m * 2048 + k * 1024); } while (0)
; #define PG8_LDB(dst, b, h) do { _Pragma("unroll") for (int n = 0; n < 2; ++n) _Pragma("unroll") for (int k = 0; k < 2; ++k) dst[n][k] = *(const LAS bf16x8*)(lds + PG8_SB(b, h) + boff + n * 2048 + k * 1024); } while (0)
; #define PG8_MMA(ai, bj, At, Bt) do { __builtin_amdgcn_s_setprio(1); _Pragma("unroll") for (int m = 0; m < 4; ++m) _Pragma("unroll") for (int n = 0; n < 2; ++n) _Pragma("unroll") for (int k = 0; k < 2; ++k) \
;         acc[ai][bj][m][n] = __builtin_amdgcn_mfma_f32_16x16x32_bf16(Bt[n][k], At[m][k], acc[ai][bj][m][n], 0, 0, 0); __builtin_amdgcn_s_setprio(0); } while (0)
; #define PG8_WAIT_V(n) asm volatile("s_waitcnt vmcnt(" #n ")" ::: "memory")
; #define PG8_WAIT_L(n) asm volatile("s_waitcnt lgkmcnt(" #n ")" ::: "memory")
; #define PG8_BAR __builtin_amdgcn_s_barrier()
; #define PG8_SCHED __builtin_amdgcn_sched_barrier(0)
; template <class Epi, bool ALIGN_EPI = PG8_ALIGN>
; __device__ __forceinline__ void gemm_phase(LAS unsigned char* lds, const Gemm g, const StaticOrder S, const Epi E) {
;     ...
;         for (int t = 0; t < nt; t += 2) {
;             const bool last = (t == nt - 2);
;             const char* a1 = cA + (size_t)(t + 1) * kstep;
;             const char* a2 = last ? nA : cA + (size_t)(t + 2) * kstep; const char* b2 = last ? nB : cB + (size_t)(t + 2) * kstep;
;             const char* a3 = a2 + kstep; const char* b3 = b2 + kstep;
;             PG8_LDB(B0, 0, 0); PG8_LDB(B1, 0, 1); PG8_SCHED; PG8_LDA(At, 0, 0); PG8_STAGE(PG8_SA(1, 1), a1 + hstepA, voffA);
;             PG8_WAIT_V(8); PG8_WAIT_L(0); PG8_BAR; PG8_MMA(0, 0, At, B0); PG8_MMA(0, 1, At, B1); PG8_BAR; PG8_SCHED;
;             PG8_LDA(At, 0, 1); PG8_STAGE(PG8_SB(0, 0), b2, voffB); PG8_STAGE(PG8_SB(0, 1), b2 + hstepB, voffB); PG8_STAGE(PG8_SA(0, 0), a2, voffA);
;             PG8_WAIT_V(8); PG8_WAIT_L(0); PG8_BAR; PG8_MMA(1, 0, At, B0); PG8_MMA(1, 1, At, B1); PG8_BAR; PG8_SCHED;
.LBB0_507:
	ds_read_b128 v[144:147], v160
	ds_read_b128 v[164:167], v160 offset:1024
	ds_read_b128 v[168:171], v160 offset:2048
	ds_read_b128 v[172:175], v160 offset:3072
	ds_read_b128 v[176:179], v161
	ds_read_b128 v[180:183], v161 offset:1024
	ds_read_b128 v[186:189], v161 offset:2048
	ds_read_b128 v[190:193], v161 offset:3072
	s_add_u32 s42, s52, 0xfff80080
	s_addc_u32 s43, s53, -1
	s_cmp_eq_u32 s35, 28
	s_cselect_b32 s61, s14, s43
	s_cselect_b32 s60, s16, s42
	s_cselect_b32 s59, s11, s34
	s_cselect_b32 s58, s17, s33
	v_lshl_add_u64 v[226:227], s[52:53], 0, v[136:137]
	s_add_i32 m0, s63, 0xc000
	ds_read_b128 v[194:197], v162
	ds_read_b128 v[198:201], v162 offset:1024
	ds_read_b128 v[202:205], v162 offset:2048
	ds_read_b128 v[206:209], v162 offset:3072
	ds_read_b128 v[210:213], v162 offset:4096
	ds_read_b128 v[214:217], v162 offset:5120
	ds_read_b128 v[218:221], v162 offset:6144
	ds_read_b128 v[222:225], v162 offset:7168
	global_load_lds_dwordx4 v[226:227], off
	v_lshl_add_u64 v[226:227], s[52:53], 0, v[138:139]
	s_add_i32 m0, s63, 0xe000
	s_nop 0
	global_load_lds_dwordx4 v[226:227], off
	s_waitcnt vmcnt(8)
	s_waitcnt lgkmcnt(0)
	s_barrier
	s_waitcnt lgkmcnt(0)
	v_mfma_f32_16x16x32_bf16 v[124:127], v[144:147], v[194:197], v[124:127]
	v_mfma_f32_16x16x32_bf16 v[120:123], v[168:171], v[194:197], v[120:123]
	v_mfma_f32_16x16x32_bf16 v[116:119], v[144:147], v[202:205], v[116:119]
	v_mfma_f32_16x16x32_bf16 v[112:115], v[168:171], v[202:205], v[112:115]
	v_mfma_f32_16x16x32_bf16 v[108:111], v[144:147], v[210:213], v[108:111]
	v_mfma_f32_16x16x32_bf16 v[104:107], v[168:171], v[210:213], v[104:107]
	v_mfma_f32_16x16x32_bf16 v[100:103], v[144:147], v[218:221], v[100:103]
	v_mfma_f32_16x16x32_bf16 v[96:99], v[168:171], v[218:221], v[96:99]
	v_mfma_f32_16x16x32_bf16 v[124:127], v[164:167], v[198:201], v[124:127]
	v_mfma_f32_16x16x32_bf16 v[120:123], v[172:175], v[198:201], v[120:123]
	v_mfma_f32_16x16x32_bf16 v[116:119], v[164:167], v[206:209], v[116:119]
	v_mfma_f32_16x16x32_bf16 v[112:115], v[172:175], v[206:209], v[112:115]
	v_mfma_f32_16x16x32_bf16 v[108:111], v[164:167], v[214:217], v[108:111]
	v_mfma_f32_16x16x32_bf16 v[104:107], v[172:175], v[214:217], v[104:107]
	v_mfma_f32_16x16x32_bf16 v[100:103], v[164:167], v[222:225], v[100:103]
	v_mfma_f32_16x16x32_bf16 v[96:99], v[172:175], v[222:225], v[96:99]
	v_mfma_f32_16x16x32_bf16 v[60:63], v[176:179], v[194:197], v[60:63]
	v_mfma_f32_16x16x32_bf16 v[56:59], v[186:189], v[194:197], v[56:59]
	v_mfma_f32_16x16x32_bf16 v[52:55], v[176:179], v[202:205], v[52:55]
	v_mfma_f32_16x16x32_bf16 v[48:51], v[186:189], v[202:205], v[48:51]
	v_mfma_f32_16x16x32_bf16 v[44:47], v[176:179], v[210:213], v[44:47]
	v_mfma_f32_16x16x32_bf16 v[40:43], v[186:189], v[210:213], v[40:43]
	v_mfma_f32_16x16x32_bf16 v[36:39], v[176:179], v[218:221], v[36:39]
	v_mfma_f32_16x16x32_bf16 v[32:35], v[186:189], v[218:221], v[32:35]
	v_mfma_f32_16x16x32_bf16 v[60:63], v[180:183], v[198:201], v[60:63]
	v_mfma_f32_16x16x32_bf16 v[56:59], v[190:193], v[198:201], v[56:59]
	v_mfma_f32_16x16x32_bf16 v[52:55], v[180:183], v[206:209], v[52:55]
	v_mfma_f32_16x16x32_bf16 v[48:51], v[190:193], v[206:209], v[48:51]
	v_mfma_f32_16x16x32_bf16 v[44:47], v[180:183], v[214:217], v[44:47]
	v_mfma_f32_16x16x32_bf16 v[40:43], v[190:193], v[214:217], v[40:43]
	v_mfma_f32_16x16x32_bf16 v[36:39], v[180:183], v[222:225], v[36:39]
	v_mfma_f32_16x16x32_bf16 v[32:35], v[190:193], v[222:225], v[32:35]
	s_barrier
	s_add_i32 s42, s72, s62
	v_lshl_add_u64 v[226:227], s[58:59], 0, v[130:131]
	s_mov_b32 m0, s42
	ds_read_b128 v[194:197], v162 offset:16384
	ds_read_b128 v[198:201], v162 offset:17408
	ds_read_b128 v[202:205], v162 offset:18432
	ds_read_b128 v[206:209], v162 offset:19456
	ds_read_b128 v[210:213], v162 offset:20480
	ds_read_b128 v[214:217], v162 offset:21504
	ds_read_b128 v[218:221], v162 offset:22528
	ds_read_b128 v[222:225], v162 offset:23552
	global_load_lds_dwordx4 v[226:227], off
	s_add_i32 m0, s42, 0x2000
	s_add_u32 s42, s58, 0x80000
	v_lshl_add_u64 v[228:229], s[58:59], 0, v[134:135]
	s_addc_u32 s43, s59, 0
	s_add_i32 s47, s73, s62
	global_load_lds_dwordx4 v[228:229], off
	v_lshl_add_u64 v[230:231], s[42:43], 0, v[130:131]
	s_mov_b32 m0, s47
	v_lshl_add_u64 v[232:233], s[60:61], 0, v[132:133]
	global_load_lds_dwordx4 v[230:231], off
	v_lshl_add_u64 v[230:231], s[42:43], 0, v[134:135]
	s_add_i32 m0, s47, 0x2000
	s_nop 0
	global_load_lds_dwordx4 v[230:231], off
	v_lshl_add_u64 v[230:231], s[60:61], 0, v[128:129]
	s_mov_b32 m0, s63
	s_nop 0
	global_load_lds_dwordx4 v[230:231], off
	s_mov_b32 m0, s64
	s_nop 0
	global_load_lds_dwordx4 v[232:233], off
	s_waitcnt vmcnt(8)
	s_waitcnt lgkmcnt(0)
	s_barrier
; #define PG8_STAGE(bufoff, gbase, voff) do { _Pragma("unroll") for (int _i = 0; _i < 2; ++_i) \
;         __builtin_amdgcn_global_load_lds((const unsigned*)((const char*)(gbase) + (voff)[_i]), (LAS unsigned*)(lds + (bufoff) + ldsw + _i * 8192), 16, 0, 0); } while (0)
; #define PG8_LDA(dst, b, h) do { _Pragma("unroll") for (int m = 0; m < 4; ++m) _Pragma("unroll") for (int k = 0; k < 2; ++k) dst[m][k] = *(const LAS bf16x8*)(lds + PG8_SA(b, h) + aoff + m * 2048 + k * 1024); } while (0)
; #define PG8_LDB(dst, b, h) do { _Pragma("unroll") for (int n = 0; n < 2; ++n) _Pragma("unroll") for (int k = 0; k < 2; ++k) dst[n][k] = *(const LAS bf16x8*)(lds + PG8_SB(b, h) + boff + n * 2048 + k * 1024); } while (0)
; #define PG8_MMA(ai, bj, At, Bt) do { __builtin_amdgcn_s_setprio(1); _Pragma("unroll") for (int m = 0; m < 4; ++m) _Pragma("unroll") for (int n = 0; n < 2; ++n) _Pragma("unroll") for (int k = 0; k < 2; ++k) \
;         acc[ai][bj][m][n] = __builtin_amdgcn_mfma_f32_16x16x32_bf16(Bt[n][k], At[m][k], acc[ai][bj][m][n], 0, 0, 0); __builtin_amdgcn_s_setprio(0); } while (0)
; #define PG8_WAIT_V(n) asm volatile("s_waitcnt vmcnt(" #n ")" ::: "memory")
; #define PG8_WAIT_L(n) asm volatile("s_waitcnt lgkmcnt(" #n ")" ::: "memory")
; #define PG8_BAR __builtin_amdgcn_s_barrier()
; #define PG8_SCHED __builtin_amdgcn_sched_barrier(0)
; template <class Epi, bool ALIGN_EPI = PG8_ALIGN>
; __device__ __forceinline__ void gemm_phase(LAS unsigned char* lds, const Gemm g, const StaticOrder S, const Epi E) {
;     ...
;             PG8_WAIT_V(8); PG8_WAIT_L(0); PG8_BAR; PG8_MMA(1, 0, At, B0); PG8_MMA(1, 1, At, B1); PG8_BAR; PG8_SCHED;
;             PG8_LDB(B0, 1, 0); PG8_LDB(B1, 1, 1); PG8_SCHED; PG8_LDA(At, 1, 0); PG8_STAGE(PG8_SA(0, 1), a2 + hstepA, voffA);
;             PG8_WAIT_V(8); PG8_WAIT_L(0); PG8_BAR; PG8_MMA(0, 0, At, B0); PG8_MMA(0, 1, At, B1); PG8_BAR; PG8_SCHED;
;             PG8_LDA(At, 1, 1); PG8_STAGE(PG8_SB(1, 0), b3, voffB); PG8_STAGE(PG8_SB(1, 1), b3 + hstepB, voffB); PG8_STAGE(PG8_SA(1, 0), a3, voffA);
;             PG8_WAIT_V(8); PG8_WAIT_L(0); PG8_BAR; PG8_MMA(1, 0, At, B0); PG8_MMA(1, 1, At, B1); PG8_BAR; PG8_SCHED;
	s_waitcnt lgkmcnt(0)
	v_mfma_f32_16x16x32_bf16 v[92:95], v[144:147], v[194:197], v[92:95]
	v_mfma_f32_16x16x32_bf16 v[88:91], v[168:171], v[194:197], v[88:91]
	v_mfma_f32_16x16x32_bf16 v[84:87], v[144:147], v[202:205], v[84:87]
	v_mfma_f32_16x16x32_bf16 v[80:83], v[168:171], v[202:205], v[80:83]
	v_mfma_f32_16x16x32_bf16 v[76:79], v[144:147], v[210:213], v[76:79]
	v_mfma_f32_16x16x32_bf16 v[72:75], v[168:171], v[210:213], v[72:75]
	v_mfma_f32_16x16x32_bf16 v[68:71], v[144:147], v[218:221], v[68:71]
	v_mfma_f32_16x16x32_bf16 v[64:67], v[168:171], v[218:221], v[64:67]
	v_mfma_f32_16x16x32_bf16 v[92:95], v[164:167], v[198:201], v[92:95]
	v_mfma_f32_16x16x32_bf16 v[88:91], v[172:175], v[198:201], v[88:91]
	v_mfma_f32_16x16x32_bf16 v[84:87], v[164:167], v[206:209], v[84:87]
	v_mfma_f32_16x16x32_bf16 v[80:83], v[172:175], v[206:209], v[80:83]
	v_mfma_f32_16x16x32_bf16 v[76:79], v[164:167], v[214:217], v[76:79]
	v_mfma_f32_16x16x32_bf16 v[72:75], v[172:175], v[214:217], v[72:75]
	v_mfma_f32_16x16x32_bf16 v[68:71], v[164:167], v[222:225], v[68:71]
	v_mfma_f32_16x16x32_bf16 v[64:67], v[172:175], v[222:225], v[64:67]
	v_mfma_f32_16x16x32_bf16 v[28:31], v[176:179], v[194:197], v[28:31]
	v_mfma_f32_16x16x32_bf16 v[24:27], v[186:189], v[194:197], v[24:27]
	v_mfma_f32_16x16x32_bf16 v[20:23], v[176:179], v[202:205], v[20:23]
	v_mfma_f32_16x16x32_bf16 v[16:19], v[186:189], v[202:205], v[16:19]
	v_mfma_f32_16x16x32_bf16 v[12:15], v[176:179], v[210:213], v[12:15]
	v_mfma_f32_16x16x32_bf16 v[8:11], v[186:189], v[210:213], v[8:11]
	v_mfma_f32_16x16x32_bf16 v[4:7], v[176:179], v[218:221], v[4:7]
	v_mfma_f32_16x16x32_bf16 v[0:3], v[186:189], v[218:221], v[0:3]
	v_mfma_f32_16x16x32_bf16 v[28:31], v[180:183], v[198:201], v[28:31]
	v_mfma_f32_16x16x32_bf16 v[24:27], v[190:193], v[198:201], v[24:27]
	v_mfma_f32_16x16x32_bf16 v[20:23], v[180:183], v[206:209], v[20:23]
	v_mfma_f32_16x16x32_bf16 v[16:19], v[190:193], v[206:209], v[16:19]
	v_mfma_f32_16x16x32_bf16 v[12:15], v[180:183], v[214:217], v[12:15]
	v_mfma_f32_16x16x32_bf16 v[8:11], v[190:193], v[214:217], v[8:11]
	v_mfma_f32_16x16x32_bf16 v[4:7], v[180:183], v[222:225], v[4:7]
	v_mfma_f32_16x16x32_bf16 v[0:3], v[190:193], v[222:225], v[0:3]
	s_barrier
	s_add_i32 s47, 0, 0x18000
	s_add_i32 s76, 0, 0x1c000
	v_add_u32_e32 v172, s47, v156
	v_add_u32_e32 v190, s76, v156
	ds_read_b128 v[144:147], v172
	ds_read_b128 v[164:167], v172 offset:1024
	ds_read_b128 v[168:171], v172 offset:2048
	ds_read_b128 v[172:175], v172 offset:3072
	ds_read_b128 v[176:179], v190
	ds_read_b128 v[180:183], v190 offset:1024
	ds_read_b128 v[186:189], v190 offset:2048
	ds_read_b128 v[190:193], v190 offset:3072
	s_add_u32 s42, s60, 0x80000
	s_addc_u32 s43, s61, 0
	s_mov_b32 m0, s65
	v_lshl_add_u64 v[234:235], s[42:43], 0, v[128:129]
	ds_read_b128 v[194:197], v162 offset:32768
	ds_read_b128 v[198:201], v162 offset:33792
	ds_read_b128 v[202:205], v162 offset:34816
	ds_read_b128 v[206:209], v162 offset:35840
	ds_read_b128 v[210:213], v162 offset:36864
	ds_read_b128 v[214:217], v162 offset:37888
	ds_read_b128 v[218:221], v162 offset:38912
	ds_read_b128 v[222:225], v162 offset:39936
	global_load_lds_dwordx4 v[234:235], off
	v_lshl_add_u64 v[234:235], s[42:43], 0, v[132:133]
	s_mov_b32 m0, s66
	s_nop 0
	global_load_lds_dwordx4 v[234:235], off
	s_waitcnt vmcnt(8)
	s_waitcnt lgkmcnt(0)
	s_barrier
	s_waitcnt lgkmcnt(0)
	v_mfma_f32_16x16x32_bf16 v[124:127], v[144:147], v[194:197], v[124:127]
	v_mfma_f32_16x16x32_bf16 v[120:123], v[168:171], v[194:197], v[120:123]
	v_mfma_f32_16x16x32_bf16 v[116:119], v[144:147], v[202:205], v[116:119]
	v_mfma_f32_16x16x32_bf16 v[112:115], v[168:171], v[202:205], v[112:115]
	v_mfma_f32_16x16x32_bf16 v[108:111], v[144:147], v[210:213], v[108:111]
	v_mfma_f32_16x16x32_bf16 v[104:107], v[168:171], v[210:213], v[104:107]
	v_mfma_f32_16x16x32_bf16 v[100:103], v[144:147], v[218:221], v[100:103]
	v_mfma_f32_16x16x32_bf16 v[96:99], v[168:171], v[218:221], v[96:99]
	v_mfma_f32_16x16x32_bf16 v[124:127], v[164:167], v[198:201], v[124:127]
	v_mfma_f32_16x16x32_bf16 v[120:123], v[172:175], v[198:201], v[120:123]
	v_mfma_f32_16x16x32_bf16 v[116:119], v[164:167], v[206:209], v[116:119]
	v_mfma_f32_16x16x32_bf16 v[112:115], v[172:175], v[206:209], v[112:115]
	v_mfma_f32_16x16x32_bf16 v[108:111], v[164:167], v[214:217], v[108:111]
	v_mfma_f32_16x16x32_bf16 v[104:107], v[172:175], v[214:217], v[104:107]
	v_mfma_f32_16x16x32_bf16 v[100:103], v[164:167], v[222:225], v[100:103]
	v_mfma_f32_16x16x32_bf16 v[96:99], v[172:175], v[222:225], v[96:99]
	v_mfma_f32_16x16x32_bf16 v[60:63], v[176:179], v[194:197], v[60:63]
	v_mfma_f32_16x16x32_bf16 v[56:59], v[186:189], v[194:197], v[56:59]
	v_mfma_f32_16x16x32_bf16 v[52:55], v[176:179], v[202:205], v[52:55]
	v_mfma_f32_16x16x32_bf16 v[48:51], v[186:189], v[202:205], v[48:51]
	v_mfma_f32_16x16x32_bf16 v[44:47], v[176:179], v[210:213], v[44:47]
	v_mfma_f32_16x16x32_bf16 v[40:43], v[186:189], v[210:213], v[40:43]
	v_mfma_f32_16x16x32_bf16 v[36:39], v[176:179], v[218:221], v[36:39]
	v_mfma_f32_16x16x32_bf16 v[32:35], v[186:189], v[218:221], v[32:35]
	v_mfma_f32_16x16x32_bf16 v[60:63], v[180:183], v[198:201], v[60:63]
	v_mfma_f32_16x16x32_bf16 v[56:59], v[190:193], v[198:201], v[56:59]
	v_mfma_f32_16x16x32_bf16 v[52:55], v[180:183], v[206:209], v[52:55]
	v_mfma_f32_16x16x32_bf16 v[48:51], v[190:193], v[206:209], v[48:51]
	v_mfma_f32_16x16x32_bf16 v[44:47], v[180:183], v[214:217], v[44:47]
	v_mfma_f32_16x16x32_bf16 v[40:43], v[190:193], v[214:217], v[40:43]
	v_mfma_f32_16x16x32_bf16 v[36:39], v[180:183], v[222:225], v[36:39]
	v_mfma_f32_16x16x32_bf16 v[32:35], v[190:193], v[222:225], v[32:35]
	s_barrier
; #define PG8_STAGE(bufoff, gbase, voff) do { _Pragma("unroll") for (int _i = 0; _i < 2; ++_i) \
;         __builtin_amdgcn_global_load_lds((const unsigned*)((const char*)(gbase) + (voff)[_i]), (LAS unsigned*)(lds + (bufoff) + ldsw + _i * 8192), 16, 0, 0); } while (0)
; #define PG8_LDA(dst, b, h) do { _Pragma("unroll") for (int m = 0; m < 4; ++m) _Pragma("unroll") for (int k = 0; k < 2; ++k) dst[m][k] = *(const LAS bf16x8*)(lds + PG8_SA(b, h) + aoff + m * 2048 + k * 1024); } while (0)
; #define PG8_MMA(ai, bj, At, Bt) do { __builtin_amdgcn_s_setprio(1); _Pragma("unroll") for (int m = 0; m < 4; ++m) _Pragma("unroll") for (int n = 0; n < 2; ++n) _Pragma("unroll") for (int k = 0; k < 2; ++k) \
;         acc[ai][bj][m][n] = __builtin_amdgcn_mfma_f32_16x16x32_bf16(Bt[n][k], At[m][k], acc[ai][bj][m][n], 0, 0, 0); __builtin_amdgcn_s_setprio(0); } while (0)
; #define PG8_WAIT_V(n) asm volatile("s_waitcnt vmcnt(" #n ")" ::: "memory")
; #define PG8_WAIT_L(n) asm volatile("s_waitcnt lgkmcnt(" #n ")" ::: "memory")
; #define PG8_BAR __builtin_amdgcn_s_barrier()
; #define PG8_SCHED __builtin_amdgcn_sched_barrier(0)
; template <class Epi, bool ALIGN_EPI = PG8_ALIGN>
; __device__ __forceinline__ void gemm_phase(LAS unsigned char* lds, const Gemm g, const StaticOrder S, const Epi E) {
;     ...
;             PG8_LDA(At, 1, 1); PG8_STAGE(PG8_SB(1, 0), b3, voffB); PG8_STAGE(PG8_SB(1, 1), b3 + hstepB, voffB); PG8_STAGE(PG8_SA(1, 0), a3, voffA);
;             PG8_WAIT_V(8); PG8_WAIT_L(0); PG8_BAR; PG8_MMA(1, 0, At, B0); PG8_MMA(1, 1, At, B1); PG8_BAR; PG8_SCHED;
;         }
;         if (ALIGN_EPI) { if (wr == 0) PG8_BAR; }
	s_add_i32 s42, s47, s62
	v_lshl_add_u64 v[226:227], v[226:227], 0, s[6:7]
	s_mov_b32 m0, s42
	ds_read_b128 v[194:197], v162 offset:49152
	ds_read_b128 v[198:201], v162 offset:50176
	ds_read_b128 v[202:205], v162 offset:51200
	ds_read_b128 v[206:209], v162 offset:52224
	ds_read_b128 v[210:213], v162 offset:53248
	ds_read_b128 v[214:217], v162 offset:54272
	ds_read_b128 v[218:221], v162 offset:55296
	ds_read_b128 v[222:225], v162 offset:56320
	global_load_lds_dwordx4 v[226:227], off
	s_add_i32 m0, s42, 0x2000
	s_add_u32 s42, s58, 0x80080
	v_lshl_add_u64 v[226:227], v[228:229], 0, s[6:7]
	s_addc_u32 s43, s59, 0
	s_add_i32 s47, s76, s62
	global_load_lds_dwordx4 v[226:227], off
	v_lshl_add_u64 v[226:227], s[42:43], 0, v[130:131]
	s_mov_b32 m0, s47
	s_nop 0
	global_load_lds_dwordx4 v[226:227], off
	v_lshl_add_u64 v[226:227], s[42:43], 0, v[134:135]
	s_add_i32 m0, s47, 0x2000
	s_nop 0
	global_load_lds_dwordx4 v[226:227], off
	v_lshl_add_u64 v[226:227], v[230:231], 0, s[6:7]
	s_mov_b32 m0, s69
	s_nop 0
	global_load_lds_dwordx4 v[226:227], off
	v_lshl_add_u64 v[226:227], v[232:233], 0, s[6:7]
	s_mov_b32 m0, s70
	s_nop 0
	global_load_lds_dwordx4 v[226:227], off
	s_waitcnt vmcnt(8)
	s_waitcnt lgkmcnt(0)
	s_barrier
	s_waitcnt lgkmcnt(0)
	v_mfma_f32_16x16x32_bf16 v[92:95], v[144:147], v[194:197], v[92:95]
	v_mfma_f32_16x16x32_bf16 v[88:91], v[168:171], v[194:197], v[88:91]
	v_mfma_f32_16x16x32_bf16 v[84:87], v[144:147], v[202:205], v[84:87]
	v_mfma_f32_16x16x32_bf16 v[80:83], v[168:171], v[202:205], v[80:83]
	v_mfma_f32_16x16x32_bf16 v[76:79], v[144:147], v[210:213], v[76:79]
	v_mfma_f32_16x16x32_bf16 v[72:75], v[168:171], v[210:213], v[72:75]
	v_mfma_f32_16x16x32_bf16 v[68:71], v[144:147], v[218:221], v[68:71]
	v_mfma_f32_16x16x32_bf16 v[64:67], v[168:171], v[218:221], v[64:67]
	v_mfma_f32_16x16x32_bf16 v[92:95], v[164:167], v[198:201], v[92:95]
	v_mfma_f32_16x16x32_bf16 v[88:91], v[172:175], v[198:201], v[88:91]
	v_mfma_f32_16x16x32_bf16 v[84:87], v[164:167], v[206:209], v[84:87]
	v_mfma_f32_16x16x32_bf16 v[80:83], v[172:175], v[206:209], v[80:83]
	v_mfma_f32_16x16x32_bf16 v[76:79], v[164:167], v[214:217], v[76:79]
	v_mfma_f32_16x16x32_bf16 v[72:75], v[172:175], v[214:217], v[72:75]
	v_mfma_f32_16x16x32_bf16 v[68:71], v[164:167], v[222:225], v[68:71]
	v_mfma_f32_16x16x32_bf16 v[64:67], v[172:175], v[222:225], v[64:67]
	v_mfma_f32_16x16x32_bf16 v[28:31], v[176:179], v[194:197], v[28:31]
	v_mfma_f32_16x16x32_bf16 v[24:27], v[186:189], v[194:197], v[24:27]
	v_mfma_f32_16x16x32_bf16 v[20:23], v[176:179], v[202:205], v[20:23]
	v_mfma_f32_16x16x32_bf16 v[16:19], v[186:189], v[202:205], v[16:19]
	v_mfma_f32_16x16x32_bf16 v[12:15], v[176:179], v[210:213], v[12:15]
	v_mfma_f32_16x16x32_bf16 v[8:11], v[186:189], v[210:213], v[8:11]
	v_mfma_f32_16x16x32_bf16 v[4:7], v[176:179], v[218:221], v[4:7]
	v_mfma_f32_16x16x32_bf16 v[0:3], v[186:189], v[218:221], v[0:3]
	v_mfma_f32_16x16x32_bf16 v[28:31], v[180:183], v[198:201], v[28:31]
	v_mfma_f32_16x16x32_bf16 v[24:27], v[190:193], v[198:201], v[24:27]
	v_mfma_f32_16x16x32_bf16 v[20:23], v[180:183], v[206:209], v[20:23]
	v_mfma_f32_16x16x32_bf16 v[16:19], v[190:193], v[206:209], v[16:19]
	v_mfma_f32_16x16x32_bf16 v[12:15], v[180:183], v[214:217], v[12:15]
	v_mfma_f32_16x16x32_bf16 v[8:11], v[190:193], v[214:217], v[8:11]
	v_mfma_f32_16x16x32_bf16 v[4:7], v[180:183], v[222:225], v[4:7]
	v_mfma_f32_16x16x32_bf16 v[0:3], v[190:193], v[222:225], v[0:3]
	s_barrier
	s_add_i32 s35, s35, 2
	s_add_u32 s52, s52, 0x100
	s_addc_u32 s53, s53, 0
	s_add_u32 s33, s33, 0x100
	s_addc_u32 s34, s34, 0
	s_cmp_gt_u32 s35, 29
	s_cbranch_scc0 .LBB0_507
	s_and_b64 vcc, exec, s[8:9]
	s_cbranch_vccz .LBB0_510
	s_barrier

; #define PG8_STAGE(bufoff, gbase, voff) do { _Pragma("unroll") for (int _i = 0; _i < 2; ++_i) \
;         __builtin_amdgcn_global_load_lds((const unsigned*)((const char*)(gbase) + (voff)[_i]), (LAS unsigned*)(lds + (bufoff) + ldsw + _i * 8192), 16, 0, 0); } while (0)
; #define PG8_LDA(dst, b, h) do { _Pragma("unroll") for (int m = 0; m < 4; ++m) _Pragma("unroll") for (int k = 0; k < 2; ++k) dst[m][k] = *(const LAS bf16x8*)(lds + PG8_SA(b, h) + aoff + m * 2048 + k * 1024); } while (0)
; #define PG8_LDB(dst, b, h) do { _Pragma("unroll") for (int n = 0; n < 2; ++n) _Pragma("unroll") for (int k = 0; k < 2; ++k) dst[n][k] = *(const LAS bf16x8*)(lds + PG8_SB(b, h) + boff + n * 2048 + k * 1024); } while (0)
; #define PG8_MMA(ai, bj, At, Bt) do { __builtin_amdgcn_s_setprio(1); _Pragma("unroll") for (int m = 0; m < 4; ++m) _Pragma("unroll") for (int n = 0; n < 2; ++n) _Pragma("unroll") for (int k = 0; k < 2; ++k) \
;         acc[ai][bj][m][n] = __builtin_amdgcn_mfma_f32_16x16x32_bf16(Bt[n][k], At[m][k], acc[ai][bj][m][n], 0, 0, 0); __builtin_amdgcn_s_setprio(0); } while (0)
; #define PG8_WAIT_V(n) asm volatile("s_waitcnt vmcnt(" #n ")" ::: "memory")
; #define PG8_WAIT_L(n) asm volatile("s_waitcnt lgkmcnt(" #n ")" ::: "memory")
; #define PG8_BAR __builtin_amdgcn_s_barrier()
; #define PG8_SCHED __builtin_amdgcn_sched_barrier(0)
; template <class Epi, bool ALIGN_EPI = PG8_ALIGN>
; __device__ __forceinline__ void gemm_phase(LAS unsigned char* lds, const Gemm g, const StaticOrder S, const Epi E) {
;     ...
;         for (int t = 0; t < nt; t += 2) {
;             const bool last = (t == nt - 2);
;             const char* a1 = cA + (size_t)(t + 1) * kstep;
;             const char* a2 = last ? nA : cA + (size_t)(t + 2) * kstep; const char* b2 = last ? nB : cB + (size_t)(t + 2) * kstep;
;             const char* a3 = a2 + kstep; const char* b3 = b2 + kstep;
;             PG8_LDB(B0, 0, 0); PG8_LDB(B1, 0, 1); PG8_SCHED; PG8_LDA(At, 0, 0); PG8_STAGE(PG8_SA(1, 1), a1 + hstepA, voffA);
;             PG8_WAIT_V(8); PG8_WAIT_L(0); PG8_BAR; PG8_MMA(0, 0, At, B0); PG8_MMA(0, 1, At, B1); PG8_BAR; PG8_SCHED;
;             PG8_LDA(At, 0, 1); PG8_STAGE(PG8_SB(0, 0), b2, voffB); PG8_STAGE(PG8_SB(0, 1), b2 + hstepB, voffB); PG8_STAGE(PG8_SA(0, 0), a2, voffA);
;             PG8_WAIT_V(8); PG8_WAIT_L(0); PG8_BAR; PG8_MMA(1, 0, At, B0); PG8_MMA(1, 1, At, B1); PG8_BAR; PG8_SCHED;
.LBB0_531:
	ds_read_b128 v[146:149], v161
	ds_read_b128 v[150:153], v161 offset:1024
	ds_read_b128 v[154:157], v161 offset:2048
	ds_read_b128 v[164:167], v161 offset:3072
	ds_read_b128 v[168:171], v162
	ds_read_b128 v[172:175], v162 offset:1024
	ds_read_b128 v[176:179], v162 offset:2048
	ds_read_b128 v[180:183], v162 offset:3072
	s_add_u32 s42, s12, 0xfff80080
	s_addc_u32 s43, s13, -1
	s_cmp_eq_u32 vcc_lo, 28
	s_cselect_b32 s67, s14, s43
	s_cselect_b32 s66, s59, s42
	s_cselect_b32 s65, s53, s97
	s_cselect_b32 s64, s93, s95
	v_lshl_add_u64 v[218:219], s[12:13], 0, v[138:139]
	s_add_i32 m0, s34, 0xc000
	ds_read_b128 v[186:189], v163
	ds_read_b128 v[190:193], v163 offset:1024
	ds_read_b128 v[194:197], v163 offset:2048
	ds_read_b128 v[198:201], v163 offset:3072
	ds_read_b128 v[202:205], v163 offset:4096
	ds_read_b128 v[206:209], v163 offset:5120
	ds_read_b128 v[210:213], v163 offset:6144
	ds_read_b128 v[214:217], v163 offset:7168
	global_load_lds_dwordx4 v[218:219], off
	v_lshl_add_u64 v[218:219], s[12:13], 0, v[140:141]
	s_add_i32 m0, s34, 0xe000
	s_nop 0
	global_load_lds_dwordx4 v[218:219], off
	s_waitcnt vmcnt(8)
	s_waitcnt lgkmcnt(0)
	s_barrier
	s_waitcnt lgkmcnt(0)
	v_mfma_f32_16x16x32_bf16 v[124:127], v[146:149], v[186:189], v[124:127]
	v_mfma_f32_16x16x32_bf16 v[120:123], v[154:157], v[186:189], v[120:123]
	v_mfma_f32_16x16x32_bf16 v[116:119], v[146:149], v[194:197], v[116:119]
	v_mfma_f32_16x16x32_bf16 v[112:115], v[154:157], v[194:197], v[112:115]
	v_mfma_f32_16x16x32_bf16 v[108:111], v[146:149], v[202:205], v[108:111]
	v_mfma_f32_16x16x32_bf16 v[104:107], v[154:157], v[202:205], v[104:107]
	v_mfma_f32_16x16x32_bf16 v[100:103], v[146:149], v[210:213], v[100:103]
	v_mfma_f32_16x16x32_bf16 v[96:99], v[154:157], v[210:213], v[96:99]
	v_mfma_f32_16x16x32_bf16 v[124:127], v[150:153], v[190:193], v[124:127]
	v_mfma_f32_16x16x32_bf16 v[120:123], v[164:167], v[190:193], v[120:123]
	v_mfma_f32_16x16x32_bf16 v[116:119], v[150:153], v[198:201], v[116:119]
	v_mfma_f32_16x16x32_bf16 v[112:115], v[164:167], v[198:201], v[112:115]
	v_mfma_f32_16x16x32_bf16 v[108:111], v[150:153], v[206:209], v[108:111]
	v_mfma_f32_16x16x32_bf16 v[104:107], v[164:167], v[206:209], v[104:107]
	v_mfma_f32_16x16x32_bf16 v[100:103], v[150:153], v[214:217], v[100:103]
	v_mfma_f32_16x16x32_bf16 v[96:99], v[164:167], v[214:217], v[96:99]
	v_mfma_f32_16x16x32_bf16 v[60:63], v[168:171], v[186:189], v[60:63]
	v_mfma_f32_16x16x32_bf16 v[56:59], v[176:179], v[186:189], v[56:59]
	v_mfma_f32_16x16x32_bf16 v[52:55], v[168:171], v[194:197], v[52:55]
	v_mfma_f32_16x16x32_bf16 v[48:51], v[176:179], v[194:197], v[48:51]
	v_mfma_f32_16x16x32_bf16 v[44:47], v[168:171], v[202:205], v[44:47]
	v_mfma_f32_16x16x32_bf16 v[40:43], v[176:179], v[202:205], v[40:43]
	v_mfma_f32_16x16x32_bf16 v[36:39], v[168:171], v[210:213], v[36:39]
	v_mfma_f32_16x16x32_bf16 v[32:35], v[176:179], v[210:213], v[32:35]
	v_mfma_f32_16x16x32_bf16 v[60:63], v[172:175], v[190:193], v[60:63]
	v_mfma_f32_16x16x32_bf16 v[56:59], v[180:183], v[190:193], v[56:59]
	v_mfma_f32_16x16x32_bf16 v[52:55], v[172:175], v[198:201], v[52:55]
	v_mfma_f32_16x16x32_bf16 v[48:51], v[180:183], v[198:201], v[48:51]
	v_mfma_f32_16x16x32_bf16 v[44:47], v[172:175], v[206:209], v[44:47]
	v_mfma_f32_16x16x32_bf16 v[40:43], v[180:183], v[206:209], v[40:43]
	v_mfma_f32_16x16x32_bf16 v[36:39], v[172:175], v[214:217], v[36:39]
	v_mfma_f32_16x16x32_bf16 v[32:35], v[180:183], v[214:217], v[32:35]
	s_barrier
	s_add_i32 s42, s79, s33
	v_lshl_add_u64 v[218:219], s[64:65], 0, v[130:131]
	s_mov_b32 m0, s42
	ds_read_b128 v[186:189], v163 offset:16384
	ds_read_b128 v[190:193], v163 offset:17408
	ds_read_b128 v[194:197], v163 offset:18432
	ds_read_b128 v[198:201], v163 offset:19456
	ds_read_b128 v[202:205], v163 offset:20480
	ds_read_b128 v[206:209], v163 offset:21504
	ds_read_b128 v[210:213], v163 offset:22528
	ds_read_b128 v[214:217], v163 offset:23552
	global_load_lds_dwordx4 v[218:219], off
	s_add_i32 m0, s42, 0x2000
	s_add_u32 s42, s64, 0x80000
	v_lshl_add_u64 v[220:221], s[64:65], 0, v[134:135]
	s_addc_u32 s43, s65, 0
	s_add_i32 s84, s81, s33
	global_load_lds_dwordx4 v[220:221], off
	v_lshl_add_u64 v[222:223], s[42:43], 0, v[130:131]
	s_mov_b32 m0, s84
	v_lshl_add_u64 v[224:225], s[66:67], 0, v[132:133]
	global_load_lds_dwordx4 v[222:223], off
	v_lshl_add_u64 v[222:223], s[42:43], 0, v[134:135]
	s_add_i32 m0, s84, 0x2000
	s_nop 0
	global_load_lds_dwordx4 v[222:223], off
	v_lshl_add_u64 v[222:223], s[66:67], 0, v[128:129]
	s_mov_b32 m0, s34
	s_nop 0
	global_load_lds_dwordx4 v[222:223], off
	s_mov_b32 m0, s35
	s_nop 0
	global_load_lds_dwordx4 v[224:225], off
	s_waitcnt vmcnt(8)
	s_waitcnt lgkmcnt(0)
	s_barrier
; #define PG8_STAGE(bufoff, gbase, voff) do { _Pragma("unroll") for (int _i = 0; _i < 2; ++_i) \
;         __builtin_amdgcn_global_load_lds((const unsigned*)((const char*)(gbase) + (voff)[_i]), (LAS unsigned*)(lds + (bufoff) + ldsw + _i * 8192), 16, 0, 0); } while (0)
; #define PG8_LDA(dst, b, h) do { _Pragma("unroll") for (int m = 0; m < 4; ++m) _Pragma("unroll") for (int k = 0; k < 2; ++k) dst[m][k] = *(const LAS bf16x8*)(lds + PG8_SA(b, h) + aoff + m * 2048 + k * 1024); } while (0)
; #define PG8_LDB(dst, b, h) do { _Pragma("unroll") for (int n = 0; n < 2; ++n) _Pragma("unroll") for (int k = 0; k < 2; ++k) dst[n][k] = *(const LAS bf16x8*)(lds + PG8_SB(b, h) + boff + n * 2048 + k * 1024); } while (0)
; #define PG8_MMA(ai, bj, At, Bt) do { __builtin_amdgcn_s_setprio(1); _Pragma("unroll") for (int m = 0; m < 4; ++m) _Pragma("unroll") for (int n = 0; n < 2; ++n) _Pragma("unroll") for (int k = 0; k < 2; ++k) \
;         acc[ai][bj][m][n] = __builtin_amdgcn_mfma_f32_16x16x32_bf16(Bt[n][k], At[m][k], acc[ai][bj][m][n], 0, 0, 0); __builtin_amdgcn_s_setprio(0); } while (0)
; #define PG8_WAIT_V(n) asm volatile("s_waitcnt vmcnt(" #n ")" ::: "memory")
; #define PG8_WAIT_L(n) asm volatile("s_waitcnt lgkmcnt(" #n ")" ::: "memory")
; #define PG8_BAR __builtin_amdgcn_s_barrier()
; #define PG8_SCHED __builtin_amdgcn_sched_barrier(0)
; template <class Epi, bool ALIGN_EPI = PG8_ALIGN>
; __device__ __forceinline__ void gemm_phase(LAS unsigned char* lds, const Gemm g, const StaticOrder S, const Epi E) {
;     ...
;             PG8_WAIT_V(8); PG8_WAIT_L(0); PG8_BAR; PG8_MMA(1, 0, At, B0); PG8_MMA(1, 1, At, B1); PG8_BAR; PG8_SCHED;
;             PG8_LDB(B0, 1, 0); PG8_LDB(B1, 1, 1); PG8_SCHED; PG8_LDA(At, 1, 0); PG8_STAGE(PG8_SA(0, 1), a2 + hstepA, voffA);
;             PG8_WAIT_V(8); PG8_WAIT_L(0); PG8_BAR; PG8_MMA(0, 0, At, B0); PG8_MMA(0, 1, At, B1); PG8_BAR; PG8_SCHED;
;             PG8_LDA(At, 1, 1); PG8_STAGE(PG8_SB(1, 0), b3, voffB); PG8_STAGE(PG8_SB(1, 1), b3 + hstepB, voffB); PG8_STAGE(PG8_SA(1, 0), a3, voffA);
;             PG8_WAIT_V(8); PG8_WAIT_L(0); PG8_BAR; PG8_MMA(1, 0, At, B0); PG8_MMA(1, 1, At, B1); PG8_BAR; PG8_SCHED;
	s_waitcnt lgkmcnt(0)
	v_mfma_f32_16x16x32_bf16 v[92:95], v[146:149], v[186:189], v[92:95]
	v_mfma_f32_16x16x32_bf16 v[88:91], v[154:157], v[186:189], v[88:91]
	v_mfma_f32_16x16x32_bf16 v[84:87], v[146:149], v[194:197], v[84:87]
	v_mfma_f32_16x16x32_bf16 v[80:83], v[154:157], v[194:197], v[80:83]
	v_mfma_f32_16x16x32_bf16 v[76:79], v[146:149], v[202:205], v[76:79]
	v_mfma_f32_16x16x32_bf16 v[72:75], v[154:157], v[202:205], v[72:75]
	v_mfma_f32_16x16x32_bf16 v[68:71], v[146:149], v[210:213], v[68:71]
	v_mfma_f32_16x16x32_bf16 v[64:67], v[154:157], v[210:213], v[64:67]
	v_mfma_f32_16x16x32_bf16 v[92:95], v[150:153], v[190:193], v[92:95]
	v_mfma_f32_16x16x32_bf16 v[88:91], v[164:167], v[190:193], v[88:91]
	v_mfma_f32_16x16x32_bf16 v[84:87], v[150:153], v[198:201], v[84:87]
	v_mfma_f32_16x16x32_bf16 v[80:83], v[164:167], v[198:201], v[80:83]
	v_mfma_f32_16x16x32_bf16 v[76:79], v[150:153], v[206:209], v[76:79]
	v_mfma_f32_16x16x32_bf16 v[72:75], v[164:167], v[206:209], v[72:75]
	v_mfma_f32_16x16x32_bf16 v[68:71], v[150:153], v[214:217], v[68:71]
	v_mfma_f32_16x16x32_bf16 v[64:67], v[164:167], v[214:217], v[64:67]
	v_mfma_f32_16x16x32_bf16 v[28:31], v[168:171], v[186:189], v[28:31]
	v_mfma_f32_16x16x32_bf16 v[24:27], v[176:179], v[186:189], v[24:27]
	v_mfma_f32_16x16x32_bf16 v[20:23], v[168:171], v[194:197], v[20:23]
	v_mfma_f32_16x16x32_bf16 v[16:19], v[176:179], v[194:197], v[16:19]
	v_mfma_f32_16x16x32_bf16 v[12:15], v[168:171], v[202:205], v[12:15]
	v_mfma_f32_16x16x32_bf16 v[8:11], v[176:179], v[202:205], v[8:11]
	v_mfma_f32_16x16x32_bf16 v[4:7], v[168:171], v[210:213], v[4:7]
	v_mfma_f32_16x16x32_bf16 v[0:3], v[176:179], v[210:213], v[0:3]
	v_mfma_f32_16x16x32_bf16 v[28:31], v[172:175], v[190:193], v[28:31]
	v_mfma_f32_16x16x32_bf16 v[24:27], v[180:183], v[190:193], v[24:27]
	v_mfma_f32_16x16x32_bf16 v[20:23], v[172:175], v[198:201], v[20:23]
	v_mfma_f32_16x16x32_bf16 v[16:19], v[180:183], v[198:201], v[16:19]
	v_mfma_f32_16x16x32_bf16 v[12:15], v[172:175], v[206:209], v[12:15]
	v_mfma_f32_16x16x32_bf16 v[8:11], v[180:183], v[206:209], v[8:11]
	v_mfma_f32_16x16x32_bf16 v[4:7], v[172:175], v[214:217], v[4:7]
	v_mfma_f32_16x16x32_bf16 v[0:3], v[180:183], v[214:217], v[0:3]
	s_barrier
	s_add_i32 s84, 0, 0x18000
	s_add_i32 s85, 0, 0x1c000
	v_add_u32_e32 v164, s84, v160
	v_add_u32_e32 v180, s85, v160
	ds_read_b128 v[146:149], v164
	ds_read_b128 v[150:153], v164 offset:1024
	ds_read_b128 v[154:157], v164 offset:2048
	ds_read_b128 v[164:167], v164 offset:3072
	ds_read_b128 v[168:171], v180
	ds_read_b128 v[172:175], v180 offset:1024
	ds_read_b128 v[176:179], v180 offset:2048
	ds_read_b128 v[180:183], v180 offset:3072
	s_add_u32 s42, s66, 0x80000
	s_addc_u32 s43, s67, 0
	s_mov_b32 m0, s49
	v_lshl_add_u64 v[226:227], s[42:43], 0, v[128:129]
	ds_read_b128 v[186:189], v163 offset:32768
	ds_read_b128 v[190:193], v163 offset:33792
	ds_read_b128 v[194:197], v163 offset:34816
	ds_read_b128 v[198:201], v163 offset:35840
	ds_read_b128 v[202:205], v163 offset:36864
	ds_read_b128 v[206:209], v163 offset:37888
	ds_read_b128 v[210:213], v163 offset:38912
	ds_read_b128 v[214:217], v163 offset:39936
	global_load_lds_dwordx4 v[226:227], off
	v_lshl_add_u64 v[226:227], s[42:43], 0, v[132:133]
	s_mov_b32 m0, s51
	s_nop 0
	global_load_lds_dwordx4 v[226:227], off
	s_waitcnt vmcnt(8)
	s_waitcnt lgkmcnt(0)
	s_barrier
	s_waitcnt lgkmcnt(0)
	v_mfma_f32_16x16x32_bf16 v[124:127], v[146:149], v[186:189], v[124:127]
	v_mfma_f32_16x16x32_bf16 v[120:123], v[154:157], v[186:189], v[120:123]
	v_mfma_f32_16x16x32_bf16 v[116:119], v[146:149], v[194:197], v[116:119]
	v_mfma_f32_16x16x32_bf16 v[112:115], v[154:157], v[194:197], v[112:115]
	v_mfma_f32_16x16x32_bf16 v[108:111], v[146:149], v[202:205], v[108:111]
	v_mfma_f32_16x16x32_bf16 v[104:107], v[154:157], v[202:205], v[104:107]
	v_mfma_f32_16x16x32_bf16 v[100:103], v[146:149], v[210:213], v[100:103]
	v_mfma_f32_16x16x32_bf16 v[96:99], v[154:157], v[210:213], v[96:99]
	v_mfma_f32_16x16x32_bf16 v[124:127], v[150:153], v[190:193], v[124:127]
	v_mfma_f32_16x16x32_bf16 v[120:123], v[164:167], v[190:193], v[120:123]
	v_mfma_f32_16x16x32_bf16 v[116:119], v[150:153], v[198:201], v[116:119]
	v_mfma_f32_16x16x32_bf16 v[112:115], v[164:167], v[198:201], v[112:115]
	v_mfma_f32_16x16x32_bf16 v[108:111], v[150:153], v[206:209], v[108:111]
	v_mfma_f32_16x16x32_bf16 v[104:107], v[164:167], v[206:209], v[104:107]
	v_mfma_f32_16x16x32_bf16 v[100:103], v[150:153], v[214:217], v[100:103]
	v_mfma_f32_16x16x32_bf16 v[96:99], v[164:167], v[214:217], v[96:99]
	v_mfma_f32_16x16x32_bf16 v[60:63], v[168:171], v[186:189], v[60:63]
	v_mfma_f32_16x16x32_bf16 v[56:59], v[176:179], v[186:189], v[56:59]
	v_mfma_f32_16x16x32_bf16 v[52:55], v[168:171], v[194:197], v[52:55]
	v_mfma_f32_16x16x32_bf16 v[48:51], v[176:179], v[194:197], v[48:51]
	v_mfma_f32_16x16x32_bf16 v[44:47], v[168:171], v[202:205], v[44:47]
	v_mfma_f32_16x16x32_bf16 v[40:43], v[176:179], v[202:205], v[40:43]
	v_mfma_f32_16x16x32_bf16 v[36:39], v[168:171], v[210:213], v[36:39]
	v_mfma_f32_16x16x32_bf16 v[32:35], v[176:179], v[210:213], v[32:35]
	v_mfma_f32_16x16x32_bf16 v[60:63], v[172:175], v[190:193], v[60:63]
	v_mfma_f32_16x16x32_bf16 v[56:59], v[180:183], v[190:193], v[56:59]
	v_mfma_f32_16x16x32_bf16 v[52:55], v[172:175], v[198:201], v[52:55]
	v_mfma_f32_16x16x32_bf16 v[48:51], v[180:183], v[198:201], v[48:51]
	v_mfma_f32_16x16x32_bf16 v[44:47], v[172:175], v[206:209], v[44:47]
	v_mfma_f32_16x16x32_bf16 v[40:43], v[180:183], v[206:209], v[40:43]
	v_mfma_f32_16x16x32_bf16 v[36:39], v[172:175], v[214:217], v[36:39]
	v_mfma_f32_16x16x32_bf16 v[32:35], v[180:183], v[214:217], v[32:35]
	s_barrier
; #define PG8_STAGE(bufoff, gbase, voff) do { _Pragma("unroll") for (int _i = 0; _i < 2; ++_i) \
;         __builtin_amdgcn_global_load_lds((const unsigned*)((const char*)(gbase) + (voff)[_i]), (LAS unsigned*)(lds + (bufoff) + ldsw + _i * 8192), 16, 0, 0); } while (0)
; #define PG8_LDA(dst, b, h) do { _Pragma("unroll") for (int m = 0; m < 4; ++m) _Pragma("unroll") for (int k = 0; k < 2; ++k) dst[m][k] = *(const LAS bf16x8*)(lds + PG8_SA(b, h) + aoff + m * 2048 + k * 1024); } while (0)
; #define PG8_MMA(ai, bj, At, Bt) do { __builtin_amdgcn_s_setprio(1); _Pragma("unroll") for (int m = 0; m < 4; ++m) _Pragma("unroll") for (int n = 0; n < 2; ++n) _Pragma("unroll") for (int k = 0; k < 2; ++k) \
;         acc[ai][bj][m][n] = __builtin_amdgcn_mfma_f32_16x16x32_bf16(Bt[n][k], At[m][k], acc[ai][bj][m][n], 0, 0, 0); __builtin_amdgcn_s_setprio(0); } while (0)
; #define PG8_WAIT_V(n) asm volatile("s_waitcnt vmcnt(" #n ")" ::: "memory")
; #define PG8_WAIT_L(n) asm volatile("s_waitcnt lgkmcnt(" #n ")" ::: "memory")
; #define PG8_BAR __builtin_amdgcn_s_barrier()
; #define PG8_SCHED __builtin_amdgcn_sched_barrier(0)
; template <class Epi, bool ALIGN_EPI = PG8_ALIGN>
; __device__ __forceinline__ void gemm_phase(LAS unsigned char* lds, const Gemm g, const StaticOrder S, const Epi E) {
;     ...
;             PG8_LDA(At, 1, 1); PG8_STAGE(PG8_SB(1, 0), b3, voffB); PG8_STAGE(PG8_SB(1, 1), b3 + hstepB, voffB); PG8_STAGE(PG8_SA(1, 0), a3, voffA);
;             PG8_WAIT_V(8); PG8_WAIT_L(0); PG8_BAR; PG8_MMA(1, 0, At, B0); PG8_MMA(1, 1, At, B1); PG8_BAR; PG8_SCHED;
;         }
;         if (ALIGN_EPI) { if (wr == 0) PG8_BAR; }
	s_add_i32 s42, s84, s33
	v_lshl_add_u64 v[218:219], v[218:219], 0, s[10:11]
	s_mov_b32 m0, s42
	ds_read_b128 v[186:189], v163 offset:49152
	ds_read_b128 v[190:193], v163 offset:50176
	ds_read_b128 v[194:197], v163 offset:51200
	ds_read_b128 v[198:201], v163 offset:52224
	ds_read_b128 v[202:205], v163 offset:53248
	ds_read_b128 v[206:209], v163 offset:54272
	ds_read_b128 v[210:213], v163 offset:55296
	ds_read_b128 v[214:217], v163 offset:56320
	global_load_lds_dwordx4 v[218:219], off
	s_add_i32 m0, s42, 0x2000
	s_add_u32 s42, s64, 0x80080
	v_lshl_add_u64 v[218:219], v[220:221], 0, s[10:11]
	s_addc_u32 s43, s65, 0
	s_add_i32 s64, s85, s33
	global_load_lds_dwordx4 v[218:219], off
	v_lshl_add_u64 v[218:219], s[42:43], 0, v[130:131]
	s_mov_b32 m0, s64
	s_nop 0
	global_load_lds_dwordx4 v[218:219], off
	v_lshl_add_u64 v[218:219], s[42:43], 0, v[134:135]
	s_add_i32 m0, s64, 0x2000
	s_nop 0
	global_load_lds_dwordx4 v[218:219], off
	v_lshl_add_u64 v[218:219], v[222:223], 0, s[10:11]
	s_mov_b32 m0, s71
	s_nop 0
	global_load_lds_dwordx4 v[218:219], off
	v_lshl_add_u64 v[218:219], v[224:225], 0, s[10:11]
	s_mov_b32 m0, s72
	s_nop 0
	global_load_lds_dwordx4 v[218:219], off
	s_waitcnt vmcnt(8)
	s_waitcnt lgkmcnt(0)
	s_barrier
	s_waitcnt lgkmcnt(0)
	v_mfma_f32_16x16x32_bf16 v[92:95], v[146:149], v[186:189], v[92:95]
	v_mfma_f32_16x16x32_bf16 v[88:91], v[154:157], v[186:189], v[88:91]
	v_mfma_f32_16x16x32_bf16 v[84:87], v[146:149], v[194:197], v[84:87]
	v_mfma_f32_16x16x32_bf16 v[80:83], v[154:157], v[194:197], v[80:83]
	v_mfma_f32_16x16x32_bf16 v[76:79], v[146:149], v[202:205], v[76:79]
	v_mfma_f32_16x16x32_bf16 v[72:75], v[154:157], v[202:205], v[72:75]
	v_mfma_f32_16x16x32_bf16 v[68:71], v[146:149], v[210:213], v[68:71]
	v_mfma_f32_16x16x32_bf16 v[64:67], v[154:157], v[210:213], v[64:67]
	v_mfma_f32_16x16x32_bf16 v[92:95], v[150:153], v[190:193], v[92:95]
	v_mfma_f32_16x16x32_bf16 v[88:91], v[164:167], v[190:193], v[88:91]
	v_mfma_f32_16x16x32_bf16 v[84:87], v[150:153], v[198:201], v[84:87]
	v_mfma_f32_16x16x32_bf16 v[80:83], v[164:167], v[198:201], v[80:83]
	v_mfma_f32_16x16x32_bf16 v[76:79], v[150:153], v[206:209], v[76:79]
	v_mfma_f32_16x16x32_bf16 v[72:75], v[164:167], v[206:209], v[72:75]
	v_mfma_f32_16x16x32_bf16 v[68:71], v[150:153], v[214:217], v[68:71]
	v_mfma_f32_16x16x32_bf16 v[64:67], v[164:167], v[214:217], v[64:67]
	v_mfma_f32_16x16x32_bf16 v[28:31], v[168:171], v[186:189], v[28:31]
	v_mfma_f32_16x16x32_bf16 v[24:27], v[176:179], v[186:189], v[24:27]
	v_mfma_f32_16x16x32_bf16 v[20:23], v[168:171], v[194:197], v[20:23]
	v_mfma_f32_16x16x32_bf16 v[16:19], v[176:179], v[194:197], v[16:19]
	v_mfma_f32_16x16x32_bf16 v[12:15], v[168:171], v[202:205], v[12:15]
	v_mfma_f32_16x16x32_bf16 v[8:11], v[176:179], v[202:205], v[8:11]
	v_mfma_f32_16x16x32_bf16 v[4:7], v[168:171], v[210:213], v[4:7]
	v_mfma_f32_16x16x32_bf16 v[0:3], v[176:179], v[210:213], v[0:3]
	v_mfma_f32_16x16x32_bf16 v[28:31], v[172:175], v[190:193], v[28:31]
	v_mfma_f32_16x16x32_bf16 v[24:27], v[180:183], v[190:193], v[24:27]
	v_mfma_f32_16x16x32_bf16 v[20:23], v[172:175], v[198:201], v[20:23]
	v_mfma_f32_16x16x32_bf16 v[16:19], v[180:183], v[198:201], v[16:19]
	v_mfma_f32_16x16x32_bf16 v[12:15], v[172:175], v[206:209], v[12:15]
	v_mfma_f32_16x16x32_bf16 v[8:11], v[180:183], v[206:209], v[8:11]
	v_mfma_f32_16x16x32_bf16 v[4:7], v[172:175], v[214:217], v[4:7]
	v_mfma_f32_16x16x32_bf16 v[0:3], v[180:183], v[214:217], v[0:3]
	s_barrier
	s_add_i32 vcc_lo, vcc_lo, 2
	s_add_u32 s12, s12, 0x100
	s_addc_u32 s13, s13, 0
	s_add_u32 s95, s95, 0x100
	s_addc_u32 s97, s97, 0
	s_cmp_gt_u32 vcc_lo, 29
	s_cbranch_scc0 .LBB0_531
	s_and_b64 vcc, exec, s[46:47]
	s_cbranch_vccz .LBB0_534
	s_barrier

; #define PG8_STAGE(bufoff, gbase, voff) do { _Pragma("unroll") for (int _i = 0; _i < 2; ++_i) \
;         __builtin_amdgcn_global_load_lds((const unsigned*)((const char*)(gbase) + (voff)[_i]), (LAS unsigned*)(lds + (bufoff) + ldsw + _i * 8192), 16, 0, 0); } while (0)
; #define PG8_LDA(dst, b, h) do { _Pragma("unroll") for (int m = 0; m < 4; ++m) _Pragma("unroll") for (int k = 0; k < 2; ++k) dst[m][k] = *(const LAS bf16x8*)(lds + PG8_SA(b, h) + aoff + m * 2048 + k * 1024); } while (0)
; #define PG8_LDB(dst, b, h) do { _Pragma("unroll") for (int n = 0; n < 2; ++n) _Pragma("unroll") for (int k = 0; k < 2; ++k) dst[n][k] = *(const LAS bf16x8*)(lds + PG8_SB(b, h) + boff + n * 2048 + k * 1024); } while (0)
; #define PG8_MMA(ai, bj, At, Bt) do { __builtin_amdgcn_s_setprio(1); _Pragma("unroll") for (int m = 0; m < 4; ++m) _Pragma("unroll") for (int n = 0; n < 2; ++n) _Pragma("unroll") for (int k = 0; k < 2; ++k) \
;         acc[ai][bj][m][n] = __builtin_amdgcn_mfma_f32_16x16x32_bf16(Bt[n][k], At[m][k], acc[ai][bj][m][n], 0, 0, 0); __builtin_amdgcn_s_setprio(0); } while (0)
; #define PG8_WAIT_V(n) asm volatile("s_waitcnt vmcnt(" #n ")" ::: "memory")
; #define PG8_WAIT_L(n) asm volatile("s_waitcnt lgkmcnt(" #n ")" ::: "memory")
; #define PG8_BAR __builtin_amdgcn_s_barrier()
; #define PG8_SCHED __builtin_amdgcn_sched_barrier(0)
; template <class Epi, bool ALIGN_EPI = PG8_ALIGN>
; __device__ __forceinline__ void gemm_phase(LAS unsigned char* lds, const Gemm g, const StaticOrder S, const Epi E) {
;     ...
;         for (int t = 0; t < nt; t += 2) {
;             const bool last = (t == nt - 2);
;             const char* a1 = cA + (size_t)(t + 1) * kstep;
;             const char* a2 = last ? nA : cA + (size_t)(t + 2) * kstep; const char* b2 = last ? nB : cB + (size_t)(t + 2) * kstep;
;             const char* a3 = a2 + kstep; const char* b3 = b2 + kstep;
;             PG8_LDB(B0, 0, 0); PG8_LDB(B1, 0, 1); PG8_SCHED; PG8_LDA(At, 0, 0); PG8_STAGE(PG8_SA(1, 1), a1 + hstepA, voffA);
;             PG8_WAIT_V(8); PG8_WAIT_L(0); PG8_BAR; PG8_MMA(0, 0, At, B0); PG8_MMA(0, 1, At, B1); PG8_BAR; PG8_SCHED;
;             PG8_LDA(At, 0, 1); PG8_STAGE(PG8_SB(0, 0), b2, voffB); PG8_STAGE(PG8_SB(0, 1), b2 + hstepB, voffB); PG8_STAGE(PG8_SA(0, 0), a2, voffA);
;             PG8_WAIT_V(8); PG8_WAIT_L(0); PG8_BAR; PG8_MMA(1, 0, At, B0); PG8_MMA(1, 1, At, B1); PG8_BAR; PG8_SCHED;
.LBB0_869:
	ds_read_b128 v[160:163], v156
	ds_read_b128 v[164:167], v156 offset:1024
	ds_read_b128 v[168:171], v156 offset:2048
	ds_read_b128 v[172:175], v156 offset:3072
	ds_read_b128 v[176:179], v157
	ds_read_b128 v[180:183], v157 offset:1024
	ds_read_b128 v[186:189], v157 offset:2048
	ds_read_b128 v[190:193], v157 offset:3072
	s_add_u32 s0, s50, 0xfffe0080
	s_addc_u32 s1, s51, -1
	s_cmp_eq_u32 s71, 4
	s_cselect_b32 s55, s29, s1
	s_cselect_b32 s54, s66, s0
	s_cselect_b32 s53, s27, s69
	s_cselect_b32 s52, s67, s68
	v_lshl_add_u64 v[226:227], s[50:51], 0, v[136:137]
	s_add_i32 m0, s25, 0xc000
	ds_read_b128 v[194:197], v158
	ds_read_b128 v[198:201], v158 offset:1024
	ds_read_b128 v[202:205], v158 offset:2048
	ds_read_b128 v[206:209], v158 offset:3072
	ds_read_b128 v[210:213], v158 offset:4096
	ds_read_b128 v[214:217], v158 offset:5120
	ds_read_b128 v[218:221], v158 offset:6144
	ds_read_b128 v[222:225], v158 offset:7168
	global_load_lds_dwordx4 v[226:227], off
	v_lshl_add_u64 v[226:227], s[50:51], 0, v[138:139]
	s_add_i32 m0, s25, 0xe000
	s_nop 0
	global_load_lds_dwordx4 v[226:227], off
	s_waitcnt vmcnt(8)
	s_waitcnt lgkmcnt(0)
	s_barrier
	s_waitcnt lgkmcnt(0)
	v_mfma_f32_16x16x32_bf16 v[124:127], v[160:163], v[194:197], v[124:127]
	v_mfma_f32_16x16x32_bf16 v[120:123], v[168:171], v[194:197], v[120:123]
	v_mfma_f32_16x16x32_bf16 v[116:119], v[160:163], v[202:205], v[116:119]
	v_mfma_f32_16x16x32_bf16 v[112:115], v[168:171], v[202:205], v[112:115]
	v_mfma_f32_16x16x32_bf16 v[108:111], v[160:163], v[210:213], v[108:111]
	v_mfma_f32_16x16x32_bf16 v[104:107], v[168:171], v[210:213], v[104:107]
	v_mfma_f32_16x16x32_bf16 v[100:103], v[160:163], v[218:221], v[100:103]
	v_mfma_f32_16x16x32_bf16 v[96:99], v[168:171], v[218:221], v[96:99]
	v_mfma_f32_16x16x32_bf16 v[124:127], v[164:167], v[198:201], v[124:127]
	v_mfma_f32_16x16x32_bf16 v[120:123], v[172:175], v[198:201], v[120:123]
	v_mfma_f32_16x16x32_bf16 v[116:119], v[164:167], v[206:209], v[116:119]
	v_mfma_f32_16x16x32_bf16 v[112:115], v[172:175], v[206:209], v[112:115]
	v_mfma_f32_16x16x32_bf16 v[108:111], v[164:167], v[214:217], v[108:111]
	v_mfma_f32_16x16x32_bf16 v[104:107], v[172:175], v[214:217], v[104:107]
	v_mfma_f32_16x16x32_bf16 v[100:103], v[164:167], v[222:225], v[100:103]
	v_mfma_f32_16x16x32_bf16 v[96:99], v[172:175], v[222:225], v[96:99]
	v_mfma_f32_16x16x32_bf16 v[84:87], v[176:179], v[194:197], v[84:87]
	v_mfma_f32_16x16x32_bf16 v[76:79], v[186:189], v[194:197], v[76:79]
	v_mfma_f32_16x16x32_bf16 v[68:71], v[176:179], v[202:205], v[68:71]
	v_mfma_f32_16x16x32_bf16 v[64:67], v[186:189], v[202:205], v[64:67]
	v_mfma_f32_16x16x32_bf16 v[52:55], v[176:179], v[210:213], v[52:55]
	v_mfma_f32_16x16x32_bf16 v[48:51], v[186:189], v[210:213], v[48:51]
	v_mfma_f32_16x16x32_bf16 v[40:43], v[176:179], v[218:221], v[40:43]
	v_mfma_f32_16x16x32_bf16 v[32:35], v[186:189], v[218:221], v[32:35]
	v_mfma_f32_16x16x32_bf16 v[84:87], v[180:183], v[198:201], v[84:87]
	v_mfma_f32_16x16x32_bf16 v[76:79], v[190:193], v[198:201], v[76:79]
	v_mfma_f32_16x16x32_bf16 v[68:71], v[180:183], v[206:209], v[68:71]
	v_mfma_f32_16x16x32_bf16 v[64:67], v[190:193], v[206:209], v[64:67]
	v_mfma_f32_16x16x32_bf16 v[52:55], v[180:183], v[214:217], v[52:55]
	v_mfma_f32_16x16x32_bf16 v[48:51], v[190:193], v[214:217], v[48:51]
	v_mfma_f32_16x16x32_bf16 v[40:43], v[180:183], v[222:225], v[40:43]
	v_mfma_f32_16x16x32_bf16 v[32:35], v[190:193], v[222:225], v[32:35]
	s_barrier
	s_add_i32 s0, s62, s14
	v_lshl_add_u64 v[226:227], s[52:53], 0, v[132:133]
	s_mov_b32 m0, s0
	ds_read_b128 v[194:197], v158 offset:16384
	ds_read_b128 v[198:201], v158 offset:17408
	ds_read_b128 v[202:205], v158 offset:18432
	ds_read_b128 v[206:209], v158 offset:19456
	ds_read_b128 v[210:213], v158 offset:20480
	ds_read_b128 v[214:217], v158 offset:21504
	ds_read_b128 v[218:221], v158 offset:22528
	ds_read_b128 v[222:225], v158 offset:23552
	global_load_lds_dwordx4 v[226:227], off
	s_add_i32 m0, s0, 0x2000
	s_add_u32 s0, s52, 0x20000
	v_lshl_add_u64 v[228:229], s[52:53], 0, v[128:129]
	s_addc_u32 s1, s53, 0
	s_add_i32 s42, s63, s14
	global_load_lds_dwordx4 v[228:229], off
	v_lshl_add_u64 v[230:231], s[0:1], 0, v[132:133]
	s_mov_b32 m0, s42
	v_lshl_add_u64 v[232:233], s[54:55], 0, v[130:131]
	global_load_lds_dwordx4 v[230:231], off
	v_lshl_add_u64 v[230:231], s[0:1], 0, v[128:129]
	s_add_i32 m0, s42, 0x2000
	s_nop 0
	global_load_lds_dwordx4 v[230:231], off
	v_lshl_add_u64 v[230:231], s[54:55], 0, v[134:135]
	s_mov_b32 m0, s25
	s_nop 0
	global_load_lds_dwordx4 v[230:231], off
	s_mov_b32 m0, s33
	s_nop 0
	global_load_lds_dwordx4 v[232:233], off
	s_waitcnt vmcnt(8)
	s_waitcnt lgkmcnt(0)
	s_barrier
; #define PG8_STAGE(bufoff, gbase, voff) do { _Pragma("unroll") for (int _i = 0; _i < 2; ++_i) \
;         __builtin_amdgcn_global_load_lds((const unsigned*)((const char*)(gbase) + (voff)[_i]), (LAS unsigned*)(lds + (bufoff) + ldsw + _i * 8192), 16, 0, 0); } while (0)
; #define PG8_LDA(dst, b, h) do { _Pragma("unroll") for (int m = 0; m < 4; ++m) _Pragma("unroll") for (int k = 0; k < 2; ++k) dst[m][k] = *(const LAS bf16x8*)(lds + PG8_SA(b, h) + aoff + m * 2048 + k * 1024); } while (0)
; #define PG8_LDB(dst, b, h) do { _Pragma("unroll") for (int n = 0; n < 2; ++n) _Pragma("unroll") for (int k = 0; k < 2; ++k) dst[n][k] = *(const LAS bf16x8*)(lds + PG8_SB(b, h) + boff + n * 2048 + k * 1024); } while (0)
; #define PG8_MMA(ai, bj, At, Bt) do { __builtin_amdgcn_s_setprio(1); _Pragma("unroll") for (int m = 0; m < 4; ++m) _Pragma("unroll") for (int n = 0; n < 2; ++n) _Pragma("unroll") for (int k = 0; k < 2; ++k) \
;         acc[ai][bj][m][n] = __builtin_amdgcn_mfma_f32_16x16x32_bf16(Bt[n][k], At[m][k], acc[ai][bj][m][n], 0, 0, 0); __builtin_amdgcn_s_setprio(0); } while (0)
; #define PG8_WAIT_V(n) asm volatile("s_waitcnt vmcnt(" #n ")" ::: "memory")
; #define PG8_WAIT_L(n) asm volatile("s_waitcnt lgkmcnt(" #n ")" ::: "memory")
; #define PG8_BAR __builtin_amdgcn_s_barrier()
; #define PG8_SCHED __builtin_amdgcn_sched_barrier(0)
; template <class Epi, bool ALIGN_EPI = PG8_ALIGN>
; __device__ __forceinline__ void gemm_phase(LAS unsigned char* lds, const Gemm g, const StaticOrder S, const Epi E) {
;     ...
;             PG8_WAIT_V(8); PG8_WAIT_L(0); PG8_BAR; PG8_MMA(1, 0, At, B0); PG8_MMA(1, 1, At, B1); PG8_BAR; PG8_SCHED;
;             PG8_LDB(B0, 1, 0); PG8_LDB(B1, 1, 1); PG8_SCHED; PG8_LDA(At, 1, 0); PG8_STAGE(PG8_SA(0, 1), a2 + hstepA, voffA);
;             PG8_WAIT_V(8); PG8_WAIT_L(0); PG8_BAR; PG8_MMA(0, 0, At, B0); PG8_MMA(0, 1, At, B1); PG8_BAR; PG8_SCHED;
;             PG8_LDA(At, 1, 1); PG8_STAGE(PG8_SB(1, 0), b3, voffB); PG8_STAGE(PG8_SB(1, 1), b3 + hstepB, voffB); PG8_STAGE(PG8_SA(1, 0), a3, voffA);
;             PG8_WAIT_V(8); PG8_WAIT_L(0); PG8_BAR; PG8_MMA(1, 0, At, B0); PG8_MMA(1, 1, At, B1); PG8_BAR; PG8_SCHED;
	s_waitcnt lgkmcnt(0)
	v_mfma_f32_16x16x32_bf16 v[92:95], v[160:163], v[194:197], v[92:95]
	v_mfma_f32_16x16x32_bf16 v[88:91], v[168:171], v[194:197], v[88:91]
	v_mfma_f32_16x16x32_bf16 v[80:83], v[160:163], v[202:205], v[80:83]
	v_mfma_f32_16x16x32_bf16 v[72:75], v[168:171], v[202:205], v[72:75]
	v_mfma_f32_16x16x32_bf16 v[60:63], v[160:163], v[210:213], v[60:63]
	v_mfma_f32_16x16x32_bf16 v[56:59], v[168:171], v[210:213], v[56:59]
	v_mfma_f32_16x16x32_bf16 v[44:47], v[160:163], v[218:221], v[44:47]
	v_mfma_f32_16x16x32_bf16 v[36:39], v[168:171], v[218:221], v[36:39]
	v_mfma_f32_16x16x32_bf16 v[92:95], v[164:167], v[198:201], v[92:95]
	v_mfma_f32_16x16x32_bf16 v[88:91], v[172:175], v[198:201], v[88:91]
	v_mfma_f32_16x16x32_bf16 v[80:83], v[164:167], v[206:209], v[80:83]
	v_mfma_f32_16x16x32_bf16 v[72:75], v[172:175], v[206:209], v[72:75]
	v_mfma_f32_16x16x32_bf16 v[60:63], v[164:167], v[214:217], v[60:63]
	v_mfma_f32_16x16x32_bf16 v[56:59], v[172:175], v[214:217], v[56:59]
	v_mfma_f32_16x16x32_bf16 v[44:47], v[164:167], v[222:225], v[44:47]
	v_mfma_f32_16x16x32_bf16 v[36:39], v[172:175], v[222:225], v[36:39]
	v_mfma_f32_16x16x32_bf16 v[28:31], v[176:179], v[194:197], v[28:31]
	v_mfma_f32_16x16x32_bf16 v[24:27], v[186:189], v[194:197], v[24:27]
	v_mfma_f32_16x16x32_bf16 v[20:23], v[176:179], v[202:205], v[20:23]
	v_mfma_f32_16x16x32_bf16 v[16:19], v[186:189], v[202:205], v[16:19]
	v_mfma_f32_16x16x32_bf16 v[12:15], v[176:179], v[210:213], v[12:15]
	v_mfma_f32_16x16x32_bf16 v[8:11], v[186:189], v[210:213], v[8:11]
	v_mfma_f32_16x16x32_bf16 v[4:7], v[176:179], v[218:221], v[4:7]
	v_mfma_f32_16x16x32_bf16 v[0:3], v[186:189], v[218:221], v[0:3]
	v_mfma_f32_16x16x32_bf16 v[28:31], v[180:183], v[198:201], v[28:31]
	v_mfma_f32_16x16x32_bf16 v[24:27], v[190:193], v[198:201], v[24:27]
	v_mfma_f32_16x16x32_bf16 v[20:23], v[180:183], v[206:209], v[20:23]
	v_mfma_f32_16x16x32_bf16 v[16:19], v[190:193], v[206:209], v[16:19]
	v_mfma_f32_16x16x32_bf16 v[12:15], v[180:183], v[214:217], v[12:15]
	v_mfma_f32_16x16x32_bf16 v[8:11], v[190:193], v[214:217], v[8:11]
	v_mfma_f32_16x16x32_bf16 v[4:7], v[180:183], v[222:225], v[4:7]
	v_mfma_f32_16x16x32_bf16 v[0:3], v[190:193], v[222:225], v[0:3]
	s_barrier
	s_add_i32 s42, 0, 0x18000
	v_add_u32_e32 v159, s42, v154
	s_add_i32 s43, 0, 0x1c000
	ds_read_b128 v[160:163], v159
	ds_read_b128 v[164:167], v159 offset:1024
	ds_read_b128 v[168:171], v159 offset:2048
	ds_read_b128 v[172:175], v159 offset:3072
	v_add_u32_e32 v159, s43, v154
	ds_read_b128 v[176:179], v159
	ds_read_b128 v[180:183], v159 offset:1024
	ds_read_b128 v[186:189], v159 offset:2048
	ds_read_b128 v[190:193], v159 offset:3072
	s_add_u32 s0, s54, 0x20000
	s_addc_u32 s1, s55, 0
	s_mov_b32 m0, s34
	v_lshl_add_u64 v[234:235], s[0:1], 0, v[134:135]
	ds_read_b128 v[194:197], v158 offset:32768
	ds_read_b128 v[198:201], v158 offset:33792
	ds_read_b128 v[202:205], v158 offset:34816
	ds_read_b128 v[206:209], v158 offset:35840
	ds_read_b128 v[210:213], v158 offset:36864
	ds_read_b128 v[214:217], v158 offset:37888
	ds_read_b128 v[218:221], v158 offset:38912
	ds_read_b128 v[222:225], v158 offset:39936
	global_load_lds_dwordx4 v[234:235], off
	v_lshl_add_u64 v[234:235], s[0:1], 0, v[130:131]
	s_mov_b32 m0, s35
	s_nop 0
	global_load_lds_dwordx4 v[234:235], off
	s_waitcnt vmcnt(8)
	s_waitcnt lgkmcnt(0)
	s_barrier
	s_waitcnt lgkmcnt(0)
	v_mfma_f32_16x16x32_bf16 v[124:127], v[160:163], v[194:197], v[124:127]
	v_mfma_f32_16x16x32_bf16 v[120:123], v[168:171], v[194:197], v[120:123]
	v_mfma_f32_16x16x32_bf16 v[116:119], v[160:163], v[202:205], v[116:119]
	v_mfma_f32_16x16x32_bf16 v[112:115], v[168:171], v[202:205], v[112:115]
	v_mfma_f32_16x16x32_bf16 v[108:111], v[160:163], v[210:213], v[108:111]
	v_mfma_f32_16x16x32_bf16 v[104:107], v[168:171], v[210:213], v[104:107]
	v_mfma_f32_16x16x32_bf16 v[100:103], v[160:163], v[218:221], v[100:103]
	v_mfma_f32_16x16x32_bf16 v[96:99], v[168:171], v[218:221], v[96:99]
	v_mfma_f32_16x16x32_bf16 v[124:127], v[164:167], v[198:201], v[124:127]
	v_mfma_f32_16x16x32_bf16 v[120:123], v[172:175], v[198:201], v[120:123]
	v_mfma_f32_16x16x32_bf16 v[116:119], v[164:167], v[206:209], v[116:119]
	v_mfma_f32_16x16x32_bf16 v[112:115], v[172:175], v[206:209], v[112:115]
	v_mfma_f32_16x16x32_bf16 v[108:111], v[164:167], v[214:217], v[108:111]
	v_mfma_f32_16x16x32_bf16 v[104:107], v[172:175], v[214:217], v[104:107]
	v_mfma_f32_16x16x32_bf16 v[100:103], v[164:167], v[222:225], v[100:103]
	v_mfma_f32_16x16x32_bf16 v[96:99], v[172:175], v[222:225], v[96:99]
	v_mfma_f32_16x16x32_bf16 v[84:87], v[176:179], v[194:197], v[84:87]
	v_mfma_f32_16x16x32_bf16 v[76:79], v[186:189], v[194:197], v[76:79]
	v_mfma_f32_16x16x32_bf16 v[68:71], v[176:179], v[202:205], v[68:71]
	v_mfma_f32_16x16x32_bf16 v[64:67], v[186:189], v[202:205], v[64:67]
	v_mfma_f32_16x16x32_bf16 v[52:55], v[176:179], v[210:213], v[52:55]
	v_mfma_f32_16x16x32_bf16 v[48:51], v[186:189], v[210:213], v[48:51]
	v_mfma_f32_16x16x32_bf16 v[40:43], v[176:179], v[218:221], v[40:43]
	v_mfma_f32_16x16x32_bf16 v[32:35], v[186:189], v[218:221], v[32:35]
	v_mfma_f32_16x16x32_bf16 v[84:87], v[180:183], v[198:201], v[84:87]
	v_mfma_f32_16x16x32_bf16 v[76:79], v[190:193], v[198:201], v[76:79]
	v_mfma_f32_16x16x32_bf16 v[68:71], v[180:183], v[206:209], v[68:71]
	v_mfma_f32_16x16x32_bf16 v[64:67], v[190:193], v[206:209], v[64:67]
	v_mfma_f32_16x16x32_bf16 v[52:55], v[180:183], v[214:217], v[52:55]
	v_mfma_f32_16x16x32_bf16 v[48:51], v[190:193], v[214:217], v[48:51]
	v_mfma_f32_16x16x32_bf16 v[40:43], v[180:183], v[222:225], v[40:43]
	v_mfma_f32_16x16x32_bf16 v[32:35], v[190:193], v[222:225], v[32:35]
	s_barrier
; #define PG8_STAGE(bufoff, gbase, voff) do { _Pragma("unroll") for (int _i = 0; _i < 2; ++_i) \
;         __builtin_amdgcn_global_load_lds((const unsigned*)((const char*)(gbase) + (voff)[_i]), (LAS unsigned*)(lds + (bufoff) + ldsw + _i * 8192), 16, 0, 0); } while (0)
; #define PG8_LDA(dst, b, h) do { _Pragma("unroll") for (int m = 0; m < 4; ++m) _Pragma("unroll") for (int k = 0; k < 2; ++k) dst[m][k] = *(const LAS bf16x8*)(lds + PG8_SA(b, h) + aoff + m * 2048 + k * 1024); } while (0)
; #define PG8_MMA(ai, bj, At, Bt) do { __builtin_amdgcn_s_setprio(1); _Pragma("unroll") for (int m = 0; m < 4; ++m) _Pragma("unroll") for (int n = 0; n < 2; ++n) _Pragma("unroll") for (int k = 0; k < 2; ++k) \
;         acc[ai][bj][m][n] = __builtin_amdgcn_mfma_f32_16x16x32_bf16(Bt[n][k], At[m][k], acc[ai][bj][m][n], 0, 0, 0); __builtin_amdgcn_s_setprio(0); } while (0)
; #define PG8_WAIT_V(n) asm volatile("s_waitcnt vmcnt(" #n ")" ::: "memory")
; #define PG8_WAIT_L(n) asm volatile("s_waitcnt lgkmcnt(" #n ")" ::: "memory")
; #define PG8_BAR __builtin_amdgcn_s_barrier()
; #define PG8_SCHED __builtin_amdgcn_sched_barrier(0)
; template <class Epi, bool ALIGN_EPI = PG8_ALIGN>
; __device__ __forceinline__ void gemm_phase(LAS unsigned char* lds, const Gemm g, const StaticOrder S, const Epi E) {
;     ...
;             PG8_LDA(At, 1, 1); PG8_STAGE(PG8_SB(1, 0), b3, voffB); PG8_STAGE(PG8_SB(1, 1), b3 + hstepB, voffB); PG8_STAGE(PG8_SA(1, 0), a3, voffA);
;             PG8_WAIT_V(8); PG8_WAIT_L(0); PG8_BAR; PG8_MMA(1, 0, At, B0); PG8_MMA(1, 1, At, B1); PG8_BAR; PG8_SCHED;
;         }
;         if (ALIGN_EPI) { if (wr == 0) PG8_BAR; }
	s_add_i32 s0, s42, s14
	v_lshl_add_u64 v[226:227], v[226:227], 0, s[12:13]
	s_mov_b32 m0, s0
	ds_read_b128 v[194:197], v158 offset:49152
	ds_read_b128 v[198:201], v158 offset:50176
	ds_read_b128 v[202:205], v158 offset:51200
	ds_read_b128 v[206:209], v158 offset:52224
	ds_read_b128 v[210:213], v158 offset:53248
	ds_read_b128 v[214:217], v158 offset:54272
	ds_read_b128 v[218:221], v158 offset:55296
	ds_read_b128 v[222:225], v158 offset:56320
	global_load_lds_dwordx4 v[226:227], off
	s_add_i32 m0, s0, 0x2000
	s_add_u32 s0, s52, 0x20080
	v_lshl_add_u64 v[226:227], v[228:229], 0, s[12:13]
	s_addc_u32 s1, s53, 0
	s_add_i32 s42, s43, s14
	global_load_lds_dwordx4 v[226:227], off
	v_lshl_add_u64 v[226:227], s[0:1], 0, v[132:133]
	s_mov_b32 m0, s42
	s_nop 0
	global_load_lds_dwordx4 v[226:227], off
	v_lshl_add_u64 v[226:227], s[0:1], 0, v[128:129]
	s_add_i32 m0, s42, 0x2000
	s_nop 0
	global_load_lds_dwordx4 v[226:227], off
	v_lshl_add_u64 v[226:227], v[230:231], 0, s[12:13]
	s_mov_b32 m0, s59
	s_nop 0
	global_load_lds_dwordx4 v[226:227], off
	v_lshl_add_u64 v[226:227], v[232:233], 0, s[12:13]
	s_mov_b32 m0, s60
	s_nop 0
	global_load_lds_dwordx4 v[226:227], off
	s_waitcnt vmcnt(8)
	s_waitcnt lgkmcnt(0)
	s_barrier
	s_waitcnt lgkmcnt(0)
	v_mfma_f32_16x16x32_bf16 v[92:95], v[160:163], v[194:197], v[92:95]
	v_mfma_f32_16x16x32_bf16 v[88:91], v[168:171], v[194:197], v[88:91]
	v_mfma_f32_16x16x32_bf16 v[80:83], v[160:163], v[202:205], v[80:83]
	v_mfma_f32_16x16x32_bf16 v[72:75], v[168:171], v[202:205], v[72:75]
	v_mfma_f32_16x16x32_bf16 v[60:63], v[160:163], v[210:213], v[60:63]
	v_mfma_f32_16x16x32_bf16 v[56:59], v[168:171], v[210:213], v[56:59]
	v_mfma_f32_16x16x32_bf16 v[44:47], v[160:163], v[218:221], v[44:47]
	v_mfma_f32_16x16x32_bf16 v[36:39], v[168:171], v[218:221], v[36:39]
	v_mfma_f32_16x16x32_bf16 v[92:95], v[164:167], v[198:201], v[92:95]
	v_mfma_f32_16x16x32_bf16 v[88:91], v[172:175], v[198:201], v[88:91]
	v_mfma_f32_16x16x32_bf16 v[80:83], v[164:167], v[206:209], v[80:83]
	v_mfma_f32_16x16x32_bf16 v[72:75], v[172:175], v[206:209], v[72:75]
	v_mfma_f32_16x16x32_bf16 v[60:63], v[164:167], v[214:217], v[60:63]
	v_mfma_f32_16x16x32_bf16 v[56:59], v[172:175], v[214:217], v[56:59]
	v_mfma_f32_16x16x32_bf16 v[44:47], v[164:167], v[222:225], v[44:47]
	v_mfma_f32_16x16x32_bf16 v[36:39], v[172:175], v[222:225], v[36:39]
	v_mfma_f32_16x16x32_bf16 v[28:31], v[176:179], v[194:197], v[28:31]
	v_mfma_f32_16x16x32_bf16 v[24:27], v[186:189], v[194:197], v[24:27]
	v_mfma_f32_16x16x32_bf16 v[20:23], v[176:179], v[202:205], v[20:23]
	v_mfma_f32_16x16x32_bf16 v[16:19], v[186:189], v[202:205], v[16:19]
	v_mfma_f32_16x16x32_bf16 v[12:15], v[176:179], v[210:213], v[12:15]
	v_mfma_f32_16x16x32_bf16 v[8:11], v[186:189], v[210:213], v[8:11]
	v_mfma_f32_16x16x32_bf16 v[4:7], v[176:179], v[218:221], v[4:7]
	v_mfma_f32_16x16x32_bf16 v[0:3], v[186:189], v[218:221], v[0:3]
	v_mfma_f32_16x16x32_bf16 v[28:31], v[180:183], v[198:201], v[28:31]
	v_mfma_f32_16x16x32_bf16 v[24:27], v[190:193], v[198:201], v[24:27]
	v_mfma_f32_16x16x32_bf16 v[20:23], v[180:183], v[206:209], v[20:23]
	v_mfma_f32_16x16x32_bf16 v[16:19], v[190:193], v[206:209], v[16:19]
	v_mfma_f32_16x16x32_bf16 v[12:15], v[180:183], v[214:217], v[12:15]
	v_mfma_f32_16x16x32_bf16 v[8:11], v[190:193], v[214:217], v[8:11]
	v_mfma_f32_16x16x32_bf16 v[4:7], v[180:183], v[222:225], v[4:7]
	v_mfma_f32_16x16x32_bf16 v[0:3], v[190:193], v[222:225], v[0:3]
	s_barrier
	s_add_i32 s71, s71, 2
	s_add_u32 s50, s50, 0x100
	s_addc_u32 s51, s51, 0
	s_add_u32 s68, s68, 0x100
	s_addc_u32 s69, s69, 0
	s_cmp_gt_u32 s71, 5
	s_cbranch_scc0 .LBB0_869
	s_and_b64 vcc, exec, s[22:23]
	s_cbranch_vccz .LBB0_872
	s_barrier

; #define PG8_STAGE(bufoff, gbase, voff) do { _Pragma("unroll") for (int _i = 0; _i < 2; ++_i) \
;         __builtin_amdgcn_global_load_lds((const unsigned*)((const char*)(gbase) + (voff)[_i]), (LAS unsigned*)(lds + (bufoff) + ldsw + _i * 8192), 16, 0, 0); } while (0)
; #define PG8_LDA(dst, b, h) do { _Pragma("unroll") for (int m = 0; m < 4; ++m) _Pragma("unroll") for (int k = 0; k < 2; ++k) dst[m][k] = *(const LAS bf16x8*)(lds + PG8_SA(b, h) + aoff + m * 2048 + k * 1024); } while (0)
; #define PG8_LDB(dst, b, h) do { _Pragma("unroll") for (int n = 0; n < 2; ++n) _Pragma("unroll") for (int k = 0; k < 2; ++k) dst[n][k] = *(const LAS bf16x8*)(lds + PG8_SB(b, h) + boff + n * 2048 + k * 1024); } while (0)
; #define PG8_MMA(ai, bj, At, Bt) do { __builtin_amdgcn_s_setprio(1); _Pragma("unroll") for (int m = 0; m < 4; ++m) _Pragma("unroll") for (int n = 0; n < 2; ++n) _Pragma("unroll") for (int k = 0; k < 2; ++k) \
;         acc[ai][bj][m][n] = __builtin_amdgcn_mfma_f32_16x16x32_bf16(Bt[n][k], At[m][k], acc[ai][bj][m][n], 0, 0, 0); __builtin_amdgcn_s_setprio(0); } while (0)
; #define PG8_BAR __builtin_amdgcn_s_barrier()
; template <class Epi, bool ALIGN_EPI = PG8_ALIGN>
; __device__ __forceinline__ void gemm_phase(LAS unsigned char* lds, const Gemm g, const StaticOrder S, const Epi E) {
;     ...
;         const bool has_next = S.next(ui + 1, nxt);
;         const char* nA = has_next ? (const char*)g.A + (size_t)nxt.pm * tstepA : cA; const char* nB = has_next ? (const char*)g.Bt + (size_t)nxt.pn * tstepB : cB;
;         for (int t = 0; t < nt; t += 2) {
;             const bool last = (t == nt - 2);
;             const char* a1 = cA + (size_t)(t + 1) * kstep;
;             const char* a2 = last ? nA : cA + (size_t)(t + 2) * kstep; const char* b2 = last ? nB : cB + (size_t)(t + 2) * kstep;
;             const char* a3 = a2 + kstep; const char* b3 = b2 + kstep;
;             PG8_LDB(B0, 0, 0); PG8_LDB(B1, 0, 1); PG8_SCHED; PG8_LDA(At, 0, 0); PG8_STAGE(PG8_SA(1, 1), a1 + hstepA, voffA);
;             PG8_WAIT_V(8); PG8_WAIT_L(0); PG8_BAR; PG8_MMA(0, 0, At, B0); PG8_MMA(0, 1, At, B1); PG8_BAR; PG8_SCHED;
;             PG8_LDA(At, 0, 1); PG8_STAGE(PG8_SB(0, 0), b2, voffB); PG8_STAGE(PG8_SB(0, 1), b2 + hstepB, voffB); PG8_STAGE(PG8_SA(0, 0), a2, voffA);
;             PG8_WAIT_V(8); PG8_WAIT_L(0); PG8_BAR; PG8_MMA(1, 0, At, B0); PG8_MMA(1, 1, At, B1); PG8_BAR; PG8_SCHED;
.LBB0_893:
	s_add_u32 s42, s44, s60
	s_addc_u32 s43, s45, 0
	s_add_u32 s61, s42, 0x100
	s_addc_u32 s62, s43, 0
	s_and_b64 s[0:1], s[58:59], exec
	s_cselect_b32 s63, s29, s62
	s_cselect_b32 s62, s83, s61
	s_add_u32 s0, s36, s60
	s_addc_u32 s1, s37, 0
	s_add_u32 s60, s0, 0x100
	s_addc_u32 s61, s1, 0
	s_and_b64 s[0:1], s[58:59], exec
	s_cselect_b32 s65, s27, s61
	s_cselect_b32 s64, s90, s60
	s_add_u32 s68, s42, 0x10080
	ds_read_b128 v[152:155], v148
	ds_read_b128 v[156:159], v148 offset:1024
	ds_read_b128 v[160:163], v148 offset:2048
	ds_read_b128 v[164:167], v148 offset:3072
	ds_read_b128 v[168:171], v149
	ds_read_b128 v[172:175], v149 offset:1024
	ds_read_b128 v[176:179], v149 offset:2048
	ds_read_b128 v[180:183], v149 offset:3072
	s_addc_u32 s69, s43, 0
	s_add_i32 vcc_hi, s78, s17
	s_add_i32 m0, s25, 0xc000
	s_add_i32 s1, s25, 0xe000
	s_add_i32 s0, vcc_hi, 0x2000
	s_add_u32 s66, s64, 0x10000
	s_addc_u32 s67, s65, 0
	s_add_i32 s43, s79, s17
	s_add_i32 s42, s43, 0x2000
	s_add_i32 vcc_lo, 0, 0x18000
	s_add_i32 s97, 0, 0x1c000
	s_add_u32 s60, s62, 0x10000
	s_addc_u32 s61, s63, 0
	s_add_i32 s95, vcc_lo, s17
	s_add_i32 s92, s95, 0x2000
	s_add_u32 s58, s64, 0x10080
	s_addc_u32 s59, s65, 0
	s_add_i32 s93, s97, s17
	s_add_i32 s91, s93, 0x2000
	v_lshl_add_u64 v[218:219], s[68:69], 0, v[128:129]
	ds_read_b128 v[186:189], v150
	ds_read_b128 v[190:193], v150 offset:1024
	ds_read_b128 v[194:197], v150 offset:2048
	ds_read_b128 v[198:201], v150 offset:3072
	ds_read_b128 v[202:205], v150 offset:4096
	ds_read_b128 v[206:209], v150 offset:5120
	ds_read_b128 v[210:213], v150 offset:6144
	ds_read_b128 v[214:217], v150 offset:7168
	global_load_lds_dwordx4 v[218:219], off
	v_lshl_add_u64 v[218:219], s[68:69], 0, v[132:133]
	s_mov_b32 m0, s1
	s_nop 0
	global_load_lds_dwordx4 v[218:219], off
	s_waitcnt vmcnt(8)
	s_waitcnt lgkmcnt(0)
	s_barrier
	s_waitcnt lgkmcnt(0)
	v_mfma_f32_16x16x32_bf16 v[124:127], v[152:155], v[186:189], v[124:127]
	v_mfma_f32_16x16x32_bf16 v[120:123], v[160:163], v[186:189], v[120:123]
	v_mfma_f32_16x16x32_bf16 v[116:119], v[152:155], v[194:197], v[116:119]
	v_mfma_f32_16x16x32_bf16 v[112:115], v[160:163], v[194:197], v[112:115]
	v_mfma_f32_16x16x32_bf16 v[108:111], v[152:155], v[202:205], v[108:111]
	v_mfma_f32_16x16x32_bf16 v[104:107], v[160:163], v[202:205], v[104:107]
	v_mfma_f32_16x16x32_bf16 v[100:103], v[152:155], v[210:213], v[100:103]
	v_mfma_f32_16x16x32_bf16 v[96:99], v[160:163], v[210:213], v[96:99]
	v_mfma_f32_16x16x32_bf16 v[124:127], v[156:159], v[190:193], v[124:127]
	v_mfma_f32_16x16x32_bf16 v[120:123], v[164:167], v[190:193], v[120:123]
	v_mfma_f32_16x16x32_bf16 v[116:119], v[156:159], v[198:201], v[116:119]
	v_mfma_f32_16x16x32_bf16 v[112:115], v[164:167], v[198:201], v[112:115]
	v_mfma_f32_16x16x32_bf16 v[108:111], v[156:159], v[206:209], v[108:111]
	v_mfma_f32_16x16x32_bf16 v[104:107], v[164:167], v[206:209], v[104:107]
	v_mfma_f32_16x16x32_bf16 v[100:103], v[156:159], v[214:217], v[100:103]
	v_mfma_f32_16x16x32_bf16 v[96:99], v[164:167], v[214:217], v[96:99]
	v_mfma_f32_16x16x32_bf16 v[84:87], v[168:171], v[186:189], v[84:87]
	v_mfma_f32_16x16x32_bf16 v[76:79], v[176:179], v[186:189], v[76:79]
	v_mfma_f32_16x16x32_bf16 v[68:71], v[168:171], v[194:197], v[68:71]
	v_mfma_f32_16x16x32_bf16 v[60:63], v[176:179], v[194:197], v[60:63]
	v_mfma_f32_16x16x32_bf16 v[52:55], v[168:171], v[202:205], v[52:55]
	v_mfma_f32_16x16x32_bf16 v[44:47], v[176:179], v[202:205], v[44:47]
	v_mfma_f32_16x16x32_bf16 v[36:39], v[168:171], v[210:213], v[36:39]
	v_mfma_f32_16x16x32_bf16 v[32:35], v[176:179], v[210:213], v[32:35]
	v_mfma_f32_16x16x32_bf16 v[84:87], v[172:175], v[190:193], v[84:87]
	v_mfma_f32_16x16x32_bf16 v[76:79], v[180:183], v[190:193], v[76:79]
	v_mfma_f32_16x16x32_bf16 v[68:71], v[172:175], v[198:201], v[68:71]
	v_mfma_f32_16x16x32_bf16 v[60:63], v[180:183], v[198:201], v[60:63]
	v_mfma_f32_16x16x32_bf16 v[52:55], v[172:175], v[206:209], v[52:55]
	v_mfma_f32_16x16x32_bf16 v[44:47], v[180:183], v[206:209], v[44:47]
	v_mfma_f32_16x16x32_bf16 v[36:39], v[172:175], v[214:217], v[36:39]
	v_mfma_f32_16x16x32_bf16 v[32:35], v[180:183], v[214:217], v[32:35]
	s_barrier
	s_mov_b32 m0, vcc_hi
	v_lshl_add_u64 v[218:219], s[64:65], 0, v[130:131]
	ds_read_b128 v[186:189], v150 offset:16384
	ds_read_b128 v[190:193], v150 offset:17408
	ds_read_b128 v[194:197], v150 offset:18432
	ds_read_b128 v[198:201], v150 offset:19456
	ds_read_b128 v[202:205], v150 offset:20480
	ds_read_b128 v[206:209], v150 offset:21504
	ds_read_b128 v[210:213], v150 offset:22528
	ds_read_b128 v[214:217], v150 offset:23552
	global_load_lds_dwordx4 v[218:219], off
	v_lshl_add_u64 v[220:221], s[64:65], 0, v[134:135]
	s_mov_b32 m0, s0
	v_lshl_add_u64 v[222:223], s[66:67], 0, v[130:131]
	global_load_lds_dwordx4 v[220:221], off
	s_mov_b32 m0, s43
	v_lshl_add_u64 v[224:225], s[62:63], 0, v[132:133]
	global_load_lds_dwordx4 v[222:223], off
	v_lshl_add_u64 v[222:223], s[66:67], 0, v[134:135]
	s_mov_b32 m0, s42
	s_nop 0
	global_load_lds_dwordx4 v[222:223], off
	v_lshl_add_u64 v[222:223], s[62:63], 0, v[128:129]
	s_mov_b32 m0, s25
	s_nop 0
	global_load_lds_dwordx4 v[222:223], off
	s_mov_b32 m0, s33
	s_nop 0
	global_load_lds_dwordx4 v[224:225], off
	s_waitcnt vmcnt(8)
	s_waitcnt lgkmcnt(0)
	s_barrier
; #define PG8_STAGE(bufoff, gbase, voff) do { _Pragma("unroll") for (int _i = 0; _i < 2; ++_i) \
;         __builtin_amdgcn_global_load_lds((const unsigned*)((const char*)(gbase) + (voff)[_i]), (LAS unsigned*)(lds + (bufoff) + ldsw + _i * 8192), 16, 0, 0); } while (0)
; #define PG8_LDA(dst, b, h) do { _Pragma("unroll") for (int m = 0; m < 4; ++m) _Pragma("unroll") for (int k = 0; k < 2; ++k) dst[m][k] = *(const LAS bf16x8*)(lds + PG8_SA(b, h) + aoff + m * 2048 + k * 1024); } while (0)
; #define PG8_LDB(dst, b, h) do { _Pragma("unroll") for (int n = 0; n < 2; ++n) _Pragma("unroll") for (int k = 0; k < 2; ++k) dst[n][k] = *(const LAS bf16x8*)(lds + PG8_SB(b, h) + boff + n * 2048 + k * 1024); } while (0)
; #define PG8_MMA(ai, bj, At, Bt) do { __builtin_amdgcn_s_setprio(1); _Pragma("unroll") for (int m = 0; m < 4; ++m) _Pragma("unroll") for (int n = 0; n < 2; ++n) _Pragma("unroll") for (int k = 0; k < 2; ++k) \
;         acc[ai][bj][m][n] = __builtin_amdgcn_mfma_f32_16x16x32_bf16(Bt[n][k], At[m][k], acc[ai][bj][m][n], 0, 0, 0); __builtin_amdgcn_s_setprio(0); } while (0)
; #define PG8_WAIT_V(n) asm volatile("s_waitcnt vmcnt(" #n ")" ::: "memory")
; #define PG8_WAIT_L(n) asm volatile("s_waitcnt lgkmcnt(" #n ")" ::: "memory")
; #define PG8_BAR __builtin_amdgcn_s_barrier()
; #define PG8_SCHED __builtin_amdgcn_sched_barrier(0)
; template <class Epi, bool ALIGN_EPI = PG8_ALIGN>
; __device__ __forceinline__ void gemm_phase(LAS unsigned char* lds, const Gemm g, const StaticOrder S, const Epi E) {
;     ...
;             PG8_WAIT_V(8); PG8_WAIT_L(0); PG8_BAR; PG8_MMA(1, 0, At, B0); PG8_MMA(1, 1, At, B1); PG8_BAR; PG8_SCHED;
;             PG8_LDB(B0, 1, 0); PG8_LDB(B1, 1, 1); PG8_SCHED; PG8_LDA(At, 1, 0); PG8_STAGE(PG8_SA(0, 1), a2 + hstepA, voffA);
;             PG8_WAIT_V(8); PG8_WAIT_L(0); PG8_BAR; PG8_MMA(0, 0, At, B0); PG8_MMA(0, 1, At, B1); PG8_BAR; PG8_SCHED;
;             PG8_LDA(At, 1, 1); PG8_STAGE(PG8_SB(1, 0), b3, voffB); PG8_STAGE(PG8_SB(1, 1), b3 + hstepB, voffB); PG8_STAGE(PG8_SA(1, 0), a3, voffA);
;             PG8_WAIT_V(8); PG8_WAIT_L(0); PG8_BAR; PG8_MMA(1, 0, At, B0); PG8_MMA(1, 1, At, B1); PG8_BAR; PG8_SCHED;
	s_waitcnt lgkmcnt(0)
	v_mfma_f32_16x16x32_bf16 v[92:95], v[152:155], v[186:189], v[92:95]
	v_mfma_f32_16x16x32_bf16 v[88:91], v[160:163], v[186:189], v[88:91]
	v_mfma_f32_16x16x32_bf16 v[80:83], v[152:155], v[194:197], v[80:83]
	v_mfma_f32_16x16x32_bf16 v[72:75], v[160:163], v[194:197], v[72:75]
	v_mfma_f32_16x16x32_bf16 v[64:67], v[152:155], v[202:205], v[64:67]
	v_mfma_f32_16x16x32_bf16 v[56:59], v[160:163], v[202:205], v[56:59]
	v_mfma_f32_16x16x32_bf16 v[48:51], v[152:155], v[210:213], v[48:51]
	v_mfma_f32_16x16x32_bf16 v[40:43], v[160:163], v[210:213], v[40:43]
	v_mfma_f32_16x16x32_bf16 v[92:95], v[156:159], v[190:193], v[92:95]
	v_mfma_f32_16x16x32_bf16 v[88:91], v[164:167], v[190:193], v[88:91]
	v_mfma_f32_16x16x32_bf16 v[80:83], v[156:159], v[198:201], v[80:83]
	v_mfma_f32_16x16x32_bf16 v[72:75], v[164:167], v[198:201], v[72:75]
	v_mfma_f32_16x16x32_bf16 v[64:67], v[156:159], v[206:209], v[64:67]
	v_mfma_f32_16x16x32_bf16 v[56:59], v[164:167], v[206:209], v[56:59]
	v_mfma_f32_16x16x32_bf16 v[48:51], v[156:159], v[214:217], v[48:51]
	v_mfma_f32_16x16x32_bf16 v[40:43], v[164:167], v[214:217], v[40:43]
	v_mfma_f32_16x16x32_bf16 v[28:31], v[168:171], v[186:189], v[28:31]
	v_mfma_f32_16x16x32_bf16 v[24:27], v[176:179], v[186:189], v[24:27]
	v_mfma_f32_16x16x32_bf16 v[20:23], v[168:171], v[194:197], v[20:23]
	v_mfma_f32_16x16x32_bf16 v[16:19], v[176:179], v[194:197], v[16:19]
	v_mfma_f32_16x16x32_bf16 v[12:15], v[168:171], v[202:205], v[12:15]
	v_mfma_f32_16x16x32_bf16 v[8:11], v[176:179], v[202:205], v[8:11]
	v_mfma_f32_16x16x32_bf16 v[4:7], v[168:171], v[210:213], v[4:7]
	v_mfma_f32_16x16x32_bf16 v[0:3], v[176:179], v[210:213], v[0:3]
	v_mfma_f32_16x16x32_bf16 v[28:31], v[172:175], v[190:193], v[28:31]
	v_mfma_f32_16x16x32_bf16 v[24:27], v[180:183], v[190:193], v[24:27]
	v_mfma_f32_16x16x32_bf16 v[20:23], v[172:175], v[198:201], v[20:23]
	v_mfma_f32_16x16x32_bf16 v[16:19], v[180:183], v[198:201], v[16:19]
	v_mfma_f32_16x16x32_bf16 v[12:15], v[172:175], v[206:209], v[12:15]
	v_mfma_f32_16x16x32_bf16 v[8:11], v[180:183], v[206:209], v[8:11]
	v_mfma_f32_16x16x32_bf16 v[4:7], v[172:175], v[214:217], v[4:7]
	v_mfma_f32_16x16x32_bf16 v[0:3], v[180:183], v[214:217], v[0:3]
	s_barrier
	v_add_u32_e32 v151, vcc_lo, v141
	ds_read_b128 v[152:155], v151
	ds_read_b128 v[156:159], v151 offset:1024
	ds_read_b128 v[160:163], v151 offset:2048
	ds_read_b128 v[164:167], v151 offset:3072
	v_add_u32_e32 v151, s97, v141
	ds_read_b128 v[168:171], v151
	ds_read_b128 v[172:175], v151 offset:1024
	ds_read_b128 v[176:179], v151 offset:2048
	ds_read_b128 v[180:183], v151 offset:3072
	s_mov_b32 m0, s34
	v_lshl_add_u64 v[226:227], s[60:61], 0, v[128:129]
	ds_read_b128 v[186:189], v150 offset:32768
	ds_read_b128 v[190:193], v150 offset:33792
	ds_read_b128 v[194:197], v150 offset:34816
	ds_read_b128 v[198:201], v150 offset:35840
	ds_read_b128 v[202:205], v150 offset:36864
	ds_read_b128 v[206:209], v150 offset:37888
	ds_read_b128 v[210:213], v150 offset:38912
	ds_read_b128 v[214:217], v150 offset:39936
	global_load_lds_dwordx4 v[226:227], off
	v_lshl_add_u64 v[226:227], s[60:61], 0, v[132:133]
	s_mov_b32 m0, s35
	s_nop 0
	global_load_lds_dwordx4 v[226:227], off
	s_waitcnt vmcnt(8)
	s_waitcnt lgkmcnt(0)
	s_barrier
	s_waitcnt lgkmcnt(0)
	v_mfma_f32_16x16x32_bf16 v[124:127], v[152:155], v[186:189], v[124:127]
	v_mfma_f32_16x16x32_bf16 v[120:123], v[160:163], v[186:189], v[120:123]
	v_mfma_f32_16x16x32_bf16 v[116:119], v[152:155], v[194:197], v[116:119]
	v_mfma_f32_16x16x32_bf16 v[112:115], v[160:163], v[194:197], v[112:115]
	v_mfma_f32_16x16x32_bf16 v[108:111], v[152:155], v[202:205], v[108:111]
	v_mfma_f32_16x16x32_bf16 v[104:107], v[160:163], v[202:205], v[104:107]
	v_mfma_f32_16x16x32_bf16 v[100:103], v[152:155], v[210:213], v[100:103]
	v_mfma_f32_16x16x32_bf16 v[96:99], v[160:163], v[210:213], v[96:99]
	v_mfma_f32_16x16x32_bf16 v[124:127], v[156:159], v[190:193], v[124:127]
	v_mfma_f32_16x16x32_bf16 v[120:123], v[164:167], v[190:193], v[120:123]
	v_mfma_f32_16x16x32_bf16 v[116:119], v[156:159], v[198:201], v[116:119]
	v_mfma_f32_16x16x32_bf16 v[112:115], v[164:167], v[198:201], v[112:115]
	v_mfma_f32_16x16x32_bf16 v[108:111], v[156:159], v[206:209], v[108:111]
	v_mfma_f32_16x16x32_bf16 v[104:107], v[164:167], v[206:209], v[104:107]
	v_mfma_f32_16x16x32_bf16 v[100:103], v[156:159], v[214:217], v[100:103]
	v_mfma_f32_16x16x32_bf16 v[96:99], v[164:167], v[214:217], v[96:99]
	v_mfma_f32_16x16x32_bf16 v[84:87], v[168:171], v[186:189], v[84:87]
	v_mfma_f32_16x16x32_bf16 v[76:79], v[176:179], v[186:189], v[76:79]
	v_mfma_f32_16x16x32_bf16 v[68:71], v[168:171], v[194:197], v[68:71]
	v_mfma_f32_16x16x32_bf16 v[60:63], v[176:179], v[194:197], v[60:63]
	v_mfma_f32_16x16x32_bf16 v[52:55], v[168:171], v[202:205], v[52:55]
	v_mfma_f32_16x16x32_bf16 v[44:47], v[176:179], v[202:205], v[44:47]
	v_mfma_f32_16x16x32_bf16 v[36:39], v[168:171], v[210:213], v[36:39]
	v_mfma_f32_16x16x32_bf16 v[32:35], v[176:179], v[210:213], v[32:35]
	v_mfma_f32_16x16x32_bf16 v[84:87], v[172:175], v[190:193], v[84:87]
	v_mfma_f32_16x16x32_bf16 v[76:79], v[180:183], v[190:193], v[76:79]
	v_mfma_f32_16x16x32_bf16 v[68:71], v[172:175], v[198:201], v[68:71]
	v_mfma_f32_16x16x32_bf16 v[60:63], v[180:183], v[198:201], v[60:63]
	v_mfma_f32_16x16x32_bf16 v[52:55], v[172:175], v[206:209], v[52:55]
	v_mfma_f32_16x16x32_bf16 v[44:47], v[180:183], v[206:209], v[44:47]
	v_mfma_f32_16x16x32_bf16 v[36:39], v[172:175], v[214:217], v[36:39]
	v_mfma_f32_16x16x32_bf16 v[32:35], v[180:183], v[214:217], v[32:35]
	s_barrier
; #define PG8_STAGE(bufoff, gbase, voff) do { _Pragma("unroll") for (int _i = 0; _i < 2; ++_i) \
;         __builtin_amdgcn_global_load_lds((const unsigned*)((const char*)(gbase) + (voff)[_i]), (LAS unsigned*)(lds + (bufoff) + ldsw + _i * 8192), 16, 0, 0); } while (0)
; #define PG8_LDA(dst, b, h) do { _Pragma("unroll") for (int m = 0; m < 4; ++m) _Pragma("unroll") for (int k = 0; k < 2; ++k) dst[m][k] = *(const LAS bf16x8*)(lds + PG8_SA(b, h) + aoff + m * 2048 + k * 1024); } while (0)
; #define PG8_MMA(ai, bj, At, Bt) do { __builtin_amdgcn_s_setprio(1); _Pragma("unroll") for (int m = 0; m < 4; ++m) _Pragma("unroll") for (int n = 0; n < 2; ++n) _Pragma("unroll") for (int k = 0; k < 2; ++k) \
;         acc[ai][bj][m][n] = __builtin_amdgcn_mfma_f32_16x16x32_bf16(Bt[n][k], At[m][k], acc[ai][bj][m][n], 0, 0, 0); __builtin_amdgcn_s_setprio(0); } while (0)
; #define PG8_WAIT_V(n) asm volatile("s_waitcnt vmcnt(" #n ")" ::: "memory")
; #define PG8_WAIT_L(n) asm volatile("s_waitcnt lgkmcnt(" #n ")" ::: "memory")
; #define PG8_BAR __builtin_amdgcn_s_barrier()
; #define PG8_SCHED __builtin_amdgcn_sched_barrier(0)
; template <class Epi, bool ALIGN_EPI = PG8_ALIGN>
; __device__ __forceinline__ void gemm_phase(LAS unsigned char* lds, const Gemm g, const StaticOrder S, const Epi E) {
;     ...
;             PG8_LDA(At, 1, 1); PG8_STAGE(PG8_SB(1, 0), b3, voffB); PG8_STAGE(PG8_SB(1, 1), b3 + hstepB, voffB); PG8_STAGE(PG8_SA(1, 0), a3, voffA);
;             PG8_WAIT_V(8); PG8_WAIT_L(0); PG8_BAR; PG8_MMA(1, 0, At, B0); PG8_MMA(1, 1, At, B1); PG8_BAR; PG8_SCHED;
;         }
;         if (ALIGN_EPI) { if (wr == 0) PG8_BAR; }
	s_mov_b32 m0, s95
	v_lshl_add_u64 v[218:219], v[218:219], 0, s[12:13]
	ds_read_b128 v[186:189], v150 offset:49152
	ds_read_b128 v[190:193], v150 offset:50176
	ds_read_b128 v[194:197], v150 offset:51200
	ds_read_b128 v[198:201], v150 offset:52224
	ds_read_b128 v[202:205], v150 offset:53248
	ds_read_b128 v[206:209], v150 offset:54272
	ds_read_b128 v[210:213], v150 offset:55296
	ds_read_b128 v[214:217], v150 offset:56320
	global_load_lds_dwordx4 v[218:219], off
	v_lshl_add_u64 v[218:219], v[220:221], 0, s[12:13]
	s_mov_b32 m0, s92
	s_nop 0
	global_load_lds_dwordx4 v[218:219], off
	v_lshl_add_u64 v[218:219], s[58:59], 0, v[130:131]
	s_mov_b32 m0, s93
	s_nop 0
	global_load_lds_dwordx4 v[218:219], off
	v_lshl_add_u64 v[218:219], s[58:59], 0, v[134:135]
	s_mov_b32 m0, s91
	s_nop 0
	global_load_lds_dwordx4 v[218:219], off
	v_lshl_add_u64 v[218:219], v[222:223], 0, s[12:13]
	s_mov_b32 m0, s75
	s_nop 0
	global_load_lds_dwordx4 v[218:219], off
	v_lshl_add_u64 v[218:219], v[224:225], 0, s[12:13]
	s_mov_b32 m0, s76
	s_nop 0
	global_load_lds_dwordx4 v[218:219], off
	s_waitcnt vmcnt(8)
	s_waitcnt lgkmcnt(0)
	s_barrier
	s_waitcnt lgkmcnt(0)
	v_mfma_f32_16x16x32_bf16 v[92:95], v[152:155], v[186:189], v[92:95]
	v_mfma_f32_16x16x32_bf16 v[88:91], v[160:163], v[186:189], v[88:91]
	v_mfma_f32_16x16x32_bf16 v[80:83], v[152:155], v[194:197], v[80:83]
	v_mfma_f32_16x16x32_bf16 v[72:75], v[160:163], v[194:197], v[72:75]
	v_mfma_f32_16x16x32_bf16 v[64:67], v[152:155], v[202:205], v[64:67]
	v_mfma_f32_16x16x32_bf16 v[56:59], v[160:163], v[202:205], v[56:59]
	v_mfma_f32_16x16x32_bf16 v[48:51], v[152:155], v[210:213], v[48:51]
	v_mfma_f32_16x16x32_bf16 v[40:43], v[160:163], v[210:213], v[40:43]
	v_mfma_f32_16x16x32_bf16 v[92:95], v[156:159], v[190:193], v[92:95]
	v_mfma_f32_16x16x32_bf16 v[88:91], v[164:167], v[190:193], v[88:91]
	v_mfma_f32_16x16x32_bf16 v[80:83], v[156:159], v[198:201], v[80:83]
	v_mfma_f32_16x16x32_bf16 v[72:75], v[164:167], v[198:201], v[72:75]
	v_mfma_f32_16x16x32_bf16 v[64:67], v[156:159], v[206:209], v[64:67]
	v_mfma_f32_16x16x32_bf16 v[56:59], v[164:167], v[206:209], v[56:59]
	v_mfma_f32_16x16x32_bf16 v[48:51], v[156:159], v[214:217], v[48:51]
	v_mfma_f32_16x16x32_bf16 v[40:43], v[164:167], v[214:217], v[40:43]
	v_mfma_f32_16x16x32_bf16 v[28:31], v[168:171], v[186:189], v[28:31]
	v_mfma_f32_16x16x32_bf16 v[24:27], v[176:179], v[186:189], v[24:27]
	v_mfma_f32_16x16x32_bf16 v[20:23], v[168:171], v[194:197], v[20:23]
	v_mfma_f32_16x16x32_bf16 v[16:19], v[176:179], v[194:197], v[16:19]
	v_mfma_f32_16x16x32_bf16 v[12:15], v[168:171], v[202:205], v[12:15]
	v_mfma_f32_16x16x32_bf16 v[8:11], v[176:179], v[202:205], v[8:11]
	v_mfma_f32_16x16x32_bf16 v[4:7], v[168:171], v[210:213], v[4:7]
	v_mfma_f32_16x16x32_bf16 v[0:3], v[176:179], v[210:213], v[0:3]
	v_mfma_f32_16x16x32_bf16 v[28:31], v[172:175], v[190:193], v[28:31]
	v_mfma_f32_16x16x32_bf16 v[24:27], v[180:183], v[190:193], v[24:27]
	v_mfma_f32_16x16x32_bf16 v[20:23], v[172:175], v[198:201], v[20:23]
	v_mfma_f32_16x16x32_bf16 v[16:19], v[180:183], v[198:201], v[16:19]
	v_mfma_f32_16x16x32_bf16 v[12:15], v[172:175], v[206:209], v[12:15]
	v_mfma_f32_16x16x32_bf16 v[8:11], v[180:183], v[206:209], v[8:11]
	v_mfma_f32_16x16x32_bf16 v[4:7], v[172:175], v[214:217], v[4:7]
	v_mfma_f32_16x16x32_bf16 v[0:3], v[180:183], v[214:217], v[0:3]
	s_barrier
	s_movk_i32 s60, 0x100
	s_andn2_b64 vcc, exec, s[54:55]
	s_mov_b64 s[58:59], -1
	s_mov_b64 s[54:55], 0
	s_cbranch_vccz .LBB0_893
	s_and_b64 vcc, exec, s[22:23]
	v_readlane_b32 s90, v238, 37
	s_cbranch_vccz .LBB0_896
	s_barrier

; #define PG8_STAGE(bufoff, gbase, voff) do { _Pragma("unroll") for (int _i = 0; _i < 2; ++_i) \
;         __builtin_amdgcn_global_load_lds((const unsigned*)((const char*)(gbase) + (voff)[_i]), (LAS unsigned*)(lds + (bufoff) + ldsw + _i * 8192), 16, 0, 0); } while (0)
; #define PG8_LDA(dst, b, h) do { _Pragma("unroll") for (int m = 0; m < 4; ++m) _Pragma("unroll") for (int k = 0; k < 2; ++k) dst[m][k] = *(const LAS bf16x8*)(lds + PG8_SA(b, h) + aoff + m * 2048 + k * 1024); } while (0)
; #define PG8_LDB(dst, b, h) do { _Pragma("unroll") for (int n = 0; n < 2; ++n) _Pragma("unroll") for (int k = 0; k < 2; ++k) dst[n][k] = *(const LAS bf16x8*)(lds + PG8_SB(b, h) + boff + n * 2048 + k * 1024); } while (0)
; #define PG8_MMA(ai, bj, At, Bt) do { __builtin_amdgcn_s_setprio(1); _Pragma("unroll") for (int m = 0; m < 4; ++m) _Pragma("unroll") for (int n = 0; n < 2; ++n) _Pragma("unroll") for (int k = 0; k < 2; ++k) \
;         acc[ai][bj][m][n] = __builtin_amdgcn_mfma_f32_16x16x32_bf16(Bt[n][k], At[m][k], acc[ai][bj][m][n], 0, 0, 0); __builtin_amdgcn_s_setprio(0); } while (0)
; #define PG8_BAR __builtin_amdgcn_s_barrier()
; template <class Epi, bool ALIGN_EPI = PG8_ALIGN>
; __device__ __forceinline__ void gemm_phase(LAS unsigned char* lds, const Gemm g, const StaticOrder S, const Epi E) {
;     ...
;         const bool has_next = S.next(ui + 1, nxt);
;         const char* nA = has_next ? (const char*)g.A + (size_t)nxt.pm * tstepA : cA; const char* nB = has_next ? (const char*)g.Bt + (size_t)nxt.pn * tstepB : cB;
;         for (int t = 0; t < nt; t += 2) {
;             const bool last = (t == nt - 2);
;             const char* a1 = cA + (size_t)(t + 1) * kstep;
;             const char* a2 = last ? nA : cA + (size_t)(t + 2) * kstep; const char* b2 = last ? nB : cB + (size_t)(t + 2) * kstep;
;             const char* a3 = a2 + kstep; const char* b3 = b2 + kstep;
;             PG8_LDB(B0, 0, 0); PG8_LDB(B1, 0, 1); PG8_SCHED; PG8_LDA(At, 0, 0); PG8_STAGE(PG8_SA(1, 1), a1 + hstepA, voffA);
;             PG8_WAIT_V(8); PG8_WAIT_L(0); PG8_BAR; PG8_MMA(0, 0, At, B0); PG8_MMA(0, 1, At, B1); PG8_BAR; PG8_SCHED;
;             PG8_LDA(At, 0, 1); PG8_STAGE(PG8_SB(0, 0), b2, voffB); PG8_STAGE(PG8_SB(0, 1), b2 + hstepB, voffB); PG8_STAGE(PG8_SA(0, 0), a2, voffA);
;             PG8_WAIT_V(8); PG8_WAIT_L(0); PG8_BAR; PG8_MMA(1, 0, At, B0); PG8_MMA(1, 1, At, B1); PG8_BAR; PG8_SCHED;
.LBB0_917:
	s_add_u32 s42, s50, s60
	s_addc_u32 s43, s51, 0
	s_add_u32 s61, s42, 0x100
	s_addc_u32 s62, s43, 0
	s_and_b64 s[0:1], s[58:59], exec
	s_cselect_b32 s63, s27, s62
	s_cselect_b32 s62, s81, s61
	s_add_u32 s0, s36, s60
	s_addc_u32 s1, s37, 0
	s_add_u32 s60, s0, 0x100
	s_addc_u32 s61, s1, 0
	s_and_b64 s[0:1], s[58:59], exec
	s_cselect_b32 s65, s25, s61
	s_cselect_b32 s64, s82, s60
	s_add_u32 s68, s42, 0x10080
	ds_read_b128 v[146:149], v143
	ds_read_b128 v[150:153], v143 offset:1024
	ds_read_b128 v[154:157], v143 offset:2048
	ds_read_b128 v[158:161], v143 offset:3072
	ds_read_b128 v[162:165], v144
	ds_read_b128 v[166:169], v144 offset:1024
	ds_read_b128 v[170:173], v144 offset:2048
	ds_read_b128 v[174:177], v144 offset:3072
	s_addc_u32 s69, s43, 0
	s_add_i32 s42, s77, s17
	s_add_i32 m0, s29, 0xc000
	s_add_i32 s0, s29, 0xe000
	s_add_i32 s97, s42, 0x2000
	s_add_u32 s66, s64, 0x10000
	s_addc_u32 s67, s65, 0
	s_add_i32 vcc_hi, s78, s17
	s_add_i32 vcc_lo, vcc_hi, 0x2000
	s_add_i32 s95, 0, 0x18000
	s_add_i32 s93, 0, 0x1c000
	s_add_u32 s60, s62, 0x10000
	s_addc_u32 s61, s63, 0
	s_add_i32 s92, s95, s17
	s_add_i32 s90, s92, 0x2000
	s_add_u32 s58, s64, 0x10080
	s_addc_u32 s59, s65, 0
	s_add_i32 s91, s93, s17
	s_add_i32 s83, s91, 0x2000
	v_lshl_add_u64 v[182:183], s[68:69], 0, v[128:129]
	ds_read_b128 v[178:181], v145
	ds_read_b128 v[186:189], v145 offset:1024
	ds_read_b128 v[190:193], v145 offset:2048
	ds_read_b128 v[194:197], v145 offset:3072
	ds_read_b128 v[198:201], v145 offset:4096
	ds_read_b128 v[202:205], v145 offset:5120
	ds_read_b128 v[206:209], v145 offset:6144
	ds_read_b128 v[210:213], v145 offset:7168
	global_load_lds_dwordx4 v[182:183], off
	v_lshl_add_u64 v[182:183], s[68:69], 0, v[132:133]
	s_mov_b32 m0, s0
	s_nop 0
	global_load_lds_dwordx4 v[182:183], off
	s_waitcnt vmcnt(8)
	s_waitcnt lgkmcnt(0)
	s_barrier
	s_waitcnt lgkmcnt(0)
	v_mfma_f32_16x16x32_bf16 v[124:127], v[146:149], v[178:181], v[124:127]
	v_mfma_f32_16x16x32_bf16 v[120:123], v[154:157], v[178:181], v[120:123]
	v_mfma_f32_16x16x32_bf16 v[116:119], v[146:149], v[190:193], v[116:119]
	v_mfma_f32_16x16x32_bf16 v[112:115], v[154:157], v[190:193], v[112:115]
	v_mfma_f32_16x16x32_bf16 v[108:111], v[146:149], v[198:201], v[108:111]
	v_mfma_f32_16x16x32_bf16 v[104:107], v[154:157], v[198:201], v[104:107]
	v_mfma_f32_16x16x32_bf16 v[100:103], v[146:149], v[206:209], v[100:103]
	v_mfma_f32_16x16x32_bf16 v[96:99], v[154:157], v[206:209], v[96:99]
	v_mfma_f32_16x16x32_bf16 v[124:127], v[150:153], v[186:189], v[124:127]
	v_mfma_f32_16x16x32_bf16 v[120:123], v[158:161], v[186:189], v[120:123]
	v_mfma_f32_16x16x32_bf16 v[116:119], v[150:153], v[194:197], v[116:119]
	v_mfma_f32_16x16x32_bf16 v[112:115], v[158:161], v[194:197], v[112:115]
	v_mfma_f32_16x16x32_bf16 v[108:111], v[150:153], v[202:205], v[108:111]
	v_mfma_f32_16x16x32_bf16 v[104:107], v[158:161], v[202:205], v[104:107]
	v_mfma_f32_16x16x32_bf16 v[100:103], v[150:153], v[210:213], v[100:103]
	v_mfma_f32_16x16x32_bf16 v[96:99], v[158:161], v[210:213], v[96:99]
	v_mfma_f32_16x16x32_bf16 v[76:79], v[162:165], v[178:181], v[76:79]
	v_mfma_f32_16x16x32_bf16 v[72:75], v[170:173], v[178:181], v[72:75]
	v_mfma_f32_16x16x32_bf16 v[64:67], v[162:165], v[190:193], v[64:67]
	v_mfma_f32_16x16x32_bf16 v[56:59], v[170:173], v[190:193], v[56:59]
	v_mfma_f32_16x16x32_bf16 v[52:55], v[162:165], v[198:201], v[52:55]
	v_mfma_f32_16x16x32_bf16 v[48:51], v[170:173], v[198:201], v[48:51]
	v_mfma_f32_16x16x32_bf16 v[36:39], v[162:165], v[206:209], v[36:39]
	v_mfma_f32_16x16x32_bf16 v[32:35], v[170:173], v[206:209], v[32:35]
	v_mfma_f32_16x16x32_bf16 v[76:79], v[166:169], v[186:189], v[76:79]
	v_mfma_f32_16x16x32_bf16 v[72:75], v[174:177], v[186:189], v[72:75]
	v_mfma_f32_16x16x32_bf16 v[64:67], v[166:169], v[194:197], v[64:67]
	v_mfma_f32_16x16x32_bf16 v[56:59], v[174:177], v[194:197], v[56:59]
	v_mfma_f32_16x16x32_bf16 v[52:55], v[166:169], v[202:205], v[52:55]
	v_mfma_f32_16x16x32_bf16 v[48:51], v[174:177], v[202:205], v[48:51]
	v_mfma_f32_16x16x32_bf16 v[36:39], v[166:169], v[210:213], v[36:39]
	v_mfma_f32_16x16x32_bf16 v[32:35], v[174:177], v[210:213], v[32:35]
	s_barrier
	s_mov_b32 m0, s42
	v_lshl_add_u64 v[182:183], s[64:65], 0, v[130:131]
	ds_read_b128 v[178:181], v145 offset:16384
	ds_read_b128 v[186:189], v145 offset:17408
	ds_read_b128 v[190:193], v145 offset:18432
	ds_read_b128 v[194:197], v145 offset:19456
	ds_read_b128 v[198:201], v145 offset:20480
	ds_read_b128 v[202:205], v145 offset:21504
	ds_read_b128 v[206:209], v145 offset:22528
	ds_read_b128 v[210:213], v145 offset:23552
	global_load_lds_dwordx4 v[182:183], off
	v_lshl_add_u64 v[214:215], s[64:65], 0, v[134:135]
	s_mov_b32 m0, s97
	v_lshl_add_u64 v[216:217], s[66:67], 0, v[130:131]
	global_load_lds_dwordx4 v[214:215], off
	s_mov_b32 m0, vcc_hi
	v_lshl_add_u64 v[218:219], s[62:63], 0, v[132:133]
	global_load_lds_dwordx4 v[216:217], off
	v_lshl_add_u64 v[216:217], s[66:67], 0, v[134:135]
	s_mov_b32 m0, vcc_lo
	s_nop 0
	global_load_lds_dwordx4 v[216:217], off
	v_lshl_add_u64 v[216:217], s[62:63], 0, v[128:129]
	s_mov_b32 m0, s29
	s_nop 0
	global_load_lds_dwordx4 v[216:217], off
	s_mov_b32 m0, s33
	s_nop 0
	global_load_lds_dwordx4 v[218:219], off
	s_waitcnt vmcnt(8)
	s_waitcnt lgkmcnt(0)
	s_barrier
; #define PG8_STAGE(bufoff, gbase, voff) do { _Pragma("unroll") for (int _i = 0; _i < 2; ++_i) \
;         __builtin_amdgcn_global_load_lds((const unsigned*)((const char*)(gbase) + (voff)[_i]), (LAS unsigned*)(lds + (bufoff) + ldsw + _i * 8192), 16, 0, 0); } while (0)
; #define PG8_LDA(dst, b, h) do { _Pragma("unroll") for (int m = 0; m < 4; ++m) _Pragma("unroll") for (int k = 0; k < 2; ++k) dst[m][k] = *(const LAS bf16x8*)(lds + PG8_SA(b, h) + aoff + m * 2048 + k * 1024); } while (0)
; #define PG8_LDB(dst, b, h) do { _Pragma("unroll") for (int n = 0; n < 2; ++n) _Pragma("unroll") for (int k = 0; k < 2; ++k) dst[n][k] = *(const LAS bf16x8*)(lds + PG8_SB(b, h) + boff + n * 2048 + k * 1024); } while (0)
; #define PG8_MMA(ai, bj, At, Bt) do { __builtin_amdgcn_s_setprio(1); _Pragma("unroll") for (int m = 0; m < 4; ++m) _Pragma("unroll") for (int n = 0; n < 2; ++n) _Pragma("unroll") for (int k = 0; k < 2; ++k) \
;         acc[ai][bj][m][n] = __builtin_amdgcn_mfma_f32_16x16x32_bf16(Bt[n][k], At[m][k], acc[ai][bj][m][n], 0, 0, 0); __builtin_amdgcn_s_setprio(0); } while (0)
; #define PG8_WAIT_V(n) asm volatile("s_waitcnt vmcnt(" #n ")" ::: "memory")
; #define PG8_WAIT_L(n) asm volatile("s_waitcnt lgkmcnt(" #n ")" ::: "memory")
; #define PG8_BAR __builtin_amdgcn_s_barrier()
; #define PG8_SCHED __builtin_amdgcn_sched_barrier(0)
; template <class Epi, bool ALIGN_EPI = PG8_ALIGN>
; __device__ __forceinline__ void gemm_phase(LAS unsigned char* lds, const Gemm g, const StaticOrder S, const Epi E) {
;     ...
;             PG8_WAIT_V(8); PG8_WAIT_L(0); PG8_BAR; PG8_MMA(1, 0, At, B0); PG8_MMA(1, 1, At, B1); PG8_BAR; PG8_SCHED;
;             PG8_LDB(B0, 1, 0); PG8_LDB(B1, 1, 1); PG8_SCHED; PG8_LDA(At, 1, 0); PG8_STAGE(PG8_SA(0, 1), a2 + hstepA, voffA);
;             PG8_WAIT_V(8); PG8_WAIT_L(0); PG8_BAR; PG8_MMA(0, 0, At, B0); PG8_MMA(0, 1, At, B1); PG8_BAR; PG8_SCHED;
;             PG8_LDA(At, 1, 1); PG8_STAGE(PG8_SB(1, 0), b3, voffB); PG8_STAGE(PG8_SB(1, 1), b3 + hstepB, voffB); PG8_STAGE(PG8_SA(1, 0), a3, voffA);
;             PG8_WAIT_V(8); PG8_WAIT_L(0); PG8_BAR; PG8_MMA(1, 0, At, B0); PG8_MMA(1, 1, At, B1); PG8_BAR; PG8_SCHED;
	s_waitcnt lgkmcnt(0)
	v_mfma_f32_16x16x32_bf16 v[92:95], v[146:149], v[178:181], v[92:95]
	v_mfma_f32_16x16x32_bf16 v[88:91], v[154:157], v[178:181], v[88:91]
	v_mfma_f32_16x16x32_bf16 v[84:87], v[146:149], v[190:193], v[84:87]
	v_mfma_f32_16x16x32_bf16 v[80:83], v[154:157], v[190:193], v[80:83]
	v_mfma_f32_16x16x32_bf16 v[68:71], v[146:149], v[198:201], v[68:71]
	v_mfma_f32_16x16x32_bf16 v[60:63], v[154:157], v[198:201], v[60:63]
	v_mfma_f32_16x16x32_bf16 v[44:47], v[146:149], v[206:209], v[44:47]
	v_mfma_f32_16x16x32_bf16 v[40:43], v[154:157], v[206:209], v[40:43]
	v_mfma_f32_16x16x32_bf16 v[92:95], v[150:153], v[186:189], v[92:95]
	v_mfma_f32_16x16x32_bf16 v[88:91], v[158:161], v[186:189], v[88:91]
	v_mfma_f32_16x16x32_bf16 v[84:87], v[150:153], v[194:197], v[84:87]
	v_mfma_f32_16x16x32_bf16 v[80:83], v[158:161], v[194:197], v[80:83]
	v_mfma_f32_16x16x32_bf16 v[68:71], v[150:153], v[202:205], v[68:71]
	v_mfma_f32_16x16x32_bf16 v[60:63], v[158:161], v[202:205], v[60:63]
	v_mfma_f32_16x16x32_bf16 v[44:47], v[150:153], v[210:213], v[44:47]
	v_mfma_f32_16x16x32_bf16 v[40:43], v[158:161], v[210:213], v[40:43]
	v_mfma_f32_16x16x32_bf16 v[28:31], v[162:165], v[178:181], v[28:31]
	v_mfma_f32_16x16x32_bf16 v[24:27], v[170:173], v[178:181], v[24:27]
	v_mfma_f32_16x16x32_bf16 v[20:23], v[162:165], v[190:193], v[20:23]
	v_mfma_f32_16x16x32_bf16 v[16:19], v[170:173], v[190:193], v[16:19]
	v_mfma_f32_16x16x32_bf16 v[12:15], v[162:165], v[198:201], v[12:15]
	v_mfma_f32_16x16x32_bf16 v[8:11], v[170:173], v[198:201], v[8:11]
	v_mfma_f32_16x16x32_bf16 v[4:7], v[162:165], v[206:209], v[4:7]
	v_mfma_f32_16x16x32_bf16 v[0:3], v[170:173], v[206:209], v[0:3]
	v_mfma_f32_16x16x32_bf16 v[28:31], v[166:169], v[186:189], v[28:31]
	v_mfma_f32_16x16x32_bf16 v[24:27], v[174:177], v[186:189], v[24:27]
	v_mfma_f32_16x16x32_bf16 v[20:23], v[166:169], v[194:197], v[20:23]
	v_mfma_f32_16x16x32_bf16 v[16:19], v[174:177], v[194:197], v[16:19]
	v_mfma_f32_16x16x32_bf16 v[12:15], v[166:169], v[202:205], v[12:15]
	v_mfma_f32_16x16x32_bf16 v[8:11], v[174:177], v[202:205], v[8:11]
	v_mfma_f32_16x16x32_bf16 v[4:7], v[166:169], v[210:213], v[4:7]
	v_mfma_f32_16x16x32_bf16 v[0:3], v[174:177], v[210:213], v[0:3]
	s_barrier
	v_add_u32_e32 v158, s95, v141
	v_add_u32_e32 v174, s93, v141
	ds_read_b128 v[146:149], v158
	ds_read_b128 v[150:153], v158 offset:1024
	ds_read_b128 v[154:157], v158 offset:2048
	ds_read_b128 v[158:161], v158 offset:3072
	ds_read_b128 v[162:165], v174
	ds_read_b128 v[166:169], v174 offset:1024
	ds_read_b128 v[170:173], v174 offset:2048
	ds_read_b128 v[174:177], v174 offset:3072
	s_mov_b32 m0, s34
	v_lshl_add_u64 v[220:221], s[60:61], 0, v[128:129]
	ds_read_b128 v[178:181], v145 offset:32768
	ds_read_b128 v[186:189], v145 offset:33792
	ds_read_b128 v[190:193], v145 offset:34816
	ds_read_b128 v[194:197], v145 offset:35840
	ds_read_b128 v[198:201], v145 offset:36864
	ds_read_b128 v[202:205], v145 offset:37888
	ds_read_b128 v[206:209], v145 offset:38912
	ds_read_b128 v[210:213], v145 offset:39936
	global_load_lds_dwordx4 v[220:221], off
	v_lshl_add_u64 v[220:221], s[60:61], 0, v[132:133]
	s_mov_b32 m0, s35
	s_nop 0
	global_load_lds_dwordx4 v[220:221], off
	s_waitcnt vmcnt(8)
	s_waitcnt lgkmcnt(0)
	s_barrier
	s_waitcnt lgkmcnt(0)
	v_mfma_f32_16x16x32_bf16 v[124:127], v[146:149], v[178:181], v[124:127]
	v_mfma_f32_16x16x32_bf16 v[120:123], v[154:157], v[178:181], v[120:123]
	v_mfma_f32_16x16x32_bf16 v[116:119], v[146:149], v[190:193], v[116:119]
	v_mfma_f32_16x16x32_bf16 v[112:115], v[154:157], v[190:193], v[112:115]
	v_mfma_f32_16x16x32_bf16 v[108:111], v[146:149], v[198:201], v[108:111]
	v_mfma_f32_16x16x32_bf16 v[104:107], v[154:157], v[198:201], v[104:107]
	v_mfma_f32_16x16x32_bf16 v[100:103], v[146:149], v[206:209], v[100:103]
	v_mfma_f32_16x16x32_bf16 v[96:99], v[154:157], v[206:209], v[96:99]
	v_mfma_f32_16x16x32_bf16 v[124:127], v[150:153], v[186:189], v[124:127]
	v_mfma_f32_16x16x32_bf16 v[120:123], v[158:161], v[186:189], v[120:123]
	v_mfma_f32_16x16x32_bf16 v[116:119], v[150:153], v[194:197], v[116:119]
	v_mfma_f32_16x16x32_bf16 v[112:115], v[158:161], v[194:197], v[112:115]
	v_mfma_f32_16x16x32_bf16 v[108:111], v[150:153], v[202:205], v[108:111]
	v_mfma_f32_16x16x32_bf16 v[104:107], v[158:161], v[202:205], v[104:107]
	v_mfma_f32_16x16x32_bf16 v[100:103], v[150:153], v[210:213], v[100:103]
	v_mfma_f32_16x16x32_bf16 v[96:99], v[158:161], v[210:213], v[96:99]
	v_mfma_f32_16x16x32_bf16 v[76:79], v[162:165], v[178:181], v[76:79]
	v_mfma_f32_16x16x32_bf16 v[72:75], v[170:173], v[178:181], v[72:75]
	v_mfma_f32_16x16x32_bf16 v[64:67], v[162:165], v[190:193], v[64:67]
	v_mfma_f32_16x16x32_bf16 v[56:59], v[170:173], v[190:193], v[56:59]
	v_mfma_f32_16x16x32_bf16 v[52:55], v[162:165], v[198:201], v[52:55]
	v_mfma_f32_16x16x32_bf16 v[48:51], v[170:173], v[198:201], v[48:51]
	v_mfma_f32_16x16x32_bf16 v[36:39], v[162:165], v[206:209], v[36:39]
	v_mfma_f32_16x16x32_bf16 v[32:35], v[170:173], v[206:209], v[32:35]
	v_mfma_f32_16x16x32_bf16 v[76:79], v[166:169], v[186:189], v[76:79]
	v_mfma_f32_16x16x32_bf16 v[72:75], v[174:177], v[186:189], v[72:75]
	v_mfma_f32_16x16x32_bf16 v[64:67], v[166:169], v[194:197], v[64:67]
	v_mfma_f32_16x16x32_bf16 v[56:59], v[174:177], v[194:197], v[56:59]
	v_mfma_f32_16x16x32_bf16 v[52:55], v[166:169], v[202:205], v[52:55]
	v_mfma_f32_16x16x32_bf16 v[48:51], v[174:177], v[202:205], v[48:51]
	v_mfma_f32_16x16x32_bf16 v[36:39], v[166:169], v[210:213], v[36:39]
	v_mfma_f32_16x16x32_bf16 v[32:35], v[174:177], v[210:213], v[32:35]
	s_barrier
; #define PG8_STAGE(bufoff, gbase, voff) do { _Pragma("unroll") for (int _i = 0; _i < 2; ++_i) \
;         __builtin_amdgcn_global_load_lds((const unsigned*)((const char*)(gbase) + (voff)[_i]), (LAS unsigned*)(lds + (bufoff) + ldsw + _i * 8192), 16, 0, 0); } while (0)
; #define PG8_LDA(dst, b, h) do { _Pragma("unroll") for (int m = 0; m < 4; ++m) _Pragma("unroll") for (int k = 0; k < 2; ++k) dst[m][k] = *(const LAS bf16x8*)(lds + PG8_SA(b, h) + aoff + m * 2048 + k * 1024); } while (0)
; #define PG8_MMA(ai, bj, At, Bt) do { __builtin_amdgcn_s_setprio(1); _Pragma("unroll") for (int m = 0; m < 4; ++m) _Pragma("unroll") for (int n = 0; n < 2; ++n) _Pragma("unroll") for (int k = 0; k < 2; ++k) \
;         acc[ai][bj][m][n] = __builtin_amdgcn_mfma_f32_16x16x32_bf16(Bt[n][k], At[m][k], acc[ai][bj][m][n], 0, 0, 0); __builtin_amdgcn_s_setprio(0); } while (0)
; #define PG8_WAIT_V(n) asm volatile("s_waitcnt vmcnt(" #n ")" ::: "memory")
; #define PG8_WAIT_L(n) asm volatile("s_waitcnt lgkmcnt(" #n ")" ::: "memory")
; #define PG8_BAR __builtin_amdgcn_s_barrier()
; #define PG8_SCHED __builtin_amdgcn_sched_barrier(0)
; template <class Epi, bool ALIGN_EPI = PG8_ALIGN>
; __device__ __forceinline__ void gemm_phase(LAS unsigned char* lds, const Gemm g, const StaticOrder S, const Epi E) {
;     ...
;             PG8_LDA(At, 1, 1); PG8_STAGE(PG8_SB(1, 0), b3, voffB); PG8_STAGE(PG8_SB(1, 1), b3 + hstepB, voffB); PG8_STAGE(PG8_SA(1, 0), a3, voffA);
;             PG8_WAIT_V(8); PG8_WAIT_L(0); PG8_BAR; PG8_MMA(1, 0, At, B0); PG8_MMA(1, 1, At, B1); PG8_BAR; PG8_SCHED;
;         }
;         if (ALIGN_EPI) { if (wr == 0) PG8_BAR; }
	s_mov_b32 m0, s92
	v_lshl_add_u64 v[182:183], v[182:183], 0, s[12:13]
	ds_read_b128 v[178:181], v145 offset:49152
	ds_read_b128 v[186:189], v145 offset:50176
	ds_read_b128 v[190:193], v145 offset:51200
	ds_read_b128 v[194:197], v145 offset:52224
	ds_read_b128 v[198:201], v145 offset:53248
	ds_read_b128 v[202:205], v145 offset:54272
	ds_read_b128 v[206:209], v145 offset:55296
	ds_read_b128 v[210:213], v145 offset:56320
	global_load_lds_dwordx4 v[182:183], off
	v_lshl_add_u64 v[182:183], v[214:215], 0, s[12:13]
	s_mov_b32 m0, s90
	s_nop 0
	global_load_lds_dwordx4 v[182:183], off
	v_lshl_add_u64 v[182:183], s[58:59], 0, v[130:131]
	s_mov_b32 m0, s91
	s_nop 0
	global_load_lds_dwordx4 v[182:183], off
	v_lshl_add_u64 v[182:183], s[58:59], 0, v[134:135]
	s_mov_b32 m0, s83
	s_nop 0
	global_load_lds_dwordx4 v[182:183], off
	v_lshl_add_u64 v[182:183], v[216:217], 0, s[12:13]
	s_mov_b32 m0, s74
	s_nop 0
	global_load_lds_dwordx4 v[182:183], off
	v_lshl_add_u64 v[182:183], v[218:219], 0, s[12:13]
	s_mov_b32 m0, s75
	s_nop 0
	global_load_lds_dwordx4 v[182:183], off
	s_waitcnt vmcnt(8)
	s_waitcnt lgkmcnt(0)
	s_barrier
	s_waitcnt lgkmcnt(0)
	v_mfma_f32_16x16x32_bf16 v[92:95], v[146:149], v[178:181], v[92:95]
	v_mfma_f32_16x16x32_bf16 v[88:91], v[154:157], v[178:181], v[88:91]
	v_mfma_f32_16x16x32_bf16 v[84:87], v[146:149], v[190:193], v[84:87]
	v_mfma_f32_16x16x32_bf16 v[80:83], v[154:157], v[190:193], v[80:83]
	v_mfma_f32_16x16x32_bf16 v[68:71], v[146:149], v[198:201], v[68:71]
	v_mfma_f32_16x16x32_bf16 v[60:63], v[154:157], v[198:201], v[60:63]
	v_mfma_f32_16x16x32_bf16 v[44:47], v[146:149], v[206:209], v[44:47]
	v_mfma_f32_16x16x32_bf16 v[40:43], v[154:157], v[206:209], v[40:43]
	v_mfma_f32_16x16x32_bf16 v[92:95], v[150:153], v[186:189], v[92:95]
	v_mfma_f32_16x16x32_bf16 v[88:91], v[158:161], v[186:189], v[88:91]
	v_mfma_f32_16x16x32_bf16 v[84:87], v[150:153], v[194:197], v[84:87]
	v_mfma_f32_16x16x32_bf16 v[80:83], v[158:161], v[194:197], v[80:83]
	v_mfma_f32_16x16x32_bf16 v[68:71], v[150:153], v[202:205], v[68:71]
	v_mfma_f32_16x16x32_bf16 v[60:63], v[158:161], v[202:205], v[60:63]
	v_mfma_f32_16x16x32_bf16 v[44:47], v[150:153], v[210:213], v[44:47]
	v_mfma_f32_16x16x32_bf16 v[40:43], v[158:161], v[210:213], v[40:43]
	v_mfma_f32_16x16x32_bf16 v[28:31], v[162:165], v[178:181], v[28:31]
	v_mfma_f32_16x16x32_bf16 v[24:27], v[170:173], v[178:181], v[24:27]
	v_mfma_f32_16x16x32_bf16 v[20:23], v[162:165], v[190:193], v[20:23]
	v_mfma_f32_16x16x32_bf16 v[16:19], v[170:173], v[190:193], v[16:19]
	v_mfma_f32_16x16x32_bf16 v[12:15], v[162:165], v[198:201], v[12:15]
	v_mfma_f32_16x16x32_bf16 v[8:11], v[170:173], v[198:201], v[8:11]
	v_mfma_f32_16x16x32_bf16 v[4:7], v[162:165], v[206:209], v[4:7]
	v_mfma_f32_16x16x32_bf16 v[0:3], v[170:173], v[206:209], v[0:3]
	v_mfma_f32_16x16x32_bf16 v[28:31], v[166:169], v[186:189], v[28:31]
	v_mfma_f32_16x16x32_bf16 v[24:27], v[174:177], v[186:189], v[24:27]
	v_mfma_f32_16x16x32_bf16 v[20:23], v[166:169], v[194:197], v[20:23]
	v_mfma_f32_16x16x32_bf16 v[16:19], v[174:177], v[194:197], v[16:19]
	v_mfma_f32_16x16x32_bf16 v[12:15], v[166:169], v[202:205], v[12:15]
	v_mfma_f32_16x16x32_bf16 v[8:11], v[174:177], v[202:205], v[8:11]
	v_mfma_f32_16x16x32_bf16 v[4:7], v[166:169], v[210:213], v[4:7]
	v_mfma_f32_16x16x32_bf16 v[0:3], v[174:177], v[210:213], v[0:3]
	s_barrier
	s_movk_i32 s60, 0x100
	s_andn2_b64 vcc, exec, s[54:55]
	s_mov_b64 s[58:59], -1
	s_mov_b64 s[54:55], 0
	s_cbranch_vccz .LBB0_917
	s_and_b64 vcc, exec, s[22:23]
	s_cbranch_vccz .LBB0_920
	s_barrier

; #define PG8_STAGE(bufoff, gbase, voff) do { _Pragma("unroll") for (int _i = 0; _i < 2; ++_i) \
;         __builtin_amdgcn_global_load_lds((const unsigned*)((const char*)(gbase) + (voff)[_i]), (LAS unsigned*)(lds + (bufoff) + ldsw + _i * 8192), 16, 0, 0); } while (0)
; #define PG8_LDA(dst, b, h) do { _Pragma("unroll") for (int m = 0; m < 4; ++m) _Pragma("unroll") for (int k = 0; k < 2; ++k) dst[m][k] = *(const LAS bf16x8*)(lds + PG8_SA(b, h) + aoff + m * 2048 + k * 1024); } while (0)
; #define PG8_LDB(dst, b, h) do { _Pragma("unroll") for (int n = 0; n < 2; ++n) _Pragma("unroll") for (int k = 0; k < 2; ++k) dst[n][k] = *(const LAS bf16x8*)(lds + PG8_SB(b, h) + boff + n * 2048 + k * 1024); } while (0)
; #define PG8_MMA(ai, bj, At, Bt) do { __builtin_amdgcn_s_setprio(1); _Pragma("unroll") for (int m = 0; m < 4; ++m) _Pragma("unroll") for (int n = 0; n < 2; ++n) _Pragma("unroll") for (int k = 0; k < 2; ++k) \
;         acc[ai][bj][m][n] = __builtin_amdgcn_mfma_f32_16x16x32_bf16(Bt[n][k], At[m][k], acc[ai][bj][m][n], 0, 0, 0); __builtin_amdgcn_s_setprio(0); } while (0)
; #define PG8_WAIT_V(n) asm volatile("s_waitcnt vmcnt(" #n ")" ::: "memory")
; #define PG8_WAIT_L(n) asm volatile("s_waitcnt lgkmcnt(" #n ")" ::: "memory")
; #define PG8_BAR __builtin_amdgcn_s_barrier()
; #define PG8_SCHED __builtin_amdgcn_sched_barrier(0)
; template <class Epi, bool ALIGN_EPI = PG8_ALIGN>
; __device__ __forceinline__ void gemm_phase(LAS unsigned char* lds, const Gemm g, const StaticOrder S, const Epi E) {
;     ...
;         for (int t = 0; t < nt; t += 2) {
;             const bool last = (t == nt - 2);
;             const char* a1 = cA + (size_t)(t + 1) * kstep;
;             const char* a2 = last ? nA : cA + (size_t)(t + 2) * kstep; const char* b2 = last ? nB : cB + (size_t)(t + 2) * kstep;
;             const char* a3 = a2 + kstep; const char* b3 = b2 + kstep;
;             PG8_LDB(B0, 0, 0); PG8_LDB(B1, 0, 1); PG8_SCHED; PG8_LDA(At, 0, 0); PG8_STAGE(PG8_SA(1, 1), a1 + hstepA, voffA);
;             PG8_WAIT_V(8); PG8_WAIT_L(0); PG8_BAR; PG8_MMA(0, 0, At, B0); PG8_MMA(0, 1, At, B1); PG8_BAR; PG8_SCHED;
;             PG8_LDA(At, 0, 1); PG8_STAGE(PG8_SB(0, 0), b2, voffB); PG8_STAGE(PG8_SB(0, 1), b2 + hstepB, voffB); PG8_STAGE(PG8_SA(0, 0), a2, voffA);
;             PG8_WAIT_V(8); PG8_WAIT_L(0); PG8_BAR; PG8_MMA(1, 0, At, B0); PG8_MMA(1, 1, At, B1); PG8_BAR; PG8_SCHED;
.LBB0_1205:
	ds_read_b128 v[146:149], v151
	ds_read_b128 v[154:157], v151 offset:1024
	ds_read_b128 v[158:161], v151 offset:2048
	ds_read_b128 v[162:165], v151 offset:3072
	ds_read_b128 v[166:169], v152
	ds_read_b128 v[170:173], v152 offset:1024
	ds_read_b128 v[174:177], v152 offset:2048
	ds_read_b128 v[178:181], v152 offset:3072
	s_add_u32 s35, s46, 0xfff80080
	s_addc_u32 s37, s47, -1
	s_cmp_eq_u32 s34, 28
	s_cselect_b32 s51, s13, s37
	s_cselect_b32 s50, s14, s35
	s_cselect_b32 s49, s16, s33
	s_cselect_b32 s48, s17, s29
	v_lshl_add_u64 v[182:183], s[46:47], 0, v[138:139]
	s_add_i32 m0, s45, 0xc000
	ds_read_b128 v[186:189], v153
	ds_read_b128 v[190:193], v153 offset:1024
	ds_read_b128 v[194:197], v153 offset:2048
	ds_read_b128 v[198:201], v153 offset:3072
	ds_read_b128 v[202:205], v153 offset:4096
	ds_read_b128 v[206:209], v153 offset:5120
	ds_read_b128 v[210:213], v153 offset:6144
	ds_read_b128 v[214:217], v153 offset:7168
	global_load_lds_dwordx4 v[182:183], off
	v_lshl_add_u64 v[182:183], s[46:47], 0, v[140:141]
	s_add_i32 m0, s45, 0xe000
	s_nop 0
	global_load_lds_dwordx4 v[182:183], off
	s_waitcnt vmcnt(8)
	s_waitcnt lgkmcnt(0)
	s_barrier
	s_waitcnt lgkmcnt(0)
	v_mfma_f32_16x16x32_bf16 v[124:127], v[146:149], v[186:189], v[124:127]
	v_mfma_f32_16x16x32_bf16 v[120:123], v[158:161], v[186:189], v[120:123]
	v_mfma_f32_16x16x32_bf16 v[108:111], v[146:149], v[194:197], v[108:111]
	v_mfma_f32_16x16x32_bf16 v[104:107], v[158:161], v[194:197], v[104:107]
	v_mfma_f32_16x16x32_bf16 v[92:95], v[146:149], v[202:205], v[92:95]
	v_mfma_f32_16x16x32_bf16 v[88:91], v[158:161], v[202:205], v[88:91]
	v_mfma_f32_16x16x32_bf16 v[76:79], v[146:149], v[210:213], v[76:79]
	v_mfma_f32_16x16x32_bf16 v[72:75], v[158:161], v[210:213], v[72:75]
	v_mfma_f32_16x16x32_bf16 v[124:127], v[154:157], v[190:193], v[124:127]
	v_mfma_f32_16x16x32_bf16 v[120:123], v[162:165], v[190:193], v[120:123]
	v_mfma_f32_16x16x32_bf16 v[108:111], v[154:157], v[198:201], v[108:111]
	v_mfma_f32_16x16x32_bf16 v[104:107], v[162:165], v[198:201], v[104:107]
	v_mfma_f32_16x16x32_bf16 v[92:95], v[154:157], v[206:209], v[92:95]
	v_mfma_f32_16x16x32_bf16 v[88:91], v[162:165], v[206:209], v[88:91]
	v_mfma_f32_16x16x32_bf16 v[76:79], v[154:157], v[214:217], v[76:79]
	v_mfma_f32_16x16x32_bf16 v[72:75], v[162:165], v[214:217], v[72:75]
	v_mfma_f32_16x16x32_bf16 v[116:119], v[166:169], v[186:189], v[116:119]
	v_mfma_f32_16x16x32_bf16 v[112:115], v[174:177], v[186:189], v[112:115]
	v_mfma_f32_16x16x32_bf16 v[100:103], v[166:169], v[194:197], v[100:103]
	v_mfma_f32_16x16x32_bf16 v[96:99], v[174:177], v[194:197], v[96:99]
	v_mfma_f32_16x16x32_bf16 v[84:87], v[166:169], v[202:205], v[84:87]
	v_mfma_f32_16x16x32_bf16 v[80:83], v[174:177], v[202:205], v[80:83]
	v_mfma_f32_16x16x32_bf16 v[68:71], v[166:169], v[210:213], v[68:71]
	v_mfma_f32_16x16x32_bf16 v[64:67], v[174:177], v[210:213], v[64:67]
	v_mfma_f32_16x16x32_bf16 v[116:119], v[170:173], v[190:193], v[116:119]
	v_mfma_f32_16x16x32_bf16 v[112:115], v[178:181], v[190:193], v[112:115]
	v_mfma_f32_16x16x32_bf16 v[100:103], v[170:173], v[198:201], v[100:103]
	v_mfma_f32_16x16x32_bf16 v[96:99], v[178:181], v[198:201], v[96:99]
	v_mfma_f32_16x16x32_bf16 v[84:87], v[170:173], v[206:209], v[84:87]
	v_mfma_f32_16x16x32_bf16 v[80:83], v[178:181], v[206:209], v[80:83]
	v_mfma_f32_16x16x32_bf16 v[68:71], v[170:173], v[214:217], v[68:71]
	v_mfma_f32_16x16x32_bf16 v[64:67], v[178:181], v[214:217], v[64:67]
	s_barrier
	s_add_i32 s35, s61, s52
	v_lshl_add_u64 v[182:183], s[48:49], 0, v[130:131]
	s_mov_b32 m0, s35
	ds_read_b128 v[186:189], v153 offset:16384
	ds_read_b128 v[190:193], v153 offset:17408
	ds_read_b128 v[194:197], v153 offset:18432
	ds_read_b128 v[198:201], v153 offset:19456
	ds_read_b128 v[202:205], v153 offset:20480
	ds_read_b128 v[206:209], v153 offset:21504
	ds_read_b128 v[210:213], v153 offset:22528
	ds_read_b128 v[214:217], v153 offset:23552
	global_load_lds_dwordx4 v[182:183], off
	s_add_i32 m0, s35, 0x2000
	s_add_u32 s64, s48, 0x80000
	v_lshl_add_u64 v[218:219], s[48:49], 0, v[134:135]
	s_addc_u32 s65, s49, 0
	s_add_i32 s35, s62, s52
	global_load_lds_dwordx4 v[218:219], off
	v_lshl_add_u64 v[220:221], s[64:65], 0, v[130:131]
	s_mov_b32 m0, s35
	v_lshl_add_u64 v[222:223], s[50:51], 0, v[132:133]
	global_load_lds_dwordx4 v[220:221], off
	v_lshl_add_u64 v[220:221], s[64:65], 0, v[134:135]
	s_add_i32 m0, s35, 0x2000
	s_nop 0
	global_load_lds_dwordx4 v[220:221], off
	v_lshl_add_u64 v[220:221], s[50:51], 0, v[128:129]
	s_mov_b32 m0, s45
	s_nop 0
	global_load_lds_dwordx4 v[220:221], off
	s_mov_b32 m0, s53
	s_nop 0
	global_load_lds_dwordx4 v[222:223], off
	s_waitcnt vmcnt(8)
	s_waitcnt lgkmcnt(0)
	s_barrier
; #define PG8_STAGE(bufoff, gbase, voff) do { _Pragma("unroll") for (int _i = 0; _i < 2; ++_i) \
;         __builtin_amdgcn_global_load_lds((const unsigned*)((const char*)(gbase) + (voff)[_i]), (LAS unsigned*)(lds + (bufoff) + ldsw + _i * 8192), 16, 0, 0); } while (0)
; #define PG8_LDA(dst, b, h) do { _Pragma("unroll") for (int m = 0; m < 4; ++m) _Pragma("unroll") for (int k = 0; k < 2; ++k) dst[m][k] = *(const LAS bf16x8*)(lds + PG8_SA(b, h) + aoff + m * 2048 + k * 1024); } while (0)
; #define PG8_LDB(dst, b, h) do { _Pragma("unroll") for (int n = 0; n < 2; ++n) _Pragma("unroll") for (int k = 0; k < 2; ++k) dst[n][k] = *(const LAS bf16x8*)(lds + PG8_SB(b, h) + boff + n * 2048 + k * 1024); } while (0)
; #define PG8_MMA(ai, bj, At, Bt) do { __builtin_amdgcn_s_setprio(1); _Pragma("unroll") for (int m = 0; m < 4; ++m) _Pragma("unroll") for (int n = 0; n < 2; ++n) _Pragma("unroll") for (int k = 0; k < 2; ++k) \
;         acc[ai][bj][m][n] = __builtin_amdgcn_mfma_f32_16x16x32_bf16(Bt[n][k], At[m][k], acc[ai][bj][m][n], 0, 0, 0); __builtin_amdgcn_s_setprio(0); } while (0)
; #define PG8_WAIT_V(n) asm volatile("s_waitcnt vmcnt(" #n ")" ::: "memory")
; #define PG8_WAIT_L(n) asm volatile("s_waitcnt lgkmcnt(" #n ")" ::: "memory")
; #define PG8_BAR __builtin_amdgcn_s_barrier()
; #define PG8_SCHED __builtin_amdgcn_sched_barrier(0)
; template <class Epi, bool ALIGN_EPI = PG8_ALIGN>
; __device__ __forceinline__ void gemm_phase(LAS unsigned char* lds, const Gemm g, const StaticOrder S, const Epi E) {
;     ...
;             PG8_WAIT_V(8); PG8_WAIT_L(0); PG8_BAR; PG8_MMA(1, 0, At, B0); PG8_MMA(1, 1, At, B1); PG8_BAR; PG8_SCHED;
;             PG8_LDB(B0, 1, 0); PG8_LDB(B1, 1, 1); PG8_SCHED; PG8_LDA(At, 1, 0); PG8_STAGE(PG8_SA(0, 1), a2 + hstepA, voffA);
;             PG8_WAIT_V(8); PG8_WAIT_L(0); PG8_BAR; PG8_MMA(0, 0, At, B0); PG8_MMA(0, 1, At, B1); PG8_BAR; PG8_SCHED;
;             PG8_LDA(At, 1, 1); PG8_STAGE(PG8_SB(1, 0), b3, voffB); PG8_STAGE(PG8_SB(1, 1), b3 + hstepB, voffB); PG8_STAGE(PG8_SA(1, 0), a3, voffA);
;             PG8_WAIT_V(8); PG8_WAIT_L(0); PG8_BAR; PG8_MMA(1, 0, At, B0); PG8_MMA(1, 1, At, B1); PG8_BAR; PG8_SCHED;
	s_waitcnt lgkmcnt(0)
	v_mfma_f32_16x16x32_bf16 v[60:63], v[146:149], v[186:189], v[60:63]
	v_mfma_f32_16x16x32_bf16 v[56:59], v[158:161], v[186:189], v[56:59]
	v_mfma_f32_16x16x32_bf16 v[44:47], v[146:149], v[194:197], v[44:47]
	v_mfma_f32_16x16x32_bf16 v[40:43], v[158:161], v[194:197], v[40:43]
	v_mfma_f32_16x16x32_bf16 v[28:31], v[146:149], v[202:205], v[28:31]
	v_mfma_f32_16x16x32_bf16 v[24:27], v[158:161], v[202:205], v[24:27]
	v_mfma_f32_16x16x32_bf16 v[12:15], v[146:149], v[210:213], v[12:15]
	v_mfma_f32_16x16x32_bf16 v[8:11], v[158:161], v[210:213], v[8:11]
	v_mfma_f32_16x16x32_bf16 v[60:63], v[154:157], v[190:193], v[60:63]
	v_mfma_f32_16x16x32_bf16 v[56:59], v[162:165], v[190:193], v[56:59]
	v_mfma_f32_16x16x32_bf16 v[44:47], v[154:157], v[198:201], v[44:47]
	v_mfma_f32_16x16x32_bf16 v[40:43], v[162:165], v[198:201], v[40:43]
	v_mfma_f32_16x16x32_bf16 v[28:31], v[154:157], v[206:209], v[28:31]
	v_mfma_f32_16x16x32_bf16 v[24:27], v[162:165], v[206:209], v[24:27]
	v_mfma_f32_16x16x32_bf16 v[12:15], v[154:157], v[214:217], v[12:15]
	v_mfma_f32_16x16x32_bf16 v[8:11], v[162:165], v[214:217], v[8:11]
	v_mfma_f32_16x16x32_bf16 v[52:55], v[166:169], v[186:189], v[52:55]
	v_mfma_f32_16x16x32_bf16 v[48:51], v[174:177], v[186:189], v[48:51]
	v_mfma_f32_16x16x32_bf16 v[36:39], v[166:169], v[194:197], v[36:39]
	v_mfma_f32_16x16x32_bf16 v[32:35], v[174:177], v[194:197], v[32:35]
	v_mfma_f32_16x16x32_bf16 v[20:23], v[166:169], v[202:205], v[20:23]
	v_mfma_f32_16x16x32_bf16 v[16:19], v[174:177], v[202:205], v[16:19]
	v_mfma_f32_16x16x32_bf16 v[4:7], v[166:169], v[210:213], v[4:7]
	v_mfma_f32_16x16x32_bf16 v[0:3], v[174:177], v[210:213], v[0:3]
	v_mfma_f32_16x16x32_bf16 v[52:55], v[170:173], v[190:193], v[52:55]
	v_mfma_f32_16x16x32_bf16 v[48:51], v[178:181], v[190:193], v[48:51]
	v_mfma_f32_16x16x32_bf16 v[36:39], v[170:173], v[198:201], v[36:39]
	v_mfma_f32_16x16x32_bf16 v[32:35], v[178:181], v[198:201], v[32:35]
	v_mfma_f32_16x16x32_bf16 v[20:23], v[170:173], v[206:209], v[20:23]
	v_mfma_f32_16x16x32_bf16 v[16:19], v[178:181], v[206:209], v[16:19]
	v_mfma_f32_16x16x32_bf16 v[4:7], v[170:173], v[214:217], v[4:7]
	v_mfma_f32_16x16x32_bf16 v[0:3], v[178:181], v[214:217], v[0:3]
	s_barrier
	s_add_i32 s35, 0, 0x18000
	s_add_i32 s37, 0, 0x1c000
	v_add_u32_e32 v162, s35, v150
	v_add_u32_e32 v178, s37, v150
	ds_read_b128 v[146:149], v162
	ds_read_b128 v[154:157], v162 offset:1024
	ds_read_b128 v[158:161], v162 offset:2048
	ds_read_b128 v[162:165], v162 offset:3072
	ds_read_b128 v[166:169], v178
	ds_read_b128 v[170:173], v178 offset:1024
	ds_read_b128 v[174:177], v178 offset:2048
	ds_read_b128 v[178:181], v178 offset:3072
	s_add_u32 s50, s50, 0x80000
	s_addc_u32 s51, s51, 0
	s_mov_b32 m0, s54
	v_lshl_add_u64 v[224:225], s[50:51], 0, v[128:129]
	ds_read_b128 v[186:189], v153 offset:32768
	ds_read_b128 v[190:193], v153 offset:33792
	ds_read_b128 v[194:197], v153 offset:34816
	ds_read_b128 v[198:201], v153 offset:35840
	ds_read_b128 v[202:205], v153 offset:36864
	ds_read_b128 v[206:209], v153 offset:37888
	ds_read_b128 v[210:213], v153 offset:38912
	ds_read_b128 v[214:217], v153 offset:39936
	global_load_lds_dwordx4 v[224:225], off
	v_lshl_add_u64 v[224:225], s[50:51], 0, v[132:133]
	s_mov_b32 m0, s55
	s_nop 0
	global_load_lds_dwordx4 v[224:225], off
	s_waitcnt vmcnt(8)
	s_waitcnt lgkmcnt(0)
	s_barrier
	s_waitcnt lgkmcnt(0)
	v_mfma_f32_16x16x32_bf16 v[124:127], v[146:149], v[186:189], v[124:127]
	v_mfma_f32_16x16x32_bf16 v[120:123], v[158:161], v[186:189], v[120:123]
	v_mfma_f32_16x16x32_bf16 v[108:111], v[146:149], v[194:197], v[108:111]
	v_mfma_f32_16x16x32_bf16 v[104:107], v[158:161], v[194:197], v[104:107]
	v_mfma_f32_16x16x32_bf16 v[92:95], v[146:149], v[202:205], v[92:95]
	v_mfma_f32_16x16x32_bf16 v[88:91], v[158:161], v[202:205], v[88:91]
	v_mfma_f32_16x16x32_bf16 v[76:79], v[146:149], v[210:213], v[76:79]
	v_mfma_f32_16x16x32_bf16 v[72:75], v[158:161], v[210:213], v[72:75]
	v_mfma_f32_16x16x32_bf16 v[124:127], v[154:157], v[190:193], v[124:127]
	v_mfma_f32_16x16x32_bf16 v[120:123], v[162:165], v[190:193], v[120:123]
	v_mfma_f32_16x16x32_bf16 v[108:111], v[154:157], v[198:201], v[108:111]
	v_mfma_f32_16x16x32_bf16 v[104:107], v[162:165], v[198:201], v[104:107]
	v_mfma_f32_16x16x32_bf16 v[92:95], v[154:157], v[206:209], v[92:95]
	v_mfma_f32_16x16x32_bf16 v[88:91], v[162:165], v[206:209], v[88:91]
	v_mfma_f32_16x16x32_bf16 v[76:79], v[154:157], v[214:217], v[76:79]
	v_mfma_f32_16x16x32_bf16 v[72:75], v[162:165], v[214:217], v[72:75]
	v_mfma_f32_16x16x32_bf16 v[116:119], v[166:169], v[186:189], v[116:119]
	v_mfma_f32_16x16x32_bf16 v[112:115], v[174:177], v[186:189], v[112:115]
	v_mfma_f32_16x16x32_bf16 v[100:103], v[166:169], v[194:197], v[100:103]
	v_mfma_f32_16x16x32_bf16 v[96:99], v[174:177], v[194:197], v[96:99]
	v_mfma_f32_16x16x32_bf16 v[84:87], v[166:169], v[202:205], v[84:87]
	v_mfma_f32_16x16x32_bf16 v[80:83], v[174:177], v[202:205], v[80:83]
	v_mfma_f32_16x16x32_bf16 v[68:71], v[166:169], v[210:213], v[68:71]
	v_mfma_f32_16x16x32_bf16 v[64:67], v[174:177], v[210:213], v[64:67]
	v_mfma_f32_16x16x32_bf16 v[116:119], v[170:173], v[190:193], v[116:119]
	v_mfma_f32_16x16x32_bf16 v[112:115], v[178:181], v[190:193], v[112:115]
	v_mfma_f32_16x16x32_bf16 v[100:103], v[170:173], v[198:201], v[100:103]
	v_mfma_f32_16x16x32_bf16 v[96:99], v[178:181], v[198:201], v[96:99]
	v_mfma_f32_16x16x32_bf16 v[84:87], v[170:173], v[206:209], v[84:87]
	v_mfma_f32_16x16x32_bf16 v[80:83], v[178:181], v[206:209], v[80:83]
	v_mfma_f32_16x16x32_bf16 v[68:71], v[170:173], v[214:217], v[68:71]
	v_mfma_f32_16x16x32_bf16 v[64:67], v[178:181], v[214:217], v[64:67]
	s_barrier
; #define PG8_STAGE(bufoff, gbase, voff) do { _Pragma("unroll") for (int _i = 0; _i < 2; ++_i) \
;         __builtin_amdgcn_global_load_lds((const unsigned*)((const char*)(gbase) + (voff)[_i]), (LAS unsigned*)(lds + (bufoff) + ldsw + _i * 8192), 16, 0, 0); } while (0)
; #define PG8_LDA(dst, b, h) do { _Pragma("unroll") for (int m = 0; m < 4; ++m) _Pragma("unroll") for (int k = 0; k < 2; ++k) dst[m][k] = *(const LAS bf16x8*)(lds + PG8_SA(b, h) + aoff + m * 2048 + k * 1024); } while (0)
; #define PG8_MMA(ai, bj, At, Bt) do { __builtin_amdgcn_s_setprio(1); _Pragma("unroll") for (int m = 0; m < 4; ++m) _Pragma("unroll") for (int n = 0; n < 2; ++n) _Pragma("unroll") for (int k = 0; k < 2; ++k) \
;         acc[ai][bj][m][n] = __builtin_amdgcn_mfma_f32_16x16x32_bf16(Bt[n][k], At[m][k], acc[ai][bj][m][n], 0, 0, 0); __builtin_amdgcn_s_setprio(0); } while (0)
; #define PG8_WAIT_V(n) asm volatile("s_waitcnt vmcnt(" #n ")" ::: "memory")
; #define PG8_WAIT_L(n) asm volatile("s_waitcnt lgkmcnt(" #n ")" ::: "memory")
; #define PG8_BAR __builtin_amdgcn_s_barrier()
; #define PG8_SCHED __builtin_amdgcn_sched_barrier(0)
; template <class Epi, bool ALIGN_EPI = PG8_ALIGN>
; __device__ __forceinline__ void gemm_phase(LAS unsigned char* lds, const Gemm g, const StaticOrder S, const Epi E) {
;     ...
;             PG8_LDA(At, 1, 1); PG8_STAGE(PG8_SB(1, 0), b3, voffB); PG8_STAGE(PG8_SB(1, 1), b3 + hstepB, voffB); PG8_STAGE(PG8_SA(1, 0), a3, voffA);
;             PG8_WAIT_V(8); PG8_WAIT_L(0); PG8_BAR; PG8_MMA(1, 0, At, B0); PG8_MMA(1, 1, At, B1); PG8_BAR; PG8_SCHED;
;         }
;         if (ALIGN_EPI) { if (wr == 0) PG8_BAR; }
	s_add_i32 s35, s35, s52
	v_lshl_add_u64 v[182:183], v[182:183], 0, s[24:25]
	s_mov_b32 m0, s35
	ds_read_b128 v[186:189], v153 offset:49152
	ds_read_b128 v[190:193], v153 offset:50176
	ds_read_b128 v[194:197], v153 offset:51200
	ds_read_b128 v[198:201], v153 offset:52224
	ds_read_b128 v[202:205], v153 offset:53248
	ds_read_b128 v[206:209], v153 offset:54272
	ds_read_b128 v[210:213], v153 offset:55296
	ds_read_b128 v[214:217], v153 offset:56320
	global_load_lds_dwordx4 v[182:183], off
	s_add_i32 m0, s35, 0x2000
	s_add_u32 s48, s48, 0x80080
	v_lshl_add_u64 v[182:183], v[218:219], 0, s[24:25]
	s_addc_u32 s49, s49, 0
	s_add_i32 s35, s37, s52
	global_load_lds_dwordx4 v[182:183], off
	v_lshl_add_u64 v[182:183], s[48:49], 0, v[130:131]
	s_mov_b32 m0, s35
	s_nop 0
	global_load_lds_dwordx4 v[182:183], off
	v_lshl_add_u64 v[182:183], s[48:49], 0, v[134:135]
	s_add_i32 m0, s35, 0x2000
	s_nop 0
	global_load_lds_dwordx4 v[182:183], off
	v_lshl_add_u64 v[182:183], v[220:221], 0, s[24:25]
	s_mov_b32 m0, s58
	s_nop 0
	global_load_lds_dwordx4 v[182:183], off
	v_lshl_add_u64 v[182:183], v[222:223], 0, s[24:25]
	s_mov_b32 m0, s59
	s_nop 0
	global_load_lds_dwordx4 v[182:183], off
	s_waitcnt vmcnt(8)
	s_waitcnt lgkmcnt(0)
	s_barrier
	s_waitcnt lgkmcnt(0)
	v_mfma_f32_16x16x32_bf16 v[60:63], v[146:149], v[186:189], v[60:63]
	v_mfma_f32_16x16x32_bf16 v[56:59], v[158:161], v[186:189], v[56:59]
	v_mfma_f32_16x16x32_bf16 v[44:47], v[146:149], v[194:197], v[44:47]
	v_mfma_f32_16x16x32_bf16 v[40:43], v[158:161], v[194:197], v[40:43]
	v_mfma_f32_16x16x32_bf16 v[28:31], v[146:149], v[202:205], v[28:31]
	v_mfma_f32_16x16x32_bf16 v[24:27], v[158:161], v[202:205], v[24:27]
	v_mfma_f32_16x16x32_bf16 v[12:15], v[146:149], v[210:213], v[12:15]
	v_mfma_f32_16x16x32_bf16 v[8:11], v[158:161], v[210:213], v[8:11]
	v_mfma_f32_16x16x32_bf16 v[60:63], v[154:157], v[190:193], v[60:63]
	v_mfma_f32_16x16x32_bf16 v[56:59], v[162:165], v[190:193], v[56:59]
	v_mfma_f32_16x16x32_bf16 v[44:47], v[154:157], v[198:201], v[44:47]
	v_mfma_f32_16x16x32_bf16 v[40:43], v[162:165], v[198:201], v[40:43]
	v_mfma_f32_16x16x32_bf16 v[28:31], v[154:157], v[206:209], v[28:31]
	v_mfma_f32_16x16x32_bf16 v[24:27], v[162:165], v[206:209], v[24:27]
	v_mfma_f32_16x16x32_bf16 v[12:15], v[154:157], v[214:217], v[12:15]
	v_mfma_f32_16x16x32_bf16 v[8:11], v[162:165], v[214:217], v[8:11]
	v_mfma_f32_16x16x32_bf16 v[52:55], v[166:169], v[186:189], v[52:55]
	v_mfma_f32_16x16x32_bf16 v[48:51], v[174:177], v[186:189], v[48:51]
	v_mfma_f32_16x16x32_bf16 v[36:39], v[166:169], v[194:197], v[36:39]
	v_mfma_f32_16x16x32_bf16 v[32:35], v[174:177], v[194:197], v[32:35]
	v_mfma_f32_16x16x32_bf16 v[20:23], v[166:169], v[202:205], v[20:23]
	v_mfma_f32_16x16x32_bf16 v[16:19], v[174:177], v[202:205], v[16:19]
	v_mfma_f32_16x16x32_bf16 v[4:7], v[166:169], v[210:213], v[4:7]
	v_mfma_f32_16x16x32_bf16 v[0:3], v[174:177], v[210:213], v[0:3]
	v_mfma_f32_16x16x32_bf16 v[52:55], v[170:173], v[190:193], v[52:55]
	v_mfma_f32_16x16x32_bf16 v[48:51], v[178:181], v[190:193], v[48:51]
	v_mfma_f32_16x16x32_bf16 v[36:39], v[170:173], v[198:201], v[36:39]
	v_mfma_f32_16x16x32_bf16 v[32:35], v[178:181], v[198:201], v[32:35]
	v_mfma_f32_16x16x32_bf16 v[20:23], v[170:173], v[206:209], v[20:23]
	v_mfma_f32_16x16x32_bf16 v[16:19], v[178:181], v[206:209], v[16:19]
	v_mfma_f32_16x16x32_bf16 v[4:7], v[170:173], v[214:217], v[4:7]
	v_mfma_f32_16x16x32_bf16 v[0:3], v[178:181], v[214:217], v[0:3]
	s_barrier
	s_add_i32 s34, s34, 2
	s_add_u32 s46, s46, 0x100
	s_addc_u32 s47, s47, 0
	s_add_u32 s29, s29, 0x100
	s_addc_u32 s33, s33, 0
	s_cmp_gt_u32 s34, 29
	s_cbranch_scc0 .LBB0_1205
	s_and_b64 vcc, exec, s[26:27]
	s_cbranch_vccz .LBB0_1208
	s_barrier

; #define PG8_STAGE(bufoff, gbase, voff) do { _Pragma("unroll") for (int _i = 0; _i < 2; ++_i) \
;         __builtin_amdgcn_global_load_lds((const unsigned*)((const char*)(gbase) + (voff)[_i]), (LAS unsigned*)(lds + (bufoff) + ldsw + _i * 8192), 16, 0, 0); } while (0)
; #define PG8_LDA(dst, b, h) do { _Pragma("unroll") for (int m = 0; m < 4; ++m) _Pragma("unroll") for (int k = 0; k < 2; ++k) dst[m][k] = *(const LAS bf16x8*)(lds + PG8_SA(b, h) + aoff + m * 2048 + k * 1024); } while (0)
; #define PG8_LDB(dst, b, h) do { _Pragma("unroll") for (int n = 0; n < 2; ++n) _Pragma("unroll") for (int k = 0; k < 2; ++k) dst[n][k] = *(const LAS bf16x8*)(lds + PG8_SB(b, h) + boff + n * 2048 + k * 1024); } while (0)
; #define PG8_MMA(ai, bj, At, Bt) do { __builtin_amdgcn_s_setprio(1); _Pragma("unroll") for (int m = 0; m < 4; ++m) _Pragma("unroll") for (int n = 0; n < 2; ++n) _Pragma("unroll") for (int k = 0; k < 2; ++k) \
;         acc[ai][bj][m][n] = __builtin_amdgcn_mfma_f32_16x16x32_bf16(Bt[n][k], At[m][k], acc[ai][bj][m][n], 0, 0, 0); __builtin_amdgcn_s_setprio(0); } while (0)
; #define PG8_WAIT_V(n) asm volatile("s_waitcnt vmcnt(" #n ")" ::: "memory")
; #define PG8_WAIT_L(n) asm volatile("s_waitcnt lgkmcnt(" #n ")" ::: "memory")
; #define PG8_BAR __builtin_amdgcn_s_barrier()
; #define PG8_SCHED __builtin_amdgcn_sched_barrier(0)
; template <class Epi, bool ALIGN_EPI = PG8_ALIGN>
; __device__ __forceinline__ void gemm_phase(LAS unsigned char* lds, const Gemm g, const StaticOrder S, const Epi E) {
;     ...
;         for (int t = 0; t < nt; t += 2) {
;             const bool last = (t == nt - 2);
;             const char* a1 = cA + (size_t)(t + 1) * kstep;
;             const char* a2 = last ? nA : cA + (size_t)(t + 2) * kstep; const char* b2 = last ? nB : cB + (size_t)(t + 2) * kstep;
;             const char* a3 = a2 + kstep; const char* b3 = b2 + kstep;
;             PG8_LDB(B0, 0, 0); PG8_LDB(B1, 0, 1); PG8_SCHED; PG8_LDA(At, 0, 0); PG8_STAGE(PG8_SA(1, 1), a1 + hstepA, voffA);
;             PG8_WAIT_V(8); PG8_WAIT_L(0); PG8_BAR; PG8_MMA(0, 0, At, B0); PG8_MMA(0, 1, At, B1); PG8_BAR; PG8_SCHED;
;             PG8_LDA(At, 0, 1); PG8_STAGE(PG8_SB(0, 0), b2, voffB); PG8_STAGE(PG8_SB(0, 1), b2 + hstepB, voffB); PG8_STAGE(PG8_SA(0, 0), a2, voffA);
;             PG8_WAIT_V(8); PG8_WAIT_L(0); PG8_BAR; PG8_MMA(1, 0, At, B0); PG8_MMA(1, 1, At, B1); PG8_BAR; PG8_SCHED;
.LBB0_1300:
	ds_read_b128 v[144:147], v161
	ds_read_b128 v[166:169], v161 offset:1024
	ds_read_b128 v[170:173], v161 offset:2048
	ds_read_b128 v[174:177], v161 offset:3072
	ds_read_b128 v[178:181], v162
	ds_read_b128 v[186:189], v162 offset:1024
	ds_read_b128 v[190:193], v162 offset:2048
	ds_read_b128 v[194:197], v162 offset:3072
	s_add_u32 s54, s52, 0xfff80080
	s_addc_u32 s55, s53, -1
	s_cmp_eq_u32 s73, 28
	s_cselect_b32 s57, s47, s55
	s_cselect_b32 s56, s69, s54
	s_cselect_b32 s55, s45, s72
	s_cselect_b32 s54, s70, s71
	v_lshl_add_u64 v[148:149], s[52:53], 0, v[136:137]
	s_add_i32 m0, s17, 0xc000
	ds_read_b128 v[198:201], v163
	ds_read_b128 v[202:205], v163 offset:1024
	ds_read_b128 v[206:209], v163 offset:2048
	ds_read_b128 v[210:213], v163 offset:3072
	ds_read_b128 v[214:217], v163 offset:4096
	ds_read_b128 v[218:221], v163 offset:5120
	ds_read_b128 v[222:225], v163 offset:6144
	ds_read_b128 v[226:229], v163 offset:7168
	global_load_lds_dwordx4 v[148:149], off
	v_lshl_add_u64 v[148:149], s[52:53], 0, v[138:139]
	s_add_i32 m0, s17, 0xe000
	s_nop 0
	global_load_lds_dwordx4 v[148:149], off
	s_waitcnt vmcnt(8)
	s_waitcnt lgkmcnt(0)
	s_barrier
	s_waitcnt lgkmcnt(0)
	v_mfma_f32_16x16x32_bf16 v[124:127], v[144:147], v[198:201], v[124:127]
	v_mfma_f32_16x16x32_bf16 v[120:123], v[170:173], v[198:201], v[120:123]
	v_mfma_f32_16x16x32_bf16 v[116:119], v[144:147], v[206:209], v[116:119]
	v_mfma_f32_16x16x32_bf16 v[112:115], v[170:173], v[206:209], v[112:115]
	v_mfma_f32_16x16x32_bf16 v[108:111], v[144:147], v[214:217], v[108:111]
	v_mfma_f32_16x16x32_bf16 v[104:107], v[170:173], v[214:217], v[104:107]
	v_mfma_f32_16x16x32_bf16 v[100:103], v[144:147], v[222:225], v[100:103]
	v_mfma_f32_16x16x32_bf16 v[96:99], v[170:173], v[222:225], v[96:99]
	v_mfma_f32_16x16x32_bf16 v[124:127], v[166:169], v[202:205], v[124:127]
	v_mfma_f32_16x16x32_bf16 v[120:123], v[174:177], v[202:205], v[120:123]
	v_mfma_f32_16x16x32_bf16 v[116:119], v[166:169], v[210:213], v[116:119]
	v_mfma_f32_16x16x32_bf16 v[112:115], v[174:177], v[210:213], v[112:115]
	v_mfma_f32_16x16x32_bf16 v[108:111], v[166:169], v[218:221], v[108:111]
	v_mfma_f32_16x16x32_bf16 v[104:107], v[174:177], v[218:221], v[104:107]
	v_mfma_f32_16x16x32_bf16 v[100:103], v[166:169], v[226:229], v[100:103]
	v_mfma_f32_16x16x32_bf16 v[96:99], v[174:177], v[226:229], v[96:99]
	v_mfma_f32_16x16x32_bf16 v[68:71], v[178:181], v[198:201], v[68:71]
	v_mfma_f32_16x16x32_bf16 v[64:67], v[190:193], v[198:201], v[64:67]
	v_mfma_f32_16x16x32_bf16 v[56:59], v[178:181], v[206:209], v[56:59]
	v_mfma_f32_16x16x32_bf16 v[48:51], v[190:193], v[206:209], v[48:51]
	v_mfma_f32_16x16x32_bf16 v[44:47], v[178:181], v[214:217], v[44:47]
	v_mfma_f32_16x16x32_bf16 v[40:43], v[190:193], v[214:217], v[40:43]
	v_mfma_f32_16x16x32_bf16 v[36:39], v[178:181], v[222:225], v[36:39]
	v_mfma_f32_16x16x32_bf16 v[32:35], v[190:193], v[222:225], v[32:35]
	v_mfma_f32_16x16x32_bf16 v[68:71], v[186:189], v[202:205], v[68:71]
	v_mfma_f32_16x16x32_bf16 v[64:67], v[194:197], v[202:205], v[64:67]
	v_mfma_f32_16x16x32_bf16 v[56:59], v[186:189], v[210:213], v[56:59]
	v_mfma_f32_16x16x32_bf16 v[48:51], v[194:197], v[210:213], v[48:51]
	v_mfma_f32_16x16x32_bf16 v[44:47], v[186:189], v[218:221], v[44:47]
	v_mfma_f32_16x16x32_bf16 v[40:43], v[194:197], v[218:221], v[40:43]
	v_mfma_f32_16x16x32_bf16 v[36:39], v[186:189], v[226:229], v[36:39]
	v_mfma_f32_16x16x32_bf16 v[32:35], v[194:197], v[226:229], v[32:35]
	s_barrier
	s_add_i32 s74, s62, s16
	v_lshl_add_u64 v[148:149], s[54:55], 0, v[130:131]
	s_mov_b32 m0, s74
	ds_read_b128 v[198:201], v163 offset:16384
	ds_read_b128 v[202:205], v163 offset:17408
	ds_read_b128 v[206:209], v163 offset:18432
	ds_read_b128 v[210:213], v163 offset:19456
	ds_read_b128 v[214:217], v163 offset:20480
	ds_read_b128 v[218:221], v163 offset:21504
	ds_read_b128 v[222:225], v163 offset:22528
	ds_read_b128 v[226:229], v163 offset:23552
	global_load_lds_dwordx4 v[148:149], off
	s_add_i32 m0, s74, 0x2000
	s_add_u32 s74, s54, 0x80000
	v_lshl_add_u64 v[182:183], s[54:55], 0, v[134:135]
	s_addc_u32 s75, s55, 0
	s_add_i32 s76, s63, s16
	global_load_lds_dwordx4 v[182:183], off
	v_lshl_add_u64 v[230:231], s[74:75], 0, v[130:131]
	s_mov_b32 m0, s76
	v_lshl_add_u64 v[232:233], s[56:57], 0, v[132:133]
	global_load_lds_dwordx4 v[230:231], off
	v_lshl_add_u64 v[230:231], s[74:75], 0, v[134:135]
	s_add_i32 m0, s76, 0x2000
	s_nop 0
	global_load_lds_dwordx4 v[230:231], off
	v_lshl_add_u64 v[230:231], s[56:57], 0, v[128:129]
	s_mov_b32 m0, s17
	s_nop 0
	global_load_lds_dwordx4 v[230:231], off
	s_mov_b32 m0, s33
	s_nop 0
	global_load_lds_dwordx4 v[232:233], off
	s_waitcnt vmcnt(8)
	s_waitcnt lgkmcnt(0)
	s_barrier
; #define PG8_STAGE(bufoff, gbase, voff) do { _Pragma("unroll") for (int _i = 0; _i < 2; ++_i) \
;         __builtin_amdgcn_global_load_lds((const unsigned*)((const char*)(gbase) + (voff)[_i]), (LAS unsigned*)(lds + (bufoff) + ldsw + _i * 8192), 16, 0, 0); } while (0)
; #define PG8_LDA(dst, b, h) do { _Pragma("unroll") for (int m = 0; m < 4; ++m) _Pragma("unroll") for (int k = 0; k < 2; ++k) dst[m][k] = *(const LAS bf16x8*)(lds + PG8_SA(b, h) + aoff + m * 2048 + k * 1024); } while (0)
; #define PG8_LDB(dst, b, h) do { _Pragma("unroll") for (int n = 0; n < 2; ++n) _Pragma("unroll") for (int k = 0; k < 2; ++k) dst[n][k] = *(const LAS bf16x8*)(lds + PG8_SB(b, h) + boff + n * 2048 + k * 1024); } while (0)
; #define PG8_MMA(ai, bj, At, Bt) do { __builtin_amdgcn_s_setprio(1); _Pragma("unroll") for (int m = 0; m < 4; ++m) _Pragma("unroll") for (int n = 0; n < 2; ++n) _Pragma("unroll") for (int k = 0; k < 2; ++k) \
;         acc[ai][bj][m][n] = __builtin_amdgcn_mfma_f32_16x16x32_bf16(Bt[n][k], At[m][k], acc[ai][bj][m][n], 0, 0, 0); __builtin_amdgcn_s_setprio(0); } while (0)
; #define PG8_WAIT_V(n) asm volatile("s_waitcnt vmcnt(" #n ")" ::: "memory")
; #define PG8_WAIT_L(n) asm volatile("s_waitcnt lgkmcnt(" #n ")" ::: "memory")
; #define PG8_BAR __builtin_amdgcn_s_barrier()
; #define PG8_SCHED __builtin_amdgcn_sched_barrier(0)
; template <class Epi, bool ALIGN_EPI = PG8_ALIGN>
; __device__ __forceinline__ void gemm_phase(LAS unsigned char* lds, const Gemm g, const StaticOrder S, const Epi E) {
;     ...
;             PG8_WAIT_V(8); PG8_WAIT_L(0); PG8_BAR; PG8_MMA(1, 0, At, B0); PG8_MMA(1, 1, At, B1); PG8_BAR; PG8_SCHED;
;             PG8_LDB(B0, 1, 0); PG8_LDB(B1, 1, 1); PG8_SCHED; PG8_LDA(At, 1, 0); PG8_STAGE(PG8_SA(0, 1), a2 + hstepA, voffA);
;             PG8_WAIT_V(8); PG8_WAIT_L(0); PG8_BAR; PG8_MMA(0, 0, At, B0); PG8_MMA(0, 1, At, B1); PG8_BAR; PG8_SCHED;
;             PG8_LDA(At, 1, 1); PG8_STAGE(PG8_SB(1, 0), b3, voffB); PG8_STAGE(PG8_SB(1, 1), b3 + hstepB, voffB); PG8_STAGE(PG8_SA(1, 0), a3, voffA);
;             PG8_WAIT_V(8); PG8_WAIT_L(0); PG8_BAR; PG8_MMA(1, 0, At, B0); PG8_MMA(1, 1, At, B1); PG8_BAR; PG8_SCHED;
	s_waitcnt lgkmcnt(0)
	v_mfma_f32_16x16x32_bf16 v[92:95], v[144:147], v[198:201], v[92:95]
	v_mfma_f32_16x16x32_bf16 v[88:91], v[170:173], v[198:201], v[88:91]
	v_mfma_f32_16x16x32_bf16 v[84:87], v[144:147], v[206:209], v[84:87]
	v_mfma_f32_16x16x32_bf16 v[80:83], v[170:173], v[206:209], v[80:83]
	v_mfma_f32_16x16x32_bf16 v[76:79], v[144:147], v[214:217], v[76:79]
	v_mfma_f32_16x16x32_bf16 v[72:75], v[170:173], v[214:217], v[72:75]
	v_mfma_f32_16x16x32_bf16 v[60:63], v[144:147], v[222:225], v[60:63]
	v_mfma_f32_16x16x32_bf16 v[52:55], v[170:173], v[222:225], v[52:55]
	v_mfma_f32_16x16x32_bf16 v[92:95], v[166:169], v[202:205], v[92:95]
	v_mfma_f32_16x16x32_bf16 v[88:91], v[174:177], v[202:205], v[88:91]
	v_mfma_f32_16x16x32_bf16 v[84:87], v[166:169], v[210:213], v[84:87]
	v_mfma_f32_16x16x32_bf16 v[80:83], v[174:177], v[210:213], v[80:83]
	v_mfma_f32_16x16x32_bf16 v[76:79], v[166:169], v[218:221], v[76:79]
	v_mfma_f32_16x16x32_bf16 v[72:75], v[174:177], v[218:221], v[72:75]
	v_mfma_f32_16x16x32_bf16 v[60:63], v[166:169], v[226:229], v[60:63]
	v_mfma_f32_16x16x32_bf16 v[52:55], v[174:177], v[226:229], v[52:55]
	v_mfma_f32_16x16x32_bf16 v[28:31], v[178:181], v[198:201], v[28:31]
	v_mfma_f32_16x16x32_bf16 v[24:27], v[190:193], v[198:201], v[24:27]
	v_mfma_f32_16x16x32_bf16 v[20:23], v[178:181], v[206:209], v[20:23]
	v_mfma_f32_16x16x32_bf16 v[16:19], v[190:193], v[206:209], v[16:19]
	v_mfma_f32_16x16x32_bf16 v[12:15], v[178:181], v[214:217], v[12:15]
	v_mfma_f32_16x16x32_bf16 v[8:11], v[190:193], v[214:217], v[8:11]
	v_mfma_f32_16x16x32_bf16 v[4:7], v[178:181], v[222:225], v[4:7]
	v_mfma_f32_16x16x32_bf16 v[0:3], v[190:193], v[222:225], v[0:3]
	v_mfma_f32_16x16x32_bf16 v[28:31], v[186:189], v[202:205], v[28:31]
	v_mfma_f32_16x16x32_bf16 v[24:27], v[194:197], v[202:205], v[24:27]
	v_mfma_f32_16x16x32_bf16 v[20:23], v[186:189], v[210:213], v[20:23]
	v_mfma_f32_16x16x32_bf16 v[16:19], v[194:197], v[210:213], v[16:19]
	v_mfma_f32_16x16x32_bf16 v[12:15], v[186:189], v[218:221], v[12:15]
	v_mfma_f32_16x16x32_bf16 v[8:11], v[194:197], v[218:221], v[8:11]
	v_mfma_f32_16x16x32_bf16 v[4:7], v[186:189], v[226:229], v[4:7]
	v_mfma_f32_16x16x32_bf16 v[0:3], v[194:197], v[226:229], v[0:3]
	s_barrier
	s_add_i32 s74, 0, 0x18000
	v_add_u32_e32 v165, s74, v159
	s_add_i32 s75, 0, 0x1c000
	ds_read_b128 v[144:147], v165
	ds_read_b128 v[166:169], v165 offset:1024
	ds_read_b128 v[170:173], v165 offset:2048
	ds_read_b128 v[174:177], v165 offset:3072
	v_add_u32_e32 v165, s75, v159
	ds_read_b128 v[178:181], v165
	ds_read_b128 v[186:189], v165 offset:1024
	ds_read_b128 v[190:193], v165 offset:2048
	ds_read_b128 v[194:197], v165 offset:3072
	s_add_u32 s56, s56, 0x80000
	s_addc_u32 s57, s57, 0
	s_mov_b32 m0, s34
	v_lshl_add_u64 v[234:235], s[56:57], 0, v[128:129]
	ds_read_b128 v[198:201], v163 offset:32768
	ds_read_b128 v[202:205], v163 offset:33792
	ds_read_b128 v[206:209], v163 offset:34816
	ds_read_b128 v[210:213], v163 offset:35840
	ds_read_b128 v[214:217], v163 offset:36864
	ds_read_b128 v[218:221], v163 offset:37888
	ds_read_b128 v[222:225], v163 offset:38912
	ds_read_b128 v[226:229], v163 offset:39936
	global_load_lds_dwordx4 v[234:235], off
	v_lshl_add_u64 v[234:235], s[56:57], 0, v[132:133]
	s_mov_b32 m0, s35
	s_nop 0
	global_load_lds_dwordx4 v[234:235], off
	s_waitcnt vmcnt(8)
	s_waitcnt lgkmcnt(0)
	s_barrier
	s_waitcnt lgkmcnt(0)
	v_mfma_f32_16x16x32_bf16 v[124:127], v[144:147], v[198:201], v[124:127]
	v_mfma_f32_16x16x32_bf16 v[120:123], v[170:173], v[198:201], v[120:123]
	v_mfma_f32_16x16x32_bf16 v[116:119], v[144:147], v[206:209], v[116:119]
	v_mfma_f32_16x16x32_bf16 v[112:115], v[170:173], v[206:209], v[112:115]
	v_mfma_f32_16x16x32_bf16 v[108:111], v[144:147], v[214:217], v[108:111]
	v_mfma_f32_16x16x32_bf16 v[104:107], v[170:173], v[214:217], v[104:107]
	v_mfma_f32_16x16x32_bf16 v[100:103], v[144:147], v[222:225], v[100:103]
	v_mfma_f32_16x16x32_bf16 v[96:99], v[170:173], v[222:225], v[96:99]
	v_mfma_f32_16x16x32_bf16 v[124:127], v[166:169], v[202:205], v[124:127]
	v_mfma_f32_16x16x32_bf16 v[120:123], v[174:177], v[202:205], v[120:123]
	v_mfma_f32_16x16x32_bf16 v[116:119], v[166:169], v[210:213], v[116:119]
	v_mfma_f32_16x16x32_bf16 v[112:115], v[174:177], v[210:213], v[112:115]
	v_mfma_f32_16x16x32_bf16 v[108:111], v[166:169], v[218:221], v[108:111]
	v_mfma_f32_16x16x32_bf16 v[104:107], v[174:177], v[218:221], v[104:107]
	v_mfma_f32_16x16x32_bf16 v[100:103], v[166:169], v[226:229], v[100:103]
	v_mfma_f32_16x16x32_bf16 v[96:99], v[174:177], v[226:229], v[96:99]
	v_mfma_f32_16x16x32_bf16 v[68:71], v[178:181], v[198:201], v[68:71]
	v_mfma_f32_16x16x32_bf16 v[64:67], v[190:193], v[198:201], v[64:67]
	v_mfma_f32_16x16x32_bf16 v[56:59], v[178:181], v[206:209], v[56:59]
	v_mfma_f32_16x16x32_bf16 v[48:51], v[190:193], v[206:209], v[48:51]
	v_mfma_f32_16x16x32_bf16 v[44:47], v[178:181], v[214:217], v[44:47]
	v_mfma_f32_16x16x32_bf16 v[40:43], v[190:193], v[214:217], v[40:43]
	v_mfma_f32_16x16x32_bf16 v[36:39], v[178:181], v[222:225], v[36:39]
	v_mfma_f32_16x16x32_bf16 v[32:35], v[190:193], v[222:225], v[32:35]
	v_mfma_f32_16x16x32_bf16 v[68:71], v[186:189], v[202:205], v[68:71]
	v_mfma_f32_16x16x32_bf16 v[64:67], v[194:197], v[202:205], v[64:67]
	v_mfma_f32_16x16x32_bf16 v[56:59], v[186:189], v[210:213], v[56:59]
	v_mfma_f32_16x16x32_bf16 v[48:51], v[194:197], v[210:213], v[48:51]
	v_mfma_f32_16x16x32_bf16 v[44:47], v[186:189], v[218:221], v[44:47]
	v_mfma_f32_16x16x32_bf16 v[40:43], v[194:197], v[218:221], v[40:43]
	v_mfma_f32_16x16x32_bf16 v[36:39], v[186:189], v[226:229], v[36:39]
	v_mfma_f32_16x16x32_bf16 v[32:35], v[194:197], v[226:229], v[32:35]
	s_barrier
; #define PG8_STAGE(bufoff, gbase, voff) do { _Pragma("unroll") for (int _i = 0; _i < 2; ++_i) \
;         __builtin_amdgcn_global_load_lds((const unsigned*)((const char*)(gbase) + (voff)[_i]), (LAS unsigned*)(lds + (bufoff) + ldsw + _i * 8192), 16, 0, 0); } while (0)
; #define PG8_LDA(dst, b, h) do { _Pragma("unroll") for (int m = 0; m < 4; ++m) _Pragma("unroll") for (int k = 0; k < 2; ++k) dst[m][k] = *(const LAS bf16x8*)(lds + PG8_SA(b, h) + aoff + m * 2048 + k * 1024); } while (0)
; #define PG8_MMA(ai, bj, At, Bt) do { __builtin_amdgcn_s_setprio(1); _Pragma("unroll") for (int m = 0; m < 4; ++m) _Pragma("unroll") for (int n = 0; n < 2; ++n) _Pragma("unroll") for (int k = 0; k < 2; ++k) \
;         acc[ai][bj][m][n] = __builtin_amdgcn_mfma_f32_16x16x32_bf16(Bt[n][k], At[m][k], acc[ai][bj][m][n], 0, 0, 0); __builtin_amdgcn_s_setprio(0); } while (0)
; #define PG8_WAIT_V(n) asm volatile("s_waitcnt vmcnt(" #n ")" ::: "memory")
; #define PG8_WAIT_L(n) asm volatile("s_waitcnt lgkmcnt(" #n ")" ::: "memory")
; #define PG8_BAR __builtin_amdgcn_s_barrier()
; #define PG8_SCHED __builtin_amdgcn_sched_barrier(0)
; template <class Epi, bool ALIGN_EPI = PG8_ALIGN>
; __device__ __forceinline__ void gemm_phase(LAS unsigned char* lds, const Gemm g, const StaticOrder S, const Epi E) {
;     ...
;             PG8_LDA(At, 1, 1); PG8_STAGE(PG8_SB(1, 0), b3, voffB); PG8_STAGE(PG8_SB(1, 1), b3 + hstepB, voffB); PG8_STAGE(PG8_SA(1, 0), a3, voffA);
;             PG8_WAIT_V(8); PG8_WAIT_L(0); PG8_BAR; PG8_MMA(1, 0, At, B0); PG8_MMA(1, 1, At, B1); PG8_BAR; PG8_SCHED;
;         }
;         if (ALIGN_EPI) { if (wr == 0) PG8_BAR; }
	s_add_i32 s56, s74, s16
	v_lshl_add_u64 v[148:149], v[148:149], 0, s[26:27]
	s_mov_b32 m0, s56
	ds_read_b128 v[198:201], v163 offset:49152
	ds_read_b128 v[202:205], v163 offset:50176
	ds_read_b128 v[206:209], v163 offset:51200
	ds_read_b128 v[210:213], v163 offset:52224
	ds_read_b128 v[214:217], v163 offset:53248
	ds_read_b128 v[218:221], v163 offset:54272
	ds_read_b128 v[222:225], v163 offset:55296
	ds_read_b128 v[226:229], v163 offset:56320
	global_load_lds_dwordx4 v[148:149], off
	s_add_i32 m0, s56, 0x2000
	s_add_u32 s54, s54, 0x80080
	v_lshl_add_u64 v[148:149], v[182:183], 0, s[26:27]
	s_addc_u32 s55, s55, 0
	s_add_i32 s56, s75, s16
	global_load_lds_dwordx4 v[148:149], off
	v_lshl_add_u64 v[148:149], s[54:55], 0, v[130:131]
	s_mov_b32 m0, s56
	s_nop 0
	global_load_lds_dwordx4 v[148:149], off
	v_lshl_add_u64 v[148:149], s[54:55], 0, v[134:135]
	s_add_i32 m0, s56, 0x2000
	s_nop 0
	global_load_lds_dwordx4 v[148:149], off
	v_lshl_add_u64 v[148:149], v[230:231], 0, s[26:27]
	s_mov_b32 m0, s59
	s_nop 0
	global_load_lds_dwordx4 v[148:149], off
	v_lshl_add_u64 v[148:149], v[232:233], 0, s[26:27]
	s_mov_b32 m0, s60
	s_nop 0
	global_load_lds_dwordx4 v[148:149], off
	s_waitcnt vmcnt(8)
	s_waitcnt lgkmcnt(0)
	s_barrier
	s_waitcnt lgkmcnt(0)
	v_mfma_f32_16x16x32_bf16 v[92:95], v[144:147], v[198:201], v[92:95]
	v_mfma_f32_16x16x32_bf16 v[88:91], v[170:173], v[198:201], v[88:91]
	v_mfma_f32_16x16x32_bf16 v[84:87], v[144:147], v[206:209], v[84:87]
	v_mfma_f32_16x16x32_bf16 v[80:83], v[170:173], v[206:209], v[80:83]
	v_mfma_f32_16x16x32_bf16 v[76:79], v[144:147], v[214:217], v[76:79]
	v_mfma_f32_16x16x32_bf16 v[72:75], v[170:173], v[214:217], v[72:75]
	v_mfma_f32_16x16x32_bf16 v[60:63], v[144:147], v[222:225], v[60:63]
	v_mfma_f32_16x16x32_bf16 v[52:55], v[170:173], v[222:225], v[52:55]
	v_mfma_f32_16x16x32_bf16 v[92:95], v[166:169], v[202:205], v[92:95]
	v_mfma_f32_16x16x32_bf16 v[88:91], v[174:177], v[202:205], v[88:91]
	v_mfma_f32_16x16x32_bf16 v[84:87], v[166:169], v[210:213], v[84:87]
	v_mfma_f32_16x16x32_bf16 v[80:83], v[174:177], v[210:213], v[80:83]
	v_mfma_f32_16x16x32_bf16 v[76:79], v[166:169], v[218:221], v[76:79]
	v_mfma_f32_16x16x32_bf16 v[72:75], v[174:177], v[218:221], v[72:75]
	v_mfma_f32_16x16x32_bf16 v[60:63], v[166:169], v[226:229], v[60:63]
	v_mfma_f32_16x16x32_bf16 v[52:55], v[174:177], v[226:229], v[52:55]
	v_mfma_f32_16x16x32_bf16 v[28:31], v[178:181], v[198:201], v[28:31]
	v_mfma_f32_16x16x32_bf16 v[24:27], v[190:193], v[198:201], v[24:27]
	v_mfma_f32_16x16x32_bf16 v[20:23], v[178:181], v[206:209], v[20:23]
	v_mfma_f32_16x16x32_bf16 v[16:19], v[190:193], v[206:209], v[16:19]
	v_mfma_f32_16x16x32_bf16 v[12:15], v[178:181], v[214:217], v[12:15]
	v_mfma_f32_16x16x32_bf16 v[8:11], v[190:193], v[214:217], v[8:11]
	v_mfma_f32_16x16x32_bf16 v[4:7], v[178:181], v[222:225], v[4:7]
	v_mfma_f32_16x16x32_bf16 v[0:3], v[190:193], v[222:225], v[0:3]
	v_mfma_f32_16x16x32_bf16 v[28:31], v[186:189], v[202:205], v[28:31]
	v_mfma_f32_16x16x32_bf16 v[24:27], v[194:197], v[202:205], v[24:27]
	v_mfma_f32_16x16x32_bf16 v[20:23], v[186:189], v[210:213], v[20:23]
	v_mfma_f32_16x16x32_bf16 v[16:19], v[194:197], v[210:213], v[16:19]
	v_mfma_f32_16x16x32_bf16 v[12:15], v[186:189], v[218:221], v[12:15]
	v_mfma_f32_16x16x32_bf16 v[8:11], v[194:197], v[218:221], v[8:11]
	v_mfma_f32_16x16x32_bf16 v[4:7], v[186:189], v[226:229], v[4:7]
	v_mfma_f32_16x16x32_bf16 v[0:3], v[194:197], v[226:229], v[0:3]
	s_barrier
	s_add_i32 s73, s73, 2
	s_add_u32 s52, s52, 0x100
	s_addc_u32 s53, s53, 0
	s_add_u32 s71, s71, 0x100
	s_addc_u32 s72, s72, 0
	s_cmp_gt_u32 s73, 29
	s_cbranch_scc0 .LBB0_1300
	s_and_b64 vcc, exec, s[28:29]
	s_cbranch_vccz .LBB0_1303
	s_barrier

; #define PG8_STAGE(bufoff, gbase, voff) do { _Pragma("unroll") for (int _i = 0; _i < 2; ++_i) \
;         __builtin_amdgcn_global_load_lds((const unsigned*)((const char*)(gbase) + (voff)[_i]), (LAS unsigned*)(lds + (bufoff) + ldsw + _i * 8192), 16, 0, 0); } while (0)
; #define PG8_LDA(dst, b, h) do { _Pragma("unroll") for (int m = 0; m < 4; ++m) _Pragma("unroll") for (int k = 0; k < 2; ++k) dst[m][k] = *(const LAS bf16x8*)(lds + PG8_SA(b, h) + aoff + m * 2048 + k * 1024); } while (0)
; #define PG8_LDB(dst, b, h) do { _Pragma("unroll") for (int n = 0; n < 2; ++n) _Pragma("unroll") for (int k = 0; k < 2; ++k) dst[n][k] = *(const LAS bf16x8*)(lds + PG8_SB(b, h) + boff + n * 2048 + k * 1024); } while (0)
; #define PG8_MMA(ai, bj, At, Bt) do { __builtin_amdgcn_s_setprio(1); _Pragma("unroll") for (int m = 0; m < 4; ++m) _Pragma("unroll") for (int n = 0; n < 2; ++n) _Pragma("unroll") for (int k = 0; k < 2; ++k) \
;         acc[ai][bj][m][n] = __builtin_amdgcn_mfma_f32_16x16x32_bf16(Bt[n][k], At[m][k], acc[ai][bj][m][n], 0, 0, 0); __builtin_amdgcn_s_setprio(0); } while (0)
; #define PG8_WAIT_V(n) asm volatile("s_waitcnt vmcnt(" #n ")" ::: "memory")
; #define PG8_WAIT_L(n) asm volatile("s_waitcnt lgkmcnt(" #n ")" ::: "memory")
; #define PG8_BAR __builtin_amdgcn_s_barrier()
; #define PG8_SCHED __builtin_amdgcn_sched_barrier(0)
; template <class Epi, bool ALIGN_EPI = PG8_ALIGN>
; __device__ __forceinline__ void gemm_phase(LAS unsigned char* lds, const Gemm g, const StaticOrder S, const Epi E) {
;     ...
;         for (int t = 0; t < nt; t += 2) {
;             const bool last = (t == nt - 2);
;             const char* a1 = cA + (size_t)(t + 1) * kstep;
;             const char* a2 = last ? nA : cA + (size_t)(t + 2) * kstep; const char* b2 = last ? nB : cB + (size_t)(t + 2) * kstep;
;             const char* a3 = a2 + kstep; const char* b3 = b2 + kstep;
;             PG8_LDB(B0, 0, 0); PG8_LDB(B1, 0, 1); PG8_SCHED; PG8_LDA(At, 0, 0); PG8_STAGE(PG8_SA(1, 1), a1 + hstepA, voffA);
;             PG8_WAIT_V(8); PG8_WAIT_L(0); PG8_BAR; PG8_MMA(0, 0, At, B0); PG8_MMA(0, 1, At, B1); PG8_BAR; PG8_SCHED;
;             PG8_LDA(At, 0, 1); PG8_STAGE(PG8_SB(0, 0), b2, voffB); PG8_STAGE(PG8_SB(0, 1), b2 + hstepB, voffB); PG8_STAGE(PG8_SA(0, 0), a2, voffA);
;             PG8_WAIT_V(8); PG8_WAIT_L(0); PG8_BAR; PG8_MMA(1, 0, At, B0); PG8_MMA(1, 1, At, B1); PG8_BAR; PG8_SCHED;
.LBB0_1324:
	ds_read_b128 v[146:149], v143
	ds_read_b128 v[158:161], v143 offset:1024
	ds_read_b128 v[162:165], v143 offset:2048
	ds_read_b128 v[166:169], v143 offset:3072
	ds_read_b128 v[170:173], v144
	ds_read_b128 v[174:177], v144 offset:1024
	ds_read_b128 v[178:181], v144 offset:2048
	ds_read_b128 v[186:189], v144 offset:3072
	s_add_u32 s52, s50, 0xfff80080
	s_addc_u32 s53, s51, -1
	s_cmp_eq_u32 s75, 28
	s_cselect_b32 s55, s45, s53
	s_cselect_b32 s54, s71, s52
	s_cselect_b32 s53, s43, s74
	s_cselect_b32 s52, s72, s73
	v_lshl_add_u64 v[182:183], s[50:51], 0, v[136:137]
	s_add_i32 m0, s35, 0xc000
	ds_read_b128 v[190:193], v145
	ds_read_b128 v[194:197], v145 offset:1024
	ds_read_b128 v[198:201], v145 offset:2048
	ds_read_b128 v[202:205], v145 offset:3072
	ds_read_b128 v[206:209], v145 offset:4096
	ds_read_b128 v[210:213], v145 offset:5120
	ds_read_b128 v[214:217], v145 offset:6144
	ds_read_b128 v[218:221], v145 offset:7168
	global_load_lds_dwordx4 v[182:183], off
	v_lshl_add_u64 v[182:183], s[50:51], 0, v[138:139]
	s_add_i32 m0, s35, 0xe000
	s_nop 0
	global_load_lds_dwordx4 v[182:183], off
	s_waitcnt vmcnt(8)
	s_waitcnt lgkmcnt(0)
	s_barrier
	s_waitcnt lgkmcnt(0)
	v_mfma_f32_16x16x32_bf16 v[124:127], v[146:149], v[190:193], v[124:127]
	v_mfma_f32_16x16x32_bf16 v[120:123], v[162:165], v[190:193], v[120:123]
	v_mfma_f32_16x16x32_bf16 v[116:119], v[146:149], v[198:201], v[116:119]
	v_mfma_f32_16x16x32_bf16 v[112:115], v[162:165], v[198:201], v[112:115]
	v_mfma_f32_16x16x32_bf16 v[108:111], v[146:149], v[206:209], v[108:111]
	v_mfma_f32_16x16x32_bf16 v[104:107], v[162:165], v[206:209], v[104:107]
	v_mfma_f32_16x16x32_bf16 v[100:103], v[146:149], v[214:217], v[100:103]
	v_mfma_f32_16x16x32_bf16 v[96:99], v[162:165], v[214:217], v[96:99]
	v_mfma_f32_16x16x32_bf16 v[124:127], v[158:161], v[194:197], v[124:127]
	v_mfma_f32_16x16x32_bf16 v[120:123], v[166:169], v[194:197], v[120:123]
	v_mfma_f32_16x16x32_bf16 v[116:119], v[158:161], v[202:205], v[116:119]
	v_mfma_f32_16x16x32_bf16 v[112:115], v[166:169], v[202:205], v[112:115]
	v_mfma_f32_16x16x32_bf16 v[108:111], v[158:161], v[210:213], v[108:111]
	v_mfma_f32_16x16x32_bf16 v[104:107], v[166:169], v[210:213], v[104:107]
	v_mfma_f32_16x16x32_bf16 v[100:103], v[158:161], v[218:221], v[100:103]
	v_mfma_f32_16x16x32_bf16 v[96:99], v[166:169], v[218:221], v[96:99]
	v_mfma_f32_16x16x32_bf16 v[80:83], v[170:173], v[190:193], v[80:83]
	v_mfma_f32_16x16x32_bf16 v[72:75], v[178:181], v[190:193], v[72:75]
	v_mfma_f32_16x16x32_bf16 v[68:71], v[170:173], v[198:201], v[68:71]
	v_mfma_f32_16x16x32_bf16 v[60:63], v[178:181], v[198:201], v[60:63]
	v_mfma_f32_16x16x32_bf16 v[52:55], v[170:173], v[206:209], v[52:55]
	v_mfma_f32_16x16x32_bf16 v[48:51], v[178:181], v[206:209], v[48:51]
	v_mfma_f32_16x16x32_bf16 v[36:39], v[170:173], v[214:217], v[36:39]
	v_mfma_f32_16x16x32_bf16 v[32:35], v[178:181], v[214:217], v[32:35]
	v_mfma_f32_16x16x32_bf16 v[80:83], v[174:177], v[194:197], v[80:83]
	v_mfma_f32_16x16x32_bf16 v[72:75], v[186:189], v[194:197], v[72:75]
	v_mfma_f32_16x16x32_bf16 v[68:71], v[174:177], v[202:205], v[68:71]
	v_mfma_f32_16x16x32_bf16 v[60:63], v[186:189], v[202:205], v[60:63]
	v_mfma_f32_16x16x32_bf16 v[52:55], v[174:177], v[210:213], v[52:55]
	v_mfma_f32_16x16x32_bf16 v[48:51], v[186:189], v[210:213], v[48:51]
	v_mfma_f32_16x16x32_bf16 v[36:39], v[174:177], v[218:221], v[36:39]
	v_mfma_f32_16x16x32_bf16 v[32:35], v[186:189], v[218:221], v[32:35]
	s_barrier
	s_add_i32 s76, s64, s34
	v_lshl_add_u64 v[182:183], s[52:53], 0, v[130:131]
	s_mov_b32 m0, s76
	ds_read_b128 v[190:193], v145 offset:16384
	ds_read_b128 v[194:197], v145 offset:17408
	ds_read_b128 v[198:201], v145 offset:18432
	ds_read_b128 v[202:205], v145 offset:19456
	ds_read_b128 v[206:209], v145 offset:20480
	ds_read_b128 v[210:213], v145 offset:21504
	ds_read_b128 v[214:217], v145 offset:22528
	ds_read_b128 v[218:221], v145 offset:23552
	global_load_lds_dwordx4 v[182:183], off
	s_add_i32 m0, s76, 0x2000
	s_add_u32 s76, s52, 0x80000
	v_lshl_add_u64 v[222:223], s[52:53], 0, v[134:135]
	s_addc_u32 s77, s53, 0
	s_add_i32 s78, s65, s34
	global_load_lds_dwordx4 v[222:223], off
	v_lshl_add_u64 v[224:225], s[76:77], 0, v[130:131]
	s_mov_b32 m0, s78
	v_lshl_add_u64 v[226:227], s[54:55], 0, v[132:133]
	global_load_lds_dwordx4 v[224:225], off
	v_lshl_add_u64 v[224:225], s[76:77], 0, v[134:135]
	s_add_i32 m0, s78, 0x2000
	s_nop 0
	global_load_lds_dwordx4 v[224:225], off
	v_lshl_add_u64 v[224:225], s[54:55], 0, v[128:129]
	s_mov_b32 m0, s35
	s_nop 0
	global_load_lds_dwordx4 v[224:225], off
	s_mov_b32 m0, s39
	s_nop 0
	global_load_lds_dwordx4 v[226:227], off
	s_waitcnt vmcnt(8)
	s_waitcnt lgkmcnt(0)
	s_barrier
; #define PG8_STAGE(bufoff, gbase, voff) do { _Pragma("unroll") for (int _i = 0; _i < 2; ++_i) \
;         __builtin_amdgcn_global_load_lds((const unsigned*)((const char*)(gbase) + (voff)[_i]), (LAS unsigned*)(lds + (bufoff) + ldsw + _i * 8192), 16, 0, 0); } while (0)
; #define PG8_LDA(dst, b, h) do { _Pragma("unroll") for (int m = 0; m < 4; ++m) _Pragma("unroll") for (int k = 0; k < 2; ++k) dst[m][k] = *(const LAS bf16x8*)(lds + PG8_SA(b, h) + aoff + m * 2048 + k * 1024); } while (0)
; #define PG8_LDB(dst, b, h) do { _Pragma("unroll") for (int n = 0; n < 2; ++n) _Pragma("unroll") for (int k = 0; k < 2; ++k) dst[n][k] = *(const LAS bf16x8*)(lds + PG8_SB(b, h) + boff + n * 2048 + k * 1024); } while (0)
; #define PG8_MMA(ai, bj, At, Bt) do { __builtin_amdgcn_s_setprio(1); _Pragma("unroll") for (int m = 0; m < 4; ++m) _Pragma("unroll") for (int n = 0; n < 2; ++n) _Pragma("unroll") for (int k = 0; k < 2; ++k) \
;         acc[ai][bj][m][n] = __builtin_amdgcn_mfma_f32_16x16x32_bf16(Bt[n][k], At[m][k], acc[ai][bj][m][n], 0, 0, 0); __builtin_amdgcn_s_setprio(0); } while (0)
; #define PG8_WAIT_V(n) asm volatile("s_waitcnt vmcnt(" #n ")" ::: "memory")
; #define PG8_WAIT_L(n) asm volatile("s_waitcnt lgkmcnt(" #n ")" ::: "memory")
; #define PG8_BAR __builtin_amdgcn_s_barrier()
; #define PG8_SCHED __builtin_amdgcn_sched_barrier(0)
; template <class Epi, bool ALIGN_EPI = PG8_ALIGN>
; __device__ __forceinline__ void gemm_phase(LAS unsigned char* lds, const Gemm g, const StaticOrder S, const Epi E) {
;     ...
;             PG8_LDA(At, 0, 1); PG8_STAGE(PG8_SB(0, 0), b2, voffB); PG8_STAGE(PG8_SB(0, 1), b2 + hstepB, voffB); PG8_STAGE(PG8_SA(0, 0), a2, voffA);
;             PG8_WAIT_V(8); PG8_WAIT_L(0); PG8_BAR; PG8_MMA(1, 0, At, B0); PG8_MMA(1, 1, At, B1); PG8_BAR; PG8_SCHED;
;             PG8_LDB(B0, 1, 0); PG8_LDB(B1, 1, 1); PG8_SCHED; PG8_LDA(At, 1, 0); PG8_STAGE(PG8_SA(0, 1), a2 + hstepA, voffA);
;             PG8_WAIT_V(8); PG8_WAIT_L(0); PG8_BAR; PG8_MMA(0, 0, At, B0); PG8_MMA(0, 1, At, B1); PG8_BAR; PG8_SCHED;
	s_waitcnt lgkmcnt(0)
	v_mfma_f32_16x16x32_bf16 v[92:95], v[146:149], v[190:193], v[92:95]
	v_mfma_f32_16x16x32_bf16 v[88:91], v[162:165], v[190:193], v[88:91]
	v_mfma_f32_16x16x32_bf16 v[84:87], v[146:149], v[198:201], v[84:87]
	v_mfma_f32_16x16x32_bf16 v[76:79], v[162:165], v[198:201], v[76:79]
	v_mfma_f32_16x16x32_bf16 v[64:67], v[146:149], v[206:209], v[64:67]
	v_mfma_f32_16x16x32_bf16 v[56:59], v[162:165], v[206:209], v[56:59]
	v_mfma_f32_16x16x32_bf16 v[44:47], v[146:149], v[214:217], v[44:47]
	v_mfma_f32_16x16x32_bf16 v[40:43], v[162:165], v[214:217], v[40:43]
	v_mfma_f32_16x16x32_bf16 v[92:95], v[158:161], v[194:197], v[92:95]
	v_mfma_f32_16x16x32_bf16 v[88:91], v[166:169], v[194:197], v[88:91]
	v_mfma_f32_16x16x32_bf16 v[84:87], v[158:161], v[202:205], v[84:87]
	v_mfma_f32_16x16x32_bf16 v[76:79], v[166:169], v[202:205], v[76:79]
	v_mfma_f32_16x16x32_bf16 v[64:67], v[158:161], v[210:213], v[64:67]
	v_mfma_f32_16x16x32_bf16 v[56:59], v[166:169], v[210:213], v[56:59]
	v_mfma_f32_16x16x32_bf16 v[44:47], v[158:161], v[218:221], v[44:47]
	v_mfma_f32_16x16x32_bf16 v[40:43], v[166:169], v[218:221], v[40:43]
	v_mfma_f32_16x16x32_bf16 v[28:31], v[170:173], v[190:193], v[28:31]
	v_mfma_f32_16x16x32_bf16 v[24:27], v[178:181], v[190:193], v[24:27]
	v_mfma_f32_16x16x32_bf16 v[20:23], v[170:173], v[198:201], v[20:23]
	v_mfma_f32_16x16x32_bf16 v[16:19], v[178:181], v[198:201], v[16:19]
	v_mfma_f32_16x16x32_bf16 v[12:15], v[170:173], v[206:209], v[12:15]
	v_mfma_f32_16x16x32_bf16 v[8:11], v[178:181], v[206:209], v[8:11]
	v_mfma_f32_16x16x32_bf16 v[4:7], v[170:173], v[214:217], v[4:7]
	v_mfma_f32_16x16x32_bf16 v[0:3], v[178:181], v[214:217], v[0:3]
	v_mfma_f32_16x16x32_bf16 v[28:31], v[174:177], v[194:197], v[28:31]
	v_mfma_f32_16x16x32_bf16 v[24:27], v[186:189], v[194:197], v[24:27]
	v_mfma_f32_16x16x32_bf16 v[20:23], v[174:177], v[202:205], v[20:23]
	v_mfma_f32_16x16x32_bf16 v[16:19], v[186:189], v[202:205], v[16:19]
	v_mfma_f32_16x16x32_bf16 v[12:15], v[174:177], v[210:213], v[12:15]
	v_mfma_f32_16x16x32_bf16 v[8:11], v[186:189], v[210:213], v[8:11]
	v_mfma_f32_16x16x32_bf16 v[4:7], v[174:177], v[218:221], v[4:7]
	v_mfma_f32_16x16x32_bf16 v[0:3], v[186:189], v[218:221], v[0:3]
	s_barrier
	s_add_i32 s76, 0, 0x18000
	s_add_i32 s77, 0, 0x1c000
	v_add_u32_e32 v166, s76, v141
	v_add_u32_e32 v186, s77, v141
	ds_read_b128 v[146:149], v166
	ds_read_b128 v[158:161], v166 offset:1024
	ds_read_b128 v[162:165], v166 offset:2048
	ds_read_b128 v[166:169], v166 offset:3072
	ds_read_b128 v[170:173], v186
	ds_read_b128 v[174:177], v186 offset:1024
	ds_read_b128 v[178:181], v186 offset:2048
	ds_read_b128 v[186:189], v186 offset:3072
	s_add_u32 s54, s54, 0x80000
	s_addc_u32 s55, s55, 0
	s_mov_b32 m0, s58
	v_lshl_add_u64 v[228:229], s[54:55], 0, v[128:129]
	ds_read_b128 v[190:193], v145 offset:32768
	ds_read_b128 v[194:197], v145 offset:33792
	ds_read_b128 v[198:201], v145 offset:34816
	ds_read_b128 v[202:205], v145 offset:35840
	ds_read_b128 v[206:209], v145 offset:36864
	ds_read_b128 v[210:213], v145 offset:37888
	ds_read_b128 v[214:217], v145 offset:38912
	ds_read_b128 v[218:221], v145 offset:39936
	global_load_lds_dwordx4 v[228:229], off
	v_lshl_add_u64 v[228:229], s[54:55], 0, v[132:133]
	s_mov_b32 m0, s59
	s_nop 0
	global_load_lds_dwordx4 v[228:229], off
	s_waitcnt vmcnt(8)
	s_waitcnt lgkmcnt(0)
	s_barrier
	s_waitcnt lgkmcnt(0)
	v_mfma_f32_16x16x32_bf16 v[124:127], v[146:149], v[190:193], v[124:127]
	v_mfma_f32_16x16x32_bf16 v[120:123], v[162:165], v[190:193], v[120:123]
	v_mfma_f32_16x16x32_bf16 v[116:119], v[146:149], v[198:201], v[116:119]
	v_mfma_f32_16x16x32_bf16 v[112:115], v[162:165], v[198:201], v[112:115]
	v_mfma_f32_16x16x32_bf16 v[108:111], v[146:149], v[206:209], v[108:111]
	v_mfma_f32_16x16x32_bf16 v[104:107], v[162:165], v[206:209], v[104:107]
	v_mfma_f32_16x16x32_bf16 v[100:103], v[146:149], v[214:217], v[100:103]
	v_mfma_f32_16x16x32_bf16 v[96:99], v[162:165], v[214:217], v[96:99]
	v_mfma_f32_16x16x32_bf16 v[124:127], v[158:161], v[194:197], v[124:127]
	v_mfma_f32_16x16x32_bf16 v[120:123], v[166:169], v[194:197], v[120:123]
	v_mfma_f32_16x16x32_bf16 v[116:119], v[158:161], v[202:205], v[116:119]
	v_mfma_f32_16x16x32_bf16 v[112:115], v[166:169], v[202:205], v[112:115]
	v_mfma_f32_16x16x32_bf16 v[108:111], v[158:161], v[210:213], v[108:111]
	v_mfma_f32_16x16x32_bf16 v[104:107], v[166:169], v[210:213], v[104:107]
	v_mfma_f32_16x16x32_bf16 v[100:103], v[158:161], v[218:221], v[100:103]
	v_mfma_f32_16x16x32_bf16 v[96:99], v[166:169], v[218:221], v[96:99]
	v_mfma_f32_16x16x32_bf16 v[80:83], v[170:173], v[190:193], v[80:83]
	v_mfma_f32_16x16x32_bf16 v[72:75], v[178:181], v[190:193], v[72:75]
	v_mfma_f32_16x16x32_bf16 v[68:71], v[170:173], v[198:201], v[68:71]
	v_mfma_f32_16x16x32_bf16 v[60:63], v[178:181], v[198:201], v[60:63]
	v_mfma_f32_16x16x32_bf16 v[52:55], v[170:173], v[206:209], v[52:55]
	v_mfma_f32_16x16x32_bf16 v[48:51], v[178:181], v[206:209], v[48:51]
	v_mfma_f32_16x16x32_bf16 v[36:39], v[170:173], v[214:217], v[36:39]
	v_mfma_f32_16x16x32_bf16 v[32:35], v[178:181], v[214:217], v[32:35]
	v_mfma_f32_16x16x32_bf16 v[80:83], v[174:177], v[194:197], v[80:83]
	v_mfma_f32_16x16x32_bf16 v[72:75], v[186:189], v[194:197], v[72:75]
	v_mfma_f32_16x16x32_bf16 v[68:71], v[174:177], v[202:205], v[68:71]
	v_mfma_f32_16x16x32_bf16 v[60:63], v[186:189], v[202:205], v[60:63]
	v_mfma_f32_16x16x32_bf16 v[52:55], v[174:177], v[210:213], v[52:55]
	v_mfma_f32_16x16x32_bf16 v[48:51], v[186:189], v[210:213], v[48:51]
	v_mfma_f32_16x16x32_bf16 v[36:39], v[174:177], v[218:221], v[36:39]
	v_mfma_f32_16x16x32_bf16 v[32:35], v[186:189], v[218:221], v[32:35]
	s_barrier
; #define PG8_STAGE(bufoff, gbase, voff) do { _Pragma("unroll") for (int _i = 0; _i < 2; ++_i) \
;         __builtin_amdgcn_global_load_lds((const unsigned*)((const char*)(gbase) + (voff)[_i]), (LAS unsigned*)(lds + (bufoff) + ldsw + _i * 8192), 16, 0, 0); } while (0)
; #define PG8_LDA(dst, b, h) do { _Pragma("unroll") for (int m = 0; m < 4; ++m) _Pragma("unroll") for (int k = 0; k < 2; ++k) dst[m][k] = *(const LAS bf16x8*)(lds + PG8_SA(b, h) + aoff + m * 2048 + k * 1024); } while (0)
; #define PG8_MMA(ai, bj, At, Bt) do { __builtin_amdgcn_s_setprio(1); _Pragma("unroll") for (int m = 0; m < 4; ++m) _Pragma("unroll") for (int n = 0; n < 2; ++n) _Pragma("unroll") for (int k = 0; k < 2; ++k) \
;         acc[ai][bj][m][n] = __builtin_amdgcn_mfma_f32_16x16x32_bf16(Bt[n][k], At[m][k], acc[ai][bj][m][n], 0, 0, 0); __builtin_amdgcn_s_setprio(0); } while (0)
; #define PG8_WAIT_V(n) asm volatile("s_waitcnt vmcnt(" #n ")" ::: "memory")
; #define PG8_WAIT_L(n) asm volatile("s_waitcnt lgkmcnt(" #n ")" ::: "memory")
; #define PG8_BAR __builtin_amdgcn_s_barrier()
; #define PG8_SCHED __builtin_amdgcn_sched_barrier(0)
; template <class Epi, bool ALIGN_EPI = PG8_ALIGN>
; __device__ __forceinline__ void gemm_phase(LAS unsigned char* lds, const Gemm g, const StaticOrder S, const Epi E) {
;     ...
;             PG8_LDA(At, 1, 1); PG8_STAGE(PG8_SB(1, 0), b3, voffB); PG8_STAGE(PG8_SB(1, 1), b3 + hstepB, voffB); PG8_STAGE(PG8_SA(1, 0), a3, voffA);
;             PG8_WAIT_V(8); PG8_WAIT_L(0); PG8_BAR; PG8_MMA(1, 0, At, B0); PG8_MMA(1, 1, At, B1); PG8_BAR; PG8_SCHED;
;         }
;         if (ALIGN_EPI) { if (wr == 0) PG8_BAR; }
	s_add_i32 s54, s76, s34
	v_lshl_add_u64 v[182:183], v[182:183], 0, s[2:3]
	s_mov_b32 m0, s54
	ds_read_b128 v[190:193], v145 offset:49152
	ds_read_b128 v[194:197], v145 offset:50176
	ds_read_b128 v[198:201], v145 offset:51200
	ds_read_b128 v[202:205], v145 offset:52224
	ds_read_b128 v[206:209], v145 offset:53248
	ds_read_b128 v[210:213], v145 offset:54272
	ds_read_b128 v[214:217], v145 offset:55296
	ds_read_b128 v[218:221], v145 offset:56320
	global_load_lds_dwordx4 v[182:183], off
	s_add_i32 m0, s54, 0x2000
	s_add_u32 s52, s52, 0x80080
	v_lshl_add_u64 v[182:183], v[222:223], 0, s[2:3]
	s_addc_u32 s53, s53, 0
	s_add_i32 s54, s77, s34
	global_load_lds_dwordx4 v[182:183], off
	v_lshl_add_u64 v[182:183], s[52:53], 0, v[130:131]
	s_mov_b32 m0, s54
	s_nop 0
	global_load_lds_dwordx4 v[182:183], off
	v_lshl_add_u64 v[182:183], s[52:53], 0, v[134:135]
	s_add_i32 m0, s54, 0x2000
	s_nop 0
	global_load_lds_dwordx4 v[182:183], off
	v_lshl_add_u64 v[182:183], v[224:225], 0, s[2:3]
	s_mov_b32 m0, s61
	s_nop 0
	global_load_lds_dwordx4 v[182:183], off
	v_lshl_add_u64 v[182:183], v[226:227], 0, s[2:3]
	s_mov_b32 m0, s62
	s_nop 0
	global_load_lds_dwordx4 v[182:183], off
	s_waitcnt vmcnt(8)
	s_waitcnt lgkmcnt(0)
	s_barrier
	s_waitcnt lgkmcnt(0)
	v_mfma_f32_16x16x32_bf16 v[92:95], v[146:149], v[190:193], v[92:95]
	v_mfma_f32_16x16x32_bf16 v[88:91], v[162:165], v[190:193], v[88:91]
	v_mfma_f32_16x16x32_bf16 v[84:87], v[146:149], v[198:201], v[84:87]
	v_mfma_f32_16x16x32_bf16 v[76:79], v[162:165], v[198:201], v[76:79]
	v_mfma_f32_16x16x32_bf16 v[64:67], v[146:149], v[206:209], v[64:67]
	v_mfma_f32_16x16x32_bf16 v[56:59], v[162:165], v[206:209], v[56:59]
	v_mfma_f32_16x16x32_bf16 v[44:47], v[146:149], v[214:217], v[44:47]
	v_mfma_f32_16x16x32_bf16 v[40:43], v[162:165], v[214:217], v[40:43]
	v_mfma_f32_16x16x32_bf16 v[92:95], v[158:161], v[194:197], v[92:95]
	v_mfma_f32_16x16x32_bf16 v[88:91], v[166:169], v[194:197], v[88:91]
	v_mfma_f32_16x16x32_bf16 v[84:87], v[158:161], v[202:205], v[84:87]
	v_mfma_f32_16x16x32_bf16 v[76:79], v[166:169], v[202:205], v[76:79]
	v_mfma_f32_16x16x32_bf16 v[64:67], v[158:161], v[210:213], v[64:67]
	v_mfma_f32_16x16x32_bf16 v[56:59], v[166:169], v[210:213], v[56:59]
	v_mfma_f32_16x16x32_bf16 v[44:47], v[158:161], v[218:221], v[44:47]
	v_mfma_f32_16x16x32_bf16 v[40:43], v[166:169], v[218:221], v[40:43]
	v_mfma_f32_16x16x32_bf16 v[28:31], v[170:173], v[190:193], v[28:31]
	v_mfma_f32_16x16x32_bf16 v[24:27], v[178:181], v[190:193], v[24:27]
	v_mfma_f32_16x16x32_bf16 v[20:23], v[170:173], v[198:201], v[20:23]
	v_mfma_f32_16x16x32_bf16 v[16:19], v[178:181], v[198:201], v[16:19]
	v_mfma_f32_16x16x32_bf16 v[12:15], v[170:173], v[206:209], v[12:15]
	v_mfma_f32_16x16x32_bf16 v[8:11], v[178:181], v[206:209], v[8:11]
	v_mfma_f32_16x16x32_bf16 v[4:7], v[170:173], v[214:217], v[4:7]
	v_mfma_f32_16x16x32_bf16 v[0:3], v[178:181], v[214:217], v[0:3]
	v_mfma_f32_16x16x32_bf16 v[28:31], v[174:177], v[194:197], v[28:31]
	v_mfma_f32_16x16x32_bf16 v[24:27], v[186:189], v[194:197], v[24:27]
	v_mfma_f32_16x16x32_bf16 v[20:23], v[174:177], v[202:205], v[20:23]
	v_mfma_f32_16x16x32_bf16 v[16:19], v[186:189], v[202:205], v[16:19]
	v_mfma_f32_16x16x32_bf16 v[12:15], v[174:177], v[210:213], v[12:15]
	v_mfma_f32_16x16x32_bf16 v[8:11], v[186:189], v[210:213], v[8:11]
	v_mfma_f32_16x16x32_bf16 v[4:7], v[174:177], v[218:221], v[4:7]
	v_mfma_f32_16x16x32_bf16 v[0:3], v[186:189], v[218:221], v[0:3]
	s_barrier
	s_add_i32 s75, s75, 2
	s_add_u32 s50, s50, 0x100
	s_addc_u32 s51, s51, 0
	s_add_u32 s73, s73, 0x100
	s_addc_u32 s74, s74, 0
	s_cmp_gt_u32 s75, 29
	s_cbranch_scc0 .LBB0_1324
	s_and_b64 vcc, exec, s[6:7]
	s_cbranch_vccz .LBB0_1327
	s_barrier

; #define PG8_STAGE(bufoff, gbase, voff) do { _Pragma("unroll") for (int _i = 0; _i < 2; ++_i) \
;         __builtin_amdgcn_global_load_lds((const unsigned*)((const char*)(gbase) + (voff)[_i]), (LAS unsigned*)(lds + (bufoff) + ldsw + _i * 8192), 16, 0, 0); } while (0)
; #define PG8_LDA(dst, b, h) do { _Pragma("unroll") for (int m = 0; m < 4; ++m) _Pragma("unroll") for (int k = 0; k < 2; ++k) dst[m][k] = *(const LAS bf16x8*)(lds + PG8_SA(b, h) + aoff + m * 2048 + k * 1024); } while (0)
; #define PG8_LDB(dst, b, h) do { _Pragma("unroll") for (int n = 0; n < 2; ++n) _Pragma("unroll") for (int k = 0; k < 2; ++k) dst[n][k] = *(const LAS bf16x8*)(lds + PG8_SB(b, h) + boff + n * 2048 + k * 1024); } while (0)
; #define PG8_MMA(ai, bj, At, Bt) do { __builtin_amdgcn_s_setprio(1); _Pragma("unroll") for (int m = 0; m < 4; ++m) _Pragma("unroll") for (int n = 0; n < 2; ++n) _Pragma("unroll") for (int k = 0; k < 2; ++k) \
;         acc[ai][bj][m][n] = __builtin_amdgcn_mfma_f32_16x16x32_bf16(Bt[n][k], At[m][k], acc[ai][bj][m][n], 0, 0, 0); __builtin_amdgcn_s_setprio(0); } while (0)
; #define PG8_WAIT_V(n) asm volatile("s_waitcnt vmcnt(" #n ")" ::: "memory")
; #define PG8_WAIT_L(n) asm volatile("s_waitcnt lgkmcnt(" #n ")" ::: "memory")
; #define PG8_BAR __builtin_amdgcn_s_barrier()
; #define PG8_SCHED __builtin_amdgcn_sched_barrier(0)
; template <class Epi, bool ALIGN_EPI = PG8_ALIGN>
; __device__ __forceinline__ void gemm_phase(LAS unsigned char* lds, const Gemm g, const StaticOrder S, const Epi E) {
;     ...
;         for (int t = 0; t < nt; t += 2) {
;             const bool last = (t == nt - 2);
;             const char* a1 = cA + (size_t)(t + 1) * kstep;
;             const char* a2 = last ? nA : cA + (size_t)(t + 2) * kstep; const char* b2 = last ? nB : cB + (size_t)(t + 2) * kstep;
;             const char* a3 = a2 + kstep; const char* b3 = b2 + kstep;
;             PG8_LDB(B0, 0, 0); PG8_LDB(B1, 0, 1); PG8_SCHED; PG8_LDA(At, 0, 0); PG8_STAGE(PG8_SA(1, 1), a1 + hstepA, voffA);
;             PG8_WAIT_V(8); PG8_WAIT_L(0); PG8_BAR; PG8_MMA(0, 0, At, B0); PG8_MMA(0, 1, At, B1); PG8_BAR; PG8_SCHED;
;             PG8_LDA(At, 0, 1); PG8_STAGE(PG8_SB(0, 0), b2, voffB); PG8_STAGE(PG8_SB(0, 1), b2 + hstepB, voffB); PG8_STAGE(PG8_SA(0, 0), a2, voffA);
;             PG8_WAIT_V(8); PG8_WAIT_L(0); PG8_BAR; PG8_MMA(1, 0, At, B0); PG8_MMA(1, 1, At, B1); PG8_BAR; PG8_SCHED;
.LBB0_1348:
	ds_read_b128 v[146:149], v143
	ds_read_b128 v[150:153], v143 offset:1024
	ds_read_b128 v[154:157], v143 offset:2048
	ds_read_b128 v[158:161], v143 offset:3072
	ds_read_b128 v[162:165], v144
	ds_read_b128 v[166:169], v144 offset:1024
	ds_read_b128 v[170:173], v144 offset:2048
	ds_read_b128 v[174:177], v144 offset:3072
	s_add_u32 s52, s50, 0xfff80080
	s_addc_u32 s53, s51, -1
	s_cmp_eq_u32 s75, 28
	s_cselect_b32 s55, s45, s53
	s_cselect_b32 s54, s71, s52
	s_cselect_b32 s53, s43, s74
	s_cselect_b32 s52, s72, s73
	v_lshl_add_u64 v[182:183], s[50:51], 0, v[136:137]
	s_add_i32 m0, s35, 0xc000
	ds_read_b128 v[178:181], v145
	ds_read_b128 v[186:189], v145 offset:1024
	ds_read_b128 v[190:193], v145 offset:2048
	ds_read_b128 v[194:197], v145 offset:3072
	ds_read_b128 v[198:201], v145 offset:4096
	ds_read_b128 v[202:205], v145 offset:5120
	ds_read_b128 v[206:209], v145 offset:6144
	ds_read_b128 v[210:213], v145 offset:7168
	global_load_lds_dwordx4 v[182:183], off
	v_lshl_add_u64 v[182:183], s[50:51], 0, v[138:139]
	s_add_i32 m0, s35, 0xe000
	s_nop 0
	global_load_lds_dwordx4 v[182:183], off
	s_waitcnt vmcnt(8)
	s_waitcnt lgkmcnt(0)
	s_barrier
	s_waitcnt lgkmcnt(0)
	v_mfma_f32_16x16x32_bf16 v[124:127], v[146:149], v[178:181], v[124:127]
	v_mfma_f32_16x16x32_bf16 v[120:123], v[154:157], v[178:181], v[120:123]
	v_mfma_f32_16x16x32_bf16 v[116:119], v[146:149], v[190:193], v[116:119]
	v_mfma_f32_16x16x32_bf16 v[112:115], v[154:157], v[190:193], v[112:115]
	v_mfma_f32_16x16x32_bf16 v[108:111], v[146:149], v[198:201], v[108:111]
	v_mfma_f32_16x16x32_bf16 v[104:107], v[154:157], v[198:201], v[104:107]
	v_mfma_f32_16x16x32_bf16 v[100:103], v[146:149], v[206:209], v[100:103]
	v_mfma_f32_16x16x32_bf16 v[96:99], v[154:157], v[206:209], v[96:99]
	v_mfma_f32_16x16x32_bf16 v[124:127], v[150:153], v[186:189], v[124:127]
	v_mfma_f32_16x16x32_bf16 v[120:123], v[158:161], v[186:189], v[120:123]
	v_mfma_f32_16x16x32_bf16 v[116:119], v[150:153], v[194:197], v[116:119]
	v_mfma_f32_16x16x32_bf16 v[112:115], v[158:161], v[194:197], v[112:115]
	v_mfma_f32_16x16x32_bf16 v[108:111], v[150:153], v[202:205], v[108:111]
	v_mfma_f32_16x16x32_bf16 v[104:107], v[158:161], v[202:205], v[104:107]
	v_mfma_f32_16x16x32_bf16 v[100:103], v[150:153], v[210:213], v[100:103]
	v_mfma_f32_16x16x32_bf16 v[96:99], v[158:161], v[210:213], v[96:99]
	v_mfma_f32_16x16x32_bf16 v[80:83], v[162:165], v[178:181], v[80:83]
	v_mfma_f32_16x16x32_bf16 v[72:75], v[170:173], v[178:181], v[72:75]
	v_mfma_f32_16x16x32_bf16 v[68:71], v[162:165], v[190:193], v[68:71]
	v_mfma_f32_16x16x32_bf16 v[60:63], v[170:173], v[190:193], v[60:63]
	v_mfma_f32_16x16x32_bf16 v[52:55], v[162:165], v[198:201], v[52:55]
	v_mfma_f32_16x16x32_bf16 v[48:51], v[170:173], v[198:201], v[48:51]
	v_mfma_f32_16x16x32_bf16 v[36:39], v[162:165], v[206:209], v[36:39]
	v_mfma_f32_16x16x32_bf16 v[32:35], v[170:173], v[206:209], v[32:35]
	v_mfma_f32_16x16x32_bf16 v[80:83], v[166:169], v[186:189], v[80:83]
	v_mfma_f32_16x16x32_bf16 v[72:75], v[174:177], v[186:189], v[72:75]
	v_mfma_f32_16x16x32_bf16 v[68:71], v[166:169], v[194:197], v[68:71]
	v_mfma_f32_16x16x32_bf16 v[60:63], v[174:177], v[194:197], v[60:63]
	v_mfma_f32_16x16x32_bf16 v[52:55], v[166:169], v[202:205], v[52:55]
	v_mfma_f32_16x16x32_bf16 v[48:51], v[174:177], v[202:205], v[48:51]
	v_mfma_f32_16x16x32_bf16 v[36:39], v[166:169], v[210:213], v[36:39]
	v_mfma_f32_16x16x32_bf16 v[32:35], v[174:177], v[210:213], v[32:35]
	s_barrier
	s_add_i32 s76, s64, s34
	v_lshl_add_u64 v[182:183], s[52:53], 0, v[130:131]
	s_mov_b32 m0, s76
	ds_read_b128 v[178:181], v145 offset:16384
	ds_read_b128 v[186:189], v145 offset:17408
	ds_read_b128 v[190:193], v145 offset:18432
	ds_read_b128 v[194:197], v145 offset:19456
	ds_read_b128 v[198:201], v145 offset:20480
	ds_read_b128 v[202:205], v145 offset:21504
	ds_read_b128 v[206:209], v145 offset:22528
	ds_read_b128 v[210:213], v145 offset:23552
	global_load_lds_dwordx4 v[182:183], off
	s_add_i32 m0, s76, 0x2000
	s_add_u32 s76, s52, 0x80000
	v_lshl_add_u64 v[214:215], s[52:53], 0, v[134:135]
	s_addc_u32 s77, s53, 0
	s_add_i32 s78, s65, s34
	global_load_lds_dwordx4 v[214:215], off
	v_lshl_add_u64 v[216:217], s[76:77], 0, v[130:131]
	s_mov_b32 m0, s78
	v_lshl_add_u64 v[218:219], s[54:55], 0, v[132:133]
	global_load_lds_dwordx4 v[216:217], off
	v_lshl_add_u64 v[216:217], s[76:77], 0, v[134:135]
	s_add_i32 m0, s78, 0x2000
	s_nop 0
	global_load_lds_dwordx4 v[216:217], off
	v_lshl_add_u64 v[216:217], s[54:55], 0, v[128:129]
	s_mov_b32 m0, s35
	s_nop 0
	global_load_lds_dwordx4 v[216:217], off
	s_mov_b32 m0, s39
	s_nop 0
	global_load_lds_dwordx4 v[218:219], off
	s_waitcnt vmcnt(8)
	s_waitcnt lgkmcnt(0)
	s_barrier
; #define PG8_STAGE(bufoff, gbase, voff) do { _Pragma("unroll") for (int _i = 0; _i < 2; ++_i) \
;         __builtin_amdgcn_global_load_lds((const unsigned*)((const char*)(gbase) + (voff)[_i]), (LAS unsigned*)(lds + (bufoff) + ldsw + _i * 8192), 16, 0, 0); } while (0)
; #define PG8_LDA(dst, b, h) do { _Pragma("unroll") for (int m = 0; m < 4; ++m) _Pragma("unroll") for (int k = 0; k < 2; ++k) dst[m][k] = *(const LAS bf16x8*)(lds + PG8_SA(b, h) + aoff + m * 2048 + k * 1024); } while (0)
; #define PG8_LDB(dst, b, h) do { _Pragma("unroll") for (int n = 0; n < 2; ++n) _Pragma("unroll") for (int k = 0; k < 2; ++k) dst[n][k] = *(const LAS bf16x8*)(lds + PG8_SB(b, h) + boff + n * 2048 + k * 1024); } while (0)
; #define PG8_MMA(ai, bj, At, Bt) do { __builtin_amdgcn_s_setprio(1); _Pragma("unroll") for (int m = 0; m < 4; ++m) _Pragma("unroll") for (int n = 0; n < 2; ++n) _Pragma("unroll") for (int k = 0; k < 2; ++k) \
;         acc[ai][bj][m][n] = __builtin_amdgcn_mfma_f32_16x16x32_bf16(Bt[n][k], At[m][k], acc[ai][bj][m][n], 0, 0, 0); __builtin_amdgcn_s_setprio(0); } while (0)
; #define PG8_WAIT_V(n) asm volatile("s_waitcnt vmcnt(" #n ")" ::: "memory")
; #define PG8_WAIT_L(n) asm volatile("s_waitcnt lgkmcnt(" #n ")" ::: "memory")
; #define PG8_BAR __builtin_amdgcn_s_barrier()
; #define PG8_SCHED __builtin_amdgcn_sched_barrier(0)
; template <class Epi, bool ALIGN_EPI = PG8_ALIGN>
; __device__ __forceinline__ void gemm_phase(LAS unsigned char* lds, const Gemm g, const StaticOrder S, const Epi E) {
;     ...
;             PG8_WAIT_V(8); PG8_WAIT_L(0); PG8_BAR; PG8_MMA(1, 0, At, B0); PG8_MMA(1, 1, At, B1); PG8_BAR; PG8_SCHED;
;             PG8_LDB(B0, 1, 0); PG8_LDB(B1, 1, 1); PG8_SCHED; PG8_LDA(At, 1, 0); PG8_STAGE(PG8_SA(0, 1), a2 + hstepA, voffA);
;             PG8_WAIT_V(8); PG8_WAIT_L(0); PG8_BAR; PG8_MMA(0, 0, At, B0); PG8_MMA(0, 1, At, B1); PG8_BAR; PG8_SCHED;
	s_waitcnt lgkmcnt(0)
	v_mfma_f32_16x16x32_bf16 v[92:95], v[146:149], v[178:181], v[92:95]
	v_mfma_f32_16x16x32_bf16 v[88:91], v[154:157], v[178:181], v[88:91]
	v_mfma_f32_16x16x32_bf16 v[84:87], v[146:149], v[190:193], v[84:87]
	v_mfma_f32_16x16x32_bf16 v[76:79], v[154:157], v[190:193], v[76:79]
	v_mfma_f32_16x16x32_bf16 v[64:67], v[146:149], v[198:201], v[64:67]
	v_mfma_f32_16x16x32_bf16 v[56:59], v[154:157], v[198:201], v[56:59]
	v_mfma_f32_16x16x32_bf16 v[44:47], v[146:149], v[206:209], v[44:47]
	v_mfma_f32_16x16x32_bf16 v[40:43], v[154:157], v[206:209], v[40:43]
	v_mfma_f32_16x16x32_bf16 v[92:95], v[150:153], v[186:189], v[92:95]
	v_mfma_f32_16x16x32_bf16 v[88:91], v[158:161], v[186:189], v[88:91]
	v_mfma_f32_16x16x32_bf16 v[84:87], v[150:153], v[194:197], v[84:87]
	v_mfma_f32_16x16x32_bf16 v[76:79], v[158:161], v[194:197], v[76:79]
	v_mfma_f32_16x16x32_bf16 v[64:67], v[150:153], v[202:205], v[64:67]
	v_mfma_f32_16x16x32_bf16 v[56:59], v[158:161], v[202:205], v[56:59]
	v_mfma_f32_16x16x32_bf16 v[44:47], v[150:153], v[210:213], v[44:47]
	v_mfma_f32_16x16x32_bf16 v[40:43], v[158:161], v[210:213], v[40:43]
	v_mfma_f32_16x16x32_bf16 v[28:31], v[162:165], v[178:181], v[28:31]
	v_mfma_f32_16x16x32_bf16 v[24:27], v[170:173], v[178:181], v[24:27]
	v_mfma_f32_16x16x32_bf16 v[20:23], v[162:165], v[190:193], v[20:23]
	v_mfma_f32_16x16x32_bf16 v[16:19], v[170:173], v[190:193], v[16:19]
	v_mfma_f32_16x16x32_bf16 v[12:15], v[162:165], v[198:201], v[12:15]
	v_mfma_f32_16x16x32_bf16 v[8:11], v[170:173], v[198:201], v[8:11]
	v_mfma_f32_16x16x32_bf16 v[4:7], v[162:165], v[206:209], v[4:7]
	v_mfma_f32_16x16x32_bf16 v[0:3], v[170:173], v[206:209], v[0:3]
	v_mfma_f32_16x16x32_bf16 v[28:31], v[166:169], v[186:189], v[28:31]
	v_mfma_f32_16x16x32_bf16 v[24:27], v[174:177], v[186:189], v[24:27]
	v_mfma_f32_16x16x32_bf16 v[20:23], v[166:169], v[194:197], v[20:23]
	v_mfma_f32_16x16x32_bf16 v[16:19], v[174:177], v[194:197], v[16:19]
	v_mfma_f32_16x16x32_bf16 v[12:15], v[166:169], v[202:205], v[12:15]
	v_mfma_f32_16x16x32_bf16 v[8:11], v[174:177], v[202:205], v[8:11]
	v_mfma_f32_16x16x32_bf16 v[4:7], v[166:169], v[210:213], v[4:7]
	v_mfma_f32_16x16x32_bf16 v[0:3], v[174:177], v[210:213], v[0:3]
	s_barrier
	s_add_i32 s76, 0, 0x18000
	s_add_i32 s77, 0, 0x1c000
	v_add_u32_e32 v158, s76, v141
	v_add_u32_e32 v174, s77, v141
	ds_read_b128 v[146:149], v158
	ds_read_b128 v[150:153], v158 offset:1024
	ds_read_b128 v[154:157], v158 offset:2048
	ds_read_b128 v[158:161], v158 offset:3072
	ds_read_b128 v[162:165], v174
	ds_read_b128 v[166:169], v174 offset:1024
	ds_read_b128 v[170:173], v174 offset:2048
	ds_read_b128 v[174:177], v174 offset:3072
	s_add_u32 s54, s54, 0x80000
	s_addc_u32 s55, s55, 0
	s_mov_b32 m0, s58
	v_lshl_add_u64 v[220:221], s[54:55], 0, v[128:129]
	ds_read_b128 v[178:181], v145 offset:32768
	ds_read_b128 v[186:189], v145 offset:33792
	ds_read_b128 v[190:193], v145 offset:34816
	ds_read_b128 v[194:197], v145 offset:35840
	ds_read_b128 v[198:201], v145 offset:36864
	ds_read_b128 v[202:205], v145 offset:37888
	ds_read_b128 v[206:209], v145 offset:38912
	ds_read_b128 v[210:213], v145 offset:39936
	global_load_lds_dwordx4 v[220:221], off
	v_lshl_add_u64 v[220:221], s[54:55], 0, v[132:133]
	s_mov_b32 m0, s59
	s_nop 0
	global_load_lds_dwordx4 v[220:221], off
	s_waitcnt vmcnt(8)
	s_waitcnt lgkmcnt(0)
	s_barrier
	s_waitcnt lgkmcnt(0)
	v_mfma_f32_16x16x32_bf16 v[124:127], v[146:149], v[178:181], v[124:127]
	v_mfma_f32_16x16x32_bf16 v[120:123], v[154:157], v[178:181], v[120:123]
	v_mfma_f32_16x16x32_bf16 v[116:119], v[146:149], v[190:193], v[116:119]
	v_mfma_f32_16x16x32_bf16 v[112:115], v[154:157], v[190:193], v[112:115]
	v_mfma_f32_16x16x32_bf16 v[108:111], v[146:149], v[198:201], v[108:111]
	v_mfma_f32_16x16x32_bf16 v[104:107], v[154:157], v[198:201], v[104:107]
	v_mfma_f32_16x16x32_bf16 v[100:103], v[146:149], v[206:209], v[100:103]
	v_mfma_f32_16x16x32_bf16 v[96:99], v[154:157], v[206:209], v[96:99]
	v_mfma_f32_16x16x32_bf16 v[124:127], v[150:153], v[186:189], v[124:127]
	v_mfma_f32_16x16x32_bf16 v[120:123], v[158:161], v[186:189], v[120:123]
	v_mfma_f32_16x16x32_bf16 v[116:119], v[150:153], v[194:197], v[116:119]
	v_mfma_f32_16x16x32_bf16 v[112:115], v[158:161], v[194:197], v[112:115]
	v_mfma_f32_16x16x32_bf16 v[108:111], v[150:153], v[202:205], v[108:111]
	v_mfma_f32_16x16x32_bf16 v[104:107], v[158:161], v[202:205], v[104:107]
	v_mfma_f32_16x16x32_bf16 v[100:103], v[150:153], v[210:213], v[100:103]
	v_mfma_f32_16x16x32_bf16 v[96:99], v[158:161], v[210:213], v[96:99]
	v_mfma_f32_16x16x32_bf16 v[80:83], v[162:165], v[178:181], v[80:83]
	v_mfma_f32_16x16x32_bf16 v[72:75], v[170:173], v[178:181], v[72:75]
	v_mfma_f32_16x16x32_bf16 v[68:71], v[162:165], v[190:193], v[68:71]
	v_mfma_f32_16x16x32_bf16 v[60:63], v[170:173], v[190:193], v[60:63]
	v_mfma_f32_16x16x32_bf16 v[52:55], v[162:165], v[198:201], v[52:55]
	v_mfma_f32_16x16x32_bf16 v[48:51], v[170:173], v[198:201], v[48:51]
	v_mfma_f32_16x16x32_bf16 v[36:39], v[162:165], v[206:209], v[36:39]
	v_mfma_f32_16x16x32_bf16 v[32:35], v[170:173], v[206:209], v[32:35]
	v_mfma_f32_16x16x32_bf16 v[80:83], v[166:169], v[186:189], v[80:83]
	v_mfma_f32_16x16x32_bf16 v[72:75], v[174:177], v[186:189], v[72:75]
	v_mfma_f32_16x16x32_bf16 v[68:71], v[166:169], v[194:197], v[68:71]
	v_mfma_f32_16x16x32_bf16 v[60:63], v[174:177], v[194:197], v[60:63]
	v_mfma_f32_16x16x32_bf16 v[52:55], v[166:169], v[202:205], v[52:55]
	v_mfma_f32_16x16x32_bf16 v[48:51], v[174:177], v[202:205], v[48:51]
	v_mfma_f32_16x16x32_bf16 v[36:39], v[166:169], v[210:213], v[36:39]
	v_mfma_f32_16x16x32_bf16 v[32:35], v[174:177], v[210:213], v[32:35]
	s_barrier
; #define PG8_STAGE(bufoff, gbase, voff) do { _Pragma("unroll") for (int _i = 0; _i < 2; ++_i) \
;         __builtin_amdgcn_global_load_lds((const unsigned*)((const char*)(gbase) + (voff)[_i]), (LAS unsigned*)(lds + (bufoff) + ldsw + _i * 8192), 16, 0, 0); } while (0)
; #define PG8_LDA(dst, b, h) do { _Pragma("unroll") for (int m = 0; m < 4; ++m) _Pragma("unroll") for (int k = 0; k < 2; ++k) dst[m][k] = *(const LAS bf16x8*)(lds + PG8_SA(b, h) + aoff + m * 2048 + k * 1024); } while (0)
; #define PG8_MMA(ai, bj, At, Bt) do { __builtin_amdgcn_s_setprio(1); _Pragma("unroll") for (int m = 0; m < 4; ++m) _Pragma("unroll") for (int n = 0; n < 2; ++n) _Pragma("unroll") for (int k = 0; k < 2; ++k) \
;         acc[ai][bj][m][n] = __builtin_amdgcn_mfma_f32_16x16x32_bf16(Bt[n][k], At[m][k], acc[ai][bj][m][n], 0, 0, 0); __builtin_amdgcn_s_setprio(0); } while (0)
; #define PG8_WAIT_V(n) asm volatile("s_waitcnt vmcnt(" #n ")" ::: "memory")
; #define PG8_WAIT_L(n) asm volatile("s_waitcnt lgkmcnt(" #n ")" ::: "memory")
; #define PG8_BAR __builtin_amdgcn_s_barrier()
; #define PG8_SCHED __builtin_amdgcn_sched_barrier(0)
; template <class Epi, bool ALIGN_EPI = PG8_ALIGN>
; __device__ __forceinline__ void gemm_phase(LAS unsigned char* lds, const Gemm g, const StaticOrder S, const Epi E) {
;     ...
;             PG8_LDA(At, 1, 1); PG8_STAGE(PG8_SB(1, 0), b3, voffB); PG8_STAGE(PG8_SB(1, 1), b3 + hstepB, voffB); PG8_STAGE(PG8_SA(1, 0), a3, voffA);
;             PG8_WAIT_V(8); PG8_WAIT_L(0); PG8_BAR; PG8_MMA(1, 0, At, B0); PG8_MMA(1, 1, At, B1); PG8_BAR; PG8_SCHED;
;         }
;         if (ALIGN_EPI) { if (wr == 0) PG8_BAR; }
	s_add_i32 s54, s76, s34
	v_lshl_add_u64 v[182:183], v[182:183], 0, s[6:7]
	s_mov_b32 m0, s54
	ds_read_b128 v[178:181], v145 offset:49152
	ds_read_b128 v[186:189], v145 offset:50176
	ds_read_b128 v[190:193], v145 offset:51200
	ds_read_b128 v[194:197], v145 offset:52224
	ds_read_b128 v[198:201], v145 offset:53248
	ds_read_b128 v[202:205], v145 offset:54272
	ds_read_b128 v[206:209], v145 offset:55296
	ds_read_b128 v[210:213], v145 offset:56320
	global_load_lds_dwordx4 v[182:183], off
	s_add_i32 m0, s54, 0x2000
	s_add_u32 s52, s52, 0x80080
	v_lshl_add_u64 v[182:183], v[214:215], 0, s[6:7]
	s_addc_u32 s53, s53, 0
	s_add_i32 s54, s77, s34
	global_load_lds_dwordx4 v[182:183], off
	v_lshl_add_u64 v[182:183], s[52:53], 0, v[130:131]
	s_mov_b32 m0, s54
	s_nop 0
	global_load_lds_dwordx4 v[182:183], off
	v_lshl_add_u64 v[182:183], s[52:53], 0, v[134:135]
	s_add_i32 m0, s54, 0x2000
	s_nop 0
	global_load_lds_dwordx4 v[182:183], off
	v_lshl_add_u64 v[182:183], v[216:217], 0, s[6:7]
	s_mov_b32 m0, s61
	s_nop 0
	global_load_lds_dwordx4 v[182:183], off
	v_lshl_add_u64 v[182:183], v[218:219], 0, s[6:7]
	s_mov_b32 m0, s62
	s_nop 0
	global_load_lds_dwordx4 v[182:183], off
	s_waitcnt vmcnt(8)
	s_waitcnt lgkmcnt(0)
	s_barrier
	s_waitcnt lgkmcnt(0)
	v_mfma_f32_16x16x32_bf16 v[92:95], v[146:149], v[178:181], v[92:95]
	v_mfma_f32_16x16x32_bf16 v[88:91], v[154:157], v[178:181], v[88:91]
	v_mfma_f32_16x16x32_bf16 v[84:87], v[146:149], v[190:193], v[84:87]
	v_mfma_f32_16x16x32_bf16 v[76:79], v[154:157], v[190:193], v[76:79]
	v_mfma_f32_16x16x32_bf16 v[64:67], v[146:149], v[198:201], v[64:67]
	v_mfma_f32_16x16x32_bf16 v[56:59], v[154:157], v[198:201], v[56:59]
	v_mfma_f32_16x16x32_bf16 v[44:47], v[146:149], v[206:209], v[44:47]
	v_mfma_f32_16x16x32_bf16 v[40:43], v[154:157], v[206:209], v[40:43]
	v_mfma_f32_16x16x32_bf16 v[92:95], v[150:153], v[186:189], v[92:95]
	v_mfma_f32_16x16x32_bf16 v[88:91], v[158:161], v[186:189], v[88:91]
	v_mfma_f32_16x16x32_bf16 v[84:87], v[150:153], v[194:197], v[84:87]
	v_mfma_f32_16x16x32_bf16 v[76:79], v[158:161], v[194:197], v[76:79]
	v_mfma_f32_16x16x32_bf16 v[64:67], v[150:153], v[202:205], v[64:67]
	v_mfma_f32_16x16x32_bf16 v[56:59], v[158:161], v[202:205], v[56:59]
	v_mfma_f32_16x16x32_bf16 v[44:47], v[150:153], v[210:213], v[44:47]
	v_mfma_f32_16x16x32_bf16 v[40:43], v[158:161], v[210:213], v[40:43]
	v_mfma_f32_16x16x32_bf16 v[28:31], v[162:165], v[178:181], v[28:31]
	v_mfma_f32_16x16x32_bf16 v[24:27], v[170:173], v[178:181], v[24:27]
	v_mfma_f32_16x16x32_bf16 v[20:23], v[162:165], v[190:193], v[20:23]
	v_mfma_f32_16x16x32_bf16 v[16:19], v[170:173], v[190:193], v[16:19]
	v_mfma_f32_16x16x32_bf16 v[12:15], v[162:165], v[198:201], v[12:15]
	v_mfma_f32_16x16x32_bf16 v[8:11], v[170:173], v[198:201], v[8:11]
	v_mfma_f32_16x16x32_bf16 v[4:7], v[162:165], v[206:209], v[4:7]
	v_mfma_f32_16x16x32_bf16 v[0:3], v[170:173], v[206:209], v[0:3]
	v_mfma_f32_16x16x32_bf16 v[28:31], v[166:169], v[186:189], v[28:31]
	v_mfma_f32_16x16x32_bf16 v[24:27], v[174:177], v[186:189], v[24:27]
	v_mfma_f32_16x16x32_bf16 v[20:23], v[166:169], v[194:197], v[20:23]
	v_mfma_f32_16x16x32_bf16 v[16:19], v[174:177], v[194:197], v[16:19]
	v_mfma_f32_16x16x32_bf16 v[12:15], v[166:169], v[202:205], v[12:15]
	v_mfma_f32_16x16x32_bf16 v[8:11], v[174:177], v[202:205], v[8:11]
	v_mfma_f32_16x16x32_bf16 v[4:7], v[166:169], v[210:213], v[4:7]
	v_mfma_f32_16x16x32_bf16 v[0:3], v[174:177], v[210:213], v[0:3]
	s_barrier
	s_add_i32 s75, s75, 2
	s_add_u32 s50, s50, 0x100
	s_addc_u32 s51, s51, 0
	s_add_u32 s73, s73, 0x100
	s_addc_u32 s74, s74, 0
	s_cmp_gt_u32 s75, 29
	s_cbranch_scc0 .LBB0_1348
	s_and_b64 vcc, exec, s[8:9]
	s_cbranch_vccz .LBB0_1351
	s_barrier

; #define PG8_STAGE(bufoff, gbase, voff) do { _Pragma("unroll") for (int _i = 0; _i < 2; ++_i) \
;         __builtin_amdgcn_global_load_lds((const unsigned*)((const char*)(gbase) + (voff)[_i]), (LAS unsigned*)(lds + (bufoff) + ldsw + _i * 8192), 16, 0, 0); } while (0)
; #define PG8_LDA(dst, b, h) do { _Pragma("unroll") for (int m = 0; m < 4; ++m) _Pragma("unroll") for (int k = 0; k < 2; ++k) dst[m][k] = *(const LAS bf16x8*)(lds + PG8_SA(b, h) + aoff + m * 2048 + k * 1024); } while (0)
; #define PG8_LDB(dst, b, h) do { _Pragma("unroll") for (int n = 0; n < 2; ++n) _Pragma("unroll") for (int k = 0; k < 2; ++k) dst[n][k] = *(const LAS bf16x8*)(lds + PG8_SB(b, h) + boff + n * 2048 + k * 1024); } while (0)
; #define PG8_MMA(ai, bj, At, Bt) do { __builtin_amdgcn_s_setprio(1); _Pragma("unroll") for (int m = 0; m < 4; ++m) _Pragma("unroll") for (int n = 0; n < 2; ++n) _Pragma("unroll") for (int k = 0; k < 2; ++k) \
;         acc[ai][bj][m][n] = __builtin_amdgcn_mfma_f32_16x16x32_bf16(Bt[n][k], At[m][k], acc[ai][bj][m][n], 0, 0, 0); __builtin_amdgcn_s_setprio(0); } while (0)
; #define PG8_WAIT_V(n) asm volatile("s_waitcnt vmcnt(" #n ")" ::: "memory")
; #define PG8_WAIT_L(n) asm volatile("s_waitcnt lgkmcnt(" #n ")" ::: "memory")
; #define PG8_BAR __builtin_amdgcn_s_barrier()
; #define PG8_SCHED __builtin_amdgcn_sched_barrier(0)
; template <class Epi, bool ALIGN_EPI = PG8_ALIGN>
; __device__ __forceinline__ void gemm_phase(LAS unsigned char* lds, const Gemm g, const StaticOrder S, const Epi E) {
;     ...
;         for (int t = 0; t < nt; t += 2) {
;             const bool last = (t == nt - 2);
;             const char* a1 = cA + (size_t)(t + 1) * kstep;
;             const char* a2 = last ? nA : cA + (size_t)(t + 2) * kstep; const char* b2 = last ? nB : cB + (size_t)(t + 2) * kstep;
;             const char* a3 = a2 + kstep; const char* b3 = b2 + kstep;
;             PG8_LDB(B0, 0, 0); PG8_LDB(B1, 0, 1); PG8_SCHED; PG8_LDA(At, 0, 0); PG8_STAGE(PG8_SA(1, 1), a1 + hstepA, voffA);
;             PG8_WAIT_V(8); PG8_WAIT_L(0); PG8_BAR; PG8_MMA(0, 0, At, B0); PG8_MMA(0, 1, At, B1); PG8_BAR; PG8_SCHED;
;             PG8_LDA(At, 0, 1); PG8_STAGE(PG8_SB(0, 0), b2, voffB); PG8_STAGE(PG8_SB(0, 1), b2 + hstepB, voffB); PG8_STAGE(PG8_SA(0, 0), a2, voffA);
;             PG8_WAIT_V(8); PG8_WAIT_L(0); PG8_BAR; PG8_MMA(1, 0, At, B0); PG8_MMA(1, 1, At, B1); PG8_BAR; PG8_SCHED;
.LBB0_1602:
	ds_read_b128 v[146:149], v151
	ds_read_b128 v[154:157], v151 offset:1024
	ds_read_b128 v[158:161], v151 offset:2048
	ds_read_b128 v[162:165], v151 offset:3072
	ds_read_b128 v[166:169], v152
	ds_read_b128 v[170:173], v152 offset:1024
	ds_read_b128 v[174:177], v152 offset:2048
	ds_read_b128 v[178:181], v152 offset:3072
	s_add_u32 s34, s36, 0xfffe0080
	s_addc_u32 s35, s37, -1
	s_cmp_eq_u32 s33, 4
	s_cselect_b32 s43, s13, s35
	s_cselect_b32 s42, s14, s34
	s_cselect_b32 s39, s16, s23
	s_cselect_b32 s38, s17, s21
	v_lshl_add_u64 v[182:183], s[36:37], 0, v[138:139]
	s_add_i32 m0, s29, 0xc000
	ds_read_b128 v[186:189], v153
	ds_read_b128 v[190:193], v153 offset:1024
	ds_read_b128 v[194:197], v153 offset:2048
	ds_read_b128 v[198:201], v153 offset:3072
	ds_read_b128 v[202:205], v153 offset:4096
	ds_read_b128 v[206:209], v153 offset:5120
	ds_read_b128 v[210:213], v153 offset:6144
	ds_read_b128 v[214:217], v153 offset:7168
	global_load_lds_dwordx4 v[182:183], off
	v_lshl_add_u64 v[182:183], s[36:37], 0, v[140:141]
	s_add_i32 m0, s29, 0xe000
	s_nop 0
	global_load_lds_dwordx4 v[182:183], off
	s_waitcnt vmcnt(8)
	s_waitcnt lgkmcnt(0)
	s_barrier
	s_waitcnt lgkmcnt(0)
	v_mfma_f32_16x16x32_bf16 v[124:127], v[146:149], v[186:189], v[124:127]
	v_mfma_f32_16x16x32_bf16 v[120:123], v[158:161], v[186:189], v[120:123]
	v_mfma_f32_16x16x32_bf16 v[108:111], v[146:149], v[194:197], v[108:111]
	v_mfma_f32_16x16x32_bf16 v[104:107], v[158:161], v[194:197], v[104:107]
	v_mfma_f32_16x16x32_bf16 v[92:95], v[146:149], v[202:205], v[92:95]
	v_mfma_f32_16x16x32_bf16 v[88:91], v[158:161], v[202:205], v[88:91]
	v_mfma_f32_16x16x32_bf16 v[76:79], v[146:149], v[210:213], v[76:79]
	v_mfma_f32_16x16x32_bf16 v[72:75], v[158:161], v[210:213], v[72:75]
	v_mfma_f32_16x16x32_bf16 v[124:127], v[154:157], v[190:193], v[124:127]
	v_mfma_f32_16x16x32_bf16 v[120:123], v[162:165], v[190:193], v[120:123]
	v_mfma_f32_16x16x32_bf16 v[108:111], v[154:157], v[198:201], v[108:111]
	v_mfma_f32_16x16x32_bf16 v[104:107], v[162:165], v[198:201], v[104:107]
	v_mfma_f32_16x16x32_bf16 v[92:95], v[154:157], v[206:209], v[92:95]
	v_mfma_f32_16x16x32_bf16 v[88:91], v[162:165], v[206:209], v[88:91]
	v_mfma_f32_16x16x32_bf16 v[76:79], v[154:157], v[214:217], v[76:79]
	v_mfma_f32_16x16x32_bf16 v[72:75], v[162:165], v[214:217], v[72:75]
	v_mfma_f32_16x16x32_bf16 v[116:119], v[166:169], v[186:189], v[116:119]
	v_mfma_f32_16x16x32_bf16 v[112:115], v[174:177], v[186:189], v[112:115]
	v_mfma_f32_16x16x32_bf16 v[100:103], v[166:169], v[194:197], v[100:103]
	v_mfma_f32_16x16x32_bf16 v[96:99], v[174:177], v[194:197], v[96:99]
	v_mfma_f32_16x16x32_bf16 v[84:87], v[166:169], v[202:205], v[84:87]
	v_mfma_f32_16x16x32_bf16 v[80:83], v[174:177], v[202:205], v[80:83]
	v_mfma_f32_16x16x32_bf16 v[68:71], v[166:169], v[210:213], v[68:71]
	v_mfma_f32_16x16x32_bf16 v[64:67], v[174:177], v[210:213], v[64:67]
	v_mfma_f32_16x16x32_bf16 v[116:119], v[170:173], v[190:193], v[116:119]
	v_mfma_f32_16x16x32_bf16 v[112:115], v[178:181], v[190:193], v[112:115]
	v_mfma_f32_16x16x32_bf16 v[100:103], v[170:173], v[198:201], v[100:103]
	v_mfma_f32_16x16x32_bf16 v[96:99], v[178:181], v[198:201], v[96:99]
	v_mfma_f32_16x16x32_bf16 v[84:87], v[170:173], v[206:209], v[84:87]
	v_mfma_f32_16x16x32_bf16 v[80:83], v[178:181], v[206:209], v[80:83]
	v_mfma_f32_16x16x32_bf16 v[68:71], v[170:173], v[214:217], v[68:71]
	v_mfma_f32_16x16x32_bf16 v[64:67], v[178:181], v[214:217], v[64:67]
	s_barrier
	s_add_i32 s34, s53, s44
	v_lshl_add_u64 v[182:183], s[38:39], 0, v[130:131]
	s_mov_b32 m0, s34
	ds_read_b128 v[186:189], v153 offset:16384
	ds_read_b128 v[190:193], v153 offset:17408
	ds_read_b128 v[194:197], v153 offset:18432
	ds_read_b128 v[198:201], v153 offset:19456
	ds_read_b128 v[202:205], v153 offset:20480
	ds_read_b128 v[206:209], v153 offset:21504
	ds_read_b128 v[210:213], v153 offset:22528
	ds_read_b128 v[214:217], v153 offset:23552
	global_load_lds_dwordx4 v[182:183], off
	s_add_i32 m0, s34, 0x2000
	s_add_u32 s34, s38, 0x20000
	v_lshl_add_u64 v[218:219], s[38:39], 0, v[134:135]
	s_addc_u32 s35, s39, 0
	s_add_i32 s55, s54, s44
	global_load_lds_dwordx4 v[218:219], off
	v_lshl_add_u64 v[220:221], s[34:35], 0, v[130:131]
	s_mov_b32 m0, s55
	v_lshl_add_u64 v[222:223], s[42:43], 0, v[132:133]
	global_load_lds_dwordx4 v[220:221], off
	v_lshl_add_u64 v[220:221], s[34:35], 0, v[134:135]
	s_add_i32 m0, s55, 0x2000
	s_nop 0
	global_load_lds_dwordx4 v[220:221], off
	v_lshl_add_u64 v[220:221], s[42:43], 0, v[128:129]
	s_mov_b32 m0, s29
	s_nop 0
	global_load_lds_dwordx4 v[220:221], off
	s_mov_b32 m0, s45
	s_nop 0
	global_load_lds_dwordx4 v[222:223], off
	s_waitcnt vmcnt(8)
	s_waitcnt lgkmcnt(0)
	s_barrier
; #define PG8_STAGE(bufoff, gbase, voff) do { _Pragma("unroll") for (int _i = 0; _i < 2; ++_i) \
;         __builtin_amdgcn_global_load_lds((const unsigned*)((const char*)(gbase) + (voff)[_i]), (LAS unsigned*)(lds + (bufoff) + ldsw + _i * 8192), 16, 0, 0); } while (0)
; #define PG8_LDA(dst, b, h) do { _Pragma("unroll") for (int m = 0; m < 4; ++m) _Pragma("unroll") for (int k = 0; k < 2; ++k) dst[m][k] = *(const LAS bf16x8*)(lds + PG8_SA(b, h) + aoff + m * 2048 + k * 1024); } while (0)
; #define PG8_LDB(dst, b, h) do { _Pragma("unroll") for (int n = 0; n < 2; ++n) _Pragma("unroll") for (int k = 0; k < 2; ++k) dst[n][k] = *(const LAS bf16x8*)(lds + PG8_SB(b, h) + boff + n * 2048 + k * 1024); } while (0)
; #define PG8_MMA(ai, bj, At, Bt) do { __builtin_amdgcn_s_setprio(1); _Pragma("unroll") for (int m = 0; m < 4; ++m) _Pragma("unroll") for (int n = 0; n < 2; ++n) _Pragma("unroll") for (int k = 0; k < 2; ++k) \
;         acc[ai][bj][m][n] = __builtin_amdgcn_mfma_f32_16x16x32_bf16(Bt[n][k], At[m][k], acc[ai][bj][m][n], 0, 0, 0); __builtin_amdgcn_s_setprio(0); } while (0)
; #define PG8_WAIT_V(n) asm volatile("s_waitcnt vmcnt(" #n ")" ::: "memory")
; #define PG8_WAIT_L(n) asm volatile("s_waitcnt lgkmcnt(" #n ")" ::: "memory")
; #define PG8_BAR __builtin_amdgcn_s_barrier()
; #define PG8_SCHED __builtin_amdgcn_sched_barrier(0)
; template <class Epi, bool ALIGN_EPI = PG8_ALIGN>
; __device__ __forceinline__ void gemm_phase(LAS unsigned char* lds, const Gemm g, const StaticOrder S, const Epi E) {
;     ...
;             PG8_WAIT_V(8); PG8_WAIT_L(0); PG8_BAR; PG8_MMA(1, 0, At, B0); PG8_MMA(1, 1, At, B1); PG8_BAR; PG8_SCHED;
;             PG8_LDB(B0, 1, 0); PG8_LDB(B1, 1, 1); PG8_SCHED; PG8_LDA(At, 1, 0); PG8_STAGE(PG8_SA(0, 1), a2 + hstepA, voffA);
;             PG8_WAIT_V(8); PG8_WAIT_L(0); PG8_BAR; PG8_MMA(0, 0, At, B0); PG8_MMA(0, 1, At, B1); PG8_BAR; PG8_SCHED;
	s_waitcnt lgkmcnt(0)
	v_mfma_f32_16x16x32_bf16 v[60:63], v[146:149], v[186:189], v[60:63]
	v_mfma_f32_16x16x32_bf16 v[56:59], v[158:161], v[186:189], v[56:59]
	v_mfma_f32_16x16x32_bf16 v[44:47], v[146:149], v[194:197], v[44:47]
	v_mfma_f32_16x16x32_bf16 v[40:43], v[158:161], v[194:197], v[40:43]
	v_mfma_f32_16x16x32_bf16 v[28:31], v[146:149], v[202:205], v[28:31]
	v_mfma_f32_16x16x32_bf16 v[24:27], v[158:161], v[202:205], v[24:27]
	v_mfma_f32_16x16x32_bf16 v[12:15], v[146:149], v[210:213], v[12:15]
	v_mfma_f32_16x16x32_bf16 v[8:11], v[158:161], v[210:213], v[8:11]
	v_mfma_f32_16x16x32_bf16 v[60:63], v[154:157], v[190:193], v[60:63]
	v_mfma_f32_16x16x32_bf16 v[56:59], v[162:165], v[190:193], v[56:59]
	v_mfma_f32_16x16x32_bf16 v[44:47], v[154:157], v[198:201], v[44:47]
	v_mfma_f32_16x16x32_bf16 v[40:43], v[162:165], v[198:201], v[40:43]
	v_mfma_f32_16x16x32_bf16 v[28:31], v[154:157], v[206:209], v[28:31]
	v_mfma_f32_16x16x32_bf16 v[24:27], v[162:165], v[206:209], v[24:27]
	v_mfma_f32_16x16x32_bf16 v[12:15], v[154:157], v[214:217], v[12:15]
	v_mfma_f32_16x16x32_bf16 v[8:11], v[162:165], v[214:217], v[8:11]
	v_mfma_f32_16x16x32_bf16 v[52:55], v[166:169], v[186:189], v[52:55]
	v_mfma_f32_16x16x32_bf16 v[48:51], v[174:177], v[186:189], v[48:51]
	v_mfma_f32_16x16x32_bf16 v[36:39], v[166:169], v[194:197], v[36:39]
	v_mfma_f32_16x16x32_bf16 v[32:35], v[174:177], v[194:197], v[32:35]
	v_mfma_f32_16x16x32_bf16 v[20:23], v[166:169], v[202:205], v[20:23]
	v_mfma_f32_16x16x32_bf16 v[16:19], v[174:177], v[202:205], v[16:19]
	v_mfma_f32_16x16x32_bf16 v[4:7], v[166:169], v[210:213], v[4:7]
	v_mfma_f32_16x16x32_bf16 v[0:3], v[174:177], v[210:213], v[0:3]
	v_mfma_f32_16x16x32_bf16 v[52:55], v[170:173], v[190:193], v[52:55]
	v_mfma_f32_16x16x32_bf16 v[48:51], v[178:181], v[190:193], v[48:51]
	v_mfma_f32_16x16x32_bf16 v[36:39], v[170:173], v[198:201], v[36:39]
	v_mfma_f32_16x16x32_bf16 v[32:35], v[178:181], v[198:201], v[32:35]
	v_mfma_f32_16x16x32_bf16 v[20:23], v[170:173], v[206:209], v[20:23]
	v_mfma_f32_16x16x32_bf16 v[16:19], v[178:181], v[206:209], v[16:19]
	v_mfma_f32_16x16x32_bf16 v[4:7], v[170:173], v[214:217], v[4:7]
	v_mfma_f32_16x16x32_bf16 v[0:3], v[178:181], v[214:217], v[0:3]
	s_barrier
	s_add_i32 s55, 0, 0x18000
	s_add_i32 s56, 0, 0x1c000
	v_add_u32_e32 v162, s55, v150
	v_add_u32_e32 v178, s56, v150
	ds_read_b128 v[146:149], v162
	ds_read_b128 v[154:157], v162 offset:1024
	ds_read_b128 v[158:161], v162 offset:2048
	ds_read_b128 v[162:165], v162 offset:3072
	ds_read_b128 v[166:169], v178
	ds_read_b128 v[170:173], v178 offset:1024
	ds_read_b128 v[174:177], v178 offset:2048
	ds_read_b128 v[178:181], v178 offset:3072
	s_add_u32 s34, s42, 0x20000
	s_addc_u32 s35, s43, 0
	s_mov_b32 m0, s46
	v_lshl_add_u64 v[224:225], s[34:35], 0, v[128:129]
	ds_read_b128 v[186:189], v153 offset:32768
	ds_read_b128 v[190:193], v153 offset:33792
	ds_read_b128 v[194:197], v153 offset:34816
	ds_read_b128 v[198:201], v153 offset:35840
	ds_read_b128 v[202:205], v153 offset:36864
	ds_read_b128 v[206:209], v153 offset:37888
	ds_read_b128 v[210:213], v153 offset:38912
	ds_read_b128 v[214:217], v153 offset:39936
	global_load_lds_dwordx4 v[224:225], off
	v_lshl_add_u64 v[224:225], s[34:35], 0, v[132:133]
	s_mov_b32 m0, s47
	s_nop 0
	global_load_lds_dwordx4 v[224:225], off
	s_waitcnt vmcnt(8)
	s_waitcnt lgkmcnt(0)
	s_barrier
	s_waitcnt lgkmcnt(0)
	v_mfma_f32_16x16x32_bf16 v[124:127], v[146:149], v[186:189], v[124:127]
	v_mfma_f32_16x16x32_bf16 v[120:123], v[158:161], v[186:189], v[120:123]
	v_mfma_f32_16x16x32_bf16 v[108:111], v[146:149], v[194:197], v[108:111]
	v_mfma_f32_16x16x32_bf16 v[104:107], v[158:161], v[194:197], v[104:107]
	v_mfma_f32_16x16x32_bf16 v[92:95], v[146:149], v[202:205], v[92:95]
	v_mfma_f32_16x16x32_bf16 v[88:91], v[158:161], v[202:205], v[88:91]
	v_mfma_f32_16x16x32_bf16 v[76:79], v[146:149], v[210:213], v[76:79]
	v_mfma_f32_16x16x32_bf16 v[72:75], v[158:161], v[210:213], v[72:75]
	v_mfma_f32_16x16x32_bf16 v[124:127], v[154:157], v[190:193], v[124:127]
	v_mfma_f32_16x16x32_bf16 v[120:123], v[162:165], v[190:193], v[120:123]
	v_mfma_f32_16x16x32_bf16 v[108:111], v[154:157], v[198:201], v[108:111]
	v_mfma_f32_16x16x32_bf16 v[104:107], v[162:165], v[198:201], v[104:107]
	v_mfma_f32_16x16x32_bf16 v[92:95], v[154:157], v[206:209], v[92:95]
	v_mfma_f32_16x16x32_bf16 v[88:91], v[162:165], v[206:209], v[88:91]
	v_mfma_f32_16x16x32_bf16 v[76:79], v[154:157], v[214:217], v[76:79]
	v_mfma_f32_16x16x32_bf16 v[72:75], v[162:165], v[214:217], v[72:75]
	v_mfma_f32_16x16x32_bf16 v[116:119], v[166:169], v[186:189], v[116:119]
	v_mfma_f32_16x16x32_bf16 v[112:115], v[174:177], v[186:189], v[112:115]
	v_mfma_f32_16x16x32_bf16 v[100:103], v[166:169], v[194:197], v[100:103]
	v_mfma_f32_16x16x32_bf16 v[96:99], v[174:177], v[194:197], v[96:99]
	v_mfma_f32_16x16x32_bf16 v[84:87], v[166:169], v[202:205], v[84:87]
	v_mfma_f32_16x16x32_bf16 v[80:83], v[174:177], v[202:205], v[80:83]
	v_mfma_f32_16x16x32_bf16 v[68:71], v[166:169], v[210:213], v[68:71]
	v_mfma_f32_16x16x32_bf16 v[64:67], v[174:177], v[210:213], v[64:67]
	v_mfma_f32_16x16x32_bf16 v[116:119], v[170:173], v[190:193], v[116:119]
	v_mfma_f32_16x16x32_bf16 v[112:115], v[178:181], v[190:193], v[112:115]
	v_mfma_f32_16x16x32_bf16 v[100:103], v[170:173], v[198:201], v[100:103]
	v_mfma_f32_16x16x32_bf16 v[96:99], v[178:181], v[198:201], v[96:99]
	v_mfma_f32_16x16x32_bf16 v[84:87], v[170:173], v[206:209], v[84:87]
	v_mfma_f32_16x16x32_bf16 v[80:83], v[178:181], v[206:209], v[80:83]
	v_mfma_f32_16x16x32_bf16 v[68:71], v[170:173], v[214:217], v[68:71]
	v_mfma_f32_16x16x32_bf16 v[64:67], v[178:181], v[214:217], v[64:67]
	s_barrier
; #define PG8_STAGE(bufoff, gbase, voff) do { _Pragma("unroll") for (int _i = 0; _i < 2; ++_i) \
;         __builtin_amdgcn_global_load_lds((const unsigned*)((const char*)(gbase) + (voff)[_i]), (LAS unsigned*)(lds + (bufoff) + ldsw + _i * 8192), 16, 0, 0); } while (0)
; #define PG8_LDA(dst, b, h) do { _Pragma("unroll") for (int m = 0; m < 4; ++m) _Pragma("unroll") for (int k = 0; k < 2; ++k) dst[m][k] = *(const LAS bf16x8*)(lds + PG8_SA(b, h) + aoff + m * 2048 + k * 1024); } while (0)
; #define PG8_MMA(ai, bj, At, Bt) do { __builtin_amdgcn_s_setprio(1); _Pragma("unroll") for (int m = 0; m < 4; ++m) _Pragma("unroll") for (int n = 0; n < 2; ++n) _Pragma("unroll") for (int k = 0; k < 2; ++k) \
;         acc[ai][bj][m][n] = __builtin_amdgcn_mfma_f32_16x16x32_bf16(Bt[n][k], At[m][k], acc[ai][bj][m][n], 0, 0, 0); __builtin_amdgcn_s_setprio(0); } while (0)
; #define PG8_WAIT_V(n) asm volatile("s_waitcnt vmcnt(" #n ")" ::: "memory")
; #define PG8_WAIT_L(n) asm volatile("s_waitcnt lgkmcnt(" #n ")" ::: "memory")
; #define PG8_BAR __builtin_amdgcn_s_barrier()
; #define PG8_SCHED __builtin_amdgcn_sched_barrier(0)
; template <class Epi, bool ALIGN_EPI = PG8_ALIGN>
; __device__ __forceinline__ void gemm_phase(LAS unsigned char* lds, const Gemm g, const StaticOrder S, const Epi E) {
;     ...
;             PG8_LDA(At, 1, 1); PG8_STAGE(PG8_SB(1, 0), b3, voffB); PG8_STAGE(PG8_SB(1, 1), b3 + hstepB, voffB); PG8_STAGE(PG8_SA(1, 0), a3, voffA);
;             PG8_WAIT_V(8); PG8_WAIT_L(0); PG8_BAR; PG8_MMA(1, 0, At, B0); PG8_MMA(1, 1, At, B1); PG8_BAR; PG8_SCHED;
;         }
;         if (ALIGN_EPI) { if (wr == 0) PG8_BAR; }
	s_add_i32 s34, s55, s44
	v_lshl_add_u64 v[182:183], v[182:183], 0, s[10:11]
	s_mov_b32 m0, s34
	ds_read_b128 v[186:189], v153 offset:49152
	ds_read_b128 v[190:193], v153 offset:50176
	ds_read_b128 v[194:197], v153 offset:51200
	ds_read_b128 v[198:201], v153 offset:52224
	ds_read_b128 v[202:205], v153 offset:53248
	ds_read_b128 v[206:209], v153 offset:54272
	ds_read_b128 v[210:213], v153 offset:55296
	ds_read_b128 v[214:217], v153 offset:56320
	global_load_lds_dwordx4 v[182:183], off
	s_add_i32 m0, s34, 0x2000
	s_add_u32 s34, s38, 0x20080
	v_lshl_add_u64 v[182:183], v[218:219], 0, s[10:11]
	s_addc_u32 s35, s39, 0
	s_add_i32 s38, s56, s44
	global_load_lds_dwordx4 v[182:183], off
	v_lshl_add_u64 v[182:183], s[34:35], 0, v[130:131]
	s_mov_b32 m0, s38
	s_nop 0
	global_load_lds_dwordx4 v[182:183], off
	v_lshl_add_u64 v[182:183], s[34:35], 0, v[134:135]
	s_add_i32 m0, s38, 0x2000
	s_nop 0
	global_load_lds_dwordx4 v[182:183], off
	v_lshl_add_u64 v[182:183], v[220:221], 0, s[10:11]
	s_mov_b32 m0, s50
	s_nop 0
	global_load_lds_dwordx4 v[182:183], off
	v_lshl_add_u64 v[182:183], v[222:223], 0, s[10:11]
	s_mov_b32 m0, s51
	s_nop 0
	global_load_lds_dwordx4 v[182:183], off
	s_waitcnt vmcnt(8)
	s_waitcnt lgkmcnt(0)
	s_barrier
	s_waitcnt lgkmcnt(0)
	v_mfma_f32_16x16x32_bf16 v[60:63], v[146:149], v[186:189], v[60:63]
	v_mfma_f32_16x16x32_bf16 v[56:59], v[158:161], v[186:189], v[56:59]
	v_mfma_f32_16x16x32_bf16 v[44:47], v[146:149], v[194:197], v[44:47]
	v_mfma_f32_16x16x32_bf16 v[40:43], v[158:161], v[194:197], v[40:43]
	v_mfma_f32_16x16x32_bf16 v[28:31], v[146:149], v[202:205], v[28:31]
	v_mfma_f32_16x16x32_bf16 v[24:27], v[158:161], v[202:205], v[24:27]
	v_mfma_f32_16x16x32_bf16 v[12:15], v[146:149], v[210:213], v[12:15]
	v_mfma_f32_16x16x32_bf16 v[8:11], v[158:161], v[210:213], v[8:11]
	v_mfma_f32_16x16x32_bf16 v[60:63], v[154:157], v[190:193], v[60:63]
	v_mfma_f32_16x16x32_bf16 v[56:59], v[162:165], v[190:193], v[56:59]
	v_mfma_f32_16x16x32_bf16 v[44:47], v[154:157], v[198:201], v[44:47]
	v_mfma_f32_16x16x32_bf16 v[40:43], v[162:165], v[198:201], v[40:43]
	v_mfma_f32_16x16x32_bf16 v[28:31], v[154:157], v[206:209], v[28:31]
	v_mfma_f32_16x16x32_bf16 v[24:27], v[162:165], v[206:209], v[24:27]
	v_mfma_f32_16x16x32_bf16 v[12:15], v[154:157], v[214:217], v[12:15]
	v_mfma_f32_16x16x32_bf16 v[8:11], v[162:165], v[214:217], v[8:11]
	v_mfma_f32_16x16x32_bf16 v[52:55], v[166:169], v[186:189], v[52:55]
	v_mfma_f32_16x16x32_bf16 v[48:51], v[174:177], v[186:189], v[48:51]
	v_mfma_f32_16x16x32_bf16 v[36:39], v[166:169], v[194:197], v[36:39]
	v_mfma_f32_16x16x32_bf16 v[32:35], v[174:177], v[194:197], v[32:35]
	v_mfma_f32_16x16x32_bf16 v[20:23], v[166:169], v[202:205], v[20:23]
	v_mfma_f32_16x16x32_bf16 v[16:19], v[174:177], v[202:205], v[16:19]
	v_mfma_f32_16x16x32_bf16 v[4:7], v[166:169], v[210:213], v[4:7]
	v_mfma_f32_16x16x32_bf16 v[0:3], v[174:177], v[210:213], v[0:3]
	v_mfma_f32_16x16x32_bf16 v[52:55], v[170:173], v[190:193], v[52:55]
	v_mfma_f32_16x16x32_bf16 v[48:51], v[178:181], v[190:193], v[48:51]
	v_mfma_f32_16x16x32_bf16 v[36:39], v[170:173], v[198:201], v[36:39]
	v_mfma_f32_16x16x32_bf16 v[32:35], v[178:181], v[198:201], v[32:35]
	v_mfma_f32_16x16x32_bf16 v[20:23], v[170:173], v[206:209], v[20:23]
	v_mfma_f32_16x16x32_bf16 v[16:19], v[178:181], v[206:209], v[16:19]
	v_mfma_f32_16x16x32_bf16 v[4:7], v[170:173], v[214:217], v[4:7]
	v_mfma_f32_16x16x32_bf16 v[0:3], v[178:181], v[214:217], v[0:3]
	s_barrier
	s_add_i32 s33, s33, 2
	s_add_u32 s36, s36, 0x100
	s_addc_u32 s37, s37, 0
	s_add_u32 s21, s21, 0x100
	s_addc_u32 s23, s23, 0
	s_cmp_gt_u32 s33, 5
	s_cbranch_scc0 .LBB0_1602
	s_and_b64 vcc, exec, s[18:19]
	s_cbranch_vccz .LBB0_1605
	s_barrier

; #define PG8_STAGE(bufoff, gbase, voff) do { _Pragma("unroll") for (int _i = 0; _i < 2; ++_i) \
;         __builtin_amdgcn_global_load_lds((const unsigned*)((const char*)(gbase) + (voff)[_i]), (LAS unsigned*)(lds + (bufoff) + ldsw + _i * 8192), 16, 0, 0); } while (0)
; #define PG8_LDA(dst, b, h) do { _Pragma("unroll") for (int m = 0; m < 4; ++m) _Pragma("unroll") for (int k = 0; k < 2; ++k) dst[m][k] = *(const LAS bf16x8*)(lds + PG8_SA(b, h) + aoff + m * 2048 + k * 1024); } while (0)
; #define PG8_LDB(dst, b, h) do { _Pragma("unroll") for (int n = 0; n < 2; ++n) _Pragma("unroll") for (int k = 0; k < 2; ++k) dst[n][k] = *(const LAS bf16x8*)(lds + PG8_SB(b, h) + boff + n * 2048 + k * 1024); } while (0)
; #define PG8_MMA(ai, bj, At, Bt) do { __builtin_amdgcn_s_setprio(1); _Pragma("unroll") for (int m = 0; m < 4; ++m) _Pragma("unroll") for (int n = 0; n < 2; ++n) _Pragma("unroll") for (int k = 0; k < 2; ++k) \
;         acc[ai][bj][m][n] = __builtin_amdgcn_mfma_f32_16x16x32_bf16(Bt[n][k], At[m][k], acc[ai][bj][m][n], 0, 0, 0); __builtin_amdgcn_s_setprio(0); } while (0)
; #define PG8_WAIT_V(n) asm volatile("s_waitcnt vmcnt(" #n ")" ::: "memory")
; #define PG8_WAIT_L(n) asm volatile("s_waitcnt lgkmcnt(" #n ")" ::: "memory")
; #define PG8_BAR __builtin_amdgcn_s_barrier()
; #define PG8_SCHED __builtin_amdgcn_sched_barrier(0)
; template <class Epi, bool ALIGN_EPI = PG8_ALIGN>
; __device__ __forceinline__ void gemm_phase(LAS unsigned char* lds, const Gemm g, const StaticOrder S, const Epi E) {
;     ...
;         for (int t = 0; t < nt; t += 2) {
;             const bool last = (t == nt - 2);
;             const char* a1 = cA + (size_t)(t + 1) * kstep;
;             const char* a2 = last ? nA : cA + (size_t)(t + 2) * kstep; const char* b2 = last ? nB : cB + (size_t)(t + 2) * kstep;
;             const char* a3 = a2 + kstep; const char* b3 = b2 + kstep;
;             PG8_LDB(B0, 0, 0); PG8_LDB(B1, 0, 1); PG8_SCHED; PG8_LDA(At, 0, 0); PG8_STAGE(PG8_SA(1, 1), a1 + hstepA, voffA);
;             PG8_WAIT_V(8); PG8_WAIT_L(0); PG8_BAR; PG8_MMA(0, 0, At, B0); PG8_MMA(0, 1, At, B1); PG8_BAR; PG8_SCHED;
;             PG8_LDA(At, 0, 1); PG8_STAGE(PG8_SB(0, 0), b2, voffB); PG8_STAGE(PG8_SB(0, 1), b2 + hstepB, voffB); PG8_STAGE(PG8_SA(0, 0), a2, voffA);
;             PG8_WAIT_V(8); PG8_WAIT_L(0); PG8_BAR; PG8_MMA(1, 0, At, B0); PG8_MMA(1, 1, At, B1); PG8_BAR; PG8_SCHED;
.LBB0_1689:
	ds_read_b128 v[144:147], v155
	ds_read_b128 v[148:151], v155 offset:1024
	ds_read_b128 v[160:163], v155 offset:2048
	ds_read_b128 v[164:167], v155 offset:3072
	ds_read_b128 v[168:171], v156
	ds_read_b128 v[172:175], v156 offset:1024
	ds_read_b128 v[176:179], v156 offset:2048
	ds_read_b128 v[180:183], v156 offset:3072
	s_add_u32 s28, s12, 0xfff80080
	s_addc_u32 s29, s13, -1
	s_cmp_eq_u32 s53, 28
	s_cselect_b32 s37, s14, s29
	s_cselect_b32 s36, s23, s28
	s_cselect_b32 s29, s21, s52
	s_cselect_b32 s28, s50, s51
	v_lshl_add_u64 v[218:219], s[12:13], 0, v[136:137]
	s_add_i32 m0, s34, 0xc000
	ds_read_b128 v[186:189], v157
	ds_read_b128 v[190:193], v157 offset:1024
	ds_read_b128 v[194:197], v157 offset:2048
	ds_read_b128 v[198:201], v157 offset:3072
	ds_read_b128 v[202:205], v157 offset:4096
	ds_read_b128 v[206:209], v157 offset:5120
	ds_read_b128 v[210:213], v157 offset:6144
	ds_read_b128 v[214:217], v157 offset:7168
	global_load_lds_dwordx4 v[218:219], off
	v_lshl_add_u64 v[218:219], s[12:13], 0, v[138:139]
	s_add_i32 m0, s34, 0xe000
	s_nop 0
	global_load_lds_dwordx4 v[218:219], off
	s_waitcnt vmcnt(8)
	s_waitcnt lgkmcnt(0)
	s_barrier
	s_waitcnt lgkmcnt(0)
	v_mfma_f32_16x16x32_bf16 v[124:127], v[144:147], v[186:189], v[124:127]
	v_mfma_f32_16x16x32_bf16 v[120:123], v[160:163], v[186:189], v[120:123]
	v_mfma_f32_16x16x32_bf16 v[108:111], v[144:147], v[194:197], v[108:111]
	v_mfma_f32_16x16x32_bf16 v[104:107], v[160:163], v[194:197], v[104:107]
	v_mfma_f32_16x16x32_bf16 v[92:95], v[144:147], v[202:205], v[92:95]
	v_mfma_f32_16x16x32_bf16 v[88:91], v[160:163], v[202:205], v[88:91]
	v_mfma_f32_16x16x32_bf16 v[76:79], v[144:147], v[210:213], v[76:79]
	v_mfma_f32_16x16x32_bf16 v[72:75], v[160:163], v[210:213], v[72:75]
	v_mfma_f32_16x16x32_bf16 v[124:127], v[148:151], v[190:193], v[124:127]
	v_mfma_f32_16x16x32_bf16 v[120:123], v[164:167], v[190:193], v[120:123]
	v_mfma_f32_16x16x32_bf16 v[108:111], v[148:151], v[198:201], v[108:111]
	v_mfma_f32_16x16x32_bf16 v[104:107], v[164:167], v[198:201], v[104:107]
	v_mfma_f32_16x16x32_bf16 v[92:95], v[148:151], v[206:209], v[92:95]
	v_mfma_f32_16x16x32_bf16 v[88:91], v[164:167], v[206:209], v[88:91]
	v_mfma_f32_16x16x32_bf16 v[76:79], v[148:151], v[214:217], v[76:79]
	v_mfma_f32_16x16x32_bf16 v[72:75], v[164:167], v[214:217], v[72:75]
	v_mfma_f32_16x16x32_bf16 v[116:119], v[168:171], v[186:189], v[116:119]
	v_mfma_f32_16x16x32_bf16 v[112:115], v[176:179], v[186:189], v[112:115]
	v_mfma_f32_16x16x32_bf16 v[100:103], v[168:171], v[194:197], v[100:103]
	v_mfma_f32_16x16x32_bf16 v[96:99], v[176:179], v[194:197], v[96:99]
	v_mfma_f32_16x16x32_bf16 v[84:87], v[168:171], v[202:205], v[84:87]
	v_mfma_f32_16x16x32_bf16 v[80:83], v[176:179], v[202:205], v[80:83]
	v_mfma_f32_16x16x32_bf16 v[68:71], v[168:171], v[210:213], v[68:71]
	v_mfma_f32_16x16x32_bf16 v[64:67], v[176:179], v[210:213], v[64:67]
	v_mfma_f32_16x16x32_bf16 v[116:119], v[172:175], v[190:193], v[116:119]
	v_mfma_f32_16x16x32_bf16 v[112:115], v[180:183], v[190:193], v[112:115]
	v_mfma_f32_16x16x32_bf16 v[100:103], v[172:175], v[198:201], v[100:103]
	v_mfma_f32_16x16x32_bf16 v[96:99], v[180:183], v[198:201], v[96:99]
	v_mfma_f32_16x16x32_bf16 v[84:87], v[172:175], v[206:209], v[84:87]
	v_mfma_f32_16x16x32_bf16 v[80:83], v[180:183], v[206:209], v[80:83]
	v_mfma_f32_16x16x32_bf16 v[68:71], v[172:175], v[214:217], v[68:71]
	v_mfma_f32_16x16x32_bf16 v[64:67], v[180:183], v[214:217], v[64:67]
	s_barrier
	s_add_i32 s54, s46, s16
	v_lshl_add_u64 v[218:219], s[28:29], 0, v[132:133]
	s_mov_b32 m0, s54
	ds_read_b128 v[186:189], v157 offset:16384
	ds_read_b128 v[190:193], v157 offset:17408
	ds_read_b128 v[194:197], v157 offset:18432
	ds_read_b128 v[198:201], v157 offset:19456
	ds_read_b128 v[202:205], v157 offset:20480
	ds_read_b128 v[206:209], v157 offset:21504
	ds_read_b128 v[210:213], v157 offset:22528
	ds_read_b128 v[214:217], v157 offset:23552
	global_load_lds_dwordx4 v[218:219], off
	s_add_i32 m0, s54, 0x2000
	s_add_u32 s54, s28, 0x80000
	v_lshl_add_u64 v[220:221], s[28:29], 0, v[128:129]
	s_addc_u32 s55, s29, 0
	s_add_i32 s56, s47, s16
	global_load_lds_dwordx4 v[220:221], off
	v_lshl_add_u64 v[222:223], s[54:55], 0, v[132:133]
	s_mov_b32 m0, s56
	v_lshl_add_u64 v[224:225], s[36:37], 0, v[130:131]
	global_load_lds_dwordx4 v[222:223], off
	v_lshl_add_u64 v[222:223], s[54:55], 0, v[128:129]
	s_add_i32 m0, s56, 0x2000
	s_nop 0
	global_load_lds_dwordx4 v[222:223], off
	v_lshl_add_u64 v[222:223], s[36:37], 0, v[134:135]
	s_mov_b32 m0, s34
	s_nop 0
	global_load_lds_dwordx4 v[222:223], off
	s_mov_b32 m0, s35
	s_nop 0
	global_load_lds_dwordx4 v[224:225], off
	s_waitcnt vmcnt(8)
	s_waitcnt lgkmcnt(0)
	s_barrier
; #define PG8_STAGE(bufoff, gbase, voff) do { _Pragma("unroll") for (int _i = 0; _i < 2; ++_i) \
;         __builtin_amdgcn_global_load_lds((const unsigned*)((const char*)(gbase) + (voff)[_i]), (LAS unsigned*)(lds + (bufoff) + ldsw + _i * 8192), 16, 0, 0); } while (0)
; #define PG8_LDA(dst, b, h) do { _Pragma("unroll") for (int m = 0; m < 4; ++m) _Pragma("unroll") for (int k = 0; k < 2; ++k) dst[m][k] = *(const LAS bf16x8*)(lds + PG8_SA(b, h) + aoff + m * 2048 + k * 1024); } while (0)
; #define PG8_LDB(dst, b, h) do { _Pragma("unroll") for (int n = 0; n < 2; ++n) _Pragma("unroll") for (int k = 0; k < 2; ++k) dst[n][k] = *(const LAS bf16x8*)(lds + PG8_SB(b, h) + boff + n * 2048 + k * 1024); } while (0)
; #define PG8_MMA(ai, bj, At, Bt) do { __builtin_amdgcn_s_setprio(1); _Pragma("unroll") for (int m = 0; m < 4; ++m) _Pragma("unroll") for (int n = 0; n < 2; ++n) _Pragma("unroll") for (int k = 0; k < 2; ++k) \
;         acc[ai][bj][m][n] = __builtin_amdgcn_mfma_f32_16x16x32_bf16(Bt[n][k], At[m][k], acc[ai][bj][m][n], 0, 0, 0); __builtin_amdgcn_s_setprio(0); } while (0)
; #define PG8_WAIT_V(n) asm volatile("s_waitcnt vmcnt(" #n ")" ::: "memory")
; #define PG8_WAIT_L(n) asm volatile("s_waitcnt lgkmcnt(" #n ")" ::: "memory")
; #define PG8_BAR __builtin_amdgcn_s_barrier()
; #define PG8_SCHED __builtin_amdgcn_sched_barrier(0)
; template <class Epi, bool ALIGN_EPI = PG8_ALIGN>
; __device__ __forceinline__ void gemm_phase(LAS unsigned char* lds, const Gemm g, const StaticOrder S, const Epi E) {
;     ...
;             PG8_WAIT_V(8); PG8_WAIT_L(0); PG8_BAR; PG8_MMA(1, 0, At, B0); PG8_MMA(1, 1, At, B1); PG8_BAR; PG8_SCHED;
;             PG8_LDB(B0, 1, 0); PG8_LDB(B1, 1, 1); PG8_SCHED; PG8_LDA(At, 1, 0); PG8_STAGE(PG8_SA(0, 1), a2 + hstepA, voffA);
;             PG8_WAIT_V(8); PG8_WAIT_L(0); PG8_BAR; PG8_MMA(0, 0, At, B0); PG8_MMA(0, 1, At, B1); PG8_BAR; PG8_SCHED;
	s_waitcnt lgkmcnt(0)
	v_mfma_f32_16x16x32_bf16 v[60:63], v[144:147], v[186:189], v[60:63]
	v_mfma_f32_16x16x32_bf16 v[56:59], v[160:163], v[186:189], v[56:59]
	v_mfma_f32_16x16x32_bf16 v[44:47], v[144:147], v[194:197], v[44:47]
	v_mfma_f32_16x16x32_bf16 v[40:43], v[160:163], v[194:197], v[40:43]
	v_mfma_f32_16x16x32_bf16 v[28:31], v[144:147], v[202:205], v[28:31]
	v_mfma_f32_16x16x32_bf16 v[24:27], v[160:163], v[202:205], v[24:27]
	v_mfma_f32_16x16x32_bf16 v[12:15], v[144:147], v[210:213], v[12:15]
	v_mfma_f32_16x16x32_bf16 v[8:11], v[160:163], v[210:213], v[8:11]
	v_mfma_f32_16x16x32_bf16 v[60:63], v[148:151], v[190:193], v[60:63]
	v_mfma_f32_16x16x32_bf16 v[56:59], v[164:167], v[190:193], v[56:59]
	v_mfma_f32_16x16x32_bf16 v[44:47], v[148:151], v[198:201], v[44:47]
	v_mfma_f32_16x16x32_bf16 v[40:43], v[164:167], v[198:201], v[40:43]
	v_mfma_f32_16x16x32_bf16 v[28:31], v[148:151], v[206:209], v[28:31]
	v_mfma_f32_16x16x32_bf16 v[24:27], v[164:167], v[206:209], v[24:27]
	v_mfma_f32_16x16x32_bf16 v[12:15], v[148:151], v[214:217], v[12:15]
	v_mfma_f32_16x16x32_bf16 v[8:11], v[164:167], v[214:217], v[8:11]
	v_mfma_f32_16x16x32_bf16 v[52:55], v[168:171], v[186:189], v[52:55]
	v_mfma_f32_16x16x32_bf16 v[48:51], v[176:179], v[186:189], v[48:51]
	v_mfma_f32_16x16x32_bf16 v[36:39], v[168:171], v[194:197], v[36:39]
	v_mfma_f32_16x16x32_bf16 v[32:35], v[176:179], v[194:197], v[32:35]
	v_mfma_f32_16x16x32_bf16 v[20:23], v[168:171], v[202:205], v[20:23]
	v_mfma_f32_16x16x32_bf16 v[16:19], v[176:179], v[202:205], v[16:19]
	v_mfma_f32_16x16x32_bf16 v[4:7], v[168:171], v[210:213], v[4:7]
	v_mfma_f32_16x16x32_bf16 v[0:3], v[176:179], v[210:213], v[0:3]
	v_mfma_f32_16x16x32_bf16 v[52:55], v[172:175], v[190:193], v[52:55]
	v_mfma_f32_16x16x32_bf16 v[48:51], v[180:183], v[190:193], v[48:51]
	v_mfma_f32_16x16x32_bf16 v[36:39], v[172:175], v[198:201], v[36:39]
	v_mfma_f32_16x16x32_bf16 v[32:35], v[180:183], v[198:201], v[32:35]
	v_mfma_f32_16x16x32_bf16 v[20:23], v[172:175], v[206:209], v[20:23]
	v_mfma_f32_16x16x32_bf16 v[16:19], v[180:183], v[206:209], v[16:19]
	v_mfma_f32_16x16x32_bf16 v[4:7], v[172:175], v[214:217], v[4:7]
	v_mfma_f32_16x16x32_bf16 v[0:3], v[180:183], v[214:217], v[0:3]
	s_barrier
	s_add_i32 s54, 0, 0x18000
	v_add_u32_e32 v159, s54, v153
	s_add_i32 s55, 0, 0x1c000
	ds_read_b128 v[144:147], v159
	ds_read_b128 v[148:151], v159 offset:1024
	ds_read_b128 v[160:163], v159 offset:2048
	ds_read_b128 v[164:167], v159 offset:3072
	v_add_u32_e32 v159, s55, v153
	ds_read_b128 v[168:171], v159
	ds_read_b128 v[172:175], v159 offset:1024
	ds_read_b128 v[176:179], v159 offset:2048
	ds_read_b128 v[180:183], v159 offset:3072
	s_add_u32 s36, s36, 0x80000
	s_addc_u32 s37, s37, 0
	s_mov_b32 m0, s38
	v_lshl_add_u64 v[226:227], s[36:37], 0, v[134:135]
	ds_read_b128 v[186:189], v157 offset:32768
	ds_read_b128 v[190:193], v157 offset:33792
	ds_read_b128 v[194:197], v157 offset:34816
	ds_read_b128 v[198:201], v157 offset:35840
	ds_read_b128 v[202:205], v157 offset:36864
	ds_read_b128 v[206:209], v157 offset:37888
	ds_read_b128 v[210:213], v157 offset:38912
	ds_read_b128 v[214:217], v157 offset:39936
	global_load_lds_dwordx4 v[226:227], off
	v_lshl_add_u64 v[226:227], s[36:37], 0, v[130:131]
	s_mov_b32 m0, s39
	s_nop 0
	global_load_lds_dwordx4 v[226:227], off
	s_waitcnt vmcnt(8)
	s_waitcnt lgkmcnt(0)
	s_barrier
	s_waitcnt lgkmcnt(0)
	v_mfma_f32_16x16x32_bf16 v[124:127], v[144:147], v[186:189], v[124:127]
	v_mfma_f32_16x16x32_bf16 v[120:123], v[160:163], v[186:189], v[120:123]
	v_mfma_f32_16x16x32_bf16 v[108:111], v[144:147], v[194:197], v[108:111]
	v_mfma_f32_16x16x32_bf16 v[104:107], v[160:163], v[194:197], v[104:107]
	v_mfma_f32_16x16x32_bf16 v[92:95], v[144:147], v[202:205], v[92:95]
	v_mfma_f32_16x16x32_bf16 v[88:91], v[160:163], v[202:205], v[88:91]
	v_mfma_f32_16x16x32_bf16 v[76:79], v[144:147], v[210:213], v[76:79]
	v_mfma_f32_16x16x32_bf16 v[72:75], v[160:163], v[210:213], v[72:75]
	v_mfma_f32_16x16x32_bf16 v[124:127], v[148:151], v[190:193], v[124:127]
	v_mfma_f32_16x16x32_bf16 v[120:123], v[164:167], v[190:193], v[120:123]
	v_mfma_f32_16x16x32_bf16 v[108:111], v[148:151], v[198:201], v[108:111]
	v_mfma_f32_16x16x32_bf16 v[104:107], v[164:167], v[198:201], v[104:107]
	v_mfma_f32_16x16x32_bf16 v[92:95], v[148:151], v[206:209], v[92:95]
	v_mfma_f32_16x16x32_bf16 v[88:91], v[164:167], v[206:209], v[88:91]
	v_mfma_f32_16x16x32_bf16 v[76:79], v[148:151], v[214:217], v[76:79]
	v_mfma_f32_16x16x32_bf16 v[72:75], v[164:167], v[214:217], v[72:75]
	v_mfma_f32_16x16x32_bf16 v[116:119], v[168:171], v[186:189], v[116:119]
	v_mfma_f32_16x16x32_bf16 v[112:115], v[176:179], v[186:189], v[112:115]
	v_mfma_f32_16x16x32_bf16 v[100:103], v[168:171], v[194:197], v[100:103]
	v_mfma_f32_16x16x32_bf16 v[96:99], v[176:179], v[194:197], v[96:99]
	v_mfma_f32_16x16x32_bf16 v[84:87], v[168:171], v[202:205], v[84:87]
	v_mfma_f32_16x16x32_bf16 v[80:83], v[176:179], v[202:205], v[80:83]
	v_mfma_f32_16x16x32_bf16 v[68:71], v[168:171], v[210:213], v[68:71]
	v_mfma_f32_16x16x32_bf16 v[64:67], v[176:179], v[210:213], v[64:67]
	v_mfma_f32_16x16x32_bf16 v[116:119], v[172:175], v[190:193], v[116:119]
	v_mfma_f32_16x16x32_bf16 v[112:115], v[180:183], v[190:193], v[112:115]
	v_mfma_f32_16x16x32_bf16 v[100:103], v[172:175], v[198:201], v[100:103]
	v_mfma_f32_16x16x32_bf16 v[96:99], v[180:183], v[198:201], v[96:99]
	v_mfma_f32_16x16x32_bf16 v[84:87], v[172:175], v[206:209], v[84:87]
	v_mfma_f32_16x16x32_bf16 v[80:83], v[180:183], v[206:209], v[80:83]
	v_mfma_f32_16x16x32_bf16 v[68:71], v[172:175], v[214:217], v[68:71]
	v_mfma_f32_16x16x32_bf16 v[64:67], v[180:183], v[214:217], v[64:67]
	s_barrier
; #define PG8_STAGE(bufoff, gbase, voff) do { _Pragma("unroll") for (int _i = 0; _i < 2; ++_i) \
;         __builtin_amdgcn_global_load_lds((const unsigned*)((const char*)(gbase) + (voff)[_i]), (LAS unsigned*)(lds + (bufoff) + ldsw + _i * 8192), 16, 0, 0); } while (0)
; #define PG8_LDA(dst, b, h) do { _Pragma("unroll") for (int m = 0; m < 4; ++m) _Pragma("unroll") for (int k = 0; k < 2; ++k) dst[m][k] = *(const LAS bf16x8*)(lds + PG8_SA(b, h) + aoff + m * 2048 + k * 1024); } while (0)
; #define PG8_MMA(ai, bj, At, Bt) do { __builtin_amdgcn_s_setprio(1); _Pragma("unroll") for (int m = 0; m < 4; ++m) _Pragma("unroll") for (int n = 0; n < 2; ++n) _Pragma("unroll") for (int k = 0; k < 2; ++k) \
;         acc[ai][bj][m][n] = __builtin_amdgcn_mfma_f32_16x16x32_bf16(Bt[n][k], At[m][k], acc[ai][bj][m][n], 0, 0, 0); __builtin_amdgcn_s_setprio(0); } while (0)
; #define PG8_WAIT_V(n) asm volatile("s_waitcnt vmcnt(" #n ")" ::: "memory")
; #define PG8_WAIT_L(n) asm volatile("s_waitcnt lgkmcnt(" #n ")" ::: "memory")
; #define PG8_BAR __builtin_amdgcn_s_barrier()
; #define PG8_SCHED __builtin_amdgcn_sched_barrier(0)
; template <class Epi, bool ALIGN_EPI = PG8_ALIGN>
; __device__ __forceinline__ void gemm_phase(LAS unsigned char* lds, const Gemm g, const StaticOrder S, const Epi E) {
;     ...
;             PG8_LDA(At, 1, 1); PG8_STAGE(PG8_SB(1, 0), b3, voffB); PG8_STAGE(PG8_SB(1, 1), b3 + hstepB, voffB); PG8_STAGE(PG8_SA(1, 0), a3, voffA);
;             PG8_WAIT_V(8); PG8_WAIT_L(0); PG8_BAR; PG8_MMA(1, 0, At, B0); PG8_MMA(1, 1, At, B1); PG8_BAR; PG8_SCHED;
;         }
;         if (ALIGN_EPI) { if (wr == 0) PG8_BAR; }
	s_add_i32 s36, s54, s16
	v_lshl_add_u64 v[218:219], v[218:219], 0, s[10:11]
	s_mov_b32 m0, s36
	ds_read_b128 v[186:189], v157 offset:49152
	ds_read_b128 v[190:193], v157 offset:50176
	ds_read_b128 v[194:197], v157 offset:51200
	ds_read_b128 v[198:201], v157 offset:52224
	ds_read_b128 v[202:205], v157 offset:53248
	ds_read_b128 v[206:209], v157 offset:54272
	ds_read_b128 v[210:213], v157 offset:55296
	ds_read_b128 v[214:217], v157 offset:56320
	global_load_lds_dwordx4 v[218:219], off
	s_add_i32 m0, s36, 0x2000
	s_add_u32 s28, s28, 0x80080
	v_lshl_add_u64 v[218:219], v[220:221], 0, s[10:11]
	s_addc_u32 s29, s29, 0
	s_add_i32 s36, s55, s16
	global_load_lds_dwordx4 v[218:219], off
	v_lshl_add_u64 v[218:219], s[28:29], 0, v[132:133]
	s_mov_b32 m0, s36
	s_nop 0
	global_load_lds_dwordx4 v[218:219], off
	v_lshl_add_u64 v[218:219], s[28:29], 0, v[128:129]
	s_add_i32 m0, s36, 0x2000
	s_nop 0
	global_load_lds_dwordx4 v[218:219], off
	v_lshl_add_u64 v[218:219], v[222:223], 0, s[10:11]
	s_mov_b32 m0, s43
	s_nop 0
	global_load_lds_dwordx4 v[218:219], off
	v_lshl_add_u64 v[218:219], v[224:225], 0, s[10:11]
	s_mov_b32 m0, s44
	s_nop 0
	global_load_lds_dwordx4 v[218:219], off
	s_waitcnt vmcnt(8)
	s_waitcnt lgkmcnt(0)
	s_barrier
	s_waitcnt lgkmcnt(0)
	v_mfma_f32_16x16x32_bf16 v[60:63], v[144:147], v[186:189], v[60:63]
	v_mfma_f32_16x16x32_bf16 v[56:59], v[160:163], v[186:189], v[56:59]
	v_mfma_f32_16x16x32_bf16 v[44:47], v[144:147], v[194:197], v[44:47]
	v_mfma_f32_16x16x32_bf16 v[40:43], v[160:163], v[194:197], v[40:43]
	v_mfma_f32_16x16x32_bf16 v[28:31], v[144:147], v[202:205], v[28:31]
	v_mfma_f32_16x16x32_bf16 v[24:27], v[160:163], v[202:205], v[24:27]
	v_mfma_f32_16x16x32_bf16 v[12:15], v[144:147], v[210:213], v[12:15]
	v_mfma_f32_16x16x32_bf16 v[8:11], v[160:163], v[210:213], v[8:11]
	v_mfma_f32_16x16x32_bf16 v[60:63], v[148:151], v[190:193], v[60:63]
	v_mfma_f32_16x16x32_bf16 v[56:59], v[164:167], v[190:193], v[56:59]
	v_mfma_f32_16x16x32_bf16 v[44:47], v[148:151], v[198:201], v[44:47]
	v_mfma_f32_16x16x32_bf16 v[40:43], v[164:167], v[198:201], v[40:43]
	v_mfma_f32_16x16x32_bf16 v[28:31], v[148:151], v[206:209], v[28:31]
	v_mfma_f32_16x16x32_bf16 v[24:27], v[164:167], v[206:209], v[24:27]
	v_mfma_f32_16x16x32_bf16 v[12:15], v[148:151], v[214:217], v[12:15]
	v_mfma_f32_16x16x32_bf16 v[8:11], v[164:167], v[214:217], v[8:11]
	v_mfma_f32_16x16x32_bf16 v[52:55], v[168:171], v[186:189], v[52:55]
	v_mfma_f32_16x16x32_bf16 v[48:51], v[176:179], v[186:189], v[48:51]
	v_mfma_f32_16x16x32_bf16 v[36:39], v[168:171], v[194:197], v[36:39]
	v_mfma_f32_16x16x32_bf16 v[32:35], v[176:179], v[194:197], v[32:35]
	v_mfma_f32_16x16x32_bf16 v[20:23], v[168:171], v[202:205], v[20:23]
	v_mfma_f32_16x16x32_bf16 v[16:19], v[176:179], v[202:205], v[16:19]
	v_mfma_f32_16x16x32_bf16 v[4:7], v[168:171], v[210:213], v[4:7]
	v_mfma_f32_16x16x32_bf16 v[0:3], v[176:179], v[210:213], v[0:3]
	v_mfma_f32_16x16x32_bf16 v[52:55], v[172:175], v[190:193], v[52:55]
	v_mfma_f32_16x16x32_bf16 v[48:51], v[180:183], v[190:193], v[48:51]
	v_mfma_f32_16x16x32_bf16 v[36:39], v[172:175], v[198:201], v[36:39]
	v_mfma_f32_16x16x32_bf16 v[32:35], v[180:183], v[198:201], v[32:35]
	v_mfma_f32_16x16x32_bf16 v[20:23], v[172:175], v[206:209], v[20:23]
	v_mfma_f32_16x16x32_bf16 v[16:19], v[180:183], v[206:209], v[16:19]
	v_mfma_f32_16x16x32_bf16 v[4:7], v[172:175], v[214:217], v[4:7]
	v_mfma_f32_16x16x32_bf16 v[0:3], v[180:183], v[214:217], v[0:3]
	s_barrier
	s_add_i32 s53, s53, 2
	s_add_u32 s12, s12, 0x100
	s_addc_u32 s13, s13, 0
	s_add_u32 s51, s51, 0x100
	s_addc_u32 s52, s52, 0
	s_cmp_gt_u32 s53, 29
	s_cbranch_scc0 .LBB0_1689
	s_and_b64 vcc, exec, s[18:19]
	s_cbranch_vccz .LBB0_1692
	s_barrier

; #define PG8_STAGE(bufoff, gbase, voff) do { _Pragma("unroll") for (int _i = 0; _i < 2; ++_i) \
;         __builtin_amdgcn_global_load_lds((const unsigned*)((const char*)(gbase) + (voff)[_i]), (LAS unsigned*)(lds + (bufoff) + ldsw + _i * 8192), 16, 0, 0); } while (0)
; #define PG8_LDA(dst, b, h) do { _Pragma("unroll") for (int m = 0; m < 4; ++m) _Pragma("unroll") for (int k = 0; k < 2; ++k) dst[m][k] = *(const LAS bf16x8*)(lds + PG8_SA(b, h) + aoff + m * 2048 + k * 1024); } while (0)
; #define PG8_LDB(dst, b, h) do { _Pragma("unroll") for (int n = 0; n < 2; ++n) _Pragma("unroll") for (int k = 0; k < 2; ++k) dst[n][k] = *(const LAS bf16x8*)(lds + PG8_SB(b, h) + boff + n * 2048 + k * 1024); } while (0)
; #define PG8_MMA(ai, bj, At, Bt) do { __builtin_amdgcn_s_setprio(1); _Pragma("unroll") for (int m = 0; m < 4; ++m) _Pragma("unroll") for (int n = 0; n < 2; ++n) _Pragma("unroll") for (int k = 0; k < 2; ++k) \
;         acc[ai][bj][m][n] = __builtin_amdgcn_mfma_f32_16x16x32_bf16(Bt[n][k], At[m][k], acc[ai][bj][m][n], 0, 0, 0); __builtin_amdgcn_s_setprio(0); } while (0)
; #define PG8_WAIT_V(n) asm volatile("s_waitcnt vmcnt(" #n ")" ::: "memory")
; #define PG8_WAIT_L(n) asm volatile("s_waitcnt lgkmcnt(" #n ")" ::: "memory")
; #define PG8_BAR __builtin_amdgcn_s_barrier()
; #define PG8_SCHED __builtin_amdgcn_sched_barrier(0)
; template <class Epi, bool ALIGN_EPI = PG8_ALIGN>
; __device__ __forceinline__ void gemm_phase(LAS unsigned char* lds, const Gemm g, const StaticOrder S, const Epi E) {
;     ...
;         for (int t = 0; t < nt; t += 2) {
;             const bool last = (t == nt - 2);
;             const char* a1 = cA + (size_t)(t + 1) * kstep;
;             const char* a2 = last ? nA : cA + (size_t)(t + 2) * kstep; const char* b2 = last ? nB : cB + (size_t)(t + 2) * kstep;
;             const char* a3 = a2 + kstep; const char* b3 = b2 + kstep;
;             PG8_LDB(B0, 0, 0); PG8_LDB(B1, 0, 1); PG8_SCHED; PG8_LDA(At, 0, 0); PG8_STAGE(PG8_SA(1, 1), a1 + hstepA, voffA);
;             PG8_WAIT_V(8); PG8_WAIT_L(0); PG8_BAR; PG8_MMA(0, 0, At, B0); PG8_MMA(0, 1, At, B1); PG8_BAR; PG8_SCHED;
;             PG8_LDA(At, 0, 1); PG8_STAGE(PG8_SB(0, 0), b2, voffB); PG8_STAGE(PG8_SB(0, 1), b2 + hstepB, voffB); PG8_STAGE(PG8_SA(0, 0), a2, voffA);
;             PG8_WAIT_V(8); PG8_WAIT_L(0); PG8_BAR; PG8_MMA(1, 0, At, B0); PG8_MMA(1, 1, At, B1); PG8_BAR; PG8_SCHED;
.LBB0_1772:
	ds_read_b128 v[146:149], v153
	ds_read_b128 v[156:159], v153 offset:1024
	ds_read_b128 v[160:163], v153 offset:2048
	ds_read_b128 v[164:167], v153 offset:3072
	ds_read_b128 v[168:171], v154
	ds_read_b128 v[172:175], v154 offset:1024
	ds_read_b128 v[176:179], v154 offset:2048
	ds_read_b128 v[180:183], v154 offset:3072
	s_add_u32 s26, s24, 0xffea0080
	s_addc_u32 s27, s25, -1
	s_cmpk_eq_i32 s52, 0x54
	s_cselect_b32 s29, s3, s27
	s_cselect_b32 s28, s2, s26
	s_cselect_b32 s27, s23, s51
	s_cselect_b32 s26, s22, s50
	v_lshl_add_u64 v[150:151], s[24:25], 0, v[138:139]
	s_add_i32 m0, s33, 0xc000
	ds_read_b128 v[184:187], v155
	ds_read_b128 v[188:191], v155 offset:1024
	ds_read_b128 v[192:195], v155 offset:2048
	ds_read_b128 v[196:199], v155 offset:3072
	ds_read_b128 v[200:203], v155 offset:4096
	ds_read_b128 v[204:207], v155 offset:5120
	ds_read_b128 v[208:211], v155 offset:6144
	ds_read_b128 v[212:215], v155 offset:7168
	global_load_lds_dwordx4 v[150:151], off
	v_lshl_add_u64 v[150:151], s[24:25], 0, v[140:141]
	s_add_i32 m0, s33, 0xe000
	s_nop 0
	global_load_lds_dwordx4 v[150:151], off
	s_waitcnt vmcnt(8)
	s_waitcnt lgkmcnt(0)
	s_barrier
	s_waitcnt lgkmcnt(0)
	v_mfma_f32_16x16x32_bf16 v[124:127], v[146:149], v[184:187], v[124:127]
	v_mfma_f32_16x16x32_bf16 v[120:123], v[160:163], v[184:187], v[120:123]
	v_mfma_f32_16x16x32_bf16 v[108:111], v[146:149], v[192:195], v[108:111]
	v_mfma_f32_16x16x32_bf16 v[104:107], v[160:163], v[192:195], v[104:107]
	v_mfma_f32_16x16x32_bf16 v[92:95], v[146:149], v[200:203], v[92:95]
	v_mfma_f32_16x16x32_bf16 v[88:91], v[160:163], v[200:203], v[88:91]
	v_mfma_f32_16x16x32_bf16 v[76:79], v[146:149], v[208:211], v[76:79]
	v_mfma_f32_16x16x32_bf16 v[72:75], v[160:163], v[208:211], v[72:75]
	v_mfma_f32_16x16x32_bf16 v[124:127], v[156:159], v[188:191], v[124:127]
	v_mfma_f32_16x16x32_bf16 v[120:123], v[164:167], v[188:191], v[120:123]
	v_mfma_f32_16x16x32_bf16 v[108:111], v[156:159], v[196:199], v[108:111]
	v_mfma_f32_16x16x32_bf16 v[104:107], v[164:167], v[196:199], v[104:107]
	v_mfma_f32_16x16x32_bf16 v[92:95], v[156:159], v[204:207], v[92:95]
	v_mfma_f32_16x16x32_bf16 v[88:91], v[164:167], v[204:207], v[88:91]
	v_mfma_f32_16x16x32_bf16 v[76:79], v[156:159], v[212:215], v[76:79]
	v_mfma_f32_16x16x32_bf16 v[72:75], v[164:167], v[212:215], v[72:75]
	v_mfma_f32_16x16x32_bf16 v[116:119], v[168:171], v[184:187], v[116:119]
	v_mfma_f32_16x16x32_bf16 v[112:115], v[176:179], v[184:187], v[112:115]
	v_mfma_f32_16x16x32_bf16 v[100:103], v[168:171], v[192:195], v[100:103]
	v_mfma_f32_16x16x32_bf16 v[96:99], v[176:179], v[192:195], v[96:99]
	v_mfma_f32_16x16x32_bf16 v[84:87], v[168:171], v[200:203], v[84:87]
	v_mfma_f32_16x16x32_bf16 v[80:83], v[176:179], v[200:203], v[80:83]
	v_mfma_f32_16x16x32_bf16 v[68:71], v[168:171], v[208:211], v[68:71]
	v_mfma_f32_16x16x32_bf16 v[64:67], v[176:179], v[208:211], v[64:67]
	v_mfma_f32_16x16x32_bf16 v[116:119], v[172:175], v[188:191], v[116:119]
	v_mfma_f32_16x16x32_bf16 v[112:115], v[180:183], v[188:191], v[112:115]
	v_mfma_f32_16x16x32_bf16 v[100:103], v[172:175], v[196:199], v[100:103]
	v_mfma_f32_16x16x32_bf16 v[96:99], v[180:183], v[196:199], v[96:99]
	v_mfma_f32_16x16x32_bf16 v[84:87], v[172:175], v[204:207], v[84:87]
	v_mfma_f32_16x16x32_bf16 v[80:83], v[180:183], v[204:207], v[80:83]
	v_mfma_f32_16x16x32_bf16 v[68:71], v[172:175], v[212:215], v[68:71]
	v_mfma_f32_16x16x32_bf16 v[64:67], v[180:183], v[212:215], v[64:67]
	s_barrier
	s_add_i32 s53, s41, s17
	v_lshl_add_u64 v[150:151], s[26:27], 0, v[130:131]
	s_mov_b32 m0, s53
	ds_read_b128 v[184:187], v155 offset:16384
	ds_read_b128 v[188:191], v155 offset:17408
	ds_read_b128 v[192:195], v155 offset:18432
	ds_read_b128 v[196:199], v155 offset:19456
	ds_read_b128 v[200:203], v155 offset:20480
	ds_read_b128 v[204:207], v155 offset:21504
	ds_read_b128 v[208:211], v155 offset:22528
	ds_read_b128 v[212:215], v155 offset:23552
	global_load_lds_dwordx4 v[150:151], off
	s_add_i32 m0, s53, 0x2000
	s_add_u32 s54, s26, 0x160000
	v_lshl_add_u64 v[216:217], s[26:27], 0, v[134:135]
	s_addc_u32 s55, s27, 0
	s_add_i32 s53, s42, s17
	global_load_lds_dwordx4 v[216:217], off
	v_lshl_add_u64 v[218:219], s[54:55], 0, v[130:131]
	s_mov_b32 m0, s53
	v_lshl_add_u64 v[220:221], s[28:29], 0, v[132:133]
	global_load_lds_dwordx4 v[218:219], off
	v_lshl_add_u64 v[218:219], s[54:55], 0, v[134:135]
	s_add_i32 m0, s53, 0x2000
	s_nop 0
	global_load_lds_dwordx4 v[218:219], off
	v_lshl_add_u64 v[218:219], s[28:29], 0, v[128:129]
	s_mov_b32 m0, s33
	s_nop 0
	global_load_lds_dwordx4 v[218:219], off
	s_mov_b32 m0, s34
	s_nop 0
	global_load_lds_dwordx4 v[220:221], off
	s_waitcnt vmcnt(8)
	s_waitcnt lgkmcnt(0)
	s_barrier
; #define PG8_STAGE(bufoff, gbase, voff) do { _Pragma("unroll") for (int _i = 0; _i < 2; ++_i) \
;         __builtin_amdgcn_global_load_lds((const unsigned*)((const char*)(gbase) + (voff)[_i]), (LAS unsigned*)(lds + (bufoff) + ldsw + _i * 8192), 16, 0, 0); } while (0)
; #define PG8_LDA(dst, b, h) do { _Pragma("unroll") for (int m = 0; m < 4; ++m) _Pragma("unroll") for (int k = 0; k < 2; ++k) dst[m][k] = *(const LAS bf16x8*)(lds + PG8_SA(b, h) + aoff + m * 2048 + k * 1024); } while (0)
; #define PG8_LDB(dst, b, h) do { _Pragma("unroll") for (int n = 0; n < 2; ++n) _Pragma("unroll") for (int k = 0; k < 2; ++k) dst[n][k] = *(const LAS bf16x8*)(lds + PG8_SB(b, h) + boff + n * 2048 + k * 1024); } while (0)
; #define PG8_MMA(ai, bj, At, Bt) do { __builtin_amdgcn_s_setprio(1); _Pragma("unroll") for (int m = 0; m < 4; ++m) _Pragma("unroll") for (int n = 0; n < 2; ++n) _Pragma("unroll") for (int k = 0; k < 2; ++k) \
;         acc[ai][bj][m][n] = __builtin_amdgcn_mfma_f32_16x16x32_bf16(Bt[n][k], At[m][k], acc[ai][bj][m][n], 0, 0, 0); __builtin_amdgcn_s_setprio(0); } while (0)
; #define PG8_WAIT_V(n) asm volatile("s_waitcnt vmcnt(" #n ")" ::: "memory")
; #define PG8_WAIT_L(n) asm volatile("s_waitcnt lgkmcnt(" #n ")" ::: "memory")
; #define PG8_BAR __builtin_amdgcn_s_barrier()
; #define PG8_SCHED __builtin_amdgcn_sched_barrier(0)
; template <class Epi, bool ALIGN_EPI = PG8_ALIGN>
; __device__ __forceinline__ void gemm_phase(LAS unsigned char* lds, const Gemm g, const StaticOrder S, const Epi E) {
;     ...
;             PG8_WAIT_V(8); PG8_WAIT_L(0); PG8_BAR; PG8_MMA(1, 0, At, B0); PG8_MMA(1, 1, At, B1); PG8_BAR; PG8_SCHED;
;             PG8_LDB(B0, 1, 0); PG8_LDB(B1, 1, 1); PG8_SCHED; PG8_LDA(At, 1, 0); PG8_STAGE(PG8_SA(0, 1), a2 + hstepA, voffA);
;             PG8_WAIT_V(8); PG8_WAIT_L(0); PG8_BAR; PG8_MMA(0, 0, At, B0); PG8_MMA(0, 1, At, B1); PG8_BAR; PG8_SCHED;
	s_waitcnt lgkmcnt(0)
	v_mfma_f32_16x16x32_bf16 v[60:63], v[146:149], v[184:187], v[60:63]
	v_mfma_f32_16x16x32_bf16 v[56:59], v[160:163], v[184:187], v[56:59]
	v_mfma_f32_16x16x32_bf16 v[44:47], v[146:149], v[192:195], v[44:47]
	v_mfma_f32_16x16x32_bf16 v[40:43], v[160:163], v[192:195], v[40:43]
	v_mfma_f32_16x16x32_bf16 v[28:31], v[146:149], v[200:203], v[28:31]
	v_mfma_f32_16x16x32_bf16 v[24:27], v[160:163], v[200:203], v[24:27]
	v_mfma_f32_16x16x32_bf16 v[12:15], v[146:149], v[208:211], v[12:15]
	v_mfma_f32_16x16x32_bf16 v[8:11], v[160:163], v[208:211], v[8:11]
	v_mfma_f32_16x16x32_bf16 v[60:63], v[156:159], v[188:191], v[60:63]
	v_mfma_f32_16x16x32_bf16 v[56:59], v[164:167], v[188:191], v[56:59]
	v_mfma_f32_16x16x32_bf16 v[44:47], v[156:159], v[196:199], v[44:47]
	v_mfma_f32_16x16x32_bf16 v[40:43], v[164:167], v[196:199], v[40:43]
	v_mfma_f32_16x16x32_bf16 v[28:31], v[156:159], v[204:207], v[28:31]
	v_mfma_f32_16x16x32_bf16 v[24:27], v[164:167], v[204:207], v[24:27]
	v_mfma_f32_16x16x32_bf16 v[12:15], v[156:159], v[212:215], v[12:15]
	v_mfma_f32_16x16x32_bf16 v[8:11], v[164:167], v[212:215], v[8:11]
	v_mfma_f32_16x16x32_bf16 v[52:55], v[168:171], v[184:187], v[52:55]
	v_mfma_f32_16x16x32_bf16 v[48:51], v[176:179], v[184:187], v[48:51]
	v_mfma_f32_16x16x32_bf16 v[36:39], v[168:171], v[192:195], v[36:39]
	v_mfma_f32_16x16x32_bf16 v[32:35], v[176:179], v[192:195], v[32:35]
	v_mfma_f32_16x16x32_bf16 v[20:23], v[168:171], v[200:203], v[20:23]
	v_mfma_f32_16x16x32_bf16 v[16:19], v[176:179], v[200:203], v[16:19]
	v_mfma_f32_16x16x32_bf16 v[4:7], v[168:171], v[208:211], v[4:7]
	v_mfma_f32_16x16x32_bf16 v[0:3], v[176:179], v[208:211], v[0:3]
	v_mfma_f32_16x16x32_bf16 v[52:55], v[172:175], v[188:191], v[52:55]
	v_mfma_f32_16x16x32_bf16 v[48:51], v[180:183], v[188:191], v[48:51]
	v_mfma_f32_16x16x32_bf16 v[36:39], v[172:175], v[196:199], v[36:39]
	v_mfma_f32_16x16x32_bf16 v[32:35], v[180:183], v[196:199], v[32:35]
	v_mfma_f32_16x16x32_bf16 v[20:23], v[172:175], v[204:207], v[20:23]
	v_mfma_f32_16x16x32_bf16 v[16:19], v[180:183], v[204:207], v[16:19]
	v_mfma_f32_16x16x32_bf16 v[4:7], v[172:175], v[212:215], v[4:7]
	v_mfma_f32_16x16x32_bf16 v[0:3], v[180:183], v[212:215], v[0:3]
	s_barrier
	s_add_i32 s53, 0, 0x18000
	s_add_i32 s54, 0, 0x1c000
	v_add_u32_e32 v164, s53, v152
	v_add_u32_e32 v180, s54, v152
	ds_read_b128 v[146:149], v164
	ds_read_b128 v[156:159], v164 offset:1024
	ds_read_b128 v[160:163], v164 offset:2048
	ds_read_b128 v[164:167], v164 offset:3072
	ds_read_b128 v[168:171], v180
	ds_read_b128 v[172:175], v180 offset:1024
	ds_read_b128 v[176:179], v180 offset:2048
	ds_read_b128 v[180:183], v180 offset:3072
	s_add_u32 s28, s28, 0x160000
	s_addc_u32 s29, s29, 0
	s_mov_b32 m0, s35
	v_lshl_add_u64 v[222:223], s[28:29], 0, v[128:129]
	ds_read_b128 v[184:187], v155 offset:32768
	ds_read_b128 v[188:191], v155 offset:33792
	ds_read_b128 v[192:195], v155 offset:34816
	ds_read_b128 v[196:199], v155 offset:35840
	ds_read_b128 v[200:203], v155 offset:36864
	ds_read_b128 v[204:207], v155 offset:37888
	ds_read_b128 v[208:211], v155 offset:38912
	ds_read_b128 v[212:215], v155 offset:39936
	global_load_lds_dwordx4 v[222:223], off
	v_lshl_add_u64 v[222:223], s[28:29], 0, v[132:133]
	s_mov_b32 m0, s36
	s_nop 0
	global_load_lds_dwordx4 v[222:223], off
	s_waitcnt vmcnt(8)
	s_waitcnt lgkmcnt(0)
	s_barrier
	s_waitcnt lgkmcnt(0)
	v_mfma_f32_16x16x32_bf16 v[124:127], v[146:149], v[184:187], v[124:127]
	v_mfma_f32_16x16x32_bf16 v[120:123], v[160:163], v[184:187], v[120:123]
	v_mfma_f32_16x16x32_bf16 v[108:111], v[146:149], v[192:195], v[108:111]
	v_mfma_f32_16x16x32_bf16 v[104:107], v[160:163], v[192:195], v[104:107]
	v_mfma_f32_16x16x32_bf16 v[92:95], v[146:149], v[200:203], v[92:95]
	v_mfma_f32_16x16x32_bf16 v[88:91], v[160:163], v[200:203], v[88:91]
	v_mfma_f32_16x16x32_bf16 v[76:79], v[146:149], v[208:211], v[76:79]
	v_mfma_f32_16x16x32_bf16 v[72:75], v[160:163], v[208:211], v[72:75]
	v_mfma_f32_16x16x32_bf16 v[124:127], v[156:159], v[188:191], v[124:127]
	v_mfma_f32_16x16x32_bf16 v[120:123], v[164:167], v[188:191], v[120:123]
	v_mfma_f32_16x16x32_bf16 v[108:111], v[156:159], v[196:199], v[108:111]
	v_mfma_f32_16x16x32_bf16 v[104:107], v[164:167], v[196:199], v[104:107]
	v_mfma_f32_16x16x32_bf16 v[92:95], v[156:159], v[204:207], v[92:95]
	v_mfma_f32_16x16x32_bf16 v[88:91], v[164:167], v[204:207], v[88:91]
	v_mfma_f32_16x16x32_bf16 v[76:79], v[156:159], v[212:215], v[76:79]
	v_mfma_f32_16x16x32_bf16 v[72:75], v[164:167], v[212:215], v[72:75]
	v_mfma_f32_16x16x32_bf16 v[116:119], v[168:171], v[184:187], v[116:119]
	v_mfma_f32_16x16x32_bf16 v[112:115], v[176:179], v[184:187], v[112:115]
	v_mfma_f32_16x16x32_bf16 v[100:103], v[168:171], v[192:195], v[100:103]
	v_mfma_f32_16x16x32_bf16 v[96:99], v[176:179], v[192:195], v[96:99]
	v_mfma_f32_16x16x32_bf16 v[84:87], v[168:171], v[200:203], v[84:87]
	v_mfma_f32_16x16x32_bf16 v[80:83], v[176:179], v[200:203], v[80:83]
	v_mfma_f32_16x16x32_bf16 v[68:71], v[168:171], v[208:211], v[68:71]
	v_mfma_f32_16x16x32_bf16 v[64:67], v[176:179], v[208:211], v[64:67]
	v_mfma_f32_16x16x32_bf16 v[116:119], v[172:175], v[188:191], v[116:119]
	v_mfma_f32_16x16x32_bf16 v[112:115], v[180:183], v[188:191], v[112:115]
	v_mfma_f32_16x16x32_bf16 v[100:103], v[172:175], v[196:199], v[100:103]
	v_mfma_f32_16x16x32_bf16 v[96:99], v[180:183], v[196:199], v[96:99]
	v_mfma_f32_16x16x32_bf16 v[84:87], v[172:175], v[204:207], v[84:87]
	v_mfma_f32_16x16x32_bf16 v[80:83], v[180:183], v[204:207], v[80:83]
	v_mfma_f32_16x16x32_bf16 v[68:71], v[172:175], v[212:215], v[68:71]
	v_mfma_f32_16x16x32_bf16 v[64:67], v[180:183], v[212:215], v[64:67]
	s_barrier
; #define PG8_STAGE(bufoff, gbase, voff) do { _Pragma("unroll") for (int _i = 0; _i < 2; ++_i) \
;         __builtin_amdgcn_global_load_lds((const unsigned*)((const char*)(gbase) + (voff)[_i]), (LAS unsigned*)(lds + (bufoff) + ldsw + _i * 8192), 16, 0, 0); } while (0)
; #define PG8_LDA(dst, b, h) do { _Pragma("unroll") for (int m = 0; m < 4; ++m) _Pragma("unroll") for (int k = 0; k < 2; ++k) dst[m][k] = *(const LAS bf16x8*)(lds + PG8_SA(b, h) + aoff + m * 2048 + k * 1024); } while (0)
; #define PG8_MMA(ai, bj, At, Bt) do { __builtin_amdgcn_s_setprio(1); _Pragma("unroll") for (int m = 0; m < 4; ++m) _Pragma("unroll") for (int n = 0; n < 2; ++n) _Pragma("unroll") for (int k = 0; k < 2; ++k) \
;         acc[ai][bj][m][n] = __builtin_amdgcn_mfma_f32_16x16x32_bf16(Bt[n][k], At[m][k], acc[ai][bj][m][n], 0, 0, 0); __builtin_amdgcn_s_setprio(0); } while (0)
; #define PG8_WAIT_V(n) asm volatile("s_waitcnt vmcnt(" #n ")" ::: "memory")
; #define PG8_WAIT_L(n) asm volatile("s_waitcnt lgkmcnt(" #n ")" ::: "memory")
; #define PG8_BAR __builtin_amdgcn_s_barrier()
; #define PG8_SCHED __builtin_amdgcn_sched_barrier(0)
; template <class Epi, bool ALIGN_EPI = PG8_ALIGN>
; __device__ __forceinline__ void gemm_phase(LAS unsigned char* lds, const Gemm g, const StaticOrder S, const Epi E) {
;     ...
;             PG8_LDA(At, 1, 1); PG8_STAGE(PG8_SB(1, 0), b3, voffB); PG8_STAGE(PG8_SB(1, 1), b3 + hstepB, voffB); PG8_STAGE(PG8_SA(1, 0), a3, voffA);
;             PG8_WAIT_V(8); PG8_WAIT_L(0); PG8_BAR; PG8_MMA(1, 0, At, B0); PG8_MMA(1, 1, At, B1); PG8_BAR; PG8_SCHED;
;         }
;         if (ALIGN_EPI) { if (wr == 0) PG8_BAR; }
	s_add_i32 s28, s53, s17
	v_lshl_add_u64 v[150:151], v[150:151], 0, s[8:9]
	s_mov_b32 m0, s28
	ds_read_b128 v[184:187], v155 offset:49152
	ds_read_b128 v[188:191], v155 offset:50176
	ds_read_b128 v[192:195], v155 offset:51200
	ds_read_b128 v[196:199], v155 offset:52224
	ds_read_b128 v[200:203], v155 offset:53248
	ds_read_b128 v[204:207], v155 offset:54272
	ds_read_b128 v[208:211], v155 offset:55296
	ds_read_b128 v[212:215], v155 offset:56320
	global_load_lds_dwordx4 v[150:151], off
	s_add_i32 m0, s28, 0x2000
	s_add_u32 s26, s26, 0x160080
	v_lshl_add_u64 v[150:151], v[216:217], 0, s[8:9]
	s_addc_u32 s27, s27, 0
	s_add_i32 s28, s54, s17
	global_load_lds_dwordx4 v[150:151], off
	v_lshl_add_u64 v[150:151], s[26:27], 0, v[130:131]
	s_mov_b32 m0, s28
	s_nop 0
	global_load_lds_dwordx4 v[150:151], off
	v_lshl_add_u64 v[150:151], s[26:27], 0, v[134:135]
	s_add_i32 m0, s28, 0x2000
	s_nop 0
	global_load_lds_dwordx4 v[150:151], off
	v_lshl_add_u64 v[150:151], v[218:219], 0, s[8:9]
	s_mov_b32 m0, s38
	s_nop 0
	global_load_lds_dwordx4 v[150:151], off
	v_lshl_add_u64 v[150:151], v[220:221], 0, s[8:9]
	s_mov_b32 m0, s39
	s_nop 0
	global_load_lds_dwordx4 v[150:151], off
	s_waitcnt vmcnt(8)
	s_waitcnt lgkmcnt(0)
	s_barrier
	s_waitcnt lgkmcnt(0)
	v_mfma_f32_16x16x32_bf16 v[60:63], v[146:149], v[184:187], v[60:63]
	v_mfma_f32_16x16x32_bf16 v[56:59], v[160:163], v[184:187], v[56:59]
	v_mfma_f32_16x16x32_bf16 v[44:47], v[146:149], v[192:195], v[44:47]
	v_mfma_f32_16x16x32_bf16 v[40:43], v[160:163], v[192:195], v[40:43]
	v_mfma_f32_16x16x32_bf16 v[28:31], v[146:149], v[200:203], v[28:31]
	v_mfma_f32_16x16x32_bf16 v[24:27], v[160:163], v[200:203], v[24:27]
	v_mfma_f32_16x16x32_bf16 v[12:15], v[146:149], v[208:211], v[12:15]
	v_mfma_f32_16x16x32_bf16 v[8:11], v[160:163], v[208:211], v[8:11]
	v_mfma_f32_16x16x32_bf16 v[60:63], v[156:159], v[188:191], v[60:63]
	v_mfma_f32_16x16x32_bf16 v[56:59], v[164:167], v[188:191], v[56:59]
	v_mfma_f32_16x16x32_bf16 v[44:47], v[156:159], v[196:199], v[44:47]
	v_mfma_f32_16x16x32_bf16 v[40:43], v[164:167], v[196:199], v[40:43]
	v_mfma_f32_16x16x32_bf16 v[28:31], v[156:159], v[204:207], v[28:31]
	v_mfma_f32_16x16x32_bf16 v[24:27], v[164:167], v[204:207], v[24:27]
	v_mfma_f32_16x16x32_bf16 v[12:15], v[156:159], v[212:215], v[12:15]
	v_mfma_f32_16x16x32_bf16 v[8:11], v[164:167], v[212:215], v[8:11]
	v_mfma_f32_16x16x32_bf16 v[52:55], v[168:171], v[184:187], v[52:55]
	v_mfma_f32_16x16x32_bf16 v[48:51], v[176:179], v[184:187], v[48:51]
	v_mfma_f32_16x16x32_bf16 v[36:39], v[168:171], v[192:195], v[36:39]
	v_mfma_f32_16x16x32_bf16 v[32:35], v[176:179], v[192:195], v[32:35]
	v_mfma_f32_16x16x32_bf16 v[20:23], v[168:171], v[200:203], v[20:23]
	v_mfma_f32_16x16x32_bf16 v[16:19], v[176:179], v[200:203], v[16:19]
	v_mfma_f32_16x16x32_bf16 v[4:7], v[168:171], v[208:211], v[4:7]
	v_mfma_f32_16x16x32_bf16 v[0:3], v[176:179], v[208:211], v[0:3]
	v_mfma_f32_16x16x32_bf16 v[52:55], v[172:175], v[188:191], v[52:55]
	v_mfma_f32_16x16x32_bf16 v[48:51], v[180:183], v[188:191], v[48:51]
	v_mfma_f32_16x16x32_bf16 v[36:39], v[172:175], v[196:199], v[36:39]
	v_mfma_f32_16x16x32_bf16 v[32:35], v[180:183], v[196:199], v[32:35]
	v_mfma_f32_16x16x32_bf16 v[20:23], v[172:175], v[204:207], v[20:23]
	v_mfma_f32_16x16x32_bf16 v[16:19], v[180:183], v[204:207], v[16:19]
	v_mfma_f32_16x16x32_bf16 v[4:7], v[172:175], v[212:215], v[4:7]
	v_mfma_f32_16x16x32_bf16 v[0:3], v[180:183], v[212:215], v[0:3]
	s_barrier
	s_add_i32 s52, s52, 2
	s_add_u32 s24, s24, 0x100
	s_addc_u32 s25, s25, 0
	s_add_u32 s50, s50, 0x100
	s_addc_u32 s51, s51, 0
	s_cmpk_gt_u32 s52, 0x55
	s_cbranch_scc0 .LBB0_1772
	s_and_b64 vcc, exec, s[10:11]
	s_cbranch_vccz .LBB0_1775
	s_barrier
